# GEMM K-loops: LDS-DMA loads take the scalar base + 32-bit lane offset directly (saddr form), 118 64-bit v_lshl_add_u64 address ops removed from the load segments
# speedup vs baseline: 1.0194x; 1.0194x over previous
;     DI bool next(int i, Unit& u) const { if (i > 0 || c >= 64) return false; u.pm = c & 31; u.pn = 0; u.src = c >> 5; return true; }
; #define PG8_STAGE(bufoff, gbase, voff) do { _Pragma("unroll") for (int _i = 0; _i < 2; ++_i) \
;         __builtin_amdgcn_global_load_lds((const unsigned*)((const char*)(gbase) + (voff)[_i]), (LAS unsigned*)(lds + (bufoff) + ldsw + _i * 8192), 16, 0, 0); } while (0)
; #define PG8_LDA(dst, b, h) do { _Pragma("unroll") for (int m = 0; m < 4; ++m) _Pragma("unroll") for (int k = 0; k < 2; ++k) dst[m][k] = *(const LAS bf16x8*)(lds + PG8_SA(b, h) + aoff + m * 2048 + k * 1024); } while (0)
; #define PG8_WAIT_V(n) asm volatile("s_waitcnt vmcnt(" #n ")" ::: "memory")
; #define PG8_WAIT_L(n) asm volatile("s_waitcnt lgkmcnt(" #n ")" ::: "memory")
; #define PG8_BAR __builtin_amdgcn_s_barrier()
; template <class Epi, class Sched>
; DI void gemm_phase(LAS unsigned char* lds, const Gemm g, const Sched& S, const Epi& E) {
;     ...
;         const bool has_next = S.next(ui + 1, nxt);
;         E.pre(pre, cur, wr, fr);
;         const char* nA = has_next ? (const char*)(nxt.src ? g.A1 : g.A0) + (size_t)nxt.pm * tstepA : cA; const char* nB = has_next ? (const char*)(nxt.src ? g.B1 : g.B0) + (size_t)nxt.pn * tstepB : cB;
;         for (int t = 0; t < nt; t += 2) {
;             const bool last = (t == nt - 2);
;             const char* a1 = cA + (size_t)(t + 1) * kstep;
;             const char* a2 = last ? nA : cA + (size_t)(t + 2) * kstep; const char* b2 = last ? nB : cB + (size_t)(t + 2) * kstep;
;             const char* a3 = a2 + kstep; const char* b3 = b2 + kstep;
;             PG8_LDB(B0, 0, 0); PG8_LDB(B1, 0, 1); PG8_SCHED; PG8_LDA(At, 0, 0); PG8_STAGE(PG8_SA(1, 1), a1 + hstepA, voffA);
;             PG8_WAIT_V(8); PG8_WAIT_L(0); PG8_BAR; PG8_MMA(0, 0, At, B0); PG8_MMA(0, 1, At, B1); PG8_BAR; PG8_SCHED;
;             PG8_LDA(At, 0, 1); PG8_STAGE(PG8_SB(0, 0), b2, voffB); PG8_STAGE(PG8_SB(0, 1), b2 + hstepB, voffB); PG8_STAGE(PG8_SA(0, 0), a2, voffA);
;             PG8_WAIT_V(8); PG8_WAIT_L(0); PG8_BAR; PG8_MMA(1, 0, At, B0); PG8_MMA(1, 1, At, B1); PG8_BAR; PG8_SCHED;
; DI void load_rows(PreRows& pr, const float* ssq, const pg8::Unit& u, int wr, int fr) {
; #pragma unroll
;     for (int ai = 0; ai < 2; ++ai)
; #pragma unroll
;         for (int m = 0; m < 4; ++m) pr.v[ai * 4 + m] = ssq[u.pm * 256 + ai * 128 + wr * 64 + m * 16 + fr];
; }
.LBB0_178:
	v_lshl_add_u32 v156, s44, 8, v147
	v_ashrrev_i32_e32 v157, 31, v156
	v_add_u32_e32 v154, 0x80, v156
	v_add_u32_e32 v152, 0x90, v156
	v_add_u32_e32 v150, 0xa0, v156
	v_add_u32_e32 v148, 0xb0, v156
	v_lshl_add_u64 v[2:3], v[156:157], 2, s[12:13]
	v_ashrrev_i32_e32 v155, 31, v154
	v_ashrrev_i32_e32 v153, 31, v152
	v_ashrrev_i32_e32 v151, 31, v150
	v_ashrrev_i32_e32 v149, 31, v148
	v_lshl_add_u64 v[4:5], v[154:155], 2, s[12:13]
	v_lshl_add_u64 v[6:7], v[152:153], 2, s[12:13]
	v_lshl_add_u64 v[8:9], v[150:151], 2, s[12:13]
	v_lshl_add_u64 v[10:11], v[148:149], 2, s[12:13]
	global_load_dword v166, v[2:3], off
	global_load_dword v165, v[2:3], off offset:64
	global_load_dword v164, v[2:3], off offset:128
	global_load_dword v157, v[2:3], off offset:192
	global_load_dword v155, v[4:5], off
	global_load_dword v153, v[6:7], off
	global_load_dword v151, v[8:9], off
	global_load_dword v149, v[10:11], off
	s_ashr_i32 s35, s34, 31
	s_lshl_b64 s[36:37], s[34:35], 19
	s_add_u32 s36, s30, s36
	s_addc_u32 s37, s31, s37
	s_and_b64 s[38:39], s[4:5], exec
	s_cselect_b32 s35, s37, s41
	s_cselect_b32 s61, s36, s40
	s_ashr_i32 s21, s20, 31
	s_lshl_b64 s[38:39], s[20:21], 19
	s_add_u32 s38, s28, s38
	s_addc_u32 s39, s29, s39
	s_and_b64 s[44:45], s[4:5], exec
	s_cselect_b32 s21, s39, s43
	s_cselect_b32 s62, s38, s42
	s_add_u32 s40, s40, 0x40080
	s_addc_u32 s41, s41, 0
	s_add_u32 s63, s42, 0x100
	s_addc_u32 s64, s43, 0
	s_mov_b32 s65, -2
	ds_read_b128 v[168:171], v162
	ds_read_b128 v[172:175], v162 offset:1024
	ds_read_b128 v[176:179], v162 offset:2048
	ds_read_b128 v[180:183], v162 offset:3072
	ds_read_b128 v[186:189], v163
	ds_read_b128 v[190:193], v163 offset:1024
	ds_read_b128 v[194:197], v163 offset:2048
	ds_read_b128 v[198:201], v163 offset:3072
	s_add_u32 s42, s40, 0xfffc0080
	s_addc_u32 s43, s41, -1
	s_cmp_eq_u32 s65, 12
	s_cselect_b32 s45, s35, s43
	s_cselect_b32 s44, s61, s42
	s_cselect_b32 s43, s21, s64
	s_cselect_b32 s42, s62, s63
	s_add_i32 m0, s49, 0xc000
	ds_read_b128 v[202:205], v160
	ds_read_b128 v[206:209], v160 offset:1024
	ds_read_b128 v[210:213], v160 offset:2048
	ds_read_b128 v[214:217], v160 offset:3072
	ds_read_b128 v[218:221], v160 offset:4096
	ds_read_b128 v[222:225], v160 offset:5120
	ds_read_b128 v[226:229], v160 offset:6144
	ds_read_b128 v[230:233], v160 offset:7168
	global_load_lds_dwordx4 v138, s[40:41]
	s_add_i32 m0, s49, 0xe000
	s_nop 0
	global_load_lds_dwordx4 v140, s[40:41]
	s_cmp_lg_u32 s99, 0
	s_cbranch_scc1 .Lpk0_w1
	s_waitcnt vmcnt(8)
.Lpk0_w1:
	s_waitcnt lgkmcnt(0)
	s_barrier
	s_setprio 1
	v_mfma_f32_16x16x32_bf16 v[126:129], v[168:171], v[202:205], 0
	v_mfma_f32_16x16x32_bf16 v[118:121], v[176:179], v[202:205], 0
	v_mfma_f32_16x16x32_bf16 v[110:113], v[168:171], v[210:213], 0
	v_mfma_f32_16x16x32_bf16 v[102:105], v[176:179], v[210:213], 0
	v_mfma_f32_16x16x32_bf16 v[94:97], v[168:171], v[218:221], 0
	v_mfma_f32_16x16x32_bf16 v[86:89], v[176:179], v[218:221], 0
	v_mfma_f32_16x16x32_bf16 v[78:81], v[168:171], v[226:229], 0
	v_mfma_f32_16x16x32_bf16 v[70:73], v[176:179], v[226:229], 0
	v_mfma_f32_16x16x32_bf16 v[126:129], v[172:175], v[206:209], v[126:129]
	v_mfma_f32_16x16x32_bf16 v[118:121], v[180:183], v[206:209], v[118:121]
	v_mfma_f32_16x16x32_bf16 v[110:113], v[172:175], v[214:217], v[110:113]
	v_mfma_f32_16x16x32_bf16 v[102:105], v[180:183], v[214:217], v[102:105]
	v_mfma_f32_16x16x32_bf16 v[94:97], v[172:175], v[222:225], v[94:97]
	v_mfma_f32_16x16x32_bf16 v[86:89], v[180:183], v[222:225], v[86:89]
	v_mfma_f32_16x16x32_bf16 v[78:81], v[172:175], v[230:233], v[78:81]
	v_mfma_f32_16x16x32_bf16 v[70:73], v[180:183], v[230:233], v[70:73]
	v_mfma_f32_16x16x32_bf16 v[122:125], v[186:189], v[202:205], 0
	v_mfma_f32_16x16x32_bf16 v[114:117], v[194:197], v[202:205], 0
	v_mfma_f32_16x16x32_bf16 v[106:109], v[186:189], v[210:213], 0
	v_mfma_f32_16x16x32_bf16 v[98:101], v[194:197], v[210:213], 0
	v_mfma_f32_16x16x32_bf16 v[90:93], v[186:189], v[218:221], 0
	v_mfma_f32_16x16x32_bf16 v[82:85], v[194:197], v[218:221], 0
	v_mfma_f32_16x16x32_bf16 v[74:77], v[186:189], v[226:229], 0
	v_mfma_f32_16x16x32_bf16 v[66:69], v[194:197], v[226:229], 0
	v_mfma_f32_16x16x32_bf16 v[122:125], v[190:193], v[206:209], v[122:125]
	v_mfma_f32_16x16x32_bf16 v[114:117], v[198:201], v[206:209], v[114:117]
	v_mfma_f32_16x16x32_bf16 v[106:109], v[190:193], v[214:217], v[106:109]
	v_mfma_f32_16x16x32_bf16 v[98:101], v[198:201], v[214:217], v[98:101]
	v_mfma_f32_16x16x32_bf16 v[90:93], v[190:193], v[222:225], v[90:93]
	v_mfma_f32_16x16x32_bf16 v[82:85], v[198:201], v[222:225], v[82:85]
	v_mfma_f32_16x16x32_bf16 v[74:77], v[190:193], v[230:233], v[74:77]
	v_mfma_f32_16x16x32_bf16 v[66:69], v[198:201], v[230:233], v[66:69]
	s_setprio 0
	s_barrier
	s_add_i32 s66, s57, s46
	v_lshl_add_u64 v[234:235], s[42:43], 0, v[134:135]
	s_mov_b32 m0, s66
	ds_read_b128 v[202:205], v160 offset:16384
	ds_read_b128 v[206:209], v160 offset:17408
	ds_read_b128 v[210:213], v160 offset:18432
	ds_read_b128 v[214:217], v160 offset:19456
	ds_read_b128 v[218:221], v160 offset:20480
	ds_read_b128 v[222:225], v160 offset:21504
	ds_read_b128 v[226:229], v160 offset:22528
	ds_read_b128 v[230:233], v160 offset:23552
	global_load_lds_dwordx4 v[234:235], off
	s_add_i32 m0, s66, 0x2000
	s_add_u32 s66, s42, 0x40000
	v_lshl_add_u64 v[236:237], s[42:43], 0, v[130:131]
	s_addc_u32 s67, s43, 0
	s_add_i32 s68, s58, s46
	global_load_lds_dwordx4 v[236:237], off
	s_mov_b32 m0, s68
	v_lshl_add_u64 v[240:241], s[44:45], 0, v[132:133]
	global_load_lds_dwordx4 v134, s[66:67]
	s_add_i32 m0, s68, 0x2000
	s_nop 0
	global_load_lds_dwordx4 v130, s[66:67]
	v_lshl_add_u64 v[238:239], s[44:45], 0, v[136:137]
	s_mov_b32 m0, s49
	s_nop 0
	global_load_lds_dwordx4 v[238:239], off
	s_mov_b32 m0, s50
	s_nop 0
	global_load_lds_dwordx4 v[240:241], off
	s_cmp_lg_u32 s99, 0
	s_cbranch_scc1 .Lpk0_w2
	s_waitcnt vmcnt(8)
; #define PG8_STAGE(bufoff, gbase, voff) do { _Pragma("unroll") for (int _i = 0; _i < 2; ++_i) \
;         __builtin_amdgcn_global_load_lds((const unsigned*)((const char*)(gbase) + (voff)[_i]), (LAS unsigned*)(lds + (bufoff) + ldsw + _i * 8192), 16, 0, 0); } while (0)
; #define PG8_LDA(dst, b, h) do { _Pragma("unroll") for (int m = 0; m < 4; ++m) _Pragma("unroll") for (int k = 0; k < 2; ++k) dst[m][k] = *(const LAS bf16x8*)(lds + PG8_SA(b, h) + aoff + m * 2048 + k * 1024); } while (0)
; #define PG8_LDB(dst, b, h) do { _Pragma("unroll") for (int n = 0; n < 2; ++n) _Pragma("unroll") for (int k = 0; k < 2; ++k) dst[n][k] = *(const LAS bf16x8*)(lds + PG8_SB(b, h) + boff + n * 2048 + k * 1024); } while (0)
; #define PG8_MMA(ai, bj, At, Bt) do { __builtin_amdgcn_s_setprio(1); _Pragma("unroll") for (int m = 0; m < 4; ++m) _Pragma("unroll") for (int n = 0; n < 2; ++n) _Pragma("unroll") for (int k = 0; k < 2; ++k) \
;         acc[ai][bj][m][n] = __builtin_amdgcn_mfma_f32_16x16x32_bf16(Bt[n][k], At[m][k], acc[ai][bj][m][n], 0, 0, 0); __builtin_amdgcn_s_setprio(0); } while (0)
; #define PG8_WAIT_V(n) asm volatile("s_waitcnt vmcnt(" #n ")" ::: "memory")
; #define PG8_WAIT_L(n) asm volatile("s_waitcnt lgkmcnt(" #n ")" ::: "memory")
; #define PG8_BAR __builtin_amdgcn_s_barrier()
; #define PG8_SCHED __builtin_amdgcn_sched_barrier(0)
; template <class Epi, class Sched>
; DI void gemm_phase(LAS unsigned char* lds, const Gemm g, const Sched& S, const Epi& E) {
;     ...
;             PG8_WAIT_V(8); PG8_WAIT_L(0); PG8_BAR; PG8_MMA(1, 0, At, B0); PG8_MMA(1, 1, At, B1); PG8_BAR; PG8_SCHED;
;             PG8_LDB(B0, 1, 0); PG8_LDB(B1, 1, 1); PG8_SCHED; PG8_LDA(At, 1, 0); PG8_STAGE(PG8_SA(0, 1), a2 + hstepA, voffA);
;             PG8_WAIT_V(8); PG8_WAIT_L(0); PG8_BAR; PG8_MMA(0, 0, At, B0); PG8_MMA(0, 1, At, B1); PG8_BAR; PG8_SCHED;
;             PG8_LDA(At, 1, 1); PG8_STAGE(PG8_SB(1, 0), b3, voffB); PG8_STAGE(PG8_SB(1, 1), b3 + hstepB, voffB); PG8_STAGE(PG8_SA(1, 0), a3, voffA);
;             PG8_WAIT_V(8); PG8_WAIT_L(0); PG8_BAR; PG8_MMA(1, 0, At, B0); PG8_MMA(1, 1, At, B1); PG8_BAR; PG8_SCHED;
.Lpk0_w2:
	s_mov_b32 s99, 0
	s_waitcnt lgkmcnt(0)
	s_barrier
	s_setprio 1
	v_mfma_f32_16x16x32_bf16 v[62:65], v[168:171], v[202:205], 0
	v_mfma_f32_16x16x32_bf16 v[54:57], v[176:179], v[202:205], 0
	v_mfma_f32_16x16x32_bf16 v[46:49], v[168:171], v[210:213], 0
	v_mfma_f32_16x16x32_bf16 v[38:41], v[176:179], v[210:213], 0
	v_mfma_f32_16x16x32_bf16 v[30:33], v[168:171], v[218:221], 0
	v_mfma_f32_16x16x32_bf16 v[22:25], v[176:179], v[218:221], 0
	v_mfma_f32_16x16x32_bf16 v[14:17], v[168:171], v[226:229], 0
	v_mfma_f32_16x16x32_bf16 v[6:9], v[176:179], v[226:229], 0
	v_mfma_f32_16x16x32_bf16 v[62:65], v[172:175], v[206:209], v[62:65]
	v_mfma_f32_16x16x32_bf16 v[54:57], v[180:183], v[206:209], v[54:57]
	v_mfma_f32_16x16x32_bf16 v[46:49], v[172:175], v[214:217], v[46:49]
	v_mfma_f32_16x16x32_bf16 v[38:41], v[180:183], v[214:217], v[38:41]
	v_mfma_f32_16x16x32_bf16 v[30:33], v[172:175], v[222:225], v[30:33]
	v_mfma_f32_16x16x32_bf16 v[22:25], v[180:183], v[222:225], v[22:25]
	v_mfma_f32_16x16x32_bf16 v[14:17], v[172:175], v[230:233], v[14:17]
	v_mfma_f32_16x16x32_bf16 v[6:9], v[180:183], v[230:233], v[6:9]
	v_mfma_f32_16x16x32_bf16 v[58:61], v[186:189], v[202:205], 0
	v_mfma_f32_16x16x32_bf16 v[50:53], v[194:197], v[202:205], 0
	v_mfma_f32_16x16x32_bf16 v[42:45], v[186:189], v[210:213], 0
	v_mfma_f32_16x16x32_bf16 v[34:37], v[194:197], v[210:213], 0
	v_mfma_f32_16x16x32_bf16 v[26:29], v[186:189], v[218:221], 0
	v_mfma_f32_16x16x32_bf16 v[18:21], v[194:197], v[218:221], 0
	v_mfma_f32_16x16x32_bf16 v[10:13], v[186:189], v[226:229], 0
	v_mfma_f32_16x16x32_bf16 v[2:5], v[194:197], v[226:229], 0
	v_mfma_f32_16x16x32_bf16 v[58:61], v[190:193], v[206:209], v[58:61]
	v_mfma_f32_16x16x32_bf16 v[50:53], v[198:201], v[206:209], v[50:53]
	v_mfma_f32_16x16x32_bf16 v[42:45], v[190:193], v[214:217], v[42:45]
	v_mfma_f32_16x16x32_bf16 v[34:37], v[198:201], v[214:217], v[34:37]
	v_mfma_f32_16x16x32_bf16 v[26:29], v[190:193], v[222:225], v[26:29]
	v_mfma_f32_16x16x32_bf16 v[18:21], v[198:201], v[222:225], v[18:21]
	v_mfma_f32_16x16x32_bf16 v[10:13], v[190:193], v[230:233], v[10:13]
	v_mfma_f32_16x16x32_bf16 v[2:5], v[198:201], v[230:233], v[2:5]
	s_setprio 0
	s_barrier
	s_add_i32 s66, 0, 0x18000
	v_add_u32_e32 v167, s66, v158
	s_add_i32 s67, 0, 0x1c000
	ds_read_b128 v[168:171], v167
	ds_read_b128 v[172:175], v167 offset:1024
	ds_read_b128 v[176:179], v167 offset:2048
	ds_read_b128 v[180:183], v167 offset:3072
	v_add_u32_e32 v167, s67, v158
	ds_read_b128 v[186:189], v167
	ds_read_b128 v[190:193], v167 offset:1024
	ds_read_b128 v[194:197], v167 offset:2048
	ds_read_b128 v[198:201], v167 offset:3072
	s_add_u32 s44, s44, 0x40000
	s_addc_u32 s45, s45, 0
	s_mov_b32 m0, s51
	ds_read_b128 v[202:205], v160 offset:32768
	ds_read_b128 v[206:209], v160 offset:33792
	ds_read_b128 v[210:213], v160 offset:34816
	ds_read_b128 v[214:217], v160 offset:35840
	ds_read_b128 v[218:221], v160 offset:36864
	ds_read_b128 v[222:225], v160 offset:37888
	ds_read_b128 v[226:229], v160 offset:38912
	ds_read_b128 v[230:233], v160 offset:39936
	global_load_lds_dwordx4 v136, s[44:45]
	s_mov_b32 m0, s52
	s_nop 0
	global_load_lds_dwordx4 v132, s[44:45]
	s_waitcnt vmcnt(8)
	s_waitcnt lgkmcnt(0)
	s_barrier
	s_setprio 1
	v_mfma_f32_16x16x32_bf16 v[126:129], v[168:171], v[202:205], v[126:129]
	v_mfma_f32_16x16x32_bf16 v[118:121], v[176:179], v[202:205], v[118:121]
	v_mfma_f32_16x16x32_bf16 v[110:113], v[168:171], v[210:213], v[110:113]
	v_mfma_f32_16x16x32_bf16 v[102:105], v[176:179], v[210:213], v[102:105]
	v_mfma_f32_16x16x32_bf16 v[94:97], v[168:171], v[218:221], v[94:97]
	v_mfma_f32_16x16x32_bf16 v[86:89], v[176:179], v[218:221], v[86:89]
	v_mfma_f32_16x16x32_bf16 v[78:81], v[168:171], v[226:229], v[78:81]
	v_mfma_f32_16x16x32_bf16 v[70:73], v[176:179], v[226:229], v[70:73]
	v_mfma_f32_16x16x32_bf16 v[126:129], v[172:175], v[206:209], v[126:129]
	v_mfma_f32_16x16x32_bf16 v[118:121], v[180:183], v[206:209], v[118:121]
	v_mfma_f32_16x16x32_bf16 v[110:113], v[172:175], v[214:217], v[110:113]
	v_mfma_f32_16x16x32_bf16 v[102:105], v[180:183], v[214:217], v[102:105]
	v_mfma_f32_16x16x32_bf16 v[94:97], v[172:175], v[222:225], v[94:97]
	v_mfma_f32_16x16x32_bf16 v[86:89], v[180:183], v[222:225], v[86:89]
	v_mfma_f32_16x16x32_bf16 v[78:81], v[172:175], v[230:233], v[78:81]
	v_mfma_f32_16x16x32_bf16 v[70:73], v[180:183], v[230:233], v[70:73]
	v_mfma_f32_16x16x32_bf16 v[122:125], v[186:189], v[202:205], v[122:125]
	v_mfma_f32_16x16x32_bf16 v[114:117], v[194:197], v[202:205], v[114:117]
	v_mfma_f32_16x16x32_bf16 v[106:109], v[186:189], v[210:213], v[106:109]
	v_mfma_f32_16x16x32_bf16 v[98:101], v[194:197], v[210:213], v[98:101]
	v_mfma_f32_16x16x32_bf16 v[90:93], v[186:189], v[218:221], v[90:93]
	v_mfma_f32_16x16x32_bf16 v[82:85], v[194:197], v[218:221], v[82:85]
	v_mfma_f32_16x16x32_bf16 v[74:77], v[186:189], v[226:229], v[74:77]
	v_mfma_f32_16x16x32_bf16 v[66:69], v[194:197], v[226:229], v[66:69]
	v_mfma_f32_16x16x32_bf16 v[122:125], v[190:193], v[206:209], v[122:125]
	v_mfma_f32_16x16x32_bf16 v[114:117], v[198:201], v[206:209], v[114:117]
	v_mfma_f32_16x16x32_bf16 v[106:109], v[190:193], v[214:217], v[106:109]
	v_mfma_f32_16x16x32_bf16 v[98:101], v[198:201], v[214:217], v[98:101]
	v_mfma_f32_16x16x32_bf16 v[90:93], v[190:193], v[222:225], v[90:93]
	v_mfma_f32_16x16x32_bf16 v[82:85], v[198:201], v[222:225], v[82:85]
	v_mfma_f32_16x16x32_bf16 v[74:77], v[190:193], v[230:233], v[74:77]
	v_mfma_f32_16x16x32_bf16 v[66:69], v[198:201], v[230:233], v[66:69]
	s_setprio 0
	s_barrier
; #define PG8_STAGE(bufoff, gbase, voff) do { _Pragma("unroll") for (int _i = 0; _i < 2; ++_i) \
;         __builtin_amdgcn_global_load_lds((const unsigned*)((const char*)(gbase) + (voff)[_i]), (LAS unsigned*)(lds + (bufoff) + ldsw + _i * 8192), 16, 0, 0); } while (0)
; #define PG8_LDA(dst, b, h) do { _Pragma("unroll") for (int m = 0; m < 4; ++m) _Pragma("unroll") for (int k = 0; k < 2; ++k) dst[m][k] = *(const LAS bf16x8*)(lds + PG8_SA(b, h) + aoff + m * 2048 + k * 1024); } while (0)
; #define PG8_LDB(dst, b, h) do { _Pragma("unroll") for (int n = 0; n < 2; ++n) _Pragma("unroll") for (int k = 0; k < 2; ++k) dst[n][k] = *(const LAS bf16x8*)(lds + PG8_SB(b, h) + boff + n * 2048 + k * 1024); } while (0)
; #define PG8_WAIT_V(n) asm volatile("s_waitcnt vmcnt(" #n ")" ::: "memory")
; #define PG8_WAIT_L(n) asm volatile("s_waitcnt lgkmcnt(" #n ")" ::: "memory")
; template <class Epi, class Sched>
; DI void gemm_phase(LAS unsigned char* lds, const Gemm g, const Sched& S, const Epi& E) {
;     ...
;         for (int t = 0; t < nt; t += 2) {
;             const bool last = (t == nt - 2);
;             const char* a1 = cA + (size_t)(t + 1) * kstep;
;             const char* a2 = last ? nA : cA + (size_t)(t + 2) * kstep; const char* b2 = last ? nB : cB + (size_t)(t + 2) * kstep;
;             const char* a3 = a2 + kstep; const char* b3 = b2 + kstep;
;             PG8_LDB(B0, 0, 0); PG8_LDB(B1, 0, 1); PG8_SCHED; PG8_LDA(At, 0, 0); PG8_STAGE(PG8_SA(1, 1), a1 + hstepA, voffA);
;             PG8_WAIT_V(8); PG8_WAIT_L(0); PG8_BAR; PG8_MMA(0, 0, At, B0); PG8_MMA(0, 1, At, B1); PG8_BAR; PG8_SCHED;
;             PG8_LDA(At, 0, 1); PG8_STAGE(PG8_SB(0, 0), b2, voffB); PG8_STAGE(PG8_SB(0, 1), b2 + hstepB, voffB); PG8_STAGE(PG8_SA(0, 0), a2, voffA);
;             PG8_WAIT_V(8); PG8_WAIT_L(0); PG8_BAR; PG8_MMA(1, 0, At, B0); PG8_MMA(1, 1, At, B1); PG8_BAR; PG8_SCHED;
;             PG8_LDB(B0, 1, 0); PG8_LDB(B1, 1, 1); PG8_SCHED; PG8_LDA(At, 1, 0); PG8_STAGE(PG8_SA(0, 1), a2 + hstepA, voffA);
;             PG8_WAIT_V(8); PG8_WAIT_L(0); PG8_BAR; PG8_MMA(0, 0, At, B0); PG8_MMA(0, 1, At, B1); PG8_BAR; PG8_SCHED;
;             PG8_LDA(At, 1, 1); PG8_STAGE(PG8_SB(1, 0), b3, voffB); PG8_STAGE(PG8_SB(1, 1), b3 + hstepB, voffB); PG8_STAGE(PG8_SA(1, 0), a3, voffA);
;             PG8_WAIT_V(8); PG8_WAIT_L(0); PG8_BAR; PG8_MMA(1, 0, At, B0); PG8_MMA(1, 1, At, B1); PG8_BAR; PG8_SCHED;
	s_add_i32 s44, s66, s46
	v_lshl_add_u64 v[234:235], v[234:235], 0, s[16:17]
	s_mov_b32 m0, s44
	ds_read_b128 v[202:205], v160 offset:49152
	ds_read_b128 v[206:209], v160 offset:50176
	ds_read_b128 v[210:213], v160 offset:51200
	ds_read_b128 v[214:217], v160 offset:52224
	ds_read_b128 v[218:221], v160 offset:53248
	ds_read_b128 v[222:225], v160 offset:54272
	ds_read_b128 v[226:229], v160 offset:55296
	ds_read_b128 v[230:233], v160 offset:56320
	global_load_lds_dwordx4 v[234:235], off
	s_add_i32 m0, s44, 0x2000
	s_add_u32 s42, s42, 0x40080
	v_lshl_add_u64 v[234:235], v[236:237], 0, s[16:17]
	s_addc_u32 s43, s43, 0
	s_add_i32 s44, s67, s46
	global_load_lds_dwordx4 v[234:235], off
	s_mov_b32 m0, s44
	s_nop 0
	global_load_lds_dwordx4 v134, s[42:43]
	s_add_i32 m0, s44, 0x2000
	s_nop 0
	global_load_lds_dwordx4 v130, s[42:43]
	v_lshl_add_u64 v[234:235], v[238:239], 0, s[16:17]
	s_mov_b32 m0, s54
	s_nop 0
	global_load_lds_dwordx4 v[234:235], off
	v_lshl_add_u64 v[234:235], v[240:241], 0, s[16:17]
	s_mov_b32 m0, s55
	s_nop 0
	global_load_lds_dwordx4 v[234:235], off
	s_waitcnt vmcnt(8)
	s_waitcnt lgkmcnt(0)
	s_barrier
	s_setprio 1
	v_mfma_f32_16x16x32_bf16 v[62:65], v[168:171], v[202:205], v[62:65]
	v_mfma_f32_16x16x32_bf16 v[54:57], v[176:179], v[202:205], v[54:57]
	v_mfma_f32_16x16x32_bf16 v[46:49], v[168:171], v[210:213], v[46:49]
	v_mfma_f32_16x16x32_bf16 v[38:41], v[176:179], v[210:213], v[38:41]
	v_mfma_f32_16x16x32_bf16 v[30:33], v[168:171], v[218:221], v[30:33]
	v_mfma_f32_16x16x32_bf16 v[22:25], v[176:179], v[218:221], v[22:25]
	v_mfma_f32_16x16x32_bf16 v[14:17], v[168:171], v[226:229], v[14:17]
	v_mfma_f32_16x16x32_bf16 v[6:9], v[176:179], v[226:229], v[6:9]
	v_mfma_f32_16x16x32_bf16 v[62:65], v[172:175], v[206:209], v[62:65]
	v_mfma_f32_16x16x32_bf16 v[54:57], v[180:183], v[206:209], v[54:57]
	v_mfma_f32_16x16x32_bf16 v[46:49], v[172:175], v[214:217], v[46:49]
	v_mfma_f32_16x16x32_bf16 v[38:41], v[180:183], v[214:217], v[38:41]
	v_mfma_f32_16x16x32_bf16 v[30:33], v[172:175], v[222:225], v[30:33]
	v_mfma_f32_16x16x32_bf16 v[22:25], v[180:183], v[222:225], v[22:25]
	v_mfma_f32_16x16x32_bf16 v[14:17], v[172:175], v[230:233], v[14:17]
	v_mfma_f32_16x16x32_bf16 v[6:9], v[180:183], v[230:233], v[6:9]
	v_mfma_f32_16x16x32_bf16 v[58:61], v[186:189], v[202:205], v[58:61]
	v_mfma_f32_16x16x32_bf16 v[50:53], v[194:197], v[202:205], v[50:53]
	v_mfma_f32_16x16x32_bf16 v[42:45], v[186:189], v[210:213], v[42:45]
	v_mfma_f32_16x16x32_bf16 v[34:37], v[194:197], v[210:213], v[34:37]
	v_mfma_f32_16x16x32_bf16 v[26:29], v[186:189], v[218:221], v[26:29]
	v_mfma_f32_16x16x32_bf16 v[18:21], v[194:197], v[218:221], v[18:21]
	v_mfma_f32_16x16x32_bf16 v[10:13], v[186:189], v[226:229], v[10:13]
	v_mfma_f32_16x16x32_bf16 v[2:5], v[194:197], v[226:229], v[2:5]
	v_mfma_f32_16x16x32_bf16 v[58:61], v[190:193], v[206:209], v[58:61]
	v_mfma_f32_16x16x32_bf16 v[50:53], v[198:201], v[206:209], v[50:53]
	v_mfma_f32_16x16x32_bf16 v[42:45], v[190:193], v[214:217], v[42:45]
	v_mfma_f32_16x16x32_bf16 v[34:37], v[198:201], v[214:217], v[34:37]
	v_mfma_f32_16x16x32_bf16 v[26:29], v[190:193], v[222:225], v[26:29]
	v_mfma_f32_16x16x32_bf16 v[18:21], v[198:201], v[222:225], v[18:21]
	v_mfma_f32_16x16x32_bf16 v[10:13], v[190:193], v[230:233], v[10:13]
	v_mfma_f32_16x16x32_bf16 v[2:5], v[198:201], v[230:233], v[2:5]
	s_setprio 0
	s_barrier
	s_add_i32 s65, s65, 2
	s_add_u32 s40, s40, 0x100
	s_addc_u32 s41, s41, 0
	s_add_u32 s63, s63, 0x100
	s_addc_u32 s64, s64, 0
	s_cmp_gt_u32 s65, 13
.LBB0_179:
	ds_read_b128 v[168:171], v162
	ds_read_b128 v[172:175], v162 offset:1024
	ds_read_b128 v[176:179], v162 offset:2048
	ds_read_b128 v[180:183], v162 offset:3072
	ds_read_b128 v[186:189], v163
	ds_read_b128 v[190:193], v163 offset:1024
	ds_read_b128 v[194:197], v163 offset:2048
	ds_read_b128 v[198:201], v163 offset:3072
	s_add_u32 s42, s40, 0xfffc0080
	s_addc_u32 s43, s41, -1
	s_cmp_eq_u32 s65, 12
	s_cselect_b32 s45, s35, s43
	s_cselect_b32 s44, s61, s42
	s_cselect_b32 s43, s21, s64
	s_cselect_b32 s42, s62, s63
	s_add_i32 m0, s49, 0xc000
	ds_read_b128 v[202:205], v160
	ds_read_b128 v[206:209], v160 offset:1024
	ds_read_b128 v[210:213], v160 offset:2048
	ds_read_b128 v[214:217], v160 offset:3072
	ds_read_b128 v[218:221], v160 offset:4096
	ds_read_b128 v[222:225], v160 offset:5120
	ds_read_b128 v[226:229], v160 offset:6144
	ds_read_b128 v[230:233], v160 offset:7168
	global_load_lds_dwordx4 v138, s[40:41]
	s_add_i32 m0, s49, 0xe000
	s_nop 0
	global_load_lds_dwordx4 v140, s[40:41]
	s_waitcnt vmcnt(8)
	s_waitcnt lgkmcnt(0)
	s_barrier
; #define PG8_STAGE(bufoff, gbase, voff) do { _Pragma("unroll") for (int _i = 0; _i < 2; ++_i) \
;         __builtin_amdgcn_global_load_lds((const unsigned*)((const char*)(gbase) + (voff)[_i]), (LAS unsigned*)(lds + (bufoff) + ldsw + _i * 8192), 16, 0, 0); } while (0)
; #define PG8_LDA(dst, b, h) do { _Pragma("unroll") for (int m = 0; m < 4; ++m) _Pragma("unroll") for (int k = 0; k < 2; ++k) dst[m][k] = *(const LAS bf16x8*)(lds + PG8_SA(b, h) + aoff + m * 2048 + k * 1024); } while (0)
; #define PG8_LDB(dst, b, h) do { _Pragma("unroll") for (int n = 0; n < 2; ++n) _Pragma("unroll") for (int k = 0; k < 2; ++k) dst[n][k] = *(const LAS bf16x8*)(lds + PG8_SB(b, h) + boff + n * 2048 + k * 1024); } while (0)
; #define PG8_MMA(ai, bj, At, Bt) do { __builtin_amdgcn_s_setprio(1); _Pragma("unroll") for (int m = 0; m < 4; ++m) _Pragma("unroll") for (int n = 0; n < 2; ++n) _Pragma("unroll") for (int k = 0; k < 2; ++k) \
;         acc[ai][bj][m][n] = __builtin_amdgcn_mfma_f32_16x16x32_bf16(Bt[n][k], At[m][k], acc[ai][bj][m][n], 0, 0, 0); __builtin_amdgcn_s_setprio(0); } while (0)
; #define PG8_WAIT_V(n) asm volatile("s_waitcnt vmcnt(" #n ")" ::: "memory")
; #define PG8_WAIT_L(n) asm volatile("s_waitcnt lgkmcnt(" #n ")" ::: "memory")
; #define PG8_BAR __builtin_amdgcn_s_barrier()
; #define PG8_SCHED __builtin_amdgcn_sched_barrier(0)
; template <class Epi, class Sched>
; DI void gemm_phase(LAS unsigned char* lds, const Gemm g, const Sched& S, const Epi& E) {
;     ...
;             PG8_WAIT_V(8); PG8_WAIT_L(0); PG8_BAR; PG8_MMA(0, 0, At, B0); PG8_MMA(0, 1, At, B1); PG8_BAR; PG8_SCHED;
;             PG8_LDA(At, 0, 1); PG8_STAGE(PG8_SB(0, 0), b2, voffB); PG8_STAGE(PG8_SB(0, 1), b2 + hstepB, voffB); PG8_STAGE(PG8_SA(0, 0), a2, voffA);
;             PG8_WAIT_V(8); PG8_WAIT_L(0); PG8_BAR; PG8_MMA(1, 0, At, B0); PG8_MMA(1, 1, At, B1); PG8_BAR; PG8_SCHED;
;             PG8_LDB(B0, 1, 0); PG8_LDB(B1, 1, 1); PG8_SCHED; PG8_LDA(At, 1, 0); PG8_STAGE(PG8_SA(0, 1), a2 + hstepA, voffA);
;             PG8_WAIT_V(8); PG8_WAIT_L(0); PG8_BAR; PG8_MMA(0, 0, At, B0); PG8_MMA(0, 1, At, B1); PG8_BAR; PG8_SCHED;
	s_setprio 1
	v_mfma_f32_16x16x32_bf16 v[126:129], v[168:171], v[202:205], v[126:129]
	v_mfma_f32_16x16x32_bf16 v[118:121], v[176:179], v[202:205], v[118:121]
	v_mfma_f32_16x16x32_bf16 v[110:113], v[168:171], v[210:213], v[110:113]
	v_mfma_f32_16x16x32_bf16 v[102:105], v[176:179], v[210:213], v[102:105]
	v_mfma_f32_16x16x32_bf16 v[94:97], v[168:171], v[218:221], v[94:97]
	v_mfma_f32_16x16x32_bf16 v[86:89], v[176:179], v[218:221], v[86:89]
	v_mfma_f32_16x16x32_bf16 v[78:81], v[168:171], v[226:229], v[78:81]
	v_mfma_f32_16x16x32_bf16 v[70:73], v[176:179], v[226:229], v[70:73]
	v_mfma_f32_16x16x32_bf16 v[126:129], v[172:175], v[206:209], v[126:129]
	v_mfma_f32_16x16x32_bf16 v[118:121], v[180:183], v[206:209], v[118:121]
	v_mfma_f32_16x16x32_bf16 v[110:113], v[172:175], v[214:217], v[110:113]
	v_mfma_f32_16x16x32_bf16 v[102:105], v[180:183], v[214:217], v[102:105]
	v_mfma_f32_16x16x32_bf16 v[94:97], v[172:175], v[222:225], v[94:97]
	v_mfma_f32_16x16x32_bf16 v[86:89], v[180:183], v[222:225], v[86:89]
	v_mfma_f32_16x16x32_bf16 v[78:81], v[172:175], v[230:233], v[78:81]
	v_mfma_f32_16x16x32_bf16 v[70:73], v[180:183], v[230:233], v[70:73]
	v_mfma_f32_16x16x32_bf16 v[122:125], v[186:189], v[202:205], v[122:125]
	v_mfma_f32_16x16x32_bf16 v[114:117], v[194:197], v[202:205], v[114:117]
	v_mfma_f32_16x16x32_bf16 v[106:109], v[186:189], v[210:213], v[106:109]
	v_mfma_f32_16x16x32_bf16 v[98:101], v[194:197], v[210:213], v[98:101]
	v_mfma_f32_16x16x32_bf16 v[90:93], v[186:189], v[218:221], v[90:93]
	v_mfma_f32_16x16x32_bf16 v[82:85], v[194:197], v[218:221], v[82:85]
	v_mfma_f32_16x16x32_bf16 v[74:77], v[186:189], v[226:229], v[74:77]
	v_mfma_f32_16x16x32_bf16 v[66:69], v[194:197], v[226:229], v[66:69]
	v_mfma_f32_16x16x32_bf16 v[122:125], v[190:193], v[206:209], v[122:125]
	v_mfma_f32_16x16x32_bf16 v[114:117], v[198:201], v[206:209], v[114:117]
	v_mfma_f32_16x16x32_bf16 v[106:109], v[190:193], v[214:217], v[106:109]
	v_mfma_f32_16x16x32_bf16 v[98:101], v[198:201], v[214:217], v[98:101]
	v_mfma_f32_16x16x32_bf16 v[90:93], v[190:193], v[222:225], v[90:93]
	v_mfma_f32_16x16x32_bf16 v[82:85], v[198:201], v[222:225], v[82:85]
	v_mfma_f32_16x16x32_bf16 v[74:77], v[190:193], v[230:233], v[74:77]
	v_mfma_f32_16x16x32_bf16 v[66:69], v[198:201], v[230:233], v[66:69]
	s_setprio 0
	s_barrier
	s_add_i32 s66, s57, s46
	v_lshl_add_u64 v[234:235], s[42:43], 0, v[134:135]
	s_mov_b32 m0, s66
	ds_read_b128 v[202:205], v160 offset:16384
	ds_read_b128 v[206:209], v160 offset:17408
	ds_read_b128 v[210:213], v160 offset:18432
	ds_read_b128 v[214:217], v160 offset:19456
	ds_read_b128 v[218:221], v160 offset:20480
	ds_read_b128 v[222:225], v160 offset:21504
	ds_read_b128 v[226:229], v160 offset:22528
	ds_read_b128 v[230:233], v160 offset:23552
	global_load_lds_dwordx4 v[234:235], off
	s_add_i32 m0, s66, 0x2000
	s_add_u32 s66, s42, 0x40000
	v_lshl_add_u64 v[236:237], s[42:43], 0, v[130:131]
	s_addc_u32 s67, s43, 0
	s_add_i32 s68, s58, s46
	global_load_lds_dwordx4 v[236:237], off
	s_mov_b32 m0, s68
	v_lshl_add_u64 v[240:241], s[44:45], 0, v[132:133]
	global_load_lds_dwordx4 v134, s[66:67]
	s_add_i32 m0, s68, 0x2000
	s_nop 0
	global_load_lds_dwordx4 v130, s[66:67]
	v_lshl_add_u64 v[238:239], s[44:45], 0, v[136:137]
	s_mov_b32 m0, s49
	s_nop 0
	global_load_lds_dwordx4 v[238:239], off
	s_mov_b32 m0, s50
	s_nop 0
	global_load_lds_dwordx4 v[240:241], off
	s_waitcnt vmcnt(8)
	s_waitcnt lgkmcnt(0)
	s_barrier
	s_setprio 1
	v_mfma_f32_16x16x32_bf16 v[62:65], v[168:171], v[202:205], v[62:65]
	v_mfma_f32_16x16x32_bf16 v[54:57], v[176:179], v[202:205], v[54:57]
	v_mfma_f32_16x16x32_bf16 v[46:49], v[168:171], v[210:213], v[46:49]
	v_mfma_f32_16x16x32_bf16 v[38:41], v[176:179], v[210:213], v[38:41]
	v_mfma_f32_16x16x32_bf16 v[30:33], v[168:171], v[218:221], v[30:33]
	v_mfma_f32_16x16x32_bf16 v[22:25], v[176:179], v[218:221], v[22:25]
	v_mfma_f32_16x16x32_bf16 v[14:17], v[168:171], v[226:229], v[14:17]
	v_mfma_f32_16x16x32_bf16 v[6:9], v[176:179], v[226:229], v[6:9]
	v_mfma_f32_16x16x32_bf16 v[62:65], v[172:175], v[206:209], v[62:65]
	v_mfma_f32_16x16x32_bf16 v[54:57], v[180:183], v[206:209], v[54:57]
	v_mfma_f32_16x16x32_bf16 v[46:49], v[172:175], v[214:217], v[46:49]
	v_mfma_f32_16x16x32_bf16 v[38:41], v[180:183], v[214:217], v[38:41]
	v_mfma_f32_16x16x32_bf16 v[30:33], v[172:175], v[222:225], v[30:33]
	v_mfma_f32_16x16x32_bf16 v[22:25], v[180:183], v[222:225], v[22:25]
	v_mfma_f32_16x16x32_bf16 v[14:17], v[172:175], v[230:233], v[14:17]
	v_mfma_f32_16x16x32_bf16 v[6:9], v[180:183], v[230:233], v[6:9]
	v_mfma_f32_16x16x32_bf16 v[58:61], v[186:189], v[202:205], v[58:61]
	v_mfma_f32_16x16x32_bf16 v[50:53], v[194:197], v[202:205], v[50:53]
	v_mfma_f32_16x16x32_bf16 v[42:45], v[186:189], v[210:213], v[42:45]
	v_mfma_f32_16x16x32_bf16 v[34:37], v[194:197], v[210:213], v[34:37]
	v_mfma_f32_16x16x32_bf16 v[26:29], v[186:189], v[218:221], v[26:29]
	v_mfma_f32_16x16x32_bf16 v[18:21], v[194:197], v[218:221], v[18:21]
	v_mfma_f32_16x16x32_bf16 v[10:13], v[186:189], v[226:229], v[10:13]
	v_mfma_f32_16x16x32_bf16 v[2:5], v[194:197], v[226:229], v[2:5]
	v_mfma_f32_16x16x32_bf16 v[58:61], v[190:193], v[206:209], v[58:61]
	v_mfma_f32_16x16x32_bf16 v[50:53], v[198:201], v[206:209], v[50:53]
	v_mfma_f32_16x16x32_bf16 v[42:45], v[190:193], v[214:217], v[42:45]
	v_mfma_f32_16x16x32_bf16 v[34:37], v[198:201], v[214:217], v[34:37]
	v_mfma_f32_16x16x32_bf16 v[26:29], v[190:193], v[222:225], v[26:29]
	v_mfma_f32_16x16x32_bf16 v[18:21], v[198:201], v[222:225], v[18:21]
	v_mfma_f32_16x16x32_bf16 v[10:13], v[190:193], v[230:233], v[10:13]
	v_mfma_f32_16x16x32_bf16 v[2:5], v[198:201], v[230:233], v[2:5]
	s_setprio 0
	s_barrier
; #define PG8_STAGE(bufoff, gbase, voff) do { _Pragma("unroll") for (int _i = 0; _i < 2; ++_i) \
;         __builtin_amdgcn_global_load_lds((const unsigned*)((const char*)(gbase) + (voff)[_i]), (LAS unsigned*)(lds + (bufoff) + ldsw + _i * 8192), 16, 0, 0); } while (0)
; #define PG8_LDA(dst, b, h) do { _Pragma("unroll") for (int m = 0; m < 4; ++m) _Pragma("unroll") for (int k = 0; k < 2; ++k) dst[m][k] = *(const LAS bf16x8*)(lds + PG8_SA(b, h) + aoff + m * 2048 + k * 1024); } while (0)
; #define PG8_LDB(dst, b, h) do { _Pragma("unroll") for (int n = 0; n < 2; ++n) _Pragma("unroll") for (int k = 0; k < 2; ++k) dst[n][k] = *(const LAS bf16x8*)(lds + PG8_SB(b, h) + boff + n * 2048 + k * 1024); } while (0)
; #define PG8_MMA(ai, bj, At, Bt) do { __builtin_amdgcn_s_setprio(1); _Pragma("unroll") for (int m = 0; m < 4; ++m) _Pragma("unroll") for (int n = 0; n < 2; ++n) _Pragma("unroll") for (int k = 0; k < 2; ++k) \
;         acc[ai][bj][m][n] = __builtin_amdgcn_mfma_f32_16x16x32_bf16(Bt[n][k], At[m][k], acc[ai][bj][m][n], 0, 0, 0); __builtin_amdgcn_s_setprio(0); } while (0)
; #define PG8_WAIT_V(n) asm volatile("s_waitcnt vmcnt(" #n ")" ::: "memory")
; #define PG8_WAIT_L(n) asm volatile("s_waitcnt lgkmcnt(" #n ")" ::: "memory")
; #define PG8_BAR __builtin_amdgcn_s_barrier()
; #define PG8_SCHED __builtin_amdgcn_sched_barrier(0)
;     DI void pre(Pre& pr, const pg8::Unit& u, int wr, int fr) const { load_rows(pr, ssq, u, wr, fr); }
;     DI void pre(Pre& pr, const pg8::Unit& u, int wr, int fr) const { load_rows(pr, ssq, u, wr, fr); }
; template <class Epi, class Sched>
; DI void gemm_phase(LAS unsigned char* lds, const Gemm g, const Sched& S, const Epi& E) {
;     ...
;             PG8_LDB(B0, 1, 0); PG8_LDB(B1, 1, 1); PG8_SCHED; PG8_LDA(At, 1, 0); PG8_STAGE(PG8_SA(0, 1), a2 + hstepA, voffA);
;             PG8_WAIT_V(8); PG8_WAIT_L(0); PG8_BAR; PG8_MMA(0, 0, At, B0); PG8_MMA(0, 1, At, B1); PG8_BAR; PG8_SCHED;
;             PG8_LDA(At, 1, 1); PG8_STAGE(PG8_SB(1, 0), b3, voffB); PG8_STAGE(PG8_SB(1, 1), b3 + hstepB, voffB); PG8_STAGE(PG8_SA(1, 0), a3, voffA);
;             PG8_WAIT_V(8); PG8_WAIT_L(0); PG8_BAR; PG8_MMA(1, 0, At, B0); PG8_MMA(1, 1, At, B1); PG8_BAR; PG8_SCHED;
;         }
;         if (wr == 0) PG8_BAR;
;         E(acc, cur, wr, wc, fr, fq, pre);
;         if (!has_next) break;
	s_add_i32 s66, 0, 0x18000
	v_add_u32_e32 v167, s66, v158
	s_add_i32 s67, 0, 0x1c000
	ds_read_b128 v[168:171], v167
	ds_read_b128 v[172:175], v167 offset:1024
	ds_read_b128 v[176:179], v167 offset:2048
	ds_read_b128 v[180:183], v167 offset:3072
	v_add_u32_e32 v167, s67, v158
	ds_read_b128 v[186:189], v167
	ds_read_b128 v[190:193], v167 offset:1024
	ds_read_b128 v[194:197], v167 offset:2048
	ds_read_b128 v[198:201], v167 offset:3072
	s_add_u32 s44, s44, 0x40000
	s_addc_u32 s45, s45, 0
	s_mov_b32 m0, s51
	ds_read_b128 v[202:205], v160 offset:32768
	ds_read_b128 v[206:209], v160 offset:33792
	ds_read_b128 v[210:213], v160 offset:34816
	ds_read_b128 v[214:217], v160 offset:35840
	ds_read_b128 v[218:221], v160 offset:36864
	ds_read_b128 v[222:225], v160 offset:37888
	ds_read_b128 v[226:229], v160 offset:38912
	ds_read_b128 v[230:233], v160 offset:39936
	global_load_lds_dwordx4 v136, s[44:45]
	s_mov_b32 m0, s52
	s_nop 0
	global_load_lds_dwordx4 v132, s[44:45]
	s_waitcnt vmcnt(8)
	s_waitcnt lgkmcnt(0)
	s_barrier
	s_setprio 1
	v_mfma_f32_16x16x32_bf16 v[126:129], v[168:171], v[202:205], v[126:129]
	v_mfma_f32_16x16x32_bf16 v[118:121], v[176:179], v[202:205], v[118:121]
	v_mfma_f32_16x16x32_bf16 v[110:113], v[168:171], v[210:213], v[110:113]
	v_mfma_f32_16x16x32_bf16 v[102:105], v[176:179], v[210:213], v[102:105]
	v_mfma_f32_16x16x32_bf16 v[94:97], v[168:171], v[218:221], v[94:97]
	v_mfma_f32_16x16x32_bf16 v[86:89], v[176:179], v[218:221], v[86:89]
	v_mfma_f32_16x16x32_bf16 v[78:81], v[168:171], v[226:229], v[78:81]
	v_mfma_f32_16x16x32_bf16 v[70:73], v[176:179], v[226:229], v[70:73]
	v_mfma_f32_16x16x32_bf16 v[126:129], v[172:175], v[206:209], v[126:129]
	v_mfma_f32_16x16x32_bf16 v[118:121], v[180:183], v[206:209], v[118:121]
	v_mfma_f32_16x16x32_bf16 v[110:113], v[172:175], v[214:217], v[110:113]
	v_mfma_f32_16x16x32_bf16 v[102:105], v[180:183], v[214:217], v[102:105]
	v_mfma_f32_16x16x32_bf16 v[94:97], v[172:175], v[222:225], v[94:97]
	v_mfma_f32_16x16x32_bf16 v[86:89], v[180:183], v[222:225], v[86:89]
	v_mfma_f32_16x16x32_bf16 v[78:81], v[172:175], v[230:233], v[78:81]
	v_mfma_f32_16x16x32_bf16 v[70:73], v[180:183], v[230:233], v[70:73]
	v_mfma_f32_16x16x32_bf16 v[122:125], v[186:189], v[202:205], v[122:125]
	v_mfma_f32_16x16x32_bf16 v[114:117], v[194:197], v[202:205], v[114:117]
	v_mfma_f32_16x16x32_bf16 v[106:109], v[186:189], v[210:213], v[106:109]
	v_mfma_f32_16x16x32_bf16 v[98:101], v[194:197], v[210:213], v[98:101]
	v_mfma_f32_16x16x32_bf16 v[90:93], v[186:189], v[218:221], v[90:93]
	v_mfma_f32_16x16x32_bf16 v[82:85], v[194:197], v[218:221], v[82:85]
	v_mfma_f32_16x16x32_bf16 v[74:77], v[186:189], v[226:229], v[74:77]
	v_mfma_f32_16x16x32_bf16 v[66:69], v[194:197], v[226:229], v[66:69]
	v_mfma_f32_16x16x32_bf16 v[122:125], v[190:193], v[206:209], v[122:125]
	v_mfma_f32_16x16x32_bf16 v[114:117], v[198:201], v[206:209], v[114:117]
	v_mfma_f32_16x16x32_bf16 v[106:109], v[190:193], v[214:217], v[106:109]
	v_mfma_f32_16x16x32_bf16 v[98:101], v[198:201], v[214:217], v[98:101]
	v_mfma_f32_16x16x32_bf16 v[90:93], v[190:193], v[222:225], v[90:93]
	v_mfma_f32_16x16x32_bf16 v[82:85], v[198:201], v[222:225], v[82:85]
	v_mfma_f32_16x16x32_bf16 v[74:77], v[190:193], v[230:233], v[74:77]
	v_mfma_f32_16x16x32_bf16 v[66:69], v[198:201], v[230:233], v[66:69]
	s_setprio 0
	s_barrier
	s_add_i32 s44, s66, s46
	v_lshl_add_u64 v[234:235], v[234:235], 0, s[16:17]
	s_mov_b32 m0, s44
	ds_read_b128 v[202:205], v160 offset:49152
	ds_read_b128 v[206:209], v160 offset:50176
	ds_read_b128 v[210:213], v160 offset:51200
	ds_read_b128 v[214:217], v160 offset:52224
	ds_read_b128 v[218:221], v160 offset:53248
	ds_read_b128 v[222:225], v160 offset:54272
	ds_read_b128 v[226:229], v160 offset:55296
	ds_read_b128 v[230:233], v160 offset:56320
	global_load_lds_dwordx4 v[234:235], off
	s_add_i32 m0, s44, 0x2000
	s_add_u32 s42, s42, 0x40080
	v_lshl_add_u64 v[234:235], v[236:237], 0, s[16:17]
	s_addc_u32 s43, s43, 0
	s_add_i32 s44, s67, s46
	global_load_lds_dwordx4 v[234:235], off
	s_mov_b32 m0, s44
	s_nop 0
	global_load_lds_dwordx4 v134, s[42:43]
	s_add_i32 m0, s44, 0x2000
	s_nop 0
	global_load_lds_dwordx4 v130, s[42:43]
	v_lshl_add_u64 v[234:235], v[238:239], 0, s[16:17]
	s_mov_b32 m0, s54
	s_nop 0
	global_load_lds_dwordx4 v[234:235], off
	v_lshl_add_u64 v[234:235], v[240:241], 0, s[16:17]
	s_mov_b32 m0, s55
	s_nop 0
	global_load_lds_dwordx4 v[234:235], off
	s_waitcnt vmcnt(8)
	s_waitcnt lgkmcnt(0)
	s_barrier
	s_setprio 1
	v_mfma_f32_16x16x32_bf16 v[62:65], v[168:171], v[202:205], v[62:65]
	v_mfma_f32_16x16x32_bf16 v[54:57], v[176:179], v[202:205], v[54:57]
	v_mfma_f32_16x16x32_bf16 v[46:49], v[168:171], v[210:213], v[46:49]
	v_mfma_f32_16x16x32_bf16 v[38:41], v[176:179], v[210:213], v[38:41]
	v_mfma_f32_16x16x32_bf16 v[30:33], v[168:171], v[218:221], v[30:33]
	v_mfma_f32_16x16x32_bf16 v[22:25], v[176:179], v[218:221], v[22:25]
	v_mfma_f32_16x16x32_bf16 v[14:17], v[168:171], v[226:229], v[14:17]
	v_mfma_f32_16x16x32_bf16 v[6:9], v[176:179], v[226:229], v[6:9]
	v_mfma_f32_16x16x32_bf16 v[62:65], v[172:175], v[206:209], v[62:65]
	v_mfma_f32_16x16x32_bf16 v[54:57], v[180:183], v[206:209], v[54:57]
	v_mfma_f32_16x16x32_bf16 v[46:49], v[172:175], v[214:217], v[46:49]
	v_mfma_f32_16x16x32_bf16 v[38:41], v[180:183], v[214:217], v[38:41]
	v_mfma_f32_16x16x32_bf16 v[30:33], v[172:175], v[222:225], v[30:33]
	v_mfma_f32_16x16x32_bf16 v[22:25], v[180:183], v[222:225], v[22:25]
	v_mfma_f32_16x16x32_bf16 v[14:17], v[172:175], v[230:233], v[14:17]
	v_mfma_f32_16x16x32_bf16 v[6:9], v[180:183], v[230:233], v[6:9]
	v_mfma_f32_16x16x32_bf16 v[58:61], v[186:189], v[202:205], v[58:61]
	v_mfma_f32_16x16x32_bf16 v[50:53], v[194:197], v[202:205], v[50:53]
	v_mfma_f32_16x16x32_bf16 v[42:45], v[186:189], v[210:213], v[42:45]
	v_mfma_f32_16x16x32_bf16 v[34:37], v[194:197], v[210:213], v[34:37]
	v_mfma_f32_16x16x32_bf16 v[26:29], v[186:189], v[218:221], v[26:29]
	v_mfma_f32_16x16x32_bf16 v[18:21], v[194:197], v[218:221], v[18:21]
	v_mfma_f32_16x16x32_bf16 v[10:13], v[186:189], v[226:229], v[10:13]
	v_mfma_f32_16x16x32_bf16 v[2:5], v[194:197], v[226:229], v[2:5]
	v_mfma_f32_16x16x32_bf16 v[58:61], v[190:193], v[206:209], v[58:61]
	v_mfma_f32_16x16x32_bf16 v[50:53], v[198:201], v[206:209], v[50:53]
	v_mfma_f32_16x16x32_bf16 v[42:45], v[190:193], v[214:217], v[42:45]
	v_mfma_f32_16x16x32_bf16 v[34:37], v[198:201], v[214:217], v[34:37]
	v_mfma_f32_16x16x32_bf16 v[26:29], v[190:193], v[222:225], v[26:29]
	v_mfma_f32_16x16x32_bf16 v[18:21], v[198:201], v[222:225], v[18:21]
	v_mfma_f32_16x16x32_bf16 v[10:13], v[190:193], v[230:233], v[10:13]
	v_mfma_f32_16x16x32_bf16 v[2:5], v[198:201], v[230:233], v[2:5]
	s_setprio 0
	s_barrier
	s_add_i32 s65, s65, 2
	s_add_u32 s40, s40, 0x100
	s_addc_u32 s41, s41, 0
	s_add_u32 s63, s63, 0x100
	s_addc_u32 s64, s64, 0
	s_cmp_gt_u32 s65, 13
	s_cbranch_scc0 .LBB0_179
	s_mov_b32 s99, 1
	s_and_b64 vcc, exec, s[18:19]
	s_cbranch_vccz .LBB0_182
	s_barrier

; #define PG8_STAGE(bufoff, gbase, voff) do { _Pragma("unroll") for (int _i = 0; _i < 2; ++_i) \
;         __builtin_amdgcn_global_load_lds((const unsigned*)((const char*)(gbase) + (voff)[_i]), (LAS unsigned*)(lds + (bufoff) + ldsw + _i * 8192), 16, 0, 0); } while (0)
; #define PG8_LDA(dst, b, h) do { _Pragma("unroll") for (int m = 0; m < 4; ++m) _Pragma("unroll") for (int k = 0; k < 2; ++k) dst[m][k] = *(const LAS bf16x8*)(lds + PG8_SA(b, h) + aoff + m * 2048 + k * 1024); } while (0)
; #define PG8_LDB(dst, b, h) do { _Pragma("unroll") for (int n = 0; n < 2; ++n) _Pragma("unroll") for (int k = 0; k < 2; ++k) dst[n][k] = *(const LAS bf16x8*)(lds + PG8_SB(b, h) + boff + n * 2048 + k * 1024); } while (0)
; #define PG8_MMA(ai, bj, At, Bt) do { __builtin_amdgcn_s_setprio(1); _Pragma("unroll") for (int m = 0; m < 4; ++m) _Pragma("unroll") for (int n = 0; n < 2; ++n) _Pragma("unroll") for (int k = 0; k < 2; ++k) \
;         acc[ai][bj][m][n] = __builtin_amdgcn_mfma_f32_16x16x32_bf16(Bt[n][k], At[m][k], acc[ai][bj][m][n], 0, 0, 0); __builtin_amdgcn_s_setprio(0); } while (0)
; #define PG8_WAIT_V(n) asm volatile("s_waitcnt vmcnt(" #n ")" ::: "memory")
; template <class Epi, class Sched>
; DI void gemm_phase(LAS unsigned char* lds, const Gemm g, const Sched& S, const Epi& E) {
;     ...
;         const char* nA = has_next ? (const char*)(nxt.src ? g.A1 : g.A0) + (size_t)nxt.pm * tstepA : cA; const char* nB = has_next ? (const char*)(nxt.src ? g.B1 : g.B0) + (size_t)nxt.pn * tstepB : cB;
;         for (int t = 0; t < nt; t += 2) {
;             const bool last = (t == nt - 2);
;             const char* a1 = cA + (size_t)(t + 1) * kstep;
;             const char* a2 = last ? nA : cA + (size_t)(t + 2) * kstep; const char* b2 = last ? nB : cB + (size_t)(t + 2) * kstep;
;             const char* a3 = a2 + kstep; const char* b3 = b2 + kstep;
;             PG8_LDB(B0, 0, 0); PG8_LDB(B1, 0, 1); PG8_SCHED; PG8_LDA(At, 0, 0); PG8_STAGE(PG8_SA(1, 1), a1 + hstepA, voffA);
;             PG8_WAIT_V(8); PG8_WAIT_L(0); PG8_BAR; PG8_MMA(0, 0, At, B0); PG8_MMA(0, 1, At, B1); PG8_BAR; PG8_SCHED;
;             PG8_LDA(At, 0, 1); PG8_STAGE(PG8_SB(0, 0), b2, voffB); PG8_STAGE(PG8_SB(0, 1), b2 + hstepB, voffB); PG8_STAGE(PG8_SA(0, 0), a2, voffA);
;             PG8_WAIT_V(8); PG8_WAIT_L(0); PG8_BAR; PG8_MMA(1, 0, At, B0); PG8_MMA(1, 1, At, B1); PG8_BAR; PG8_SCHED;
.LBB0_277:
	s_add_u32 s36, s36, 0xb0080
	s_addc_u32 s37, s37, 0
	s_add_u32 s60, s38, 0x100
	s_addc_u32 s61, s39, 0
	s_mov_b32 s62, -2
	s_waitcnt lgkmcnt(0)
	ds_read_b128 v[148:151], v154
	ds_read_b128 v[158:161], v154 offset:1024
	ds_read_b128 v[162:165], v154 offset:2048
	ds_read_b128 v[166:169], v154 offset:3072
	ds_read_b128 v[170:173], v155
	ds_read_b128 v[174:177], v155 offset:1024
	ds_read_b128 v[178:181], v155 offset:2048
	ds_read_b128 v[186:189], v155 offset:3072
	s_add_u32 s38, s36, 0xfff50080
	s_addc_u32 s39, s37, -1
	s_cmp_eq_u32 s62, 40
	s_cselect_b32 s41, s9, s39
	s_cselect_b32 s40, s8, s38
	s_cselect_b32 s39, s35, s61
	s_cselect_b32 s38, s34, s60
	s_add_i32 m0, s45, 0xc000
	ds_read_b128 v[190:193], v156
	ds_read_b128 v[194:197], v156 offset:1024
	ds_read_b128 v[198:201], v156 offset:2048
	ds_read_b128 v[202:205], v156 offset:3072
	ds_read_b128 v[206:209], v156 offset:4096
	ds_read_b128 v[210:213], v156 offset:5120
	ds_read_b128 v[214:217], v156 offset:6144
	ds_read_b128 v[218:221], v156 offset:7168
	global_load_lds_dwordx4 v138, s[36:37]
	s_add_i32 m0, s45, 0xe000
	s_nop 0
	global_load_lds_dwordx4 v140, s[36:37]
	s_cmp_lg_u32 s99, 0
	s_cbranch_scc1 .Lpk1_w1
	s_waitcnt vmcnt(8)
.Lpk1_w1:
	s_waitcnt lgkmcnt(0)
	s_barrier
	s_setprio 1
	v_mfma_f32_16x16x32_bf16 v[126:129], v[148:151], v[190:193], 0
	v_mfma_f32_16x16x32_bf16 v[122:125], v[162:165], v[190:193], 0
	v_mfma_f32_16x16x32_bf16 v[110:113], v[148:151], v[198:201], 0
	v_mfma_f32_16x16x32_bf16 v[106:109], v[162:165], v[198:201], 0
	v_mfma_f32_16x16x32_bf16 v[94:97], v[148:151], v[206:209], 0
	v_mfma_f32_16x16x32_bf16 v[90:93], v[162:165], v[206:209], 0
	v_mfma_f32_16x16x32_bf16 v[78:81], v[148:151], v[214:217], 0
	v_mfma_f32_16x16x32_bf16 v[74:77], v[162:165], v[214:217], 0
	v_mfma_f32_16x16x32_bf16 v[126:129], v[158:161], v[194:197], v[126:129]
	v_mfma_f32_16x16x32_bf16 v[122:125], v[166:169], v[194:197], v[122:125]
	v_mfma_f32_16x16x32_bf16 v[110:113], v[158:161], v[202:205], v[110:113]
	v_mfma_f32_16x16x32_bf16 v[106:109], v[166:169], v[202:205], v[106:109]
	v_mfma_f32_16x16x32_bf16 v[94:97], v[158:161], v[210:213], v[94:97]
	v_mfma_f32_16x16x32_bf16 v[90:93], v[166:169], v[210:213], v[90:93]
	v_mfma_f32_16x16x32_bf16 v[78:81], v[158:161], v[218:221], v[78:81]
	v_mfma_f32_16x16x32_bf16 v[74:77], v[166:169], v[218:221], v[74:77]
	v_mfma_f32_16x16x32_bf16 v[118:121], v[170:173], v[190:193], 0
	v_mfma_f32_16x16x32_bf16 v[114:117], v[178:181], v[190:193], 0
	v_mfma_f32_16x16x32_bf16 v[102:105], v[170:173], v[198:201], 0
	v_mfma_f32_16x16x32_bf16 v[98:101], v[178:181], v[198:201], 0
	v_mfma_f32_16x16x32_bf16 v[86:89], v[170:173], v[206:209], 0
	v_mfma_f32_16x16x32_bf16 v[82:85], v[178:181], v[206:209], 0
	v_mfma_f32_16x16x32_bf16 v[70:73], v[170:173], v[214:217], 0
	v_mfma_f32_16x16x32_bf16 v[66:69], v[178:181], v[214:217], 0
	v_mfma_f32_16x16x32_bf16 v[118:121], v[174:177], v[194:197], v[118:121]
	v_mfma_f32_16x16x32_bf16 v[114:117], v[186:189], v[194:197], v[114:117]
	v_mfma_f32_16x16x32_bf16 v[102:105], v[174:177], v[202:205], v[102:105]
	v_mfma_f32_16x16x32_bf16 v[98:101], v[186:189], v[202:205], v[98:101]
	v_mfma_f32_16x16x32_bf16 v[86:89], v[174:177], v[210:213], v[86:89]
	v_mfma_f32_16x16x32_bf16 v[82:85], v[186:189], v[210:213], v[82:85]
	v_mfma_f32_16x16x32_bf16 v[70:73], v[174:177], v[218:221], v[70:73]
	v_mfma_f32_16x16x32_bf16 v[66:69], v[186:189], v[218:221], v[66:69]
	s_setprio 0
	s_barrier
	s_add_i32 s63, s54, s44
	v_lshl_add_u64 v[182:183], s[38:39], 0, v[132:133]
	s_mov_b32 m0, s63
	ds_read_b128 v[190:193], v156 offset:16384
	ds_read_b128 v[194:197], v156 offset:17408
	ds_read_b128 v[198:201], v156 offset:18432
	ds_read_b128 v[202:205], v156 offset:19456
	ds_read_b128 v[206:209], v156 offset:20480
	ds_read_b128 v[210:213], v156 offset:21504
	ds_read_b128 v[214:217], v156 offset:22528
	ds_read_b128 v[218:221], v156 offset:23552
	global_load_lds_dwordx4 v[182:183], off
	s_add_i32 m0, s63, 0x2000
	s_add_u32 s64, s38, 0xb0000
	v_lshl_add_u64 v[222:223], s[38:39], 0, v[136:137]
	s_addc_u32 s65, s39, 0
	s_add_i32 s63, s55, s44
	global_load_lds_dwordx4 v[222:223], off
	s_mov_b32 m0, s63
	v_lshl_add_u64 v[226:227], s[40:41], 0, v[134:135]
	global_load_lds_dwordx4 v132, s[64:65]
	s_add_i32 m0, s63, 0x2000
	s_nop 0
	global_load_lds_dwordx4 v136, s[64:65]
	v_lshl_add_u64 v[224:225], s[40:41], 0, v[130:131]
	s_mov_b32 m0, s45
	s_nop 0
	global_load_lds_dwordx4 v[224:225], off
	s_mov_b32 m0, s46
	s_nop 0
	global_load_lds_dwordx4 v[226:227], off
	s_cmp_lg_u32 s99, 0
	s_cbranch_scc1 .Lpk1_w2
	s_waitcnt vmcnt(8)
; #define PG8_STAGE(bufoff, gbase, voff) do { _Pragma("unroll") for (int _i = 0; _i < 2; ++_i) \
;         __builtin_amdgcn_global_load_lds((const unsigned*)((const char*)(gbase) + (voff)[_i]), (LAS unsigned*)(lds + (bufoff) + ldsw + _i * 8192), 16, 0, 0); } while (0)
; #define PG8_LDA(dst, b, h) do { _Pragma("unroll") for (int m = 0; m < 4; ++m) _Pragma("unroll") for (int k = 0; k < 2; ++k) dst[m][k] = *(const LAS bf16x8*)(lds + PG8_SA(b, h) + aoff + m * 2048 + k * 1024); } while (0)
; #define PG8_LDB(dst, b, h) do { _Pragma("unroll") for (int n = 0; n < 2; ++n) _Pragma("unroll") for (int k = 0; k < 2; ++k) dst[n][k] = *(const LAS bf16x8*)(lds + PG8_SB(b, h) + boff + n * 2048 + k * 1024); } while (0)
; #define PG8_MMA(ai, bj, At, Bt) do { __builtin_amdgcn_s_setprio(1); _Pragma("unroll") for (int m = 0; m < 4; ++m) _Pragma("unroll") for (int n = 0; n < 2; ++n) _Pragma("unroll") for (int k = 0; k < 2; ++k) \
;         acc[ai][bj][m][n] = __builtin_amdgcn_mfma_f32_16x16x32_bf16(Bt[n][k], At[m][k], acc[ai][bj][m][n], 0, 0, 0); __builtin_amdgcn_s_setprio(0); } while (0)
; #define PG8_WAIT_V(n) asm volatile("s_waitcnt vmcnt(" #n ")" ::: "memory")
; #define PG8_WAIT_L(n) asm volatile("s_waitcnt lgkmcnt(" #n ")" ::: "memory")
; #define PG8_BAR __builtin_amdgcn_s_barrier()
; #define PG8_SCHED __builtin_amdgcn_sched_barrier(0)
; template <class Epi, class Sched>
; DI void gemm_phase(LAS unsigned char* lds, const Gemm g, const Sched& S, const Epi& E) {
;     ...
;             PG8_WAIT_V(8); PG8_WAIT_L(0); PG8_BAR; PG8_MMA(1, 0, At, B0); PG8_MMA(1, 1, At, B1); PG8_BAR; PG8_SCHED;
;             PG8_LDB(B0, 1, 0); PG8_LDB(B1, 1, 1); PG8_SCHED; PG8_LDA(At, 1, 0); PG8_STAGE(PG8_SA(0, 1), a2 + hstepA, voffA);
;             PG8_WAIT_V(8); PG8_WAIT_L(0); PG8_BAR; PG8_MMA(0, 0, At, B0); PG8_MMA(0, 1, At, B1); PG8_BAR; PG8_SCHED;
;             PG8_LDA(At, 1, 1); PG8_STAGE(PG8_SB(1, 0), b3, voffB); PG8_STAGE(PG8_SB(1, 1), b3 + hstepB, voffB); PG8_STAGE(PG8_SA(1, 0), a3, voffA);
;             PG8_WAIT_V(8); PG8_WAIT_L(0); PG8_BAR; PG8_MMA(1, 0, At, B0); PG8_MMA(1, 1, At, B1); PG8_BAR; PG8_SCHED;
.Lpk1_w2:
	s_mov_b32 s99, 0
	s_waitcnt lgkmcnt(0)
	s_barrier
	s_setprio 1
	v_mfma_f32_16x16x32_bf16 v[62:65], v[148:151], v[190:193], 0
	v_mfma_f32_16x16x32_bf16 v[58:61], v[162:165], v[190:193], 0
	v_mfma_f32_16x16x32_bf16 v[46:49], v[148:151], v[198:201], 0
	v_mfma_f32_16x16x32_bf16 v[42:45], v[162:165], v[198:201], 0
	v_mfma_f32_16x16x32_bf16 v[30:33], v[148:151], v[206:209], 0
	v_mfma_f32_16x16x32_bf16 v[26:29], v[162:165], v[206:209], 0
	v_mfma_f32_16x16x32_bf16 v[14:17], v[148:151], v[214:217], 0
	v_mfma_f32_16x16x32_bf16 v[10:13], v[162:165], v[214:217], 0
	v_mfma_f32_16x16x32_bf16 v[62:65], v[158:161], v[194:197], v[62:65]
	v_mfma_f32_16x16x32_bf16 v[58:61], v[166:169], v[194:197], v[58:61]
	v_mfma_f32_16x16x32_bf16 v[46:49], v[158:161], v[202:205], v[46:49]
	v_mfma_f32_16x16x32_bf16 v[42:45], v[166:169], v[202:205], v[42:45]
	v_mfma_f32_16x16x32_bf16 v[30:33], v[158:161], v[210:213], v[30:33]
	v_mfma_f32_16x16x32_bf16 v[26:29], v[166:169], v[210:213], v[26:29]
	v_mfma_f32_16x16x32_bf16 v[14:17], v[158:161], v[218:221], v[14:17]
	v_mfma_f32_16x16x32_bf16 v[10:13], v[166:169], v[218:221], v[10:13]
	v_mfma_f32_16x16x32_bf16 v[54:57], v[170:173], v[190:193], 0
	v_mfma_f32_16x16x32_bf16 v[50:53], v[178:181], v[190:193], 0
	v_mfma_f32_16x16x32_bf16 v[38:41], v[170:173], v[198:201], 0
	v_mfma_f32_16x16x32_bf16 v[34:37], v[178:181], v[198:201], 0
	v_mfma_f32_16x16x32_bf16 v[22:25], v[170:173], v[206:209], 0
	v_mfma_f32_16x16x32_bf16 v[18:21], v[178:181], v[206:209], 0
	v_mfma_f32_16x16x32_bf16 v[6:9], v[170:173], v[214:217], 0
	v_mfma_f32_16x16x32_bf16 v[2:5], v[178:181], v[214:217], 0
	v_mfma_f32_16x16x32_bf16 v[54:57], v[174:177], v[194:197], v[54:57]
	v_mfma_f32_16x16x32_bf16 v[50:53], v[186:189], v[194:197], v[50:53]
	v_mfma_f32_16x16x32_bf16 v[38:41], v[174:177], v[202:205], v[38:41]
	v_mfma_f32_16x16x32_bf16 v[34:37], v[186:189], v[202:205], v[34:37]
	v_mfma_f32_16x16x32_bf16 v[22:25], v[174:177], v[210:213], v[22:25]
	v_mfma_f32_16x16x32_bf16 v[18:21], v[186:189], v[210:213], v[18:21]
	v_mfma_f32_16x16x32_bf16 v[6:9], v[174:177], v[218:221], v[6:9]
	v_mfma_f32_16x16x32_bf16 v[2:5], v[186:189], v[218:221], v[2:5]
	s_setprio 0
	s_barrier
	s_add_i32 s63, 0, 0x18000
	s_add_i32 s64, 0, 0x1c000
	v_add_u32_e32 v166, s63, v152
	v_add_u32_e32 v185, s64, v152
	ds_read_b128 v[148:151], v166
	ds_read_b128 v[158:161], v166 offset:1024
	ds_read_b128 v[162:165], v166 offset:2048
	ds_read_b128 v[166:169], v166 offset:3072
	ds_read_b128 v[170:173], v185
	ds_read_b128 v[174:177], v185 offset:1024
	ds_read_b128 v[178:181], v185 offset:2048
	ds_read_b128 v[186:189], v185 offset:3072
	s_add_u32 s40, s40, 0xb0000
	s_addc_u32 s41, s41, 0
	s_mov_b32 m0, s47
	ds_read_b128 v[190:193], v156 offset:32768
	ds_read_b128 v[194:197], v156 offset:33792
	ds_read_b128 v[198:201], v156 offset:34816
	ds_read_b128 v[202:205], v156 offset:35840
	ds_read_b128 v[206:209], v156 offset:36864
	ds_read_b128 v[210:213], v156 offset:37888
	ds_read_b128 v[214:217], v156 offset:38912
	ds_read_b128 v[218:221], v156 offset:39936
	global_load_lds_dwordx4 v130, s[40:41]
	s_mov_b32 m0, s48
	s_nop 0
	global_load_lds_dwordx4 v134, s[40:41]
	s_waitcnt vmcnt(8)
	s_waitcnt lgkmcnt(0)
	s_barrier
	s_setprio 1
	v_mfma_f32_16x16x32_bf16 v[126:129], v[148:151], v[190:193], v[126:129]
	v_mfma_f32_16x16x32_bf16 v[122:125], v[162:165], v[190:193], v[122:125]
	v_mfma_f32_16x16x32_bf16 v[110:113], v[148:151], v[198:201], v[110:113]
	v_mfma_f32_16x16x32_bf16 v[106:109], v[162:165], v[198:201], v[106:109]
	v_mfma_f32_16x16x32_bf16 v[94:97], v[148:151], v[206:209], v[94:97]
	v_mfma_f32_16x16x32_bf16 v[90:93], v[162:165], v[206:209], v[90:93]
	v_mfma_f32_16x16x32_bf16 v[78:81], v[148:151], v[214:217], v[78:81]
	v_mfma_f32_16x16x32_bf16 v[74:77], v[162:165], v[214:217], v[74:77]
	v_mfma_f32_16x16x32_bf16 v[126:129], v[158:161], v[194:197], v[126:129]
	v_mfma_f32_16x16x32_bf16 v[122:125], v[166:169], v[194:197], v[122:125]
	v_mfma_f32_16x16x32_bf16 v[110:113], v[158:161], v[202:205], v[110:113]
	v_mfma_f32_16x16x32_bf16 v[106:109], v[166:169], v[202:205], v[106:109]
	v_mfma_f32_16x16x32_bf16 v[94:97], v[158:161], v[210:213], v[94:97]
	v_mfma_f32_16x16x32_bf16 v[90:93], v[166:169], v[210:213], v[90:93]
	v_mfma_f32_16x16x32_bf16 v[78:81], v[158:161], v[218:221], v[78:81]
	v_mfma_f32_16x16x32_bf16 v[74:77], v[166:169], v[218:221], v[74:77]
	v_mfma_f32_16x16x32_bf16 v[118:121], v[170:173], v[190:193], v[118:121]
	v_mfma_f32_16x16x32_bf16 v[114:117], v[178:181], v[190:193], v[114:117]
	v_mfma_f32_16x16x32_bf16 v[102:105], v[170:173], v[198:201], v[102:105]
	v_mfma_f32_16x16x32_bf16 v[98:101], v[178:181], v[198:201], v[98:101]
	v_mfma_f32_16x16x32_bf16 v[86:89], v[170:173], v[206:209], v[86:89]
	v_mfma_f32_16x16x32_bf16 v[82:85], v[178:181], v[206:209], v[82:85]
	v_mfma_f32_16x16x32_bf16 v[70:73], v[170:173], v[214:217], v[70:73]
	v_mfma_f32_16x16x32_bf16 v[66:69], v[178:181], v[214:217], v[66:69]
	v_mfma_f32_16x16x32_bf16 v[118:121], v[174:177], v[194:197], v[118:121]
	v_mfma_f32_16x16x32_bf16 v[114:117], v[186:189], v[194:197], v[114:117]
	v_mfma_f32_16x16x32_bf16 v[102:105], v[174:177], v[202:205], v[102:105]
	v_mfma_f32_16x16x32_bf16 v[98:101], v[186:189], v[202:205], v[98:101]
	v_mfma_f32_16x16x32_bf16 v[86:89], v[174:177], v[210:213], v[86:89]
	v_mfma_f32_16x16x32_bf16 v[82:85], v[186:189], v[210:213], v[82:85]
	v_mfma_f32_16x16x32_bf16 v[70:73], v[174:177], v[218:221], v[70:73]
	v_mfma_f32_16x16x32_bf16 v[66:69], v[186:189], v[218:221], v[66:69]
	s_setprio 0
	s_barrier
; #define PG8_STAGE(bufoff, gbase, voff) do { _Pragma("unroll") for (int _i = 0; _i < 2; ++_i) \
;         __builtin_amdgcn_global_load_lds((const unsigned*)((const char*)(gbase) + (voff)[_i]), (LAS unsigned*)(lds + (bufoff) + ldsw + _i * 8192), 16, 0, 0); } while (0)
; #define PG8_LDA(dst, b, h) do { _Pragma("unroll") for (int m = 0; m < 4; ++m) _Pragma("unroll") for (int k = 0; k < 2; ++k) dst[m][k] = *(const LAS bf16x8*)(lds + PG8_SA(b, h) + aoff + m * 2048 + k * 1024); } while (0)
; #define PG8_LDB(dst, b, h) do { _Pragma("unroll") for (int n = 0; n < 2; ++n) _Pragma("unroll") for (int k = 0; k < 2; ++k) dst[n][k] = *(const LAS bf16x8*)(lds + PG8_SB(b, h) + boff + n * 2048 + k * 1024); } while (0)
; #define PG8_WAIT_V(n) asm volatile("s_waitcnt vmcnt(" #n ")" ::: "memory")
; #define PG8_WAIT_L(n) asm volatile("s_waitcnt lgkmcnt(" #n ")" ::: "memory")
; template <class Epi, class Sched>
; DI void gemm_phase(LAS unsigned char* lds, const Gemm g, const Sched& S, const Epi& E) {
;     ...
;         for (int t = 0; t < nt; t += 2) {
;             const bool last = (t == nt - 2);
;             const char* a1 = cA + (size_t)(t + 1) * kstep;
;             const char* a2 = last ? nA : cA + (size_t)(t + 2) * kstep; const char* b2 = last ? nB : cB + (size_t)(t + 2) * kstep;
;             const char* a3 = a2 + kstep; const char* b3 = b2 + kstep;
;             PG8_LDB(B0, 0, 0); PG8_LDB(B1, 0, 1); PG8_SCHED; PG8_LDA(At, 0, 0); PG8_STAGE(PG8_SA(1, 1), a1 + hstepA, voffA);
;             PG8_WAIT_V(8); PG8_WAIT_L(0); PG8_BAR; PG8_MMA(0, 0, At, B0); PG8_MMA(0, 1, At, B1); PG8_BAR; PG8_SCHED;
;             PG8_LDA(At, 0, 1); PG8_STAGE(PG8_SB(0, 0), b2, voffB); PG8_STAGE(PG8_SB(0, 1), b2 + hstepB, voffB); PG8_STAGE(PG8_SA(0, 0), a2, voffA);
;             PG8_WAIT_V(8); PG8_WAIT_L(0); PG8_BAR; PG8_MMA(1, 0, At, B0); PG8_MMA(1, 1, At, B1); PG8_BAR; PG8_SCHED;
;             PG8_LDB(B0, 1, 0); PG8_LDB(B1, 1, 1); PG8_SCHED; PG8_LDA(At, 1, 0); PG8_STAGE(PG8_SA(0, 1), a2 + hstepA, voffA);
;             PG8_WAIT_V(8); PG8_WAIT_L(0); PG8_BAR; PG8_MMA(0, 0, At, B0); PG8_MMA(0, 1, At, B1); PG8_BAR; PG8_SCHED;
;             PG8_LDA(At, 1, 1); PG8_STAGE(PG8_SB(1, 0), b3, voffB); PG8_STAGE(PG8_SB(1, 1), b3 + hstepB, voffB); PG8_STAGE(PG8_SA(1, 0), a3, voffA);
;             PG8_WAIT_V(8); PG8_WAIT_L(0); PG8_BAR; PG8_MMA(1, 0, At, B0); PG8_MMA(1, 1, At, B1); PG8_BAR; PG8_SCHED;
	s_add_i32 s40, s63, s44
	v_lshl_add_u64 v[182:183], v[182:183], 0, s[16:17]
	s_mov_b32 m0, s40
	ds_read_b128 v[190:193], v156 offset:49152
	ds_read_b128 v[194:197], v156 offset:50176
	ds_read_b128 v[198:201], v156 offset:51200
	ds_read_b128 v[202:205], v156 offset:52224
	ds_read_b128 v[206:209], v156 offset:53248
	ds_read_b128 v[210:213], v156 offset:54272
	ds_read_b128 v[214:217], v156 offset:55296
	ds_read_b128 v[218:221], v156 offset:56320
	global_load_lds_dwordx4 v[182:183], off
	s_add_i32 m0, s40, 0x2000
	s_add_u32 s38, s38, 0xb0080
	v_lshl_add_u64 v[182:183], v[222:223], 0, s[16:17]
	s_addc_u32 s39, s39, 0
	s_add_i32 s40, s64, s44
	global_load_lds_dwordx4 v[182:183], off
	s_mov_b32 m0, s40
	s_nop 0
	global_load_lds_dwordx4 v132, s[38:39]
	s_add_i32 m0, s40, 0x2000
	s_nop 0
	global_load_lds_dwordx4 v136, s[38:39]
	v_lshl_add_u64 v[182:183], v[224:225], 0, s[16:17]
	s_mov_b32 m0, s50
	s_nop 0
	global_load_lds_dwordx4 v[182:183], off
	v_lshl_add_u64 v[182:183], v[226:227], 0, s[16:17]
	s_mov_b32 m0, s51
	s_nop 0
	global_load_lds_dwordx4 v[182:183], off
	s_waitcnt vmcnt(8)
	s_waitcnt lgkmcnt(0)
	s_barrier
	s_setprio 1
	v_mfma_f32_16x16x32_bf16 v[62:65], v[148:151], v[190:193], v[62:65]
	v_mfma_f32_16x16x32_bf16 v[58:61], v[162:165], v[190:193], v[58:61]
	v_mfma_f32_16x16x32_bf16 v[46:49], v[148:151], v[198:201], v[46:49]
	v_mfma_f32_16x16x32_bf16 v[42:45], v[162:165], v[198:201], v[42:45]
	v_mfma_f32_16x16x32_bf16 v[30:33], v[148:151], v[206:209], v[30:33]
	v_mfma_f32_16x16x32_bf16 v[26:29], v[162:165], v[206:209], v[26:29]
	v_mfma_f32_16x16x32_bf16 v[14:17], v[148:151], v[214:217], v[14:17]
	v_mfma_f32_16x16x32_bf16 v[10:13], v[162:165], v[214:217], v[10:13]
	v_mfma_f32_16x16x32_bf16 v[62:65], v[158:161], v[194:197], v[62:65]
	v_mfma_f32_16x16x32_bf16 v[58:61], v[166:169], v[194:197], v[58:61]
	v_mfma_f32_16x16x32_bf16 v[46:49], v[158:161], v[202:205], v[46:49]
	v_mfma_f32_16x16x32_bf16 v[42:45], v[166:169], v[202:205], v[42:45]
	v_mfma_f32_16x16x32_bf16 v[30:33], v[158:161], v[210:213], v[30:33]
	v_mfma_f32_16x16x32_bf16 v[26:29], v[166:169], v[210:213], v[26:29]
	v_mfma_f32_16x16x32_bf16 v[14:17], v[158:161], v[218:221], v[14:17]
	v_mfma_f32_16x16x32_bf16 v[10:13], v[166:169], v[218:221], v[10:13]
	v_mfma_f32_16x16x32_bf16 v[54:57], v[170:173], v[190:193], v[54:57]
	v_mfma_f32_16x16x32_bf16 v[50:53], v[178:181], v[190:193], v[50:53]
	v_mfma_f32_16x16x32_bf16 v[38:41], v[170:173], v[198:201], v[38:41]
	v_mfma_f32_16x16x32_bf16 v[34:37], v[178:181], v[198:201], v[34:37]
	v_mfma_f32_16x16x32_bf16 v[22:25], v[170:173], v[206:209], v[22:25]
	v_mfma_f32_16x16x32_bf16 v[18:21], v[178:181], v[206:209], v[18:21]
	v_mfma_f32_16x16x32_bf16 v[6:9], v[170:173], v[214:217], v[6:9]
	v_mfma_f32_16x16x32_bf16 v[2:5], v[178:181], v[214:217], v[2:5]
	v_mfma_f32_16x16x32_bf16 v[54:57], v[174:177], v[194:197], v[54:57]
	v_mfma_f32_16x16x32_bf16 v[50:53], v[186:189], v[194:197], v[50:53]
	v_mfma_f32_16x16x32_bf16 v[38:41], v[174:177], v[202:205], v[38:41]
	v_mfma_f32_16x16x32_bf16 v[34:37], v[186:189], v[202:205], v[34:37]
	v_mfma_f32_16x16x32_bf16 v[22:25], v[174:177], v[210:213], v[22:25]
	v_mfma_f32_16x16x32_bf16 v[18:21], v[186:189], v[210:213], v[18:21]
	v_mfma_f32_16x16x32_bf16 v[6:9], v[174:177], v[218:221], v[6:9]
	v_mfma_f32_16x16x32_bf16 v[2:5], v[186:189], v[218:221], v[2:5]
	s_setprio 0
	s_barrier
	s_add_i32 s62, s62, 2
	s_add_u32 s36, s36, 0x100
	s_addc_u32 s37, s37, 0
	s_add_u32 s60, s60, 0x100
	s_addc_u32 s61, s61, 0
	s_cmp_gt_u32 s62, 41
.LBB0_278:
	ds_read_b128 v[148:151], v154
	ds_read_b128 v[158:161], v154 offset:1024
	ds_read_b128 v[162:165], v154 offset:2048
	ds_read_b128 v[166:169], v154 offset:3072
	ds_read_b128 v[170:173], v155
	ds_read_b128 v[174:177], v155 offset:1024
	ds_read_b128 v[178:181], v155 offset:2048
	ds_read_b128 v[186:189], v155 offset:3072
	s_add_u32 s38, s36, 0xfff50080
	s_addc_u32 s39, s37, -1
	s_cmp_eq_u32 s62, 40
	s_cselect_b32 s41, s9, s39
	s_cselect_b32 s40, s8, s38
	s_cselect_b32 s39, s35, s61
	s_cselect_b32 s38, s34, s60
	s_add_i32 m0, s45, 0xc000
	ds_read_b128 v[190:193], v156
	ds_read_b128 v[194:197], v156 offset:1024
	ds_read_b128 v[198:201], v156 offset:2048
	ds_read_b128 v[202:205], v156 offset:3072
	ds_read_b128 v[206:209], v156 offset:4096
	ds_read_b128 v[210:213], v156 offset:5120
	ds_read_b128 v[214:217], v156 offset:6144
	ds_read_b128 v[218:221], v156 offset:7168
	global_load_lds_dwordx4 v138, s[36:37]
	s_add_i32 m0, s45, 0xe000
	s_nop 0
	global_load_lds_dwordx4 v140, s[36:37]
	s_waitcnt vmcnt(8)
	s_waitcnt lgkmcnt(0)
	s_barrier
; #define PG8_STAGE(bufoff, gbase, voff) do { _Pragma("unroll") for (int _i = 0; _i < 2; ++_i) \
;         __builtin_amdgcn_global_load_lds((const unsigned*)((const char*)(gbase) + (voff)[_i]), (LAS unsigned*)(lds + (bufoff) + ldsw + _i * 8192), 16, 0, 0); } while (0)
; #define PG8_LDA(dst, b, h) do { _Pragma("unroll") for (int m = 0; m < 4; ++m) _Pragma("unroll") for (int k = 0; k < 2; ++k) dst[m][k] = *(const LAS bf16x8*)(lds + PG8_SA(b, h) + aoff + m * 2048 + k * 1024); } while (0)
; #define PG8_LDB(dst, b, h) do { _Pragma("unroll") for (int n = 0; n < 2; ++n) _Pragma("unroll") for (int k = 0; k < 2; ++k) dst[n][k] = *(const LAS bf16x8*)(lds + PG8_SB(b, h) + boff + n * 2048 + k * 1024); } while (0)
; #define PG8_MMA(ai, bj, At, Bt) do { __builtin_amdgcn_s_setprio(1); _Pragma("unroll") for (int m = 0; m < 4; ++m) _Pragma("unroll") for (int n = 0; n < 2; ++n) _Pragma("unroll") for (int k = 0; k < 2; ++k) \
;         acc[ai][bj][m][n] = __builtin_amdgcn_mfma_f32_16x16x32_bf16(Bt[n][k], At[m][k], acc[ai][bj][m][n], 0, 0, 0); __builtin_amdgcn_s_setprio(0); } while (0)
; #define PG8_WAIT_V(n) asm volatile("s_waitcnt vmcnt(" #n ")" ::: "memory")
; #define PG8_WAIT_L(n) asm volatile("s_waitcnt lgkmcnt(" #n ")" ::: "memory")
; #define PG8_BAR __builtin_amdgcn_s_barrier()
; #define PG8_SCHED __builtin_amdgcn_sched_barrier(0)
; template <class Epi, class Sched>
; DI void gemm_phase(LAS unsigned char* lds, const Gemm g, const Sched& S, const Epi& E) {
;     ...
;             PG8_WAIT_V(8); PG8_WAIT_L(0); PG8_BAR; PG8_MMA(0, 0, At, B0); PG8_MMA(0, 1, At, B1); PG8_BAR; PG8_SCHED;
;             PG8_LDA(At, 0, 1); PG8_STAGE(PG8_SB(0, 0), b2, voffB); PG8_STAGE(PG8_SB(0, 1), b2 + hstepB, voffB); PG8_STAGE(PG8_SA(0, 0), a2, voffA);
;             PG8_WAIT_V(8); PG8_WAIT_L(0); PG8_BAR; PG8_MMA(1, 0, At, B0); PG8_MMA(1, 1, At, B1); PG8_BAR; PG8_SCHED;
;             PG8_LDB(B0, 1, 0); PG8_LDB(B1, 1, 1); PG8_SCHED; PG8_LDA(At, 1, 0); PG8_STAGE(PG8_SA(0, 1), a2 + hstepA, voffA);
;             PG8_WAIT_V(8); PG8_WAIT_L(0); PG8_BAR; PG8_MMA(0, 0, At, B0); PG8_MMA(0, 1, At, B1); PG8_BAR; PG8_SCHED;
	s_setprio 1
	v_mfma_f32_16x16x32_bf16 v[126:129], v[148:151], v[190:193], v[126:129]
	v_mfma_f32_16x16x32_bf16 v[122:125], v[162:165], v[190:193], v[122:125]
	v_mfma_f32_16x16x32_bf16 v[110:113], v[148:151], v[198:201], v[110:113]
	v_mfma_f32_16x16x32_bf16 v[106:109], v[162:165], v[198:201], v[106:109]
	v_mfma_f32_16x16x32_bf16 v[94:97], v[148:151], v[206:209], v[94:97]
	v_mfma_f32_16x16x32_bf16 v[90:93], v[162:165], v[206:209], v[90:93]
	v_mfma_f32_16x16x32_bf16 v[78:81], v[148:151], v[214:217], v[78:81]
	v_mfma_f32_16x16x32_bf16 v[74:77], v[162:165], v[214:217], v[74:77]
	v_mfma_f32_16x16x32_bf16 v[126:129], v[158:161], v[194:197], v[126:129]
	v_mfma_f32_16x16x32_bf16 v[122:125], v[166:169], v[194:197], v[122:125]
	v_mfma_f32_16x16x32_bf16 v[110:113], v[158:161], v[202:205], v[110:113]
	v_mfma_f32_16x16x32_bf16 v[106:109], v[166:169], v[202:205], v[106:109]
	v_mfma_f32_16x16x32_bf16 v[94:97], v[158:161], v[210:213], v[94:97]
	v_mfma_f32_16x16x32_bf16 v[90:93], v[166:169], v[210:213], v[90:93]
	v_mfma_f32_16x16x32_bf16 v[78:81], v[158:161], v[218:221], v[78:81]
	v_mfma_f32_16x16x32_bf16 v[74:77], v[166:169], v[218:221], v[74:77]
	v_mfma_f32_16x16x32_bf16 v[118:121], v[170:173], v[190:193], v[118:121]
	v_mfma_f32_16x16x32_bf16 v[114:117], v[178:181], v[190:193], v[114:117]
	v_mfma_f32_16x16x32_bf16 v[102:105], v[170:173], v[198:201], v[102:105]
	v_mfma_f32_16x16x32_bf16 v[98:101], v[178:181], v[198:201], v[98:101]
	v_mfma_f32_16x16x32_bf16 v[86:89], v[170:173], v[206:209], v[86:89]
	v_mfma_f32_16x16x32_bf16 v[82:85], v[178:181], v[206:209], v[82:85]
	v_mfma_f32_16x16x32_bf16 v[70:73], v[170:173], v[214:217], v[70:73]
	v_mfma_f32_16x16x32_bf16 v[66:69], v[178:181], v[214:217], v[66:69]
	v_mfma_f32_16x16x32_bf16 v[118:121], v[174:177], v[194:197], v[118:121]
	v_mfma_f32_16x16x32_bf16 v[114:117], v[186:189], v[194:197], v[114:117]
	v_mfma_f32_16x16x32_bf16 v[102:105], v[174:177], v[202:205], v[102:105]
	v_mfma_f32_16x16x32_bf16 v[98:101], v[186:189], v[202:205], v[98:101]
	v_mfma_f32_16x16x32_bf16 v[86:89], v[174:177], v[210:213], v[86:89]
	v_mfma_f32_16x16x32_bf16 v[82:85], v[186:189], v[210:213], v[82:85]
	v_mfma_f32_16x16x32_bf16 v[70:73], v[174:177], v[218:221], v[70:73]
	v_mfma_f32_16x16x32_bf16 v[66:69], v[186:189], v[218:221], v[66:69]
	s_setprio 0
	s_barrier
	s_add_i32 s63, s54, s44
	v_lshl_add_u64 v[182:183], s[38:39], 0, v[132:133]
	s_mov_b32 m0, s63
	ds_read_b128 v[190:193], v156 offset:16384
	ds_read_b128 v[194:197], v156 offset:17408
	ds_read_b128 v[198:201], v156 offset:18432
	ds_read_b128 v[202:205], v156 offset:19456
	ds_read_b128 v[206:209], v156 offset:20480
	ds_read_b128 v[210:213], v156 offset:21504
	ds_read_b128 v[214:217], v156 offset:22528
	ds_read_b128 v[218:221], v156 offset:23552
	global_load_lds_dwordx4 v[182:183], off
	s_add_i32 m0, s63, 0x2000
	s_add_u32 s64, s38, 0xb0000
	v_lshl_add_u64 v[222:223], s[38:39], 0, v[136:137]
	s_addc_u32 s65, s39, 0
	s_add_i32 s63, s55, s44
	global_load_lds_dwordx4 v[222:223], off
	s_mov_b32 m0, s63
	v_lshl_add_u64 v[226:227], s[40:41], 0, v[134:135]
	global_load_lds_dwordx4 v132, s[64:65]
	s_add_i32 m0, s63, 0x2000
	s_nop 0
	global_load_lds_dwordx4 v136, s[64:65]
	v_lshl_add_u64 v[224:225], s[40:41], 0, v[130:131]
	s_mov_b32 m0, s45
	s_nop 0
	global_load_lds_dwordx4 v[224:225], off
	s_mov_b32 m0, s46
	s_nop 0
	global_load_lds_dwordx4 v[226:227], off
	s_waitcnt vmcnt(8)
	s_waitcnt lgkmcnt(0)
	s_barrier
	s_setprio 1
	v_mfma_f32_16x16x32_bf16 v[62:65], v[148:151], v[190:193], v[62:65]
	v_mfma_f32_16x16x32_bf16 v[58:61], v[162:165], v[190:193], v[58:61]
	v_mfma_f32_16x16x32_bf16 v[46:49], v[148:151], v[198:201], v[46:49]
	v_mfma_f32_16x16x32_bf16 v[42:45], v[162:165], v[198:201], v[42:45]
	v_mfma_f32_16x16x32_bf16 v[30:33], v[148:151], v[206:209], v[30:33]
	v_mfma_f32_16x16x32_bf16 v[26:29], v[162:165], v[206:209], v[26:29]
	v_mfma_f32_16x16x32_bf16 v[14:17], v[148:151], v[214:217], v[14:17]
	v_mfma_f32_16x16x32_bf16 v[10:13], v[162:165], v[214:217], v[10:13]
	v_mfma_f32_16x16x32_bf16 v[62:65], v[158:161], v[194:197], v[62:65]
	v_mfma_f32_16x16x32_bf16 v[58:61], v[166:169], v[194:197], v[58:61]
	v_mfma_f32_16x16x32_bf16 v[46:49], v[158:161], v[202:205], v[46:49]
	v_mfma_f32_16x16x32_bf16 v[42:45], v[166:169], v[202:205], v[42:45]
	v_mfma_f32_16x16x32_bf16 v[30:33], v[158:161], v[210:213], v[30:33]
	v_mfma_f32_16x16x32_bf16 v[26:29], v[166:169], v[210:213], v[26:29]
	v_mfma_f32_16x16x32_bf16 v[14:17], v[158:161], v[218:221], v[14:17]
	v_mfma_f32_16x16x32_bf16 v[10:13], v[166:169], v[218:221], v[10:13]
	v_mfma_f32_16x16x32_bf16 v[54:57], v[170:173], v[190:193], v[54:57]
	v_mfma_f32_16x16x32_bf16 v[50:53], v[178:181], v[190:193], v[50:53]
	v_mfma_f32_16x16x32_bf16 v[38:41], v[170:173], v[198:201], v[38:41]
	v_mfma_f32_16x16x32_bf16 v[34:37], v[178:181], v[198:201], v[34:37]
	v_mfma_f32_16x16x32_bf16 v[22:25], v[170:173], v[206:209], v[22:25]
	v_mfma_f32_16x16x32_bf16 v[18:21], v[178:181], v[206:209], v[18:21]
	v_mfma_f32_16x16x32_bf16 v[6:9], v[170:173], v[214:217], v[6:9]
	v_mfma_f32_16x16x32_bf16 v[2:5], v[178:181], v[214:217], v[2:5]
	v_mfma_f32_16x16x32_bf16 v[54:57], v[174:177], v[194:197], v[54:57]
	v_mfma_f32_16x16x32_bf16 v[50:53], v[186:189], v[194:197], v[50:53]
	v_mfma_f32_16x16x32_bf16 v[38:41], v[174:177], v[202:205], v[38:41]
	v_mfma_f32_16x16x32_bf16 v[34:37], v[186:189], v[202:205], v[34:37]
	v_mfma_f32_16x16x32_bf16 v[22:25], v[174:177], v[210:213], v[22:25]
	v_mfma_f32_16x16x32_bf16 v[18:21], v[186:189], v[210:213], v[18:21]
	v_mfma_f32_16x16x32_bf16 v[6:9], v[174:177], v[218:221], v[6:9]
	v_mfma_f32_16x16x32_bf16 v[2:5], v[186:189], v[218:221], v[2:5]
	s_setprio 0
	s_barrier
; #define PG8_STAGE(bufoff, gbase, voff) do { _Pragma("unroll") for (int _i = 0; _i < 2; ++_i) \
;         __builtin_amdgcn_global_load_lds((const unsigned*)((const char*)(gbase) + (voff)[_i]), (LAS unsigned*)(lds + (bufoff) + ldsw + _i * 8192), 16, 0, 0); } while (0)
; #define PG8_LDA(dst, b, h) do { _Pragma("unroll") for (int m = 0; m < 4; ++m) _Pragma("unroll") for (int k = 0; k < 2; ++k) dst[m][k] = *(const LAS bf16x8*)(lds + PG8_SA(b, h) + aoff + m * 2048 + k * 1024); } while (0)
; #define PG8_LDB(dst, b, h) do { _Pragma("unroll") for (int n = 0; n < 2; ++n) _Pragma("unroll") for (int k = 0; k < 2; ++k) dst[n][k] = *(const LAS bf16x8*)(lds + PG8_SB(b, h) + boff + n * 2048 + k * 1024); } while (0)
; #define PG8_MMA(ai, bj, At, Bt) do { __builtin_amdgcn_s_setprio(1); _Pragma("unroll") for (int m = 0; m < 4; ++m) _Pragma("unroll") for (int n = 0; n < 2; ++n) _Pragma("unroll") for (int k = 0; k < 2; ++k) \
;         acc[ai][bj][m][n] = __builtin_amdgcn_mfma_f32_16x16x32_bf16(Bt[n][k], At[m][k], acc[ai][bj][m][n], 0, 0, 0); __builtin_amdgcn_s_setprio(0); } while (0)
; #define PG8_WAIT_V(n) asm volatile("s_waitcnt vmcnt(" #n ")" ::: "memory")
; #define PG8_WAIT_L(n) asm volatile("s_waitcnt lgkmcnt(" #n ")" ::: "memory")
; #define PG8_BAR __builtin_amdgcn_s_barrier()
; #define PG8_SCHED __builtin_amdgcn_sched_barrier(0)
;     DI void pre(Pre& pr, const pg8::Unit& u, int wr, int fr) const { load_rows(pr, ssq, u, wr, fr); }
;     DI void pre(Pre& pr, const pg8::Unit& u, int wr, int fr) const { load_rows(pr, ssq, u, wr, fr); }
; template <class Epi, class Sched>
; DI void gemm_phase(LAS unsigned char* lds, const Gemm g, const Sched& S, const Epi& E) {
;     ...
;             PG8_LDB(B0, 1, 0); PG8_LDB(B1, 1, 1); PG8_SCHED; PG8_LDA(At, 1, 0); PG8_STAGE(PG8_SA(0, 1), a2 + hstepA, voffA);
;             PG8_WAIT_V(8); PG8_WAIT_L(0); PG8_BAR; PG8_MMA(0, 0, At, B0); PG8_MMA(0, 1, At, B1); PG8_BAR; PG8_SCHED;
;             PG8_LDA(At, 1, 1); PG8_STAGE(PG8_SB(1, 0), b3, voffB); PG8_STAGE(PG8_SB(1, 1), b3 + hstepB, voffB); PG8_STAGE(PG8_SA(1, 0), a3, voffA);
;             PG8_WAIT_V(8); PG8_WAIT_L(0); PG8_BAR; PG8_MMA(1, 0, At, B0); PG8_MMA(1, 1, At, B1); PG8_BAR; PG8_SCHED;
;         }
;         if (wr == 0) PG8_BAR;
;         E(acc, cur, wr, wc, fr, fq, pre);
;         if (!has_next) break;
	s_add_i32 s63, 0, 0x18000
	s_add_i32 s64, 0, 0x1c000
	v_add_u32_e32 v166, s63, v152
	v_add_u32_e32 v185, s64, v152
	ds_read_b128 v[148:151], v166
	ds_read_b128 v[158:161], v166 offset:1024
	ds_read_b128 v[162:165], v166 offset:2048
	ds_read_b128 v[166:169], v166 offset:3072
	ds_read_b128 v[170:173], v185
	ds_read_b128 v[174:177], v185 offset:1024
	ds_read_b128 v[178:181], v185 offset:2048
	ds_read_b128 v[186:189], v185 offset:3072
	s_add_u32 s40, s40, 0xb0000
	s_addc_u32 s41, s41, 0
	s_mov_b32 m0, s47
	ds_read_b128 v[190:193], v156 offset:32768
	ds_read_b128 v[194:197], v156 offset:33792
	ds_read_b128 v[198:201], v156 offset:34816
	ds_read_b128 v[202:205], v156 offset:35840
	ds_read_b128 v[206:209], v156 offset:36864
	ds_read_b128 v[210:213], v156 offset:37888
	ds_read_b128 v[214:217], v156 offset:38912
	ds_read_b128 v[218:221], v156 offset:39936
	global_load_lds_dwordx4 v130, s[40:41]
	s_mov_b32 m0, s48
	s_nop 0
	global_load_lds_dwordx4 v134, s[40:41]
	s_waitcnt vmcnt(8)
	s_waitcnt lgkmcnt(0)
	s_barrier
	s_setprio 1
	v_mfma_f32_16x16x32_bf16 v[126:129], v[148:151], v[190:193], v[126:129]
	v_mfma_f32_16x16x32_bf16 v[122:125], v[162:165], v[190:193], v[122:125]
	v_mfma_f32_16x16x32_bf16 v[110:113], v[148:151], v[198:201], v[110:113]
	v_mfma_f32_16x16x32_bf16 v[106:109], v[162:165], v[198:201], v[106:109]
	v_mfma_f32_16x16x32_bf16 v[94:97], v[148:151], v[206:209], v[94:97]
	v_mfma_f32_16x16x32_bf16 v[90:93], v[162:165], v[206:209], v[90:93]
	v_mfma_f32_16x16x32_bf16 v[78:81], v[148:151], v[214:217], v[78:81]
	v_mfma_f32_16x16x32_bf16 v[74:77], v[162:165], v[214:217], v[74:77]
	v_mfma_f32_16x16x32_bf16 v[126:129], v[158:161], v[194:197], v[126:129]
	v_mfma_f32_16x16x32_bf16 v[122:125], v[166:169], v[194:197], v[122:125]
	v_mfma_f32_16x16x32_bf16 v[110:113], v[158:161], v[202:205], v[110:113]
	v_mfma_f32_16x16x32_bf16 v[106:109], v[166:169], v[202:205], v[106:109]
	v_mfma_f32_16x16x32_bf16 v[94:97], v[158:161], v[210:213], v[94:97]
	v_mfma_f32_16x16x32_bf16 v[90:93], v[166:169], v[210:213], v[90:93]
	v_mfma_f32_16x16x32_bf16 v[78:81], v[158:161], v[218:221], v[78:81]
	v_mfma_f32_16x16x32_bf16 v[74:77], v[166:169], v[218:221], v[74:77]
	v_mfma_f32_16x16x32_bf16 v[118:121], v[170:173], v[190:193], v[118:121]
	v_mfma_f32_16x16x32_bf16 v[114:117], v[178:181], v[190:193], v[114:117]
	v_mfma_f32_16x16x32_bf16 v[102:105], v[170:173], v[198:201], v[102:105]
	v_mfma_f32_16x16x32_bf16 v[98:101], v[178:181], v[198:201], v[98:101]
	v_mfma_f32_16x16x32_bf16 v[86:89], v[170:173], v[206:209], v[86:89]
	v_mfma_f32_16x16x32_bf16 v[82:85], v[178:181], v[206:209], v[82:85]
	v_mfma_f32_16x16x32_bf16 v[70:73], v[170:173], v[214:217], v[70:73]
	v_mfma_f32_16x16x32_bf16 v[66:69], v[178:181], v[214:217], v[66:69]
	v_mfma_f32_16x16x32_bf16 v[118:121], v[174:177], v[194:197], v[118:121]
	v_mfma_f32_16x16x32_bf16 v[114:117], v[186:189], v[194:197], v[114:117]
	v_mfma_f32_16x16x32_bf16 v[102:105], v[174:177], v[202:205], v[102:105]
	v_mfma_f32_16x16x32_bf16 v[98:101], v[186:189], v[202:205], v[98:101]
	v_mfma_f32_16x16x32_bf16 v[86:89], v[174:177], v[210:213], v[86:89]
	v_mfma_f32_16x16x32_bf16 v[82:85], v[186:189], v[210:213], v[82:85]
	v_mfma_f32_16x16x32_bf16 v[70:73], v[174:177], v[218:221], v[70:73]
	v_mfma_f32_16x16x32_bf16 v[66:69], v[186:189], v[218:221], v[66:69]
	s_setprio 0
	s_barrier
	s_add_i32 s40, s63, s44
	v_lshl_add_u64 v[182:183], v[182:183], 0, s[16:17]
	s_mov_b32 m0, s40
	ds_read_b128 v[190:193], v156 offset:49152
	ds_read_b128 v[194:197], v156 offset:50176
	ds_read_b128 v[198:201], v156 offset:51200
	ds_read_b128 v[202:205], v156 offset:52224
	ds_read_b128 v[206:209], v156 offset:53248
	ds_read_b128 v[210:213], v156 offset:54272
	ds_read_b128 v[214:217], v156 offset:55296
	ds_read_b128 v[218:221], v156 offset:56320
	global_load_lds_dwordx4 v[182:183], off
	s_add_i32 m0, s40, 0x2000
	s_add_u32 s38, s38, 0xb0080
	v_lshl_add_u64 v[182:183], v[222:223], 0, s[16:17]
	s_addc_u32 s39, s39, 0
	s_add_i32 s40, s64, s44
	global_load_lds_dwordx4 v[182:183], off
	s_mov_b32 m0, s40
	s_nop 0
	global_load_lds_dwordx4 v132, s[38:39]
	s_add_i32 m0, s40, 0x2000
	s_nop 0
	global_load_lds_dwordx4 v136, s[38:39]
	v_lshl_add_u64 v[182:183], v[224:225], 0, s[16:17]
	s_mov_b32 m0, s50
	s_nop 0
	global_load_lds_dwordx4 v[182:183], off
	v_lshl_add_u64 v[182:183], v[226:227], 0, s[16:17]
	s_mov_b32 m0, s51
	s_nop 0
	global_load_lds_dwordx4 v[182:183], off
	s_waitcnt vmcnt(8)
	s_waitcnt lgkmcnt(0)
	s_barrier
	s_setprio 1
	v_mfma_f32_16x16x32_bf16 v[62:65], v[148:151], v[190:193], v[62:65]
	v_mfma_f32_16x16x32_bf16 v[58:61], v[162:165], v[190:193], v[58:61]
	v_mfma_f32_16x16x32_bf16 v[46:49], v[148:151], v[198:201], v[46:49]
	v_mfma_f32_16x16x32_bf16 v[42:45], v[162:165], v[198:201], v[42:45]
	v_mfma_f32_16x16x32_bf16 v[30:33], v[148:151], v[206:209], v[30:33]
	v_mfma_f32_16x16x32_bf16 v[26:29], v[162:165], v[206:209], v[26:29]
	v_mfma_f32_16x16x32_bf16 v[14:17], v[148:151], v[214:217], v[14:17]
	v_mfma_f32_16x16x32_bf16 v[10:13], v[162:165], v[214:217], v[10:13]
	v_mfma_f32_16x16x32_bf16 v[62:65], v[158:161], v[194:197], v[62:65]
	v_mfma_f32_16x16x32_bf16 v[58:61], v[166:169], v[194:197], v[58:61]
	v_mfma_f32_16x16x32_bf16 v[46:49], v[158:161], v[202:205], v[46:49]
	v_mfma_f32_16x16x32_bf16 v[42:45], v[166:169], v[202:205], v[42:45]
	v_mfma_f32_16x16x32_bf16 v[30:33], v[158:161], v[210:213], v[30:33]
	v_mfma_f32_16x16x32_bf16 v[26:29], v[166:169], v[210:213], v[26:29]
	v_mfma_f32_16x16x32_bf16 v[14:17], v[158:161], v[218:221], v[14:17]
	v_mfma_f32_16x16x32_bf16 v[10:13], v[166:169], v[218:221], v[10:13]
	v_mfma_f32_16x16x32_bf16 v[54:57], v[170:173], v[190:193], v[54:57]
	v_mfma_f32_16x16x32_bf16 v[50:53], v[178:181], v[190:193], v[50:53]
	v_mfma_f32_16x16x32_bf16 v[38:41], v[170:173], v[198:201], v[38:41]
	v_mfma_f32_16x16x32_bf16 v[34:37], v[178:181], v[198:201], v[34:37]
	v_mfma_f32_16x16x32_bf16 v[22:25], v[170:173], v[206:209], v[22:25]
	v_mfma_f32_16x16x32_bf16 v[18:21], v[178:181], v[206:209], v[18:21]
	v_mfma_f32_16x16x32_bf16 v[6:9], v[170:173], v[214:217], v[6:9]
	v_mfma_f32_16x16x32_bf16 v[2:5], v[178:181], v[214:217], v[2:5]
	v_mfma_f32_16x16x32_bf16 v[54:57], v[174:177], v[194:197], v[54:57]
	v_mfma_f32_16x16x32_bf16 v[50:53], v[186:189], v[194:197], v[50:53]
	v_mfma_f32_16x16x32_bf16 v[38:41], v[174:177], v[202:205], v[38:41]
	v_mfma_f32_16x16x32_bf16 v[34:37], v[186:189], v[202:205], v[34:37]
	v_mfma_f32_16x16x32_bf16 v[22:25], v[174:177], v[210:213], v[22:25]
	v_mfma_f32_16x16x32_bf16 v[18:21], v[186:189], v[210:213], v[18:21]
	v_mfma_f32_16x16x32_bf16 v[6:9], v[174:177], v[218:221], v[6:9]
	v_mfma_f32_16x16x32_bf16 v[2:5], v[186:189], v[218:221], v[2:5]
	s_setprio 0
	s_barrier
	s_add_i32 s62, s62, 2
	s_add_u32 s36, s36, 0x100
	s_addc_u32 s37, s37, 0
	s_add_u32 s60, s60, 0x100
	s_addc_u32 s61, s61, 0
	s_cmp_gt_u32 s62, 41
	s_cbranch_scc0 .LBB0_278
	s_mov_b32 s99, 1
	s_and_b64 vcc, exec, s[18:19]
	s_cbranch_vccz .LBB0_281
	s_barrier

;     DI bool next(int i, Unit& u) const { if (i > 0 || c >= 64) return false; u.pm = c & 31; u.pn = 0; u.src = c >> 5; return true; }
; #define PG8_STAGE(bufoff, gbase, voff) do { _Pragma("unroll") for (int _i = 0; _i < 2; ++_i) \
;         __builtin_amdgcn_global_load_lds((const unsigned*)((const char*)(gbase) + (voff)[_i]), (LAS unsigned*)(lds + (bufoff) + ldsw + _i * 8192), 16, 0, 0); } while (0)
; #define PG8_LDA(dst, b, h) do { _Pragma("unroll") for (int m = 0; m < 4; ++m) _Pragma("unroll") for (int k = 0; k < 2; ++k) dst[m][k] = *(const LAS bf16x8*)(lds + PG8_SA(b, h) + aoff + m * 2048 + k * 1024); } while (0)
; #define PG8_WAIT_V(n) asm volatile("s_waitcnt vmcnt(" #n ")" ::: "memory")
; #define PG8_WAIT_L(n) asm volatile("s_waitcnt lgkmcnt(" #n ")" ::: "memory")
; #define PG8_BAR __builtin_amdgcn_s_barrier()
; template <class Epi, class Sched>
; DI void gemm_phase(LAS unsigned char* lds, const Gemm g, const Sched& S, const Epi& E) {
;     ...
;         const bool has_next = S.next(ui + 1, nxt);
;         E.pre(pre, cur, wr, fr);
;         const char* nA = has_next ? (const char*)(nxt.src ? g.A1 : g.A0) + (size_t)nxt.pm * tstepA : cA; const char* nB = has_next ? (const char*)(nxt.src ? g.B1 : g.B0) + (size_t)nxt.pn * tstepB : cB;
;         for (int t = 0; t < nt; t += 2) {
;             const bool last = (t == nt - 2);
;             const char* a1 = cA + (size_t)(t + 1) * kstep;
;             const char* a2 = last ? nA : cA + (size_t)(t + 2) * kstep; const char* b2 = last ? nB : cB + (size_t)(t + 2) * kstep;
;             const char* a3 = a2 + kstep; const char* b3 = b2 + kstep;
;             PG8_LDB(B0, 0, 0); PG8_LDB(B1, 0, 1); PG8_SCHED; PG8_LDA(At, 0, 0); PG8_STAGE(PG8_SA(1, 1), a1 + hstepA, voffA);
;             PG8_WAIT_V(8); PG8_WAIT_L(0); PG8_BAR; PG8_MMA(0, 0, At, B0); PG8_MMA(0, 1, At, B1); PG8_BAR; PG8_SCHED;
;             PG8_LDA(At, 0, 1); PG8_STAGE(PG8_SB(0, 0), b2, voffB); PG8_STAGE(PG8_SB(0, 1), b2 + hstepB, voffB); PG8_STAGE(PG8_SA(0, 0), a2, voffA);
;             PG8_WAIT_V(8); PG8_WAIT_L(0); PG8_BAR; PG8_MMA(1, 0, At, B0); PG8_MMA(1, 1, At, B1); PG8_BAR; PG8_SCHED;
; DI void load_rows(PreRows& pr, const float* ssq, const pg8::Unit& u, int wr, int fr) {
; #pragma unroll
;     for (int ai = 0; ai < 2; ++ai)
; #pragma unroll
;         for (int m = 0; m < 4; ++m) pr.v[ai * 4 + m] = ssq[u.pm * 256 + ai * 128 + wr * 64 + m * 16 + fr];
; }
.LBB0_380:
	s_lshl_b32 s28, s10, 8
	s_add_i32 s28, s28, s85
	v_or_b32_e32 v170, s28, v147
	v_ashrrev_i32_e32 v171, 31, v170
	v_add_u32_e32 v136, 0x80, v170
	v_add_u32_e32 v134, 0x90, v170
	v_add_u32_e32 v132, 0xa0, v170
	v_add_u32_e32 v130, 0xb0, v170
	v_lshl_add_u64 v[2:3], v[170:171], 2, s[20:21]
	v_ashrrev_i32_e32 v137, 31, v136
	v_ashrrev_i32_e32 v135, 31, v134
	v_ashrrev_i32_e32 v133, 31, v132
	v_ashrrev_i32_e32 v131, 31, v130
	v_lshl_add_u64 v[4:5], v[136:137], 2, s[20:21]
	v_lshl_add_u64 v[6:7], v[134:135], 2, s[20:21]
	v_lshl_add_u64 v[8:9], v[132:133], 2, s[20:21]
	v_lshl_add_u64 v[10:11], v[130:131], 2, s[20:21]
	global_load_dword v174, v[2:3], off
	global_load_dword v197, v[2:3], off offset:64
	global_load_dword v196, v[2:3], off offset:128
	global_load_dword v195, v[2:3], off offset:192
	global_load_dword v194, v[4:5], off
	global_load_dword v193, v[6:7], off
	global_load_dword v192, v[8:9], off
	global_load_dword v191, v[10:11], off
	s_ashr_i32 s59, s58, 31
	s_lshl_b64 s[10:11], s[58:59], 19
	s_add_u32 s60, s30, s10
	s_addc_u32 s61, s31, s11
	s_and_b64 s[10:11], s[8:9], exec
	s_cselect_b32 s13, s61, s67
	s_cselect_b32 s29, s60, s66
	s_ashr_i32 s57, s56, 31
	s_lshl_b64 s[10:11], s[56:57], 19
	s_add_u32 s62, s75, s10
	s_addc_u32 s63, s76, s11
	s_and_b64 s[10:11], s[8:9], exec
	s_cselect_b32 s36, s63, s65
	s_cselect_b32 s57, s62, s64
	s_add_u32 s10, s66, 0x40080
	s_addc_u32 s11, s67, 0
	s_add_u32 s59, s64, 0x100
	s_addc_u32 s68, s65, 0
	s_mov_b32 s69, -2
	s_waitcnt lgkmcnt(0)
	ds_read_b128 v[138:141], v188
	ds_read_b128 v[142:145], v188 offset:1024
	ds_read_b128 v[176:179], v188 offset:2048
	ds_read_b128 v[198:201], v188 offset:3072
	ds_read_b128 v[202:205], v189
	ds_read_b128 v[206:209], v189 offset:1024
	ds_read_b128 v[210:213], v189 offset:2048
	ds_read_b128 v[214:217], v189 offset:3072
	s_add_u32 s64, s10, 0xfffc0080
	s_addc_u32 s65, s11, -1
	s_cmp_eq_u32 s69, 12
	s_cselect_b32 s67, s13, s65
	s_cselect_b32 s66, s29, s64
	s_cselect_b32 s65, s36, s68
	s_cselect_b32 s64, s57, s59
	s_add_i32 m0, s79, 0xc000
	ds_read_b128 v[218:221], v186
	ds_read_b128 v[222:225], v186 offset:1024
	ds_read_b128 v[226:229], v186 offset:2048
	ds_read_b128 v[230:233], v186 offset:3072
	ds_read_b128 v[234:237], v186 offset:4096
	ds_read_b128 v[238:241], v186 offset:5120
	ds_read_b128 v[242:245], v186 offset:6144
	ds_read_b128 v[246:249], v186 offset:7168
	global_load_lds_dwordx4 v162, s[10:11]
	s_add_i32 m0, s79, 0xe000
	s_nop 0
	global_load_lds_dwordx4 v164, s[10:11]
	s_cmp_lg_u32 s99, 0
	s_cbranch_scc1 .Lpk2_w1
	s_waitcnt vmcnt(8)
.Lpk2_w1:
	s_waitcnt lgkmcnt(0)
	s_barrier
	s_setprio 1
	v_mfma_f32_16x16x32_bf16 v[126:129], v[138:141], v[218:221], 0
	v_mfma_f32_16x16x32_bf16 v[122:125], v[176:179], v[218:221], 0
	v_mfma_f32_16x16x32_bf16 v[110:113], v[138:141], v[226:229], 0
	v_mfma_f32_16x16x32_bf16 v[106:109], v[176:179], v[226:229], 0
	v_mfma_f32_16x16x32_bf16 v[94:97], v[138:141], v[234:237], 0
	v_mfma_f32_16x16x32_bf16 v[90:93], v[176:179], v[234:237], 0
	v_mfma_f32_16x16x32_bf16 v[78:81], v[138:141], v[242:245], 0
	v_mfma_f32_16x16x32_bf16 v[74:77], v[176:179], v[242:245], 0
	v_mfma_f32_16x16x32_bf16 v[126:129], v[142:145], v[222:225], v[126:129]
	v_mfma_f32_16x16x32_bf16 v[122:125], v[198:201], v[222:225], v[122:125]
	v_mfma_f32_16x16x32_bf16 v[110:113], v[142:145], v[230:233], v[110:113]
	v_mfma_f32_16x16x32_bf16 v[106:109], v[198:201], v[230:233], v[106:109]
	v_mfma_f32_16x16x32_bf16 v[94:97], v[142:145], v[238:241], v[94:97]
	v_mfma_f32_16x16x32_bf16 v[90:93], v[198:201], v[238:241], v[90:93]
	v_mfma_f32_16x16x32_bf16 v[78:81], v[142:145], v[246:249], v[78:81]
	v_mfma_f32_16x16x32_bf16 v[74:77], v[198:201], v[246:249], v[74:77]
	v_mfma_f32_16x16x32_bf16 v[118:121], v[202:205], v[218:221], 0
	v_mfma_f32_16x16x32_bf16 v[114:117], v[210:213], v[218:221], 0
	v_mfma_f32_16x16x32_bf16 v[102:105], v[202:205], v[226:229], 0
	v_mfma_f32_16x16x32_bf16 v[98:101], v[210:213], v[226:229], 0
	v_mfma_f32_16x16x32_bf16 v[86:89], v[202:205], v[234:237], 0
	v_mfma_f32_16x16x32_bf16 v[82:85], v[210:213], v[234:237], 0
	v_mfma_f32_16x16x32_bf16 v[70:73], v[202:205], v[242:245], 0
	v_mfma_f32_16x16x32_bf16 v[66:69], v[210:213], v[242:245], 0
	v_mfma_f32_16x16x32_bf16 v[118:121], v[206:209], v[222:225], v[118:121]
	v_mfma_f32_16x16x32_bf16 v[114:117], v[214:217], v[222:225], v[114:117]
	v_mfma_f32_16x16x32_bf16 v[102:105], v[206:209], v[230:233], v[102:105]
	v_mfma_f32_16x16x32_bf16 v[98:101], v[214:217], v[230:233], v[98:101]
	v_mfma_f32_16x16x32_bf16 v[86:89], v[206:209], v[238:241], v[86:89]
	v_mfma_f32_16x16x32_bf16 v[82:85], v[214:217], v[238:241], v[82:85]
	v_mfma_f32_16x16x32_bf16 v[70:73], v[206:209], v[246:249], v[70:73]
	v_mfma_f32_16x16x32_bf16 v[66:69], v[214:217], v[246:249], v[66:69]
	s_setprio 0
	s_barrier
	s_add_i32 s70, s94, s78
	v_lshl_add_u64 v[172:173], s[64:65], 0, v[150:151]
	s_mov_b32 m0, s70
	ds_read_b128 v[218:221], v186 offset:16384
	ds_read_b128 v[222:225], v186 offset:17408
	ds_read_b128 v[226:229], v186 offset:18432
	ds_read_b128 v[230:233], v186 offset:19456
	ds_read_b128 v[234:237], v186 offset:20480
	ds_read_b128 v[238:241], v186 offset:21504
	ds_read_b128 v[242:245], v186 offset:22528
	ds_read_b128 v[246:249], v186 offset:23552
	global_load_lds_dwordx4 v[172:173], off
	s_add_i32 m0, s70, 0x2000
	s_add_u32 s70, s64, 0x40000
	v_lshl_add_u64 v[180:181], s[64:65], 0, v[154:155]
	s_addc_u32 s71, s65, 0
	s_add_i32 s72, s95, s78
	global_load_lds_dwordx4 v[180:181], off
	s_mov_b32 m0, s72
	v_lshl_add_u64 v[252:253], s[66:67], 0, v[152:153]
	global_load_lds_dwordx4 v150, s[70:71]
	s_add_i32 m0, s72, 0x2000
	s_nop 0
	global_load_lds_dwordx4 v154, s[70:71]
	v_lshl_add_u64 v[250:251], s[66:67], 0, v[148:149]
	s_mov_b32 m0, s79
	s_nop 0
	global_load_lds_dwordx4 v[250:251], off
	s_mov_b32 m0, s80
	s_nop 0
	global_load_lds_dwordx4 v[252:253], off
	s_cmp_lg_u32 s99, 0
	s_cbranch_scc1 .Lpk2_w2
	s_waitcnt vmcnt(8)
; #define PG8_STAGE(bufoff, gbase, voff) do { _Pragma("unroll") for (int _i = 0; _i < 2; ++_i) \
;         __builtin_amdgcn_global_load_lds((const unsigned*)((const char*)(gbase) + (voff)[_i]), (LAS unsigned*)(lds + (bufoff) + ldsw + _i * 8192), 16, 0, 0); } while (0)
; #define PG8_LDA(dst, b, h) do { _Pragma("unroll") for (int m = 0; m < 4; ++m) _Pragma("unroll") for (int k = 0; k < 2; ++k) dst[m][k] = *(const LAS bf16x8*)(lds + PG8_SA(b, h) + aoff + m * 2048 + k * 1024); } while (0)
; #define PG8_LDB(dst, b, h) do { _Pragma("unroll") for (int n = 0; n < 2; ++n) _Pragma("unroll") for (int k = 0; k < 2; ++k) dst[n][k] = *(const LAS bf16x8*)(lds + PG8_SB(b, h) + boff + n * 2048 + k * 1024); } while (0)
; #define PG8_MMA(ai, bj, At, Bt) do { __builtin_amdgcn_s_setprio(1); _Pragma("unroll") for (int m = 0; m < 4; ++m) _Pragma("unroll") for (int n = 0; n < 2; ++n) _Pragma("unroll") for (int k = 0; k < 2; ++k) \
;         acc[ai][bj][m][n] = __builtin_amdgcn_mfma_f32_16x16x32_bf16(Bt[n][k], At[m][k], acc[ai][bj][m][n], 0, 0, 0); __builtin_amdgcn_s_setprio(0); } while (0)
; #define PG8_WAIT_V(n) asm volatile("s_waitcnt vmcnt(" #n ")" ::: "memory")
; #define PG8_WAIT_L(n) asm volatile("s_waitcnt lgkmcnt(" #n ")" ::: "memory")
; #define PG8_BAR __builtin_amdgcn_s_barrier()
; #define PG8_SCHED __builtin_amdgcn_sched_barrier(0)
; template <class Epi, class Sched>
; DI void gemm_phase(LAS unsigned char* lds, const Gemm g, const Sched& S, const Epi& E) {
;     ...
;             PG8_WAIT_V(8); PG8_WAIT_L(0); PG8_BAR; PG8_MMA(1, 0, At, B0); PG8_MMA(1, 1, At, B1); PG8_BAR; PG8_SCHED;
;             PG8_LDB(B0, 1, 0); PG8_LDB(B1, 1, 1); PG8_SCHED; PG8_LDA(At, 1, 0); PG8_STAGE(PG8_SA(0, 1), a2 + hstepA, voffA);
;             PG8_WAIT_V(8); PG8_WAIT_L(0); PG8_BAR; PG8_MMA(0, 0, At, B0); PG8_MMA(0, 1, At, B1); PG8_BAR; PG8_SCHED;
;             PG8_LDA(At, 1, 1); PG8_STAGE(PG8_SB(1, 0), b3, voffB); PG8_STAGE(PG8_SB(1, 1), b3 + hstepB, voffB); PG8_STAGE(PG8_SA(1, 0), a3, voffA);
;             PG8_WAIT_V(8); PG8_WAIT_L(0); PG8_BAR; PG8_MMA(1, 0, At, B0); PG8_MMA(1, 1, At, B1); PG8_BAR; PG8_SCHED;
.Lpk2_w2:
	s_mov_b32 s99, 0
	s_waitcnt lgkmcnt(0)
	s_barrier
	s_setprio 1
	v_mfma_f32_16x16x32_bf16 v[62:65], v[138:141], v[218:221], 0
	v_mfma_f32_16x16x32_bf16 v[58:61], v[176:179], v[218:221], 0
	v_mfma_f32_16x16x32_bf16 v[46:49], v[138:141], v[226:229], 0
	v_mfma_f32_16x16x32_bf16 v[42:45], v[176:179], v[226:229], 0
	v_mfma_f32_16x16x32_bf16 v[30:33], v[138:141], v[234:237], 0
	v_mfma_f32_16x16x32_bf16 v[26:29], v[176:179], v[234:237], 0
	v_mfma_f32_16x16x32_bf16 v[14:17], v[138:141], v[242:245], 0
	v_mfma_f32_16x16x32_bf16 v[10:13], v[176:179], v[242:245], 0
	v_mfma_f32_16x16x32_bf16 v[62:65], v[142:145], v[222:225], v[62:65]
	v_mfma_f32_16x16x32_bf16 v[58:61], v[198:201], v[222:225], v[58:61]
	v_mfma_f32_16x16x32_bf16 v[46:49], v[142:145], v[230:233], v[46:49]
	v_mfma_f32_16x16x32_bf16 v[42:45], v[198:201], v[230:233], v[42:45]
	v_mfma_f32_16x16x32_bf16 v[30:33], v[142:145], v[238:241], v[30:33]
	v_mfma_f32_16x16x32_bf16 v[26:29], v[198:201], v[238:241], v[26:29]
	v_mfma_f32_16x16x32_bf16 v[14:17], v[142:145], v[246:249], v[14:17]
	v_mfma_f32_16x16x32_bf16 v[10:13], v[198:201], v[246:249], v[10:13]
	v_mfma_f32_16x16x32_bf16 v[54:57], v[202:205], v[218:221], 0
	v_mfma_f32_16x16x32_bf16 v[50:53], v[210:213], v[218:221], 0
	v_mfma_f32_16x16x32_bf16 v[38:41], v[202:205], v[226:229], 0
	v_mfma_f32_16x16x32_bf16 v[34:37], v[210:213], v[226:229], 0
	v_mfma_f32_16x16x32_bf16 v[22:25], v[202:205], v[234:237], 0
	v_mfma_f32_16x16x32_bf16 v[18:21], v[210:213], v[234:237], 0
	v_mfma_f32_16x16x32_bf16 v[6:9], v[202:205], v[242:245], 0
	v_mfma_f32_16x16x32_bf16 v[2:5], v[210:213], v[242:245], 0
	v_mfma_f32_16x16x32_bf16 v[54:57], v[206:209], v[222:225], v[54:57]
	v_mfma_f32_16x16x32_bf16 v[50:53], v[214:217], v[222:225], v[50:53]
	v_mfma_f32_16x16x32_bf16 v[38:41], v[206:209], v[230:233], v[38:41]
	v_mfma_f32_16x16x32_bf16 v[34:37], v[214:217], v[230:233], v[34:37]
	v_mfma_f32_16x16x32_bf16 v[22:25], v[206:209], v[238:241], v[22:25]
	v_mfma_f32_16x16x32_bf16 v[18:21], v[214:217], v[238:241], v[18:21]
	v_mfma_f32_16x16x32_bf16 v[6:9], v[206:209], v[246:249], v[6:9]
	v_mfma_f32_16x16x32_bf16 v[2:5], v[214:217], v[246:249], v[2:5]
	s_setprio 0
	s_barrier
	s_add_i32 s70, 0, 0x18000
	v_add_u32_e32 v156, s70, v159
	s_add_i32 s71, 0, 0x1c000
	ds_read_b128 v[138:141], v156
	ds_read_b128 v[142:145], v156 offset:1024
	ds_read_b128 v[176:179], v156 offset:2048
	ds_read_b128 v[198:201], v156 offset:3072
	v_add_u32_e32 v156, s71, v159
	ds_read_b128 v[202:205], v156
	ds_read_b128 v[206:209], v156 offset:1024
	ds_read_b128 v[210:213], v156 offset:2048
	ds_read_b128 v[214:217], v156 offset:3072
	s_add_u32 s66, s66, 0x40000
	s_addc_u32 s67, s67, 0
	s_mov_b32 m0, s81
	ds_read_b128 v[218:221], v186 offset:32768
	ds_read_b128 v[222:225], v186 offset:33792
	ds_read_b128 v[226:229], v186 offset:34816
	ds_read_b128 v[230:233], v186 offset:35840
	ds_read_b128 v[234:237], v186 offset:36864
	ds_read_b128 v[238:241], v186 offset:37888
	ds_read_b128 v[242:245], v186 offset:38912
	ds_read_b128 v[246:249], v186 offset:39936
	global_load_lds_dwordx4 v148, s[66:67]
	s_mov_b32 m0, s82
	s_nop 0
	global_load_lds_dwordx4 v152, s[66:67]
	s_waitcnt vmcnt(8)
	s_waitcnt lgkmcnt(0)
	s_barrier
	s_setprio 1
	v_mfma_f32_16x16x32_bf16 v[126:129], v[138:141], v[218:221], v[126:129]
	v_mfma_f32_16x16x32_bf16 v[122:125], v[176:179], v[218:221], v[122:125]
	v_mfma_f32_16x16x32_bf16 v[110:113], v[138:141], v[226:229], v[110:113]
	v_mfma_f32_16x16x32_bf16 v[106:109], v[176:179], v[226:229], v[106:109]
	v_mfma_f32_16x16x32_bf16 v[94:97], v[138:141], v[234:237], v[94:97]
	v_mfma_f32_16x16x32_bf16 v[90:93], v[176:179], v[234:237], v[90:93]
	v_mfma_f32_16x16x32_bf16 v[78:81], v[138:141], v[242:245], v[78:81]
	v_mfma_f32_16x16x32_bf16 v[74:77], v[176:179], v[242:245], v[74:77]
	v_mfma_f32_16x16x32_bf16 v[126:129], v[142:145], v[222:225], v[126:129]
	v_mfma_f32_16x16x32_bf16 v[122:125], v[198:201], v[222:225], v[122:125]
	v_mfma_f32_16x16x32_bf16 v[110:113], v[142:145], v[230:233], v[110:113]
	v_mfma_f32_16x16x32_bf16 v[106:109], v[198:201], v[230:233], v[106:109]
	v_mfma_f32_16x16x32_bf16 v[94:97], v[142:145], v[238:241], v[94:97]
	v_mfma_f32_16x16x32_bf16 v[90:93], v[198:201], v[238:241], v[90:93]
	v_mfma_f32_16x16x32_bf16 v[78:81], v[142:145], v[246:249], v[78:81]
	v_mfma_f32_16x16x32_bf16 v[74:77], v[198:201], v[246:249], v[74:77]
	v_mfma_f32_16x16x32_bf16 v[118:121], v[202:205], v[218:221], v[118:121]
	v_mfma_f32_16x16x32_bf16 v[114:117], v[210:213], v[218:221], v[114:117]
	v_mfma_f32_16x16x32_bf16 v[102:105], v[202:205], v[226:229], v[102:105]
	v_mfma_f32_16x16x32_bf16 v[98:101], v[210:213], v[226:229], v[98:101]
	v_mfma_f32_16x16x32_bf16 v[86:89], v[202:205], v[234:237], v[86:89]
	v_mfma_f32_16x16x32_bf16 v[82:85], v[210:213], v[234:237], v[82:85]
	v_mfma_f32_16x16x32_bf16 v[70:73], v[202:205], v[242:245], v[70:73]
	v_mfma_f32_16x16x32_bf16 v[66:69], v[210:213], v[242:245], v[66:69]
	v_mfma_f32_16x16x32_bf16 v[118:121], v[206:209], v[222:225], v[118:121]
	v_mfma_f32_16x16x32_bf16 v[114:117], v[214:217], v[222:225], v[114:117]
	v_mfma_f32_16x16x32_bf16 v[102:105], v[206:209], v[230:233], v[102:105]
	v_mfma_f32_16x16x32_bf16 v[98:101], v[214:217], v[230:233], v[98:101]
	v_mfma_f32_16x16x32_bf16 v[86:89], v[206:209], v[238:241], v[86:89]
	v_mfma_f32_16x16x32_bf16 v[82:85], v[214:217], v[238:241], v[82:85]
	v_mfma_f32_16x16x32_bf16 v[70:73], v[206:209], v[246:249], v[70:73]
	v_mfma_f32_16x16x32_bf16 v[66:69], v[214:217], v[246:249], v[66:69]
	s_setprio 0
	s_barrier
; #define PG8_STAGE(bufoff, gbase, voff) do { _Pragma("unroll") for (int _i = 0; _i < 2; ++_i) \
;         __builtin_amdgcn_global_load_lds((const unsigned*)((const char*)(gbase) + (voff)[_i]), (LAS unsigned*)(lds + (bufoff) + ldsw + _i * 8192), 16, 0, 0); } while (0)
; #define PG8_LDA(dst, b, h) do { _Pragma("unroll") for (int m = 0; m < 4; ++m) _Pragma("unroll") for (int k = 0; k < 2; ++k) dst[m][k] = *(const LAS bf16x8*)(lds + PG8_SA(b, h) + aoff + m * 2048 + k * 1024); } while (0)
; #define PG8_LDB(dst, b, h) do { _Pragma("unroll") for (int n = 0; n < 2; ++n) _Pragma("unroll") for (int k = 0; k < 2; ++k) dst[n][k] = *(const LAS bf16x8*)(lds + PG8_SB(b, h) + boff + n * 2048 + k * 1024); } while (0)
; #define PG8_WAIT_V(n) asm volatile("s_waitcnt vmcnt(" #n ")" ::: "memory")
; #define PG8_WAIT_L(n) asm volatile("s_waitcnt lgkmcnt(" #n ")" ::: "memory")
; template <class Epi, class Sched>
; DI void gemm_phase(LAS unsigned char* lds, const Gemm g, const Sched& S, const Epi& E) {
;     ...
;         for (int t = 0; t < nt; t += 2) {
;             const bool last = (t == nt - 2);
;             const char* a1 = cA + (size_t)(t + 1) * kstep;
;             const char* a2 = last ? nA : cA + (size_t)(t + 2) * kstep; const char* b2 = last ? nB : cB + (size_t)(t + 2) * kstep;
;             const char* a3 = a2 + kstep; const char* b3 = b2 + kstep;
;             PG8_LDB(B0, 0, 0); PG8_LDB(B1, 0, 1); PG8_SCHED; PG8_LDA(At, 0, 0); PG8_STAGE(PG8_SA(1, 1), a1 + hstepA, voffA);
;             PG8_WAIT_V(8); PG8_WAIT_L(0); PG8_BAR; PG8_MMA(0, 0, At, B0); PG8_MMA(0, 1, At, B1); PG8_BAR; PG8_SCHED;
;             PG8_LDA(At, 0, 1); PG8_STAGE(PG8_SB(0, 0), b2, voffB); PG8_STAGE(PG8_SB(0, 1), b2 + hstepB, voffB); PG8_STAGE(PG8_SA(0, 0), a2, voffA);
;             PG8_WAIT_V(8); PG8_WAIT_L(0); PG8_BAR; PG8_MMA(1, 0, At, B0); PG8_MMA(1, 1, At, B1); PG8_BAR; PG8_SCHED;
;             PG8_LDB(B0, 1, 0); PG8_LDB(B1, 1, 1); PG8_SCHED; PG8_LDA(At, 1, 0); PG8_STAGE(PG8_SA(0, 1), a2 + hstepA, voffA);
;             PG8_WAIT_V(8); PG8_WAIT_L(0); PG8_BAR; PG8_MMA(0, 0, At, B0); PG8_MMA(0, 1, At, B1); PG8_BAR; PG8_SCHED;
;             PG8_LDA(At, 1, 1); PG8_STAGE(PG8_SB(1, 0), b3, voffB); PG8_STAGE(PG8_SB(1, 1), b3 + hstepB, voffB); PG8_STAGE(PG8_SA(1, 0), a3, voffA);
;             PG8_WAIT_V(8); PG8_WAIT_L(0); PG8_BAR; PG8_MMA(1, 0, At, B0); PG8_MMA(1, 1, At, B1); PG8_BAR; PG8_SCHED;
	s_add_i32 s66, s70, s78
	v_lshl_add_u64 v[172:173], v[172:173], 0, s[50:51]
	s_mov_b32 m0, s66
	ds_read_b128 v[218:221], v186 offset:49152
	ds_read_b128 v[222:225], v186 offset:50176
	ds_read_b128 v[226:229], v186 offset:51200
	ds_read_b128 v[230:233], v186 offset:52224
	ds_read_b128 v[234:237], v186 offset:53248
	ds_read_b128 v[238:241], v186 offset:54272
	ds_read_b128 v[242:245], v186 offset:55296
	ds_read_b128 v[246:249], v186 offset:56320
	global_load_lds_dwordx4 v[172:173], off
	s_add_i32 m0, s66, 0x2000
	s_add_u32 s64, s64, 0x40080
	v_lshl_add_u64 v[172:173], v[180:181], 0, s[50:51]
	s_addc_u32 s65, s65, 0
	s_add_i32 s66, s71, s78
	global_load_lds_dwordx4 v[172:173], off
	s_mov_b32 m0, s66
	s_nop 0
	global_load_lds_dwordx4 v150, s[64:65]
	s_add_i32 m0, s66, 0x2000
	s_nop 0
	global_load_lds_dwordx4 v154, s[64:65]
	v_lshl_add_u64 v[172:173], v[250:251], 0, s[50:51]
	s_mov_b32 m0, s86
	s_nop 0
	global_load_lds_dwordx4 v[172:173], off
	v_lshl_add_u64 v[172:173], v[252:253], 0, s[50:51]
	s_mov_b32 m0, s87
	s_nop 0
	global_load_lds_dwordx4 v[172:173], off
	s_waitcnt vmcnt(8)
	s_waitcnt lgkmcnt(0)
	s_barrier
	s_setprio 1
	v_mfma_f32_16x16x32_bf16 v[62:65], v[138:141], v[218:221], v[62:65]
	v_mfma_f32_16x16x32_bf16 v[58:61], v[176:179], v[218:221], v[58:61]
	v_mfma_f32_16x16x32_bf16 v[46:49], v[138:141], v[226:229], v[46:49]
	v_mfma_f32_16x16x32_bf16 v[42:45], v[176:179], v[226:229], v[42:45]
	v_mfma_f32_16x16x32_bf16 v[30:33], v[138:141], v[234:237], v[30:33]
	v_mfma_f32_16x16x32_bf16 v[26:29], v[176:179], v[234:237], v[26:29]
	v_mfma_f32_16x16x32_bf16 v[14:17], v[138:141], v[242:245], v[14:17]
	v_mfma_f32_16x16x32_bf16 v[10:13], v[176:179], v[242:245], v[10:13]
	v_mfma_f32_16x16x32_bf16 v[62:65], v[142:145], v[222:225], v[62:65]
	v_mfma_f32_16x16x32_bf16 v[58:61], v[198:201], v[222:225], v[58:61]
	v_mfma_f32_16x16x32_bf16 v[46:49], v[142:145], v[230:233], v[46:49]
	v_mfma_f32_16x16x32_bf16 v[42:45], v[198:201], v[230:233], v[42:45]
	v_mfma_f32_16x16x32_bf16 v[30:33], v[142:145], v[238:241], v[30:33]
	v_mfma_f32_16x16x32_bf16 v[26:29], v[198:201], v[238:241], v[26:29]
	v_mfma_f32_16x16x32_bf16 v[14:17], v[142:145], v[246:249], v[14:17]
	v_mfma_f32_16x16x32_bf16 v[10:13], v[198:201], v[246:249], v[10:13]
	v_mfma_f32_16x16x32_bf16 v[54:57], v[202:205], v[218:221], v[54:57]
	v_mfma_f32_16x16x32_bf16 v[50:53], v[210:213], v[218:221], v[50:53]
	v_mfma_f32_16x16x32_bf16 v[38:41], v[202:205], v[226:229], v[38:41]
	v_mfma_f32_16x16x32_bf16 v[34:37], v[210:213], v[226:229], v[34:37]
	v_mfma_f32_16x16x32_bf16 v[22:25], v[202:205], v[234:237], v[22:25]
	v_mfma_f32_16x16x32_bf16 v[18:21], v[210:213], v[234:237], v[18:21]
	v_mfma_f32_16x16x32_bf16 v[6:9], v[202:205], v[242:245], v[6:9]
	v_mfma_f32_16x16x32_bf16 v[2:5], v[210:213], v[242:245], v[2:5]
	v_mfma_f32_16x16x32_bf16 v[54:57], v[206:209], v[222:225], v[54:57]
	v_mfma_f32_16x16x32_bf16 v[50:53], v[214:217], v[222:225], v[50:53]
	v_mfma_f32_16x16x32_bf16 v[38:41], v[206:209], v[230:233], v[38:41]
	v_mfma_f32_16x16x32_bf16 v[34:37], v[214:217], v[230:233], v[34:37]
	v_mfma_f32_16x16x32_bf16 v[22:25], v[206:209], v[238:241], v[22:25]
	v_mfma_f32_16x16x32_bf16 v[18:21], v[214:217], v[238:241], v[18:21]
	v_mfma_f32_16x16x32_bf16 v[6:9], v[206:209], v[246:249], v[6:9]
	v_mfma_f32_16x16x32_bf16 v[2:5], v[214:217], v[246:249], v[2:5]
	s_setprio 0
	s_barrier
	s_add_i32 s69, s69, 2
	s_add_u32 s10, s10, 0x100
	s_addc_u32 s11, s11, 0
	s_add_u32 s59, s59, 0x100
	s_addc_u32 s68, s68, 0
	s_cmp_gt_u32 s69, 13
.LBB0_381:
	ds_read_b128 v[138:141], v188
	ds_read_b128 v[142:145], v188 offset:1024
	ds_read_b128 v[176:179], v188 offset:2048
	ds_read_b128 v[198:201], v188 offset:3072
	ds_read_b128 v[202:205], v189
	ds_read_b128 v[206:209], v189 offset:1024
	ds_read_b128 v[210:213], v189 offset:2048
	ds_read_b128 v[214:217], v189 offset:3072
	s_add_u32 s64, s10, 0xfffc0080
	s_addc_u32 s65, s11, -1
	s_cmp_eq_u32 s69, 12
	s_cselect_b32 s67, s13, s65
	s_cselect_b32 s66, s29, s64
	s_cselect_b32 s65, s36, s68
	s_cselect_b32 s64, s57, s59
	s_add_i32 m0, s79, 0xc000
	ds_read_b128 v[218:221], v186
	ds_read_b128 v[222:225], v186 offset:1024
	ds_read_b128 v[226:229], v186 offset:2048
	ds_read_b128 v[230:233], v186 offset:3072
	ds_read_b128 v[234:237], v186 offset:4096
	ds_read_b128 v[238:241], v186 offset:5120
	ds_read_b128 v[242:245], v186 offset:6144
	ds_read_b128 v[246:249], v186 offset:7168
	global_load_lds_dwordx4 v162, s[10:11]
	s_add_i32 m0, s79, 0xe000
	s_nop 0
	global_load_lds_dwordx4 v164, s[10:11]
	s_waitcnt vmcnt(8)
	s_waitcnt lgkmcnt(0)
	s_barrier
; #define PG8_STAGE(bufoff, gbase, voff) do { _Pragma("unroll") for (int _i = 0; _i < 2; ++_i) \
;         __builtin_amdgcn_global_load_lds((const unsigned*)((const char*)(gbase) + (voff)[_i]), (LAS unsigned*)(lds + (bufoff) + ldsw + _i * 8192), 16, 0, 0); } while (0)
; #define PG8_LDA(dst, b, h) do { _Pragma("unroll") for (int m = 0; m < 4; ++m) _Pragma("unroll") for (int k = 0; k < 2; ++k) dst[m][k] = *(const LAS bf16x8*)(lds + PG8_SA(b, h) + aoff + m * 2048 + k * 1024); } while (0)
; #define PG8_MMA(ai, bj, At, Bt) do { __builtin_amdgcn_s_setprio(1); _Pragma("unroll") for (int m = 0; m < 4; ++m) _Pragma("unroll") for (int n = 0; n < 2; ++n) _Pragma("unroll") for (int k = 0; k < 2; ++k) \
;         acc[ai][bj][m][n] = __builtin_amdgcn_mfma_f32_16x16x32_bf16(Bt[n][k], At[m][k], acc[ai][bj][m][n], 0, 0, 0); __builtin_amdgcn_s_setprio(0); } while (0)
; #define PG8_WAIT_V(n) asm volatile("s_waitcnt vmcnt(" #n ")" ::: "memory")
; #define PG8_WAIT_L(n) asm volatile("s_waitcnt lgkmcnt(" #n ")" ::: "memory")
; #define PG8_BAR __builtin_amdgcn_s_barrier()
; #define PG8_SCHED __builtin_amdgcn_sched_barrier(0)
; template <class Epi, class Sched>
; DI void gemm_phase(LAS unsigned char* lds, const Gemm g, const Sched& S, const Epi& E) {
;     ...
;             PG8_WAIT_V(8); PG8_WAIT_L(0); PG8_BAR; PG8_MMA(0, 0, At, B0); PG8_MMA(0, 1, At, B1); PG8_BAR; PG8_SCHED;
;             PG8_LDA(At, 0, 1); PG8_STAGE(PG8_SB(0, 0), b2, voffB); PG8_STAGE(PG8_SB(0, 1), b2 + hstepB, voffB); PG8_STAGE(PG8_SA(0, 0), a2, voffA);
;             PG8_WAIT_V(8); PG8_WAIT_L(0); PG8_BAR; PG8_MMA(1, 0, At, B0); PG8_MMA(1, 1, At, B1); PG8_BAR; PG8_SCHED;
	s_setprio 1
	v_mfma_f32_16x16x32_bf16 v[126:129], v[138:141], v[218:221], v[126:129]
	v_mfma_f32_16x16x32_bf16 v[122:125], v[176:179], v[218:221], v[122:125]
	v_mfma_f32_16x16x32_bf16 v[110:113], v[138:141], v[226:229], v[110:113]
	v_mfma_f32_16x16x32_bf16 v[106:109], v[176:179], v[226:229], v[106:109]
	v_mfma_f32_16x16x32_bf16 v[94:97], v[138:141], v[234:237], v[94:97]
	v_mfma_f32_16x16x32_bf16 v[90:93], v[176:179], v[234:237], v[90:93]
	v_mfma_f32_16x16x32_bf16 v[78:81], v[138:141], v[242:245], v[78:81]
	v_mfma_f32_16x16x32_bf16 v[74:77], v[176:179], v[242:245], v[74:77]
	v_mfma_f32_16x16x32_bf16 v[126:129], v[142:145], v[222:225], v[126:129]
	v_mfma_f32_16x16x32_bf16 v[122:125], v[198:201], v[222:225], v[122:125]
	v_mfma_f32_16x16x32_bf16 v[110:113], v[142:145], v[230:233], v[110:113]
	v_mfma_f32_16x16x32_bf16 v[106:109], v[198:201], v[230:233], v[106:109]
	v_mfma_f32_16x16x32_bf16 v[94:97], v[142:145], v[238:241], v[94:97]
	v_mfma_f32_16x16x32_bf16 v[90:93], v[198:201], v[238:241], v[90:93]
	v_mfma_f32_16x16x32_bf16 v[78:81], v[142:145], v[246:249], v[78:81]
	v_mfma_f32_16x16x32_bf16 v[74:77], v[198:201], v[246:249], v[74:77]
	v_mfma_f32_16x16x32_bf16 v[118:121], v[202:205], v[218:221], v[118:121]
	v_mfma_f32_16x16x32_bf16 v[114:117], v[210:213], v[218:221], v[114:117]
	v_mfma_f32_16x16x32_bf16 v[102:105], v[202:205], v[226:229], v[102:105]
	v_mfma_f32_16x16x32_bf16 v[98:101], v[210:213], v[226:229], v[98:101]
	v_mfma_f32_16x16x32_bf16 v[86:89], v[202:205], v[234:237], v[86:89]
	v_mfma_f32_16x16x32_bf16 v[82:85], v[210:213], v[234:237], v[82:85]
	v_mfma_f32_16x16x32_bf16 v[70:73], v[202:205], v[242:245], v[70:73]
	v_mfma_f32_16x16x32_bf16 v[66:69], v[210:213], v[242:245], v[66:69]
	v_mfma_f32_16x16x32_bf16 v[118:121], v[206:209], v[222:225], v[118:121]
	v_mfma_f32_16x16x32_bf16 v[114:117], v[214:217], v[222:225], v[114:117]
	v_mfma_f32_16x16x32_bf16 v[102:105], v[206:209], v[230:233], v[102:105]
	v_mfma_f32_16x16x32_bf16 v[98:101], v[214:217], v[230:233], v[98:101]
	v_mfma_f32_16x16x32_bf16 v[86:89], v[206:209], v[238:241], v[86:89]
	v_mfma_f32_16x16x32_bf16 v[82:85], v[214:217], v[238:241], v[82:85]
	v_mfma_f32_16x16x32_bf16 v[70:73], v[206:209], v[246:249], v[70:73]
	v_mfma_f32_16x16x32_bf16 v[66:69], v[214:217], v[246:249], v[66:69]
	s_setprio 0
	s_barrier
	s_add_i32 s70, s94, s78
	v_lshl_add_u64 v[172:173], s[64:65], 0, v[150:151]
	s_mov_b32 m0, s70
	ds_read_b128 v[218:221], v186 offset:16384
	ds_read_b128 v[222:225], v186 offset:17408
	ds_read_b128 v[226:229], v186 offset:18432
	ds_read_b128 v[230:233], v186 offset:19456
	ds_read_b128 v[234:237], v186 offset:20480
	ds_read_b128 v[238:241], v186 offset:21504
	ds_read_b128 v[242:245], v186 offset:22528
	ds_read_b128 v[246:249], v186 offset:23552
	global_load_lds_dwordx4 v[172:173], off
	s_add_i32 m0, s70, 0x2000
	s_add_u32 s70, s64, 0x40000
	v_lshl_add_u64 v[180:181], s[64:65], 0, v[154:155]
	s_addc_u32 s71, s65, 0
	s_add_i32 s72, s95, s78
	global_load_lds_dwordx4 v[180:181], off
	s_mov_b32 m0, s72
	v_lshl_add_u64 v[252:253], s[66:67], 0, v[152:153]
	global_load_lds_dwordx4 v150, s[70:71]
	s_add_i32 m0, s72, 0x2000
	s_nop 0
	global_load_lds_dwordx4 v154, s[70:71]
	v_lshl_add_u64 v[250:251], s[66:67], 0, v[148:149]
	s_mov_b32 m0, s79
	s_nop 0
	global_load_lds_dwordx4 v[250:251], off
	s_mov_b32 m0, s80
	s_nop 0
	global_load_lds_dwordx4 v[252:253], off
	s_waitcnt vmcnt(8)
	s_waitcnt lgkmcnt(0)
	s_barrier
	s_setprio 1
	v_mfma_f32_16x16x32_bf16 v[62:65], v[138:141], v[218:221], v[62:65]
	v_mfma_f32_16x16x32_bf16 v[58:61], v[176:179], v[218:221], v[58:61]
	v_mfma_f32_16x16x32_bf16 v[46:49], v[138:141], v[226:229], v[46:49]
	v_mfma_f32_16x16x32_bf16 v[42:45], v[176:179], v[226:229], v[42:45]
	v_mfma_f32_16x16x32_bf16 v[30:33], v[138:141], v[234:237], v[30:33]
	v_mfma_f32_16x16x32_bf16 v[26:29], v[176:179], v[234:237], v[26:29]
	v_mfma_f32_16x16x32_bf16 v[14:17], v[138:141], v[242:245], v[14:17]
	v_mfma_f32_16x16x32_bf16 v[10:13], v[176:179], v[242:245], v[10:13]
	v_mfma_f32_16x16x32_bf16 v[62:65], v[142:145], v[222:225], v[62:65]
	v_mfma_f32_16x16x32_bf16 v[58:61], v[198:201], v[222:225], v[58:61]
	v_mfma_f32_16x16x32_bf16 v[46:49], v[142:145], v[230:233], v[46:49]
	v_mfma_f32_16x16x32_bf16 v[42:45], v[198:201], v[230:233], v[42:45]
	v_mfma_f32_16x16x32_bf16 v[30:33], v[142:145], v[238:241], v[30:33]
	v_mfma_f32_16x16x32_bf16 v[26:29], v[198:201], v[238:241], v[26:29]
	v_mfma_f32_16x16x32_bf16 v[14:17], v[142:145], v[246:249], v[14:17]
	v_mfma_f32_16x16x32_bf16 v[10:13], v[198:201], v[246:249], v[10:13]
	v_mfma_f32_16x16x32_bf16 v[54:57], v[202:205], v[218:221], v[54:57]
	v_mfma_f32_16x16x32_bf16 v[50:53], v[210:213], v[218:221], v[50:53]
	v_mfma_f32_16x16x32_bf16 v[38:41], v[202:205], v[226:229], v[38:41]
	v_mfma_f32_16x16x32_bf16 v[34:37], v[210:213], v[226:229], v[34:37]
	v_mfma_f32_16x16x32_bf16 v[22:25], v[202:205], v[234:237], v[22:25]
	v_mfma_f32_16x16x32_bf16 v[18:21], v[210:213], v[234:237], v[18:21]
	v_mfma_f32_16x16x32_bf16 v[6:9], v[202:205], v[242:245], v[6:9]
	v_mfma_f32_16x16x32_bf16 v[2:5], v[210:213], v[242:245], v[2:5]
	v_mfma_f32_16x16x32_bf16 v[54:57], v[206:209], v[222:225], v[54:57]
	v_mfma_f32_16x16x32_bf16 v[50:53], v[214:217], v[222:225], v[50:53]
	v_mfma_f32_16x16x32_bf16 v[38:41], v[206:209], v[230:233], v[38:41]
	v_mfma_f32_16x16x32_bf16 v[34:37], v[214:217], v[230:233], v[34:37]
	v_mfma_f32_16x16x32_bf16 v[22:25], v[206:209], v[238:241], v[22:25]
	v_mfma_f32_16x16x32_bf16 v[18:21], v[214:217], v[238:241], v[18:21]
	v_mfma_f32_16x16x32_bf16 v[6:9], v[206:209], v[246:249], v[6:9]
	v_mfma_f32_16x16x32_bf16 v[2:5], v[214:217], v[246:249], v[2:5]
	s_setprio 0
	s_barrier
; #define PG8_STAGE(bufoff, gbase, voff) do { _Pragma("unroll") for (int _i = 0; _i < 2; ++_i) \
;         __builtin_amdgcn_global_load_lds((const unsigned*)((const char*)(gbase) + (voff)[_i]), (LAS unsigned*)(lds + (bufoff) + ldsw + _i * 8192), 16, 0, 0); } while (0)
; #define PG8_LDA(dst, b, h) do { _Pragma("unroll") for (int m = 0; m < 4; ++m) _Pragma("unroll") for (int k = 0; k < 2; ++k) dst[m][k] = *(const LAS bf16x8*)(lds + PG8_SA(b, h) + aoff + m * 2048 + k * 1024); } while (0)
; #define PG8_LDB(dst, b, h) do { _Pragma("unroll") for (int n = 0; n < 2; ++n) _Pragma("unroll") for (int k = 0; k < 2; ++k) dst[n][k] = *(const LAS bf16x8*)(lds + PG8_SB(b, h) + boff + n * 2048 + k * 1024); } while (0)
; #define PG8_MMA(ai, bj, At, Bt) do { __builtin_amdgcn_s_setprio(1); _Pragma("unroll") for (int m = 0; m < 4; ++m) _Pragma("unroll") for (int n = 0; n < 2; ++n) _Pragma("unroll") for (int k = 0; k < 2; ++k) \
;         acc[ai][bj][m][n] = __builtin_amdgcn_mfma_f32_16x16x32_bf16(Bt[n][k], At[m][k], acc[ai][bj][m][n], 0, 0, 0); __builtin_amdgcn_s_setprio(0); } while (0)
; #define PG8_WAIT_V(n) asm volatile("s_waitcnt vmcnt(" #n ")" ::: "memory")
; #define PG8_WAIT_L(n) asm volatile("s_waitcnt lgkmcnt(" #n ")" ::: "memory")
; #define PG8_BAR __builtin_amdgcn_s_barrier()
; #define PG8_SCHED __builtin_amdgcn_sched_barrier(0)
; template <class Epi, class Sched>
; DI void gemm_phase(LAS unsigned char* lds, const Gemm g, const Sched& S, const Epi& E) {
;     ...
;             PG8_LDB(B0, 1, 0); PG8_LDB(B1, 1, 1); PG8_SCHED; PG8_LDA(At, 1, 0); PG8_STAGE(PG8_SA(0, 1), a2 + hstepA, voffA);
;             PG8_WAIT_V(8); PG8_WAIT_L(0); PG8_BAR; PG8_MMA(0, 0, At, B0); PG8_MMA(0, 1, At, B1); PG8_BAR; PG8_SCHED;
;             PG8_LDA(At, 1, 1); PG8_STAGE(PG8_SB(1, 0), b3, voffB); PG8_STAGE(PG8_SB(1, 1), b3 + hstepB, voffB); PG8_STAGE(PG8_SA(1, 0), a3, voffA);
;             PG8_WAIT_V(8); PG8_WAIT_L(0); PG8_BAR; PG8_MMA(1, 0, At, B0); PG8_MMA(1, 1, At, B1); PG8_BAR; PG8_SCHED;
;         }
	s_add_i32 s70, 0, 0x18000
	v_add_u32_e32 v156, s70, v159
	s_add_i32 s71, 0, 0x1c000
	ds_read_b128 v[138:141], v156
	ds_read_b128 v[142:145], v156 offset:1024
	ds_read_b128 v[176:179], v156 offset:2048
	ds_read_b128 v[198:201], v156 offset:3072
	v_add_u32_e32 v156, s71, v159
	ds_read_b128 v[202:205], v156
	ds_read_b128 v[206:209], v156 offset:1024
	ds_read_b128 v[210:213], v156 offset:2048
	ds_read_b128 v[214:217], v156 offset:3072
	s_add_u32 s66, s66, 0x40000
	s_addc_u32 s67, s67, 0
	s_mov_b32 m0, s81
	ds_read_b128 v[218:221], v186 offset:32768
	ds_read_b128 v[222:225], v186 offset:33792
	ds_read_b128 v[226:229], v186 offset:34816
	ds_read_b128 v[230:233], v186 offset:35840
	ds_read_b128 v[234:237], v186 offset:36864
	ds_read_b128 v[238:241], v186 offset:37888
	ds_read_b128 v[242:245], v186 offset:38912
	ds_read_b128 v[246:249], v186 offset:39936
	global_load_lds_dwordx4 v148, s[66:67]
	s_mov_b32 m0, s82
	s_nop 0
	global_load_lds_dwordx4 v152, s[66:67]
	s_waitcnt vmcnt(8)
	s_waitcnt lgkmcnt(0)
	s_barrier
	s_setprio 1
	v_mfma_f32_16x16x32_bf16 v[126:129], v[138:141], v[218:221], v[126:129]
	v_mfma_f32_16x16x32_bf16 v[122:125], v[176:179], v[218:221], v[122:125]
	v_mfma_f32_16x16x32_bf16 v[110:113], v[138:141], v[226:229], v[110:113]
	v_mfma_f32_16x16x32_bf16 v[106:109], v[176:179], v[226:229], v[106:109]
	v_mfma_f32_16x16x32_bf16 v[94:97], v[138:141], v[234:237], v[94:97]
	v_mfma_f32_16x16x32_bf16 v[90:93], v[176:179], v[234:237], v[90:93]
	v_mfma_f32_16x16x32_bf16 v[78:81], v[138:141], v[242:245], v[78:81]
	v_mfma_f32_16x16x32_bf16 v[74:77], v[176:179], v[242:245], v[74:77]
	v_mfma_f32_16x16x32_bf16 v[126:129], v[142:145], v[222:225], v[126:129]
	v_mfma_f32_16x16x32_bf16 v[122:125], v[198:201], v[222:225], v[122:125]
	v_mfma_f32_16x16x32_bf16 v[110:113], v[142:145], v[230:233], v[110:113]
	v_mfma_f32_16x16x32_bf16 v[106:109], v[198:201], v[230:233], v[106:109]
	v_mfma_f32_16x16x32_bf16 v[94:97], v[142:145], v[238:241], v[94:97]
	v_mfma_f32_16x16x32_bf16 v[90:93], v[198:201], v[238:241], v[90:93]
	v_mfma_f32_16x16x32_bf16 v[78:81], v[142:145], v[246:249], v[78:81]
	v_mfma_f32_16x16x32_bf16 v[74:77], v[198:201], v[246:249], v[74:77]
	v_mfma_f32_16x16x32_bf16 v[118:121], v[202:205], v[218:221], v[118:121]
	v_mfma_f32_16x16x32_bf16 v[114:117], v[210:213], v[218:221], v[114:117]
	v_mfma_f32_16x16x32_bf16 v[102:105], v[202:205], v[226:229], v[102:105]
	v_mfma_f32_16x16x32_bf16 v[98:101], v[210:213], v[226:229], v[98:101]
	v_mfma_f32_16x16x32_bf16 v[86:89], v[202:205], v[234:237], v[86:89]
	v_mfma_f32_16x16x32_bf16 v[82:85], v[210:213], v[234:237], v[82:85]
	v_mfma_f32_16x16x32_bf16 v[70:73], v[202:205], v[242:245], v[70:73]
	v_mfma_f32_16x16x32_bf16 v[66:69], v[210:213], v[242:245], v[66:69]
	v_mfma_f32_16x16x32_bf16 v[118:121], v[206:209], v[222:225], v[118:121]
	v_mfma_f32_16x16x32_bf16 v[114:117], v[214:217], v[222:225], v[114:117]
	v_mfma_f32_16x16x32_bf16 v[102:105], v[206:209], v[230:233], v[102:105]
	v_mfma_f32_16x16x32_bf16 v[98:101], v[214:217], v[230:233], v[98:101]
	v_mfma_f32_16x16x32_bf16 v[86:89], v[206:209], v[238:241], v[86:89]
	v_mfma_f32_16x16x32_bf16 v[82:85], v[214:217], v[238:241], v[82:85]
	v_mfma_f32_16x16x32_bf16 v[70:73], v[206:209], v[246:249], v[70:73]
	v_mfma_f32_16x16x32_bf16 v[66:69], v[214:217], v[246:249], v[66:69]
	s_setprio 0
	s_barrier
	s_add_i32 s66, s70, s78
	v_lshl_add_u64 v[172:173], v[172:173], 0, s[50:51]
	s_mov_b32 m0, s66
	ds_read_b128 v[218:221], v186 offset:49152
	ds_read_b128 v[222:225], v186 offset:50176
	ds_read_b128 v[226:229], v186 offset:51200
	ds_read_b128 v[230:233], v186 offset:52224
	ds_read_b128 v[234:237], v186 offset:53248
	ds_read_b128 v[238:241], v186 offset:54272
	ds_read_b128 v[242:245], v186 offset:55296
	ds_read_b128 v[246:249], v186 offset:56320
	global_load_lds_dwordx4 v[172:173], off
	s_add_i32 m0, s66, 0x2000
	s_add_u32 s64, s64, 0x40080
	v_lshl_add_u64 v[172:173], v[180:181], 0, s[50:51]
	s_addc_u32 s65, s65, 0
	s_add_i32 s66, s71, s78
	global_load_lds_dwordx4 v[172:173], off
	s_mov_b32 m0, s66
	s_nop 0
	global_load_lds_dwordx4 v150, s[64:65]
	s_add_i32 m0, s66, 0x2000
	s_nop 0
	global_load_lds_dwordx4 v154, s[64:65]
	v_lshl_add_u64 v[172:173], v[250:251], 0, s[50:51]
	s_mov_b32 m0, s86
	s_nop 0
	global_load_lds_dwordx4 v[172:173], off
	v_lshl_add_u64 v[172:173], v[252:253], 0, s[50:51]
	s_mov_b32 m0, s87
	s_nop 0
	global_load_lds_dwordx4 v[172:173], off
	s_waitcnt vmcnt(8)
	s_waitcnt lgkmcnt(0)
	s_barrier
	s_setprio 1
	v_mfma_f32_16x16x32_bf16 v[62:65], v[138:141], v[218:221], v[62:65]
	v_mfma_f32_16x16x32_bf16 v[58:61], v[176:179], v[218:221], v[58:61]
	v_mfma_f32_16x16x32_bf16 v[46:49], v[138:141], v[226:229], v[46:49]
	v_mfma_f32_16x16x32_bf16 v[42:45], v[176:179], v[226:229], v[42:45]
	v_mfma_f32_16x16x32_bf16 v[30:33], v[138:141], v[234:237], v[30:33]
	v_mfma_f32_16x16x32_bf16 v[26:29], v[176:179], v[234:237], v[26:29]
	v_mfma_f32_16x16x32_bf16 v[14:17], v[138:141], v[242:245], v[14:17]
	v_mfma_f32_16x16x32_bf16 v[10:13], v[176:179], v[242:245], v[10:13]
	v_mfma_f32_16x16x32_bf16 v[62:65], v[142:145], v[222:225], v[62:65]
	v_mfma_f32_16x16x32_bf16 v[58:61], v[198:201], v[222:225], v[58:61]
	v_mfma_f32_16x16x32_bf16 v[46:49], v[142:145], v[230:233], v[46:49]
	v_mfma_f32_16x16x32_bf16 v[42:45], v[198:201], v[230:233], v[42:45]
	v_mfma_f32_16x16x32_bf16 v[30:33], v[142:145], v[238:241], v[30:33]
	v_mfma_f32_16x16x32_bf16 v[26:29], v[198:201], v[238:241], v[26:29]
	v_mfma_f32_16x16x32_bf16 v[14:17], v[142:145], v[246:249], v[14:17]
	v_mfma_f32_16x16x32_bf16 v[10:13], v[198:201], v[246:249], v[10:13]
	v_mfma_f32_16x16x32_bf16 v[54:57], v[202:205], v[218:221], v[54:57]
	v_mfma_f32_16x16x32_bf16 v[50:53], v[210:213], v[218:221], v[50:53]
	v_mfma_f32_16x16x32_bf16 v[38:41], v[202:205], v[226:229], v[38:41]
	v_mfma_f32_16x16x32_bf16 v[34:37], v[210:213], v[226:229], v[34:37]
	v_mfma_f32_16x16x32_bf16 v[22:25], v[202:205], v[234:237], v[22:25]
	v_mfma_f32_16x16x32_bf16 v[18:21], v[210:213], v[234:237], v[18:21]
	v_mfma_f32_16x16x32_bf16 v[6:9], v[202:205], v[242:245], v[6:9]
	v_mfma_f32_16x16x32_bf16 v[2:5], v[210:213], v[242:245], v[2:5]
	v_mfma_f32_16x16x32_bf16 v[54:57], v[206:209], v[222:225], v[54:57]
	v_mfma_f32_16x16x32_bf16 v[50:53], v[214:217], v[222:225], v[50:53]
	v_mfma_f32_16x16x32_bf16 v[38:41], v[206:209], v[230:233], v[38:41]
	v_mfma_f32_16x16x32_bf16 v[34:37], v[214:217], v[230:233], v[34:37]
	v_mfma_f32_16x16x32_bf16 v[22:25], v[206:209], v[238:241], v[22:25]
	v_mfma_f32_16x16x32_bf16 v[18:21], v[214:217], v[238:241], v[18:21]
	v_mfma_f32_16x16x32_bf16 v[6:9], v[206:209], v[246:249], v[6:9]
	v_mfma_f32_16x16x32_bf16 v[2:5], v[214:217], v[246:249], v[2:5]
	s_setprio 0
	s_barrier
	s_add_i32 s69, s69, 2
	s_add_u32 s10, s10, 0x100
	s_addc_u32 s11, s11, 0
	s_add_u32 s59, s59, 0x100
	s_addc_u32 s68, s68, 0
	s_cmp_gt_u32 s69, 13
	s_cbranch_scc0 .LBB0_381
	s_waitcnt vmcnt(0)
	s_mov_b32 s99, 1
	s_and_b64 vcc, exec, s[52:53]
	s_cbranch_vccnz .LBB0_386
	s_cmp_gt_i32 s12, 4
	s_mov_b64 s[10:11], -1
	s_cbranch_scc1 .LBB0_387

; #define PG8_STAGE(bufoff, gbase, voff) do { _Pragma("unroll") for (int _i = 0; _i < 2; ++_i) \
;         __builtin_amdgcn_global_load_lds((const unsigned*)((const char*)(gbase) + (voff)[_i]), (LAS unsigned*)(lds + (bufoff) + ldsw + _i * 8192), 16, 0, 0); } while (0)
; #define PG8_LDA(dst, b, h) do { _Pragma("unroll") for (int m = 0; m < 4; ++m) _Pragma("unroll") for (int k = 0; k < 2; ++k) dst[m][k] = *(const LAS bf16x8*)(lds + PG8_SA(b, h) + aoff + m * 2048 + k * 1024); } while (0)
; #define PG8_LDB(dst, b, h) do { _Pragma("unroll") for (int n = 0; n < 2; ++n) _Pragma("unroll") for (int k = 0; k < 2; ++k) dst[n][k] = *(const LAS bf16x8*)(lds + PG8_SB(b, h) + boff + n * 2048 + k * 1024); } while (0)
; #define PG8_MMA(ai, bj, At, Bt) do { __builtin_amdgcn_s_setprio(1); _Pragma("unroll") for (int m = 0; m < 4; ++m) _Pragma("unroll") for (int n = 0; n < 2; ++n) _Pragma("unroll") for (int k = 0; k < 2; ++k) \
;         acc[ai][bj][m][n] = __builtin_amdgcn_mfma_f32_16x16x32_bf16(Bt[n][k], At[m][k], acc[ai][bj][m][n], 0, 0, 0); __builtin_amdgcn_s_setprio(0); } while (0)
; #define PG8_WAIT_V(n) asm volatile("s_waitcnt vmcnt(" #n ")" ::: "memory")
; #define PG8_WAIT_L(n) asm volatile("s_waitcnt lgkmcnt(" #n ")" ::: "memory")
; #define PG8_BAR __builtin_amdgcn_s_barrier()
; #define PG8_SCHED __builtin_amdgcn_sched_barrier(0)
; template <class Epi, class Sched>
; DI void gemm_phase(LAS unsigned char* lds, const Gemm g, const Sched& S, const Epi& E) {
;     ...
;             PG8_LDB(B0, 0, 0); PG8_LDB(B1, 0, 1); PG8_SCHED; PG8_LDA(At, 0, 0); PG8_STAGE(PG8_SA(1, 1), a1 + hstepA, voffA);
;             PG8_WAIT_V(8); PG8_WAIT_L(0); PG8_BAR; PG8_MMA(0, 0, At, B0); PG8_MMA(0, 1, At, B1); PG8_BAR; PG8_SCHED;
;             PG8_LDA(At, 0, 1); PG8_STAGE(PG8_SB(0, 0), b2, voffB); PG8_STAGE(PG8_SB(0, 1), b2 + hstepB, voffB); PG8_STAGE(PG8_SA(0, 0), a2, voffA);
;             PG8_WAIT_V(8); PG8_WAIT_L(0); PG8_BAR; PG8_MMA(1, 0, At, B0); PG8_MMA(1, 1, At, B1); PG8_BAR; PG8_SCHED;
.LBB0_579:
	ds_read_b128 v[150:153], v142
	ds_read_b128 v[154:157], v142 offset:1024
	ds_read_b128 v[158:161], v142 offset:2048
	ds_read_b128 v[162:165], v142 offset:3072
	ds_read_b128 v[166:169], v143
	ds_read_b128 v[170:173], v143 offset:1024
	ds_read_b128 v[174:177], v143 offset:2048
	ds_read_b128 v[178:181], v143 offset:3072
	s_add_u32 s16, s8, s12
	s_addc_u32 s17, s9, s13
	s_add_u32 s16, s16, 0x100
	s_addc_u32 s17, s17, 0
	s_add_u32 s52, s39, s12
	s_addc_u32 s53, s40, s13
	s_cmpk_eq_i32 s12, 0xf00
	s_cselect_b32 s19, s9, s17
	s_cselect_b32 s18, s8, s16
	s_cselect_b32 s17, s7, s53
	s_cselect_b32 s16, s6, s52
	s_mov_b32 m0, s42
	v_lshl_add_u64 v[182:183], v[138:139], 0, s[12:13]
	ds_read_b128 v[186:189], v145
	ds_read_b128 v[190:193], v145 offset:1024
	ds_read_b128 v[194:197], v145 offset:2048
	ds_read_b128 v[198:201], v145 offset:3072
	ds_read_b128 v[202:205], v145 offset:4096
	ds_read_b128 v[206:209], v145 offset:5120
	ds_read_b128 v[210:213], v145 offset:6144
	ds_read_b128 v[214:217], v145 offset:7168
	global_load_lds_dwordx4 v[182:183], off
	v_lshl_add_u64 v[182:183], v[140:141], 0, s[12:13]
	s_mov_b32 m0, s43
	s_nop 0
	global_load_lds_dwordx4 v[182:183], off
	s_waitcnt vmcnt(8)
	s_waitcnt lgkmcnt(0)
	s_barrier
	s_setprio 1
	v_mfma_f32_16x16x32_bf16 v[126:129], v[150:153], v[186:189], v[126:129]
	v_mfma_f32_16x16x32_bf16 v[122:125], v[158:161], v[186:189], v[122:125]
	v_mfma_f32_16x16x32_bf16 v[118:121], v[150:153], v[194:197], v[118:121]
	v_mfma_f32_16x16x32_bf16 v[114:117], v[158:161], v[194:197], v[114:117]
	v_mfma_f32_16x16x32_bf16 v[110:113], v[150:153], v[202:205], v[110:113]
	v_mfma_f32_16x16x32_bf16 v[106:109], v[158:161], v[202:205], v[106:109]
	v_mfma_f32_16x16x32_bf16 v[102:105], v[150:153], v[210:213], v[102:105]
	v_mfma_f32_16x16x32_bf16 v[98:101], v[158:161], v[210:213], v[98:101]
	v_mfma_f32_16x16x32_bf16 v[126:129], v[154:157], v[190:193], v[126:129]
	v_mfma_f32_16x16x32_bf16 v[122:125], v[162:165], v[190:193], v[122:125]
	v_mfma_f32_16x16x32_bf16 v[118:121], v[154:157], v[198:201], v[118:121]
	v_mfma_f32_16x16x32_bf16 v[114:117], v[162:165], v[198:201], v[114:117]
	v_mfma_f32_16x16x32_bf16 v[110:113], v[154:157], v[206:209], v[110:113]
	v_mfma_f32_16x16x32_bf16 v[106:109], v[162:165], v[206:209], v[106:109]
	v_mfma_f32_16x16x32_bf16 v[102:105], v[154:157], v[214:217], v[102:105]
	v_mfma_f32_16x16x32_bf16 v[98:101], v[162:165], v[214:217], v[98:101]
	v_mfma_f32_16x16x32_bf16 v[62:65], v[166:169], v[186:189], v[62:65]
	v_mfma_f32_16x16x32_bf16 v[58:61], v[174:177], v[186:189], v[58:61]
	v_mfma_f32_16x16x32_bf16 v[54:57], v[166:169], v[194:197], v[54:57]
	v_mfma_f32_16x16x32_bf16 v[50:53], v[174:177], v[194:197], v[50:53]
	v_mfma_f32_16x16x32_bf16 v[46:49], v[166:169], v[202:205], v[46:49]
	v_mfma_f32_16x16x32_bf16 v[42:45], v[174:177], v[202:205], v[42:45]
	v_mfma_f32_16x16x32_bf16 v[38:41], v[166:169], v[210:213], v[38:41]
	v_mfma_f32_16x16x32_bf16 v[34:37], v[174:177], v[210:213], v[34:37]
	v_mfma_f32_16x16x32_bf16 v[62:65], v[170:173], v[190:193], v[62:65]
	v_mfma_f32_16x16x32_bf16 v[58:61], v[178:181], v[190:193], v[58:61]
	v_mfma_f32_16x16x32_bf16 v[54:57], v[170:173], v[198:201], v[54:57]
	v_mfma_f32_16x16x32_bf16 v[50:53], v[178:181], v[198:201], v[50:53]
	v_mfma_f32_16x16x32_bf16 v[46:49], v[170:173], v[206:209], v[46:49]
	v_mfma_f32_16x16x32_bf16 v[42:45], v[178:181], v[206:209], v[42:45]
	v_mfma_f32_16x16x32_bf16 v[38:41], v[170:173], v[214:217], v[38:41]
	v_mfma_f32_16x16x32_bf16 v[34:37], v[178:181], v[214:217], v[34:37]
	s_setprio 0
	s_barrier
	s_mov_b32 m0, s44
	v_lshl_add_u64 v[182:183], s[16:17], 0, v[134:135]
	s_add_u32 s52, s16, 0x80000
	ds_read_b128 v[186:189], v145 offset:16384
	ds_read_b128 v[190:193], v145 offset:17408
	ds_read_b128 v[194:197], v145 offset:18432
	ds_read_b128 v[198:201], v145 offset:19456
	ds_read_b128 v[202:205], v145 offset:20480
	ds_read_b128 v[206:209], v145 offset:21504
	ds_read_b128 v[210:213], v145 offset:22528
	ds_read_b128 v[214:217], v145 offset:23552
	global_load_lds_dwordx4 v[182:183], off
	v_lshl_add_u64 v[218:219], s[16:17], 0, v[130:131]
	s_mov_b32 m0, s45
	s_addc_u32 s53, s17, 0
	global_load_lds_dwordx4 v[218:219], off
	s_mov_b32 m0, s46
	v_lshl_add_u64 v[222:223], s[18:19], 0, v[132:133]
	global_load_lds_dwordx4 v134, s[52:53]
	s_mov_b32 m0, s47
	s_nop 0
	global_load_lds_dwordx4 v130, s[52:53]
	v_lshl_add_u64 v[220:221], s[18:19], 0, v[136:137]
	s_mov_b32 m0, s28
	s_nop 0
	global_load_lds_dwordx4 v[220:221], off
	s_mov_b32 m0, s29
	s_nop 0
	global_load_lds_dwordx4 v[222:223], off
	s_waitcnt vmcnt(8)
	s_waitcnt lgkmcnt(0)
	s_barrier
; #define PG8_STAGE(bufoff, gbase, voff) do { _Pragma("unroll") for (int _i = 0; _i < 2; ++_i) \
;         __builtin_amdgcn_global_load_lds((const unsigned*)((const char*)(gbase) + (voff)[_i]), (LAS unsigned*)(lds + (bufoff) + ldsw + _i * 8192), 16, 0, 0); } while (0)
; #define PG8_LDA(dst, b, h) do { _Pragma("unroll") for (int m = 0; m < 4; ++m) _Pragma("unroll") for (int k = 0; k < 2; ++k) dst[m][k] = *(const LAS bf16x8*)(lds + PG8_SA(b, h) + aoff + m * 2048 + k * 1024); } while (0)
; #define PG8_LDB(dst, b, h) do { _Pragma("unroll") for (int n = 0; n < 2; ++n) _Pragma("unroll") for (int k = 0; k < 2; ++k) dst[n][k] = *(const LAS bf16x8*)(lds + PG8_SB(b, h) + boff + n * 2048 + k * 1024); } while (0)
; #define PG8_MMA(ai, bj, At, Bt) do { __builtin_amdgcn_s_setprio(1); _Pragma("unroll") for (int m = 0; m < 4; ++m) _Pragma("unroll") for (int n = 0; n < 2; ++n) _Pragma("unroll") for (int k = 0; k < 2; ++k) \
;         acc[ai][bj][m][n] = __builtin_amdgcn_mfma_f32_16x16x32_bf16(Bt[n][k], At[m][k], acc[ai][bj][m][n], 0, 0, 0); __builtin_amdgcn_s_setprio(0); } while (0)
; #define PG8_WAIT_V(n) asm volatile("s_waitcnt vmcnt(" #n ")" ::: "memory")
; #define PG8_WAIT_L(n) asm volatile("s_waitcnt lgkmcnt(" #n ")" ::: "memory")
; #define PG8_BAR __builtin_amdgcn_s_barrier()
; #define PG8_SCHED __builtin_amdgcn_sched_barrier(0)
; template <class Epi, class Sched>
; DI void gemm_phase(LAS unsigned char* lds, const Gemm g, const Sched& S, const Epi& E) {
;     ...
;             PG8_WAIT_V(8); PG8_WAIT_L(0); PG8_BAR; PG8_MMA(1, 0, At, B0); PG8_MMA(1, 1, At, B1); PG8_BAR; PG8_SCHED;
;             PG8_LDB(B0, 1, 0); PG8_LDB(B1, 1, 1); PG8_SCHED; PG8_LDA(At, 1, 0); PG8_STAGE(PG8_SA(0, 1), a2 + hstepA, voffA);
;             PG8_WAIT_V(8); PG8_WAIT_L(0); PG8_BAR; PG8_MMA(0, 0, At, B0); PG8_MMA(0, 1, At, B1); PG8_BAR; PG8_SCHED;
	s_setprio 1
	v_mfma_f32_16x16x32_bf16 v[94:97], v[150:153], v[186:189], v[94:97]
	v_mfma_f32_16x16x32_bf16 v[90:93], v[158:161], v[186:189], v[90:93]
	v_mfma_f32_16x16x32_bf16 v[86:89], v[150:153], v[194:197], v[86:89]
	v_mfma_f32_16x16x32_bf16 v[82:85], v[158:161], v[194:197], v[82:85]
	v_mfma_f32_16x16x32_bf16 v[78:81], v[150:153], v[202:205], v[78:81]
	v_mfma_f32_16x16x32_bf16 v[74:77], v[158:161], v[202:205], v[74:77]
	v_mfma_f32_16x16x32_bf16 v[70:73], v[150:153], v[210:213], v[70:73]
	v_mfma_f32_16x16x32_bf16 v[66:69], v[158:161], v[210:213], v[66:69]
	v_mfma_f32_16x16x32_bf16 v[94:97], v[154:157], v[190:193], v[94:97]
	v_mfma_f32_16x16x32_bf16 v[90:93], v[162:165], v[190:193], v[90:93]
	v_mfma_f32_16x16x32_bf16 v[86:89], v[154:157], v[198:201], v[86:89]
	v_mfma_f32_16x16x32_bf16 v[82:85], v[162:165], v[198:201], v[82:85]
	v_mfma_f32_16x16x32_bf16 v[78:81], v[154:157], v[206:209], v[78:81]
	v_mfma_f32_16x16x32_bf16 v[74:77], v[162:165], v[206:209], v[74:77]
	v_mfma_f32_16x16x32_bf16 v[70:73], v[154:157], v[214:217], v[70:73]
	v_mfma_f32_16x16x32_bf16 v[66:69], v[162:165], v[214:217], v[66:69]
	v_mfma_f32_16x16x32_bf16 v[30:33], v[166:169], v[186:189], v[30:33]
	v_mfma_f32_16x16x32_bf16 v[26:29], v[174:177], v[186:189], v[26:29]
	v_mfma_f32_16x16x32_bf16 v[22:25], v[166:169], v[194:197], v[22:25]
	v_mfma_f32_16x16x32_bf16 v[18:21], v[174:177], v[194:197], v[18:21]
	v_mfma_f32_16x16x32_bf16 v[14:17], v[166:169], v[202:205], v[14:17]
	v_mfma_f32_16x16x32_bf16 v[10:13], v[174:177], v[202:205], v[10:13]
	v_mfma_f32_16x16x32_bf16 v[6:9], v[166:169], v[210:213], v[6:9]
	v_mfma_f32_16x16x32_bf16 v[2:5], v[174:177], v[210:213], v[2:5]
	v_mfma_f32_16x16x32_bf16 v[30:33], v[170:173], v[190:193], v[30:33]
	v_mfma_f32_16x16x32_bf16 v[26:29], v[178:181], v[190:193], v[26:29]
	v_mfma_f32_16x16x32_bf16 v[22:25], v[170:173], v[198:201], v[22:25]
	v_mfma_f32_16x16x32_bf16 v[18:21], v[178:181], v[198:201], v[18:21]
	v_mfma_f32_16x16x32_bf16 v[14:17], v[170:173], v[206:209], v[14:17]
	v_mfma_f32_16x16x32_bf16 v[10:13], v[178:181], v[206:209], v[10:13]
	v_mfma_f32_16x16x32_bf16 v[6:9], v[170:173], v[214:217], v[6:9]
	v_mfma_f32_16x16x32_bf16 v[2:5], v[178:181], v[214:217], v[2:5]
	s_setprio 0
	s_barrier
	ds_read_b128 v[150:153], v147
	ds_read_b128 v[154:157], v147 offset:1024
	ds_read_b128 v[158:161], v147 offset:2048
	ds_read_b128 v[162:165], v147 offset:3072
	ds_read_b128 v[166:169], v148
	ds_read_b128 v[170:173], v148 offset:1024
	ds_read_b128 v[174:177], v148 offset:2048
	ds_read_b128 v[178:181], v148 offset:3072
	s_add_u32 s18, s18, 0x40000
	s_addc_u32 s19, s19, 0
	s_mov_b32 m0, s34
	ds_read_b128 v[186:189], v145 offset:32768
	ds_read_b128 v[190:193], v145 offset:33792
	ds_read_b128 v[194:197], v145 offset:34816
	ds_read_b128 v[198:201], v145 offset:35840
	ds_read_b128 v[202:205], v145 offset:36864
	ds_read_b128 v[206:209], v145 offset:37888
	ds_read_b128 v[210:213], v145 offset:38912
	ds_read_b128 v[214:217], v145 offset:39936
	global_load_lds_dwordx4 v136, s[18:19]
	s_mov_b32 m0, s35
	s_nop 0
	global_load_lds_dwordx4 v132, s[18:19]
	s_waitcnt vmcnt(8)
	s_waitcnt lgkmcnt(0)
	s_barrier
	s_setprio 1
	v_mfma_f32_16x16x32_bf16 v[126:129], v[150:153], v[186:189], v[126:129]
	v_mfma_f32_16x16x32_bf16 v[122:125], v[158:161], v[186:189], v[122:125]
	v_mfma_f32_16x16x32_bf16 v[118:121], v[150:153], v[194:197], v[118:121]
	v_mfma_f32_16x16x32_bf16 v[114:117], v[158:161], v[194:197], v[114:117]
	v_mfma_f32_16x16x32_bf16 v[110:113], v[150:153], v[202:205], v[110:113]
	v_mfma_f32_16x16x32_bf16 v[106:109], v[158:161], v[202:205], v[106:109]
	v_mfma_f32_16x16x32_bf16 v[102:105], v[150:153], v[210:213], v[102:105]
	v_mfma_f32_16x16x32_bf16 v[98:101], v[158:161], v[210:213], v[98:101]
	v_mfma_f32_16x16x32_bf16 v[126:129], v[154:157], v[190:193], v[126:129]
	v_mfma_f32_16x16x32_bf16 v[122:125], v[162:165], v[190:193], v[122:125]
	v_mfma_f32_16x16x32_bf16 v[118:121], v[154:157], v[198:201], v[118:121]
	v_mfma_f32_16x16x32_bf16 v[114:117], v[162:165], v[198:201], v[114:117]
	v_mfma_f32_16x16x32_bf16 v[110:113], v[154:157], v[206:209], v[110:113]
	v_mfma_f32_16x16x32_bf16 v[106:109], v[162:165], v[206:209], v[106:109]
	v_mfma_f32_16x16x32_bf16 v[102:105], v[154:157], v[214:217], v[102:105]
	v_mfma_f32_16x16x32_bf16 v[98:101], v[162:165], v[214:217], v[98:101]
	v_mfma_f32_16x16x32_bf16 v[62:65], v[166:169], v[186:189], v[62:65]
	v_mfma_f32_16x16x32_bf16 v[58:61], v[174:177], v[186:189], v[58:61]
	v_mfma_f32_16x16x32_bf16 v[54:57], v[166:169], v[194:197], v[54:57]
	v_mfma_f32_16x16x32_bf16 v[50:53], v[174:177], v[194:197], v[50:53]
	v_mfma_f32_16x16x32_bf16 v[46:49], v[166:169], v[202:205], v[46:49]
	v_mfma_f32_16x16x32_bf16 v[42:45], v[174:177], v[202:205], v[42:45]
	v_mfma_f32_16x16x32_bf16 v[38:41], v[166:169], v[210:213], v[38:41]
	v_mfma_f32_16x16x32_bf16 v[34:37], v[174:177], v[210:213], v[34:37]
	v_mfma_f32_16x16x32_bf16 v[62:65], v[170:173], v[190:193], v[62:65]
	v_mfma_f32_16x16x32_bf16 v[58:61], v[178:181], v[190:193], v[58:61]
	v_mfma_f32_16x16x32_bf16 v[54:57], v[170:173], v[198:201], v[54:57]
	v_mfma_f32_16x16x32_bf16 v[50:53], v[178:181], v[198:201], v[50:53]
	v_mfma_f32_16x16x32_bf16 v[46:49], v[170:173], v[206:209], v[46:49]
	v_mfma_f32_16x16x32_bf16 v[42:45], v[178:181], v[206:209], v[42:45]
	v_mfma_f32_16x16x32_bf16 v[38:41], v[170:173], v[214:217], v[38:41]
	v_mfma_f32_16x16x32_bf16 v[34:37], v[178:181], v[214:217], v[34:37]
	s_setprio 0
	s_barrier
; #define PG8_STAGE(bufoff, gbase, voff) do { _Pragma("unroll") for (int _i = 0; _i < 2; ++_i) \
;         __builtin_amdgcn_global_load_lds((const unsigned*)((const char*)(gbase) + (voff)[_i]), (LAS unsigned*)(lds + (bufoff) + ldsw + _i * 8192), 16, 0, 0); } while (0)
; #define PG8_LDA(dst, b, h) do { _Pragma("unroll") for (int m = 0; m < 4; ++m) _Pragma("unroll") for (int k = 0; k < 2; ++k) dst[m][k] = *(const LAS bf16x8*)(lds + PG8_SA(b, h) + aoff + m * 2048 + k * 1024); } while (0)
; #define PG8_MMA(ai, bj, At, Bt) do { __builtin_amdgcn_s_setprio(1); _Pragma("unroll") for (int m = 0; m < 4; ++m) _Pragma("unroll") for (int n = 0; n < 2; ++n) _Pragma("unroll") for (int k = 0; k < 2; ++k) \
;         acc[ai][bj][m][n] = __builtin_amdgcn_mfma_f32_16x16x32_bf16(Bt[n][k], At[m][k], acc[ai][bj][m][n], 0, 0, 0); __builtin_amdgcn_s_setprio(0); } while (0)
; #define PG8_WAIT_V(n) asm volatile("s_waitcnt vmcnt(" #n ")" ::: "memory")
; #define PG8_WAIT_L(n) asm volatile("s_waitcnt lgkmcnt(" #n ")" ::: "memory")
; #define PG8_BAR __builtin_amdgcn_s_barrier()
; #define PG8_SCHED __builtin_amdgcn_sched_barrier(0)
; template <class Epi, class Sched>
; DI void gemm_phase(LAS unsigned char* lds, const Gemm g, const Sched& S, const Epi& E) {
;     ...
;             PG8_LDA(At, 1, 1); PG8_STAGE(PG8_SB(1, 0), b3, voffB); PG8_STAGE(PG8_SB(1, 1), b3 + hstepB, voffB); PG8_STAGE(PG8_SA(1, 0), a3, voffA);
;             PG8_WAIT_V(8); PG8_WAIT_L(0); PG8_BAR; PG8_MMA(1, 0, At, B0); PG8_MMA(1, 1, At, B1); PG8_BAR; PG8_SCHED;
;         }
;         if (wr == 0) PG8_BAR;
	s_mov_b32 m0, s48
	v_lshl_add_u64 v[182:183], v[182:183], 0, s[10:11]
	s_add_u32 s16, s16, 0x80080
	ds_read_b128 v[186:189], v145 offset:49152
	ds_read_b128 v[190:193], v145 offset:50176
	ds_read_b128 v[194:197], v145 offset:51200
	ds_read_b128 v[198:201], v145 offset:52224
	ds_read_b128 v[202:205], v145 offset:53248
	ds_read_b128 v[206:209], v145 offset:54272
	ds_read_b128 v[210:213], v145 offset:55296
	ds_read_b128 v[214:217], v145 offset:56320
	global_load_lds_dwordx4 v[182:183], off
	v_lshl_add_u64 v[182:183], v[218:219], 0, s[10:11]
	s_mov_b32 m0, s49
	s_addc_u32 s17, s17, 0
	global_load_lds_dwordx4 v[182:183], off
	s_mov_b32 m0, s50
	s_nop 0
	global_load_lds_dwordx4 v134, s[16:17]
	s_mov_b32 m0, s51
	s_nop 0
	global_load_lds_dwordx4 v130, s[16:17]
	v_lshl_add_u64 v[182:183], v[220:221], 0, s[10:11]
	s_mov_b32 m0, s37
	s_nop 0
	global_load_lds_dwordx4 v[182:183], off
	v_lshl_add_u64 v[182:183], v[222:223], 0, s[10:11]
	s_mov_b32 m0, s38
	s_nop 0
	global_load_lds_dwordx4 v[182:183], off
	s_waitcnt vmcnt(8)
	s_waitcnt lgkmcnt(0)
	s_barrier
	s_setprio 1
	v_mfma_f32_16x16x32_bf16 v[94:97], v[150:153], v[186:189], v[94:97]
	v_mfma_f32_16x16x32_bf16 v[90:93], v[158:161], v[186:189], v[90:93]
	v_mfma_f32_16x16x32_bf16 v[86:89], v[150:153], v[194:197], v[86:89]
	v_mfma_f32_16x16x32_bf16 v[82:85], v[158:161], v[194:197], v[82:85]
	v_mfma_f32_16x16x32_bf16 v[78:81], v[150:153], v[202:205], v[78:81]
	v_mfma_f32_16x16x32_bf16 v[74:77], v[158:161], v[202:205], v[74:77]
	v_mfma_f32_16x16x32_bf16 v[70:73], v[150:153], v[210:213], v[70:73]
	v_mfma_f32_16x16x32_bf16 v[66:69], v[158:161], v[210:213], v[66:69]
	v_mfma_f32_16x16x32_bf16 v[94:97], v[154:157], v[190:193], v[94:97]
	v_mfma_f32_16x16x32_bf16 v[90:93], v[162:165], v[190:193], v[90:93]
	v_mfma_f32_16x16x32_bf16 v[86:89], v[154:157], v[198:201], v[86:89]
	v_mfma_f32_16x16x32_bf16 v[82:85], v[162:165], v[198:201], v[82:85]
	v_mfma_f32_16x16x32_bf16 v[78:81], v[154:157], v[206:209], v[78:81]
	v_mfma_f32_16x16x32_bf16 v[74:77], v[162:165], v[206:209], v[74:77]
	v_mfma_f32_16x16x32_bf16 v[70:73], v[154:157], v[214:217], v[70:73]
	v_mfma_f32_16x16x32_bf16 v[66:69], v[162:165], v[214:217], v[66:69]
	v_mfma_f32_16x16x32_bf16 v[30:33], v[166:169], v[186:189], v[30:33]
	v_mfma_f32_16x16x32_bf16 v[26:29], v[174:177], v[186:189], v[26:29]
	v_mfma_f32_16x16x32_bf16 v[22:25], v[166:169], v[194:197], v[22:25]
	v_mfma_f32_16x16x32_bf16 v[18:21], v[174:177], v[194:197], v[18:21]
	v_mfma_f32_16x16x32_bf16 v[14:17], v[166:169], v[202:205], v[14:17]
	v_mfma_f32_16x16x32_bf16 v[10:13], v[174:177], v[202:205], v[10:13]
	v_mfma_f32_16x16x32_bf16 v[6:9], v[166:169], v[210:213], v[6:9]
	v_mfma_f32_16x16x32_bf16 v[2:5], v[174:177], v[210:213], v[2:5]
	v_mfma_f32_16x16x32_bf16 v[30:33], v[170:173], v[190:193], v[30:33]
	v_mfma_f32_16x16x32_bf16 v[26:29], v[178:181], v[190:193], v[26:29]
	v_mfma_f32_16x16x32_bf16 v[22:25], v[170:173], v[198:201], v[22:25]
	v_mfma_f32_16x16x32_bf16 v[18:21], v[178:181], v[198:201], v[18:21]
	v_mfma_f32_16x16x32_bf16 v[14:17], v[170:173], v[206:209], v[14:17]
	v_mfma_f32_16x16x32_bf16 v[10:13], v[178:181], v[206:209], v[10:13]
	v_mfma_f32_16x16x32_bf16 v[6:9], v[170:173], v[214:217], v[6:9]
	v_mfma_f32_16x16x32_bf16 v[2:5], v[178:181], v[214:217], v[2:5]
	s_setprio 0
	s_barrier
	s_add_i32 s41, s41, 2
	s_add_u32 s12, s12, 0x100
	s_addc_u32 s13, s13, 0
	s_cmp_gt_u32 s41, 29
	s_cbranch_scc0 .LBB0_579
	s_cmpk_lt_u32 s21, 0x100
	s_cbranch_scc0 .LBB0_582
	s_barrier

; #define PG8_STAGE(bufoff, gbase, voff) do { _Pragma("unroll") for (int _i = 0; _i < 2; ++_i) \
;         __builtin_amdgcn_global_load_lds((const unsigned*)((const char*)(gbase) + (voff)[_i]), (LAS unsigned*)(lds + (bufoff) + ldsw + _i * 8192), 16, 0, 0); } while (0)
; #define PG8_LDA(dst, b, h) do { _Pragma("unroll") for (int m = 0; m < 4; ++m) _Pragma("unroll") for (int k = 0; k < 2; ++k) dst[m][k] = *(const LAS bf16x8*)(lds + PG8_SA(b, h) + aoff + m * 2048 + k * 1024); } while (0)
; #define PG8_LDB(dst, b, h) do { _Pragma("unroll") for (int n = 0; n < 2; ++n) _Pragma("unroll") for (int k = 0; k < 2; ++k) dst[n][k] = *(const LAS bf16x8*)(lds + PG8_SB(b, h) + boff + n * 2048 + k * 1024); } while (0)
; #define PG8_MMA(ai, bj, At, Bt) do { __builtin_amdgcn_s_setprio(1); _Pragma("unroll") for (int m = 0; m < 4; ++m) _Pragma("unroll") for (int n = 0; n < 2; ++n) _Pragma("unroll") for (int k = 0; k < 2; ++k) \
;         acc[ai][bj][m][n] = __builtin_amdgcn_mfma_f32_16x16x32_bf16(Bt[n][k], At[m][k], acc[ai][bj][m][n], 0, 0, 0); __builtin_amdgcn_s_setprio(0); } while (0)
; #define PG8_WAIT_V(n) asm volatile("s_waitcnt vmcnt(" #n ")" ::: "memory")
; #define PG8_WAIT_L(n) asm volatile("s_waitcnt lgkmcnt(" #n ")" ::: "memory")
; #define PG8_BAR __builtin_amdgcn_s_barrier()
; template <class Epi, class Sched>
; DI void gemm_phase(LAS unsigned char* lds, const Gemm g, const Sched& S, const Epi& E) {
;     ...
;         const char* nA = has_next ? (const char*)(nxt.src ? g.A1 : g.A0) + (size_t)nxt.pm * tstepA : cA; const char* nB = has_next ? (const char*)(nxt.src ? g.B1 : g.B0) + (size_t)nxt.pn * tstepB : cB;
;         for (int t = 0; t < nt; t += 2) {
;             const bool last = (t == nt - 2);
;             const char* a1 = cA + (size_t)(t + 1) * kstep;
;             const char* a2 = last ? nA : cA + (size_t)(t + 2) * kstep; const char* b2 = last ? nB : cB + (size_t)(t + 2) * kstep;
;             const char* a3 = a2 + kstep; const char* b3 = b2 + kstep;
;             PG8_LDB(B0, 0, 0); PG8_LDB(B1, 0, 1); PG8_SCHED; PG8_LDA(At, 0, 0); PG8_STAGE(PG8_SA(1, 1), a1 + hstepA, voffA);
;             PG8_WAIT_V(8); PG8_WAIT_L(0); PG8_BAR; PG8_MMA(0, 0, At, B0); PG8_MMA(0, 1, At, B1); PG8_BAR; PG8_SCHED;
;             PG8_LDA(At, 0, 1); PG8_STAGE(PG8_SB(0, 0), b2, voffB); PG8_STAGE(PG8_SB(0, 1), b2 + hstepB, voffB); PG8_STAGE(PG8_SA(0, 0), a2, voffA);
.LBB0_971:
	s_ashr_i32 s39, s38, 31
	s_and_b32 s67, s66, 1
	s_lshl_b64 s[40:41], s[38:39], 18
	s_cmp_eq_u32 s67, 0
	s_cselect_b32 s39, s28, s57
	s_cselect_b32 s37, s29, s58
	s_cselect_b32 s48, s50, s59
	s_cselect_b32 s49, s51, s60
	s_add_u32 s40, s39, s40
	s_addc_u32 s41, s37, s41
	s_and_b64 s[42:43], s[4:5], exec
	s_cselect_b32 s39, s41, s45
	s_cselect_b32 s68, s40, s44
	s_ashr_i32 s37, s36, 31
	s_lshl_b64 s[42:43], s[36:37], 18
	s_add_u32 s42, s48, s42
	s_addc_u32 s43, s49, s43
	s_and_b64 s[48:49], s[4:5], exec
	s_cselect_b32 s37, s43, s47
	s_cselect_b32 s69, s42, s46
	s_add_u32 s44, s44, 0x20080
	s_addc_u32 s45, s45, 0
	s_add_u32 s70, s46, 0x100
	s_addc_u32 s71, s47, 0
	s_mov_b32 s72, -2
	v_add_u32_e32 v158, s64, v162
	v_add_u32_e32 v180, s65, v162
	ds_read_b128 v[146:149], v158
	ds_read_b128 v[150:153], v158 offset:1024
	ds_read_b128 v[154:157], v158 offset:2048
	ds_read_b128 v[158:161], v158 offset:3072
	ds_read_b128 v[168:171], v180
	ds_read_b128 v[172:175], v180 offset:1024
	ds_read_b128 v[176:179], v180 offset:2048
	ds_read_b128 v[180:183], v180 offset:3072
	s_add_u32 s46, s44, 0xfffe0080
	s_addc_u32 s47, s45, -1
	s_cmp_eq_u32 s72, 4
	s_cselect_b32 s49, s39, s47
	s_cselect_b32 s48, s68, s46
	s_cselect_b32 s47, s37, s71
	s_cselect_b32 s46, s69, s70
	s_add_i32 m0, s53, 0xc000
	ds_read_b128 v[186:189], v167
	ds_read_b128 v[190:193], v167 offset:1024
	ds_read_b128 v[194:197], v167 offset:2048
	ds_read_b128 v[198:201], v167 offset:3072
	ds_read_b128 v[202:205], v167 offset:4096
	ds_read_b128 v[206:209], v167 offset:5120
	ds_read_b128 v[210:213], v167 offset:6144
	ds_read_b128 v[214:217], v167 offset:7168
	global_load_lds_dwordx4 v138, s[44:45]
	s_add_i32 m0, s53, 0xe000
	s_nop 0
	global_load_lds_dwordx4 v140, s[44:45]
	s_cmp_lg_u32 s99, 0
	s_cbranch_scc1 .Lpk3_w1
	s_waitcnt vmcnt(8)
.Lpk3_w1:
	s_waitcnt lgkmcnt(0)
	s_barrier
	s_setprio 1
	v_mfma_f32_16x16x32_bf16 v[126:129], v[146:149], v[186:189], v[126:129]
	v_mfma_f32_16x16x32_bf16 v[122:125], v[154:157], v[186:189], v[122:125]
	v_mfma_f32_16x16x32_bf16 v[118:121], v[146:149], v[194:197], v[118:121]
	v_mfma_f32_16x16x32_bf16 v[114:117], v[154:157], v[194:197], v[114:117]
	v_mfma_f32_16x16x32_bf16 v[110:113], v[146:149], v[202:205], v[110:113]
	v_mfma_f32_16x16x32_bf16 v[106:109], v[154:157], v[202:205], v[106:109]
	v_mfma_f32_16x16x32_bf16 v[102:105], v[146:149], v[210:213], v[102:105]
	v_mfma_f32_16x16x32_bf16 v[98:101], v[154:157], v[210:213], v[98:101]
	v_mfma_f32_16x16x32_bf16 v[126:129], v[150:153], v[190:193], v[126:129]
	v_mfma_f32_16x16x32_bf16 v[122:125], v[158:161], v[190:193], v[122:125]
	v_mfma_f32_16x16x32_bf16 v[118:121], v[150:153], v[198:201], v[118:121]
	v_mfma_f32_16x16x32_bf16 v[114:117], v[158:161], v[198:201], v[114:117]
	v_mfma_f32_16x16x32_bf16 v[110:113], v[150:153], v[206:209], v[110:113]
	v_mfma_f32_16x16x32_bf16 v[106:109], v[158:161], v[206:209], v[106:109]
	v_mfma_f32_16x16x32_bf16 v[102:105], v[150:153], v[214:217], v[102:105]
	v_mfma_f32_16x16x32_bf16 v[98:101], v[158:161], v[214:217], v[98:101]
	v_mfma_f32_16x16x32_bf16 v[94:97], v[168:171], v[186:189], v[94:97]
	v_mfma_f32_16x16x32_bf16 v[90:93], v[176:179], v[186:189], v[90:93]
	v_mfma_f32_16x16x32_bf16 v[86:89], v[168:171], v[194:197], v[86:89]
	v_mfma_f32_16x16x32_bf16 v[82:85], v[176:179], v[194:197], v[82:85]
	v_mfma_f32_16x16x32_bf16 v[78:81], v[168:171], v[202:205], v[78:81]
	v_mfma_f32_16x16x32_bf16 v[74:77], v[176:179], v[202:205], v[74:77]
	v_mfma_f32_16x16x32_bf16 v[70:73], v[168:171], v[210:213], v[70:73]
	v_mfma_f32_16x16x32_bf16 v[66:69], v[176:179], v[210:213], v[66:69]
	v_mfma_f32_16x16x32_bf16 v[94:97], v[172:175], v[190:193], v[94:97]
	v_mfma_f32_16x16x32_bf16 v[90:93], v[180:183], v[190:193], v[90:93]
	v_mfma_f32_16x16x32_bf16 v[86:89], v[172:175], v[198:201], v[86:89]
	v_mfma_f32_16x16x32_bf16 v[82:85], v[180:183], v[198:201], v[82:85]
	v_mfma_f32_16x16x32_bf16 v[78:81], v[172:175], v[206:209], v[78:81]
	v_mfma_f32_16x16x32_bf16 v[74:77], v[180:183], v[206:209], v[74:77]
	v_mfma_f32_16x16x32_bf16 v[70:73], v[172:175], v[214:217], v[70:73]
	v_mfma_f32_16x16x32_bf16 v[66:69], v[180:183], v[214:217], v[66:69]
	s_setprio 0
	s_barrier
	s_add_i32 s73, s64, s52
	v_lshl_add_u64 v[218:219], s[46:47], 0, v[132:133]
	s_mov_b32 m0, s73
	ds_read_b128 v[186:189], v167 offset:16384
	ds_read_b128 v[190:193], v167 offset:17408
	ds_read_b128 v[194:197], v167 offset:18432
	ds_read_b128 v[198:201], v167 offset:19456
	ds_read_b128 v[202:205], v167 offset:20480
	ds_read_b128 v[206:209], v167 offset:21504
	ds_read_b128 v[210:213], v167 offset:22528
	ds_read_b128 v[214:217], v167 offset:23552
	global_load_lds_dwordx4 v[218:219], off
	s_add_i32 m0, s73, 0x2000
	s_add_u32 s74, s46, 0x20000
	v_lshl_add_u64 v[220:221], s[46:47], 0, v[136:137]
	s_addc_u32 s75, s47, 0
	s_add_i32 s73, s65, s52
	global_load_lds_dwordx4 v[220:221], off
	s_mov_b32 m0, s73
	v_lshl_add_u64 v[224:225], s[48:49], 0, v[134:135]
	global_load_lds_dwordx4 v132, s[74:75]
	s_add_i32 m0, s73, 0x2000
	s_nop 0
	global_load_lds_dwordx4 v136, s[74:75]
	v_lshl_add_u64 v[222:223], s[48:49], 0, v[130:131]
	s_mov_b32 m0, s53
	s_nop 0
	global_load_lds_dwordx4 v[222:223], off
	s_mov_b32 m0, s54
	s_nop 0
	global_load_lds_dwordx4 v[224:225], off
	s_cmp_lg_u32 s99, 0
	s_cbranch_scc1 .Lpk3_w2
	s_waitcnt vmcnt(8)
; #define PG8_STAGE(bufoff, gbase, voff) do { _Pragma("unroll") for (int _i = 0; _i < 2; ++_i) \
;         __builtin_amdgcn_global_load_lds((const unsigned*)((const char*)(gbase) + (voff)[_i]), (LAS unsigned*)(lds + (bufoff) + ldsw + _i * 8192), 16, 0, 0); } while (0)
; #define PG8_LDA(dst, b, h) do { _Pragma("unroll") for (int m = 0; m < 4; ++m) _Pragma("unroll") for (int k = 0; k < 2; ++k) dst[m][k] = *(const LAS bf16x8*)(lds + PG8_SA(b, h) + aoff + m * 2048 + k * 1024); } while (0)
; #define PG8_LDB(dst, b, h) do { _Pragma("unroll") for (int n = 0; n < 2; ++n) _Pragma("unroll") for (int k = 0; k < 2; ++k) dst[n][k] = *(const LAS bf16x8*)(lds + PG8_SB(b, h) + boff + n * 2048 + k * 1024); } while (0)
; #define PG8_MMA(ai, bj, At, Bt) do { __builtin_amdgcn_s_setprio(1); _Pragma("unroll") for (int m = 0; m < 4; ++m) _Pragma("unroll") for (int n = 0; n < 2; ++n) _Pragma("unroll") for (int k = 0; k < 2; ++k) \
;         acc[ai][bj][m][n] = __builtin_amdgcn_mfma_f32_16x16x32_bf16(Bt[n][k], At[m][k], acc[ai][bj][m][n], 0, 0, 0); __builtin_amdgcn_s_setprio(0); } while (0)
; #define PG8_WAIT_V(n) asm volatile("s_waitcnt vmcnt(" #n ")" ::: "memory")
; #define PG8_WAIT_L(n) asm volatile("s_waitcnt lgkmcnt(" #n ")" ::: "memory")
; #define PG8_BAR __builtin_amdgcn_s_barrier()
; #define PG8_SCHED __builtin_amdgcn_sched_barrier(0)
; template <class Epi, class Sched>
; DI void gemm_phase(LAS unsigned char* lds, const Gemm g, const Sched& S, const Epi& E) {
;     ...
;             PG8_WAIT_V(8); PG8_WAIT_L(0); PG8_BAR; PG8_MMA(1, 0, At, B0); PG8_MMA(1, 1, At, B1); PG8_BAR; PG8_SCHED;
;             PG8_LDB(B0, 1, 0); PG8_LDB(B1, 1, 1); PG8_SCHED; PG8_LDA(At, 1, 0); PG8_STAGE(PG8_SA(0, 1), a2 + hstepA, voffA);
;             PG8_WAIT_V(8); PG8_WAIT_L(0); PG8_BAR; PG8_MMA(0, 0, At, B0); PG8_MMA(0, 1, At, B1); PG8_BAR; PG8_SCHED;
.Lpk3_w2:
	s_mov_b32 s99, 0
	s_waitcnt lgkmcnt(0)
	s_barrier
	s_setprio 1
	v_mfma_f32_16x16x32_bf16 v[62:65], v[146:149], v[186:189], v[62:65]
	v_mfma_f32_16x16x32_bf16 v[58:61], v[154:157], v[186:189], v[58:61]
	v_mfma_f32_16x16x32_bf16 v[54:57], v[146:149], v[194:197], v[54:57]
	v_mfma_f32_16x16x32_bf16 v[50:53], v[154:157], v[194:197], v[50:53]
	v_mfma_f32_16x16x32_bf16 v[46:49], v[146:149], v[202:205], v[46:49]
	v_mfma_f32_16x16x32_bf16 v[42:45], v[154:157], v[202:205], v[42:45]
	v_mfma_f32_16x16x32_bf16 v[38:41], v[146:149], v[210:213], v[38:41]
	v_mfma_f32_16x16x32_bf16 v[34:37], v[154:157], v[210:213], v[34:37]
	v_mfma_f32_16x16x32_bf16 v[62:65], v[150:153], v[190:193], v[62:65]
	v_mfma_f32_16x16x32_bf16 v[58:61], v[158:161], v[190:193], v[58:61]
	v_mfma_f32_16x16x32_bf16 v[54:57], v[150:153], v[198:201], v[54:57]
	v_mfma_f32_16x16x32_bf16 v[50:53], v[158:161], v[198:201], v[50:53]
	v_mfma_f32_16x16x32_bf16 v[46:49], v[150:153], v[206:209], v[46:49]
	v_mfma_f32_16x16x32_bf16 v[42:45], v[158:161], v[206:209], v[42:45]
	v_mfma_f32_16x16x32_bf16 v[38:41], v[150:153], v[214:217], v[38:41]
	v_mfma_f32_16x16x32_bf16 v[34:37], v[158:161], v[214:217], v[34:37]
	v_mfma_f32_16x16x32_bf16 v[30:33], v[168:171], v[186:189], v[30:33]
	v_mfma_f32_16x16x32_bf16 v[26:29], v[176:179], v[186:189], v[26:29]
	v_mfma_f32_16x16x32_bf16 v[22:25], v[168:171], v[194:197], v[22:25]
	v_mfma_f32_16x16x32_bf16 v[18:21], v[176:179], v[194:197], v[18:21]
	v_mfma_f32_16x16x32_bf16 v[14:17], v[168:171], v[202:205], v[14:17]
	v_mfma_f32_16x16x32_bf16 v[10:13], v[176:179], v[202:205], v[10:13]
	v_mfma_f32_16x16x32_bf16 v[6:9], v[168:171], v[210:213], v[6:9]
	v_mfma_f32_16x16x32_bf16 v[2:5], v[176:179], v[210:213], v[2:5]
	v_mfma_f32_16x16x32_bf16 v[30:33], v[172:175], v[190:193], v[30:33]
	v_mfma_f32_16x16x32_bf16 v[26:29], v[180:183], v[190:193], v[26:29]
	v_mfma_f32_16x16x32_bf16 v[22:25], v[172:175], v[198:201], v[22:25]
	v_mfma_f32_16x16x32_bf16 v[18:21], v[180:183], v[198:201], v[18:21]
	v_mfma_f32_16x16x32_bf16 v[14:17], v[172:175], v[206:209], v[14:17]
	v_mfma_f32_16x16x32_bf16 v[10:13], v[180:183], v[206:209], v[10:13]
	v_mfma_f32_16x16x32_bf16 v[6:9], v[172:175], v[214:217], v[6:9]
	v_mfma_f32_16x16x32_bf16 v[2:5], v[180:183], v[214:217], v[2:5]
	s_setprio 0
	s_barrier
	s_add_i32 s73, 0, 0x18000
	s_add_i32 s74, 0, 0x1c000
	v_add_u32_e32 v158, s73, v162
	v_add_u32_e32 v180, s74, v162
	ds_read_b128 v[146:149], v158
	ds_read_b128 v[150:153], v158 offset:1024
	ds_read_b128 v[154:157], v158 offset:2048
	ds_read_b128 v[158:161], v158 offset:3072
	ds_read_b128 v[168:171], v180
	ds_read_b128 v[172:175], v180 offset:1024
	ds_read_b128 v[176:179], v180 offset:2048
	ds_read_b128 v[180:183], v180 offset:3072
	s_add_u32 s48, s48, 0x20000
	s_addc_u32 s49, s49, 0
	s_mov_b32 m0, s55
	ds_read_b128 v[186:189], v167 offset:32768
	ds_read_b128 v[190:193], v167 offset:33792
	ds_read_b128 v[194:197], v167 offset:34816
	ds_read_b128 v[198:201], v167 offset:35840
	ds_read_b128 v[202:205], v167 offset:36864
	ds_read_b128 v[206:209], v167 offset:37888
	ds_read_b128 v[210:213], v167 offset:38912
	ds_read_b128 v[214:217], v167 offset:39936
	global_load_lds_dwordx4 v130, s[48:49]
	s_mov_b32 m0, s56
	s_nop 0
	global_load_lds_dwordx4 v134, s[48:49]
	s_waitcnt vmcnt(8)
	s_waitcnt lgkmcnt(0)
	s_barrier
	s_setprio 1
	v_mfma_f32_16x16x32_bf16 v[126:129], v[146:149], v[186:189], v[126:129]
	v_mfma_f32_16x16x32_bf16 v[122:125], v[154:157], v[186:189], v[122:125]
	v_mfma_f32_16x16x32_bf16 v[118:121], v[146:149], v[194:197], v[118:121]
	v_mfma_f32_16x16x32_bf16 v[114:117], v[154:157], v[194:197], v[114:117]
	v_mfma_f32_16x16x32_bf16 v[110:113], v[146:149], v[202:205], v[110:113]
	v_mfma_f32_16x16x32_bf16 v[106:109], v[154:157], v[202:205], v[106:109]
	v_mfma_f32_16x16x32_bf16 v[102:105], v[146:149], v[210:213], v[102:105]
	v_mfma_f32_16x16x32_bf16 v[98:101], v[154:157], v[210:213], v[98:101]
	v_mfma_f32_16x16x32_bf16 v[126:129], v[150:153], v[190:193], v[126:129]
	v_mfma_f32_16x16x32_bf16 v[122:125], v[158:161], v[190:193], v[122:125]
	v_mfma_f32_16x16x32_bf16 v[118:121], v[150:153], v[198:201], v[118:121]
	v_mfma_f32_16x16x32_bf16 v[114:117], v[158:161], v[198:201], v[114:117]
	v_mfma_f32_16x16x32_bf16 v[110:113], v[150:153], v[206:209], v[110:113]
	v_mfma_f32_16x16x32_bf16 v[106:109], v[158:161], v[206:209], v[106:109]
	v_mfma_f32_16x16x32_bf16 v[102:105], v[150:153], v[214:217], v[102:105]
	v_mfma_f32_16x16x32_bf16 v[98:101], v[158:161], v[214:217], v[98:101]
	v_mfma_f32_16x16x32_bf16 v[94:97], v[168:171], v[186:189], v[94:97]
	v_mfma_f32_16x16x32_bf16 v[90:93], v[176:179], v[186:189], v[90:93]
	v_mfma_f32_16x16x32_bf16 v[86:89], v[168:171], v[194:197], v[86:89]
	v_mfma_f32_16x16x32_bf16 v[82:85], v[176:179], v[194:197], v[82:85]
	v_mfma_f32_16x16x32_bf16 v[78:81], v[168:171], v[202:205], v[78:81]
	v_mfma_f32_16x16x32_bf16 v[74:77], v[176:179], v[202:205], v[74:77]
	v_mfma_f32_16x16x32_bf16 v[70:73], v[168:171], v[210:213], v[70:73]
	v_mfma_f32_16x16x32_bf16 v[66:69], v[176:179], v[210:213], v[66:69]
	v_mfma_f32_16x16x32_bf16 v[94:97], v[172:175], v[190:193], v[94:97]
	v_mfma_f32_16x16x32_bf16 v[90:93], v[180:183], v[190:193], v[90:93]
	v_mfma_f32_16x16x32_bf16 v[86:89], v[172:175], v[198:201], v[86:89]
	v_mfma_f32_16x16x32_bf16 v[82:85], v[180:183], v[198:201], v[82:85]
	v_mfma_f32_16x16x32_bf16 v[78:81], v[172:175], v[206:209], v[78:81]
	v_mfma_f32_16x16x32_bf16 v[74:77], v[180:183], v[206:209], v[74:77]
	v_mfma_f32_16x16x32_bf16 v[70:73], v[172:175], v[214:217], v[70:73]
	v_mfma_f32_16x16x32_bf16 v[66:69], v[180:183], v[214:217], v[66:69]
	s_setprio 0
	s_barrier
; #define PG8_STAGE(bufoff, gbase, voff) do { _Pragma("unroll") for (int _i = 0; _i < 2; ++_i) \
;         __builtin_amdgcn_global_load_lds((const unsigned*)((const char*)(gbase) + (voff)[_i]), (LAS unsigned*)(lds + (bufoff) + ldsw + _i * 8192), 16, 0, 0); } while (0)
; #define PG8_LDA(dst, b, h) do { _Pragma("unroll") for (int m = 0; m < 4; ++m) _Pragma("unroll") for (int k = 0; k < 2; ++k) dst[m][k] = *(const LAS bf16x8*)(lds + PG8_SA(b, h) + aoff + m * 2048 + k * 1024); } while (0)
; #define PG8_LDB(dst, b, h) do { _Pragma("unroll") for (int n = 0; n < 2; ++n) _Pragma("unroll") for (int k = 0; k < 2; ++k) dst[n][k] = *(const LAS bf16x8*)(lds + PG8_SB(b, h) + boff + n * 2048 + k * 1024); } while (0)
; #define PG8_MMA(ai, bj, At, Bt) do { __builtin_amdgcn_s_setprio(1); _Pragma("unroll") for (int m = 0; m < 4; ++m) _Pragma("unroll") for (int n = 0; n < 2; ++n) _Pragma("unroll") for (int k = 0; k < 2; ++k) \
;         acc[ai][bj][m][n] = __builtin_amdgcn_mfma_f32_16x16x32_bf16(Bt[n][k], At[m][k], acc[ai][bj][m][n], 0, 0, 0); __builtin_amdgcn_s_setprio(0); } while (0)
; #define PG8_WAIT_V(n) asm volatile("s_waitcnt vmcnt(" #n ")" ::: "memory")
; #define PG8_WAIT_L(n) asm volatile("s_waitcnt lgkmcnt(" #n ")" ::: "memory")
; template <class Epi, class Sched>
; DI void gemm_phase(LAS unsigned char* lds, const Gemm g, const Sched& S, const Epi& E) {
;     ...
;             PG8_LDB(B0, 0, 0); PG8_LDB(B1, 0, 1); PG8_SCHED; PG8_LDA(At, 0, 0); PG8_STAGE(PG8_SA(1, 1), a1 + hstepA, voffA);
;             PG8_WAIT_V(8); PG8_WAIT_L(0); PG8_BAR; PG8_MMA(0, 0, At, B0); PG8_MMA(0, 1, At, B1); PG8_BAR; PG8_SCHED;
;             PG8_LDA(At, 0, 1); PG8_STAGE(PG8_SB(0, 0), b2, voffB); PG8_STAGE(PG8_SB(0, 1), b2 + hstepB, voffB); PG8_STAGE(PG8_SA(0, 0), a2, voffA);
;             PG8_WAIT_V(8); PG8_WAIT_L(0); PG8_BAR; PG8_MMA(1, 0, At, B0); PG8_MMA(1, 1, At, B1); PG8_BAR; PG8_SCHED;
;             PG8_LDB(B0, 1, 0); PG8_LDB(B1, 1, 1); PG8_SCHED; PG8_LDA(At, 1, 0); PG8_STAGE(PG8_SA(0, 1), a2 + hstepA, voffA);
;             PG8_WAIT_V(8); PG8_WAIT_L(0); PG8_BAR; PG8_MMA(0, 0, At, B0); PG8_MMA(0, 1, At, B1); PG8_BAR; PG8_SCHED;
;             PG8_LDA(At, 1, 1); PG8_STAGE(PG8_SB(1, 0), b3, voffB); PG8_STAGE(PG8_SB(1, 1), b3 + hstepB, voffB); PG8_STAGE(PG8_SA(1, 0), a3, voffA);
;             PG8_WAIT_V(8); PG8_WAIT_L(0); PG8_BAR; PG8_MMA(1, 0, At, B0); PG8_MMA(1, 1, At, B1); PG8_BAR; PG8_SCHED;
	s_add_i32 s48, s73, s52
	v_lshl_add_u64 v[218:219], v[218:219], 0, s[20:21]
	s_mov_b32 m0, s48
	ds_read_b128 v[186:189], v167 offset:49152
	ds_read_b128 v[190:193], v167 offset:50176
	ds_read_b128 v[194:197], v167 offset:51200
	ds_read_b128 v[198:201], v167 offset:52224
	ds_read_b128 v[202:205], v167 offset:53248
	ds_read_b128 v[206:209], v167 offset:54272
	ds_read_b128 v[210:213], v167 offset:55296
	ds_read_b128 v[214:217], v167 offset:56320
	global_load_lds_dwordx4 v[218:219], off
	s_add_i32 m0, s48, 0x2000
	s_add_u32 s46, s46, 0x20080
	v_lshl_add_u64 v[218:219], v[220:221], 0, s[20:21]
	s_addc_u32 s47, s47, 0
	s_add_i32 s48, s74, s52
	global_load_lds_dwordx4 v[218:219], off
	s_mov_b32 m0, s48
	s_nop 0
	global_load_lds_dwordx4 v132, s[46:47]
	s_add_i32 m0, s48, 0x2000
	s_nop 0
	global_load_lds_dwordx4 v136, s[46:47]
	v_lshl_add_u64 v[218:219], v[222:223], 0, s[20:21]
	s_mov_b32 m0, s61
	s_nop 0
	global_load_lds_dwordx4 v[218:219], off
	v_lshl_add_u64 v[218:219], v[224:225], 0, s[20:21]
	s_mov_b32 m0, s62
	s_nop 0
	global_load_lds_dwordx4 v[218:219], off
	s_waitcnt vmcnt(8)
	s_waitcnt lgkmcnt(0)
	s_barrier
	s_setprio 1
	v_mfma_f32_16x16x32_bf16 v[62:65], v[146:149], v[186:189], v[62:65]
	v_mfma_f32_16x16x32_bf16 v[58:61], v[154:157], v[186:189], v[58:61]
	v_mfma_f32_16x16x32_bf16 v[54:57], v[146:149], v[194:197], v[54:57]
	v_mfma_f32_16x16x32_bf16 v[50:53], v[154:157], v[194:197], v[50:53]
	v_mfma_f32_16x16x32_bf16 v[46:49], v[146:149], v[202:205], v[46:49]
	v_mfma_f32_16x16x32_bf16 v[42:45], v[154:157], v[202:205], v[42:45]
	v_mfma_f32_16x16x32_bf16 v[38:41], v[146:149], v[210:213], v[38:41]
	v_mfma_f32_16x16x32_bf16 v[34:37], v[154:157], v[210:213], v[34:37]
	v_mfma_f32_16x16x32_bf16 v[62:65], v[150:153], v[190:193], v[62:65]
	v_mfma_f32_16x16x32_bf16 v[58:61], v[158:161], v[190:193], v[58:61]
	v_mfma_f32_16x16x32_bf16 v[54:57], v[150:153], v[198:201], v[54:57]
	v_mfma_f32_16x16x32_bf16 v[50:53], v[158:161], v[198:201], v[50:53]
	v_mfma_f32_16x16x32_bf16 v[46:49], v[150:153], v[206:209], v[46:49]
	v_mfma_f32_16x16x32_bf16 v[42:45], v[158:161], v[206:209], v[42:45]
	v_mfma_f32_16x16x32_bf16 v[38:41], v[150:153], v[214:217], v[38:41]
	v_mfma_f32_16x16x32_bf16 v[34:37], v[158:161], v[214:217], v[34:37]
	v_mfma_f32_16x16x32_bf16 v[30:33], v[168:171], v[186:189], v[30:33]
	v_mfma_f32_16x16x32_bf16 v[26:29], v[176:179], v[186:189], v[26:29]
	v_mfma_f32_16x16x32_bf16 v[22:25], v[168:171], v[194:197], v[22:25]
	v_mfma_f32_16x16x32_bf16 v[18:21], v[176:179], v[194:197], v[18:21]
	v_mfma_f32_16x16x32_bf16 v[14:17], v[168:171], v[202:205], v[14:17]
	v_mfma_f32_16x16x32_bf16 v[10:13], v[176:179], v[202:205], v[10:13]
	v_mfma_f32_16x16x32_bf16 v[6:9], v[168:171], v[210:213], v[6:9]
	v_mfma_f32_16x16x32_bf16 v[2:5], v[176:179], v[210:213], v[2:5]
	v_mfma_f32_16x16x32_bf16 v[30:33], v[172:175], v[190:193], v[30:33]
	v_mfma_f32_16x16x32_bf16 v[26:29], v[180:183], v[190:193], v[26:29]
	v_mfma_f32_16x16x32_bf16 v[22:25], v[172:175], v[198:201], v[22:25]
	v_mfma_f32_16x16x32_bf16 v[18:21], v[180:183], v[198:201], v[18:21]
	v_mfma_f32_16x16x32_bf16 v[14:17], v[172:175], v[206:209], v[14:17]
	v_mfma_f32_16x16x32_bf16 v[10:13], v[180:183], v[206:209], v[10:13]
	v_mfma_f32_16x16x32_bf16 v[6:9], v[172:175], v[214:217], v[6:9]
	v_mfma_f32_16x16x32_bf16 v[2:5], v[180:183], v[214:217], v[2:5]
	s_setprio 0
	s_barrier
	s_add_i32 s72, s72, 2
	s_add_u32 s44, s44, 0x100
	s_addc_u32 s45, s45, 0
	s_add_u32 s70, s70, 0x100
	s_addc_u32 s71, s71, 0
	s_cmp_gt_u32 s72, 5
.LBB0_972:
	v_add_u32_e32 v158, s64, v162
	v_add_u32_e32 v180, s65, v162
	ds_read_b128 v[146:149], v158
	ds_read_b128 v[150:153], v158 offset:1024
	ds_read_b128 v[154:157], v158 offset:2048
	ds_read_b128 v[158:161], v158 offset:3072
	ds_read_b128 v[168:171], v180
	ds_read_b128 v[172:175], v180 offset:1024
	ds_read_b128 v[176:179], v180 offset:2048
	ds_read_b128 v[180:183], v180 offset:3072
	s_add_u32 s46, s44, 0xfffe0080
	s_addc_u32 s47, s45, -1
	s_cmp_eq_u32 s72, 4
	s_cselect_b32 s49, s39, s47
	s_cselect_b32 s48, s68, s46
	s_cselect_b32 s47, s37, s71
	s_cselect_b32 s46, s69, s70
	s_add_i32 m0, s53, 0xc000
	ds_read_b128 v[186:189], v167
	ds_read_b128 v[190:193], v167 offset:1024
	ds_read_b128 v[194:197], v167 offset:2048
	ds_read_b128 v[198:201], v167 offset:3072
	ds_read_b128 v[202:205], v167 offset:4096
	ds_read_b128 v[206:209], v167 offset:5120
	ds_read_b128 v[210:213], v167 offset:6144
	ds_read_b128 v[214:217], v167 offset:7168
	global_load_lds_dwordx4 v138, s[44:45]
	s_add_i32 m0, s53, 0xe000
	s_nop 0
	global_load_lds_dwordx4 v140, s[44:45]
	s_waitcnt vmcnt(8)
	s_waitcnt lgkmcnt(0)
	s_barrier
; #define PG8_STAGE(bufoff, gbase, voff) do { _Pragma("unroll") for (int _i = 0; _i < 2; ++_i) \
;         __builtin_amdgcn_global_load_lds((const unsigned*)((const char*)(gbase) + (voff)[_i]), (LAS unsigned*)(lds + (bufoff) + ldsw + _i * 8192), 16, 0, 0); } while (0)
; #define PG8_LDA(dst, b, h) do { _Pragma("unroll") for (int m = 0; m < 4; ++m) _Pragma("unroll") for (int k = 0; k < 2; ++k) dst[m][k] = *(const LAS bf16x8*)(lds + PG8_SA(b, h) + aoff + m * 2048 + k * 1024); } while (0)
; #define PG8_MMA(ai, bj, At, Bt) do { __builtin_amdgcn_s_setprio(1); _Pragma("unroll") for (int m = 0; m < 4; ++m) _Pragma("unroll") for (int n = 0; n < 2; ++n) _Pragma("unroll") for (int k = 0; k < 2; ++k) \
;         acc[ai][bj][m][n] = __builtin_amdgcn_mfma_f32_16x16x32_bf16(Bt[n][k], At[m][k], acc[ai][bj][m][n], 0, 0, 0); __builtin_amdgcn_s_setprio(0); } while (0)
; #define PG8_WAIT_V(n) asm volatile("s_waitcnt vmcnt(" #n ")" ::: "memory")
; #define PG8_WAIT_L(n) asm volatile("s_waitcnt lgkmcnt(" #n ")" ::: "memory")
; #define PG8_BAR __builtin_amdgcn_s_barrier()
; #define PG8_SCHED __builtin_amdgcn_sched_barrier(0)
; template <class Epi, class Sched>
; DI void gemm_phase(LAS unsigned char* lds, const Gemm g, const Sched& S, const Epi& E) {
;     ...
;             PG8_WAIT_V(8); PG8_WAIT_L(0); PG8_BAR; PG8_MMA(0, 0, At, B0); PG8_MMA(0, 1, At, B1); PG8_BAR; PG8_SCHED;
;             PG8_LDA(At, 0, 1); PG8_STAGE(PG8_SB(0, 0), b2, voffB); PG8_STAGE(PG8_SB(0, 1), b2 + hstepB, voffB); PG8_STAGE(PG8_SA(0, 0), a2, voffA);
;             PG8_WAIT_V(8); PG8_WAIT_L(0); PG8_BAR; PG8_MMA(1, 0, At, B0); PG8_MMA(1, 1, At, B1); PG8_BAR; PG8_SCHED;
	s_setprio 1
	v_mfma_f32_16x16x32_bf16 v[126:129], v[146:149], v[186:189], v[126:129]
	v_mfma_f32_16x16x32_bf16 v[122:125], v[154:157], v[186:189], v[122:125]
	v_mfma_f32_16x16x32_bf16 v[118:121], v[146:149], v[194:197], v[118:121]
	v_mfma_f32_16x16x32_bf16 v[114:117], v[154:157], v[194:197], v[114:117]
	v_mfma_f32_16x16x32_bf16 v[110:113], v[146:149], v[202:205], v[110:113]
	v_mfma_f32_16x16x32_bf16 v[106:109], v[154:157], v[202:205], v[106:109]
	v_mfma_f32_16x16x32_bf16 v[102:105], v[146:149], v[210:213], v[102:105]
	v_mfma_f32_16x16x32_bf16 v[98:101], v[154:157], v[210:213], v[98:101]
	v_mfma_f32_16x16x32_bf16 v[126:129], v[150:153], v[190:193], v[126:129]
	v_mfma_f32_16x16x32_bf16 v[122:125], v[158:161], v[190:193], v[122:125]
	v_mfma_f32_16x16x32_bf16 v[118:121], v[150:153], v[198:201], v[118:121]
	v_mfma_f32_16x16x32_bf16 v[114:117], v[158:161], v[198:201], v[114:117]
	v_mfma_f32_16x16x32_bf16 v[110:113], v[150:153], v[206:209], v[110:113]
	v_mfma_f32_16x16x32_bf16 v[106:109], v[158:161], v[206:209], v[106:109]
	v_mfma_f32_16x16x32_bf16 v[102:105], v[150:153], v[214:217], v[102:105]
	v_mfma_f32_16x16x32_bf16 v[98:101], v[158:161], v[214:217], v[98:101]
	v_mfma_f32_16x16x32_bf16 v[94:97], v[168:171], v[186:189], v[94:97]
	v_mfma_f32_16x16x32_bf16 v[90:93], v[176:179], v[186:189], v[90:93]
	v_mfma_f32_16x16x32_bf16 v[86:89], v[168:171], v[194:197], v[86:89]
	v_mfma_f32_16x16x32_bf16 v[82:85], v[176:179], v[194:197], v[82:85]
	v_mfma_f32_16x16x32_bf16 v[78:81], v[168:171], v[202:205], v[78:81]
	v_mfma_f32_16x16x32_bf16 v[74:77], v[176:179], v[202:205], v[74:77]
	v_mfma_f32_16x16x32_bf16 v[70:73], v[168:171], v[210:213], v[70:73]
	v_mfma_f32_16x16x32_bf16 v[66:69], v[176:179], v[210:213], v[66:69]
	v_mfma_f32_16x16x32_bf16 v[94:97], v[172:175], v[190:193], v[94:97]
	v_mfma_f32_16x16x32_bf16 v[90:93], v[180:183], v[190:193], v[90:93]
	v_mfma_f32_16x16x32_bf16 v[86:89], v[172:175], v[198:201], v[86:89]
	v_mfma_f32_16x16x32_bf16 v[82:85], v[180:183], v[198:201], v[82:85]
	v_mfma_f32_16x16x32_bf16 v[78:81], v[172:175], v[206:209], v[78:81]
	v_mfma_f32_16x16x32_bf16 v[74:77], v[180:183], v[206:209], v[74:77]
	v_mfma_f32_16x16x32_bf16 v[70:73], v[172:175], v[214:217], v[70:73]
	v_mfma_f32_16x16x32_bf16 v[66:69], v[180:183], v[214:217], v[66:69]
	s_setprio 0
	s_barrier
	s_add_i32 s73, s64, s52
	v_lshl_add_u64 v[218:219], s[46:47], 0, v[132:133]
	s_mov_b32 m0, s73
	ds_read_b128 v[186:189], v167 offset:16384
	ds_read_b128 v[190:193], v167 offset:17408
	ds_read_b128 v[194:197], v167 offset:18432
	ds_read_b128 v[198:201], v167 offset:19456
	ds_read_b128 v[202:205], v167 offset:20480
	ds_read_b128 v[206:209], v167 offset:21504
	ds_read_b128 v[210:213], v167 offset:22528
	ds_read_b128 v[214:217], v167 offset:23552
	global_load_lds_dwordx4 v[218:219], off
	s_add_i32 m0, s73, 0x2000
	s_add_u32 s74, s46, 0x20000
	v_lshl_add_u64 v[220:221], s[46:47], 0, v[136:137]
	s_addc_u32 s75, s47, 0
	s_add_i32 s73, s65, s52
	global_load_lds_dwordx4 v[220:221], off
	s_mov_b32 m0, s73
	v_lshl_add_u64 v[224:225], s[48:49], 0, v[134:135]
	global_load_lds_dwordx4 v132, s[74:75]
	s_add_i32 m0, s73, 0x2000
	s_nop 0
	global_load_lds_dwordx4 v136, s[74:75]
	v_lshl_add_u64 v[222:223], s[48:49], 0, v[130:131]
	s_mov_b32 m0, s53
	s_nop 0
	global_load_lds_dwordx4 v[222:223], off
	s_mov_b32 m0, s54
	s_nop 0
	global_load_lds_dwordx4 v[224:225], off
	s_waitcnt vmcnt(8)
	s_waitcnt lgkmcnt(0)
	s_barrier
	s_setprio 1
	v_mfma_f32_16x16x32_bf16 v[62:65], v[146:149], v[186:189], v[62:65]
	v_mfma_f32_16x16x32_bf16 v[58:61], v[154:157], v[186:189], v[58:61]
	v_mfma_f32_16x16x32_bf16 v[54:57], v[146:149], v[194:197], v[54:57]
	v_mfma_f32_16x16x32_bf16 v[50:53], v[154:157], v[194:197], v[50:53]
	v_mfma_f32_16x16x32_bf16 v[46:49], v[146:149], v[202:205], v[46:49]
	v_mfma_f32_16x16x32_bf16 v[42:45], v[154:157], v[202:205], v[42:45]
	v_mfma_f32_16x16x32_bf16 v[38:41], v[146:149], v[210:213], v[38:41]
	v_mfma_f32_16x16x32_bf16 v[34:37], v[154:157], v[210:213], v[34:37]
	v_mfma_f32_16x16x32_bf16 v[62:65], v[150:153], v[190:193], v[62:65]
	v_mfma_f32_16x16x32_bf16 v[58:61], v[158:161], v[190:193], v[58:61]
	v_mfma_f32_16x16x32_bf16 v[54:57], v[150:153], v[198:201], v[54:57]
	v_mfma_f32_16x16x32_bf16 v[50:53], v[158:161], v[198:201], v[50:53]
	v_mfma_f32_16x16x32_bf16 v[46:49], v[150:153], v[206:209], v[46:49]
	v_mfma_f32_16x16x32_bf16 v[42:45], v[158:161], v[206:209], v[42:45]
	v_mfma_f32_16x16x32_bf16 v[38:41], v[150:153], v[214:217], v[38:41]
	v_mfma_f32_16x16x32_bf16 v[34:37], v[158:161], v[214:217], v[34:37]
	v_mfma_f32_16x16x32_bf16 v[30:33], v[168:171], v[186:189], v[30:33]
	v_mfma_f32_16x16x32_bf16 v[26:29], v[176:179], v[186:189], v[26:29]
	v_mfma_f32_16x16x32_bf16 v[22:25], v[168:171], v[194:197], v[22:25]
	v_mfma_f32_16x16x32_bf16 v[18:21], v[176:179], v[194:197], v[18:21]
	v_mfma_f32_16x16x32_bf16 v[14:17], v[168:171], v[202:205], v[14:17]
	v_mfma_f32_16x16x32_bf16 v[10:13], v[176:179], v[202:205], v[10:13]
	v_mfma_f32_16x16x32_bf16 v[6:9], v[168:171], v[210:213], v[6:9]
	v_mfma_f32_16x16x32_bf16 v[2:5], v[176:179], v[210:213], v[2:5]
	v_mfma_f32_16x16x32_bf16 v[30:33], v[172:175], v[190:193], v[30:33]
	v_mfma_f32_16x16x32_bf16 v[26:29], v[180:183], v[190:193], v[26:29]
	v_mfma_f32_16x16x32_bf16 v[22:25], v[172:175], v[198:201], v[22:25]
	v_mfma_f32_16x16x32_bf16 v[18:21], v[180:183], v[198:201], v[18:21]
	v_mfma_f32_16x16x32_bf16 v[14:17], v[172:175], v[206:209], v[14:17]
	v_mfma_f32_16x16x32_bf16 v[10:13], v[180:183], v[206:209], v[10:13]
	v_mfma_f32_16x16x32_bf16 v[6:9], v[172:175], v[214:217], v[6:9]
	v_mfma_f32_16x16x32_bf16 v[2:5], v[180:183], v[214:217], v[2:5]
	s_setprio 0
	s_barrier
; #define PG8_STAGE(bufoff, gbase, voff) do { _Pragma("unroll") for (int _i = 0; _i < 2; ++_i) \
;         __builtin_amdgcn_global_load_lds((const unsigned*)((const char*)(gbase) + (voff)[_i]), (LAS unsigned*)(lds + (bufoff) + ldsw + _i * 8192), 16, 0, 0); } while (0)
; #define PG8_LDA(dst, b, h) do { _Pragma("unroll") for (int m = 0; m < 4; ++m) _Pragma("unroll") for (int k = 0; k < 2; ++k) dst[m][k] = *(const LAS bf16x8*)(lds + PG8_SA(b, h) + aoff + m * 2048 + k * 1024); } while (0)
; #define PG8_LDB(dst, b, h) do { _Pragma("unroll") for (int n = 0; n < 2; ++n) _Pragma("unroll") for (int k = 0; k < 2; ++k) dst[n][k] = *(const LAS bf16x8*)(lds + PG8_SB(b, h) + boff + n * 2048 + k * 1024); } while (0)
; #define PG8_MMA(ai, bj, At, Bt) do { __builtin_amdgcn_s_setprio(1); _Pragma("unroll") for (int m = 0; m < 4; ++m) _Pragma("unroll") for (int n = 0; n < 2; ++n) _Pragma("unroll") for (int k = 0; k < 2; ++k) \
;         acc[ai][bj][m][n] = __builtin_amdgcn_mfma_f32_16x16x32_bf16(Bt[n][k], At[m][k], acc[ai][bj][m][n], 0, 0, 0); __builtin_amdgcn_s_setprio(0); } while (0)
; #define PG8_WAIT_V(n) asm volatile("s_waitcnt vmcnt(" #n ")" ::: "memory")
; #define PG8_WAIT_L(n) asm volatile("s_waitcnt lgkmcnt(" #n ")" ::: "memory")
; #define PG8_BAR __builtin_amdgcn_s_barrier()
; #define PG8_SCHED __builtin_amdgcn_sched_barrier(0)
; template <class Epi, class Sched>
; DI void gemm_phase(LAS unsigned char* lds, const Gemm g, const Sched& S, const Epi& E) {
;     ...
;             PG8_LDB(B0, 1, 0); PG8_LDB(B1, 1, 1); PG8_SCHED; PG8_LDA(At, 1, 0); PG8_STAGE(PG8_SA(0, 1), a2 + hstepA, voffA);
;             PG8_WAIT_V(8); PG8_WAIT_L(0); PG8_BAR; PG8_MMA(0, 0, At, B0); PG8_MMA(0, 1, At, B1); PG8_BAR; PG8_SCHED;
;             PG8_LDA(At, 1, 1); PG8_STAGE(PG8_SB(1, 0), b3, voffB); PG8_STAGE(PG8_SB(1, 1), b3 + hstepB, voffB); PG8_STAGE(PG8_SA(1, 0), a3, voffA);
;             PG8_WAIT_V(8); PG8_WAIT_L(0); PG8_BAR; PG8_MMA(1, 0, At, B0); PG8_MMA(1, 1, At, B1); PG8_BAR; PG8_SCHED;
;         }
	s_add_i32 s73, 0, 0x18000
	s_add_i32 s74, 0, 0x1c000
	v_add_u32_e32 v158, s73, v162
	v_add_u32_e32 v180, s74, v162
	ds_read_b128 v[146:149], v158
	ds_read_b128 v[150:153], v158 offset:1024
	ds_read_b128 v[154:157], v158 offset:2048
	ds_read_b128 v[158:161], v158 offset:3072
	ds_read_b128 v[168:171], v180
	ds_read_b128 v[172:175], v180 offset:1024
	ds_read_b128 v[176:179], v180 offset:2048
	ds_read_b128 v[180:183], v180 offset:3072
	s_add_u32 s48, s48, 0x20000
	s_addc_u32 s49, s49, 0
	s_mov_b32 m0, s55
	ds_read_b128 v[186:189], v167 offset:32768
	ds_read_b128 v[190:193], v167 offset:33792
	ds_read_b128 v[194:197], v167 offset:34816
	ds_read_b128 v[198:201], v167 offset:35840
	ds_read_b128 v[202:205], v167 offset:36864
	ds_read_b128 v[206:209], v167 offset:37888
	ds_read_b128 v[210:213], v167 offset:38912
	ds_read_b128 v[214:217], v167 offset:39936
	global_load_lds_dwordx4 v130, s[48:49]
	s_mov_b32 m0, s56
	s_nop 0
	global_load_lds_dwordx4 v134, s[48:49]
	s_waitcnt vmcnt(8)
	s_waitcnt lgkmcnt(0)
	s_barrier
	s_setprio 1
	v_mfma_f32_16x16x32_bf16 v[126:129], v[146:149], v[186:189], v[126:129]
	v_mfma_f32_16x16x32_bf16 v[122:125], v[154:157], v[186:189], v[122:125]
	v_mfma_f32_16x16x32_bf16 v[118:121], v[146:149], v[194:197], v[118:121]
	v_mfma_f32_16x16x32_bf16 v[114:117], v[154:157], v[194:197], v[114:117]
	v_mfma_f32_16x16x32_bf16 v[110:113], v[146:149], v[202:205], v[110:113]
	v_mfma_f32_16x16x32_bf16 v[106:109], v[154:157], v[202:205], v[106:109]
	v_mfma_f32_16x16x32_bf16 v[102:105], v[146:149], v[210:213], v[102:105]
	v_mfma_f32_16x16x32_bf16 v[98:101], v[154:157], v[210:213], v[98:101]
	v_mfma_f32_16x16x32_bf16 v[126:129], v[150:153], v[190:193], v[126:129]
	v_mfma_f32_16x16x32_bf16 v[122:125], v[158:161], v[190:193], v[122:125]
	v_mfma_f32_16x16x32_bf16 v[118:121], v[150:153], v[198:201], v[118:121]
	v_mfma_f32_16x16x32_bf16 v[114:117], v[158:161], v[198:201], v[114:117]
	v_mfma_f32_16x16x32_bf16 v[110:113], v[150:153], v[206:209], v[110:113]
	v_mfma_f32_16x16x32_bf16 v[106:109], v[158:161], v[206:209], v[106:109]
	v_mfma_f32_16x16x32_bf16 v[102:105], v[150:153], v[214:217], v[102:105]
	v_mfma_f32_16x16x32_bf16 v[98:101], v[158:161], v[214:217], v[98:101]
	v_mfma_f32_16x16x32_bf16 v[94:97], v[168:171], v[186:189], v[94:97]
	v_mfma_f32_16x16x32_bf16 v[90:93], v[176:179], v[186:189], v[90:93]
	v_mfma_f32_16x16x32_bf16 v[86:89], v[168:171], v[194:197], v[86:89]
	v_mfma_f32_16x16x32_bf16 v[82:85], v[176:179], v[194:197], v[82:85]
	v_mfma_f32_16x16x32_bf16 v[78:81], v[168:171], v[202:205], v[78:81]
	v_mfma_f32_16x16x32_bf16 v[74:77], v[176:179], v[202:205], v[74:77]
	v_mfma_f32_16x16x32_bf16 v[70:73], v[168:171], v[210:213], v[70:73]
	v_mfma_f32_16x16x32_bf16 v[66:69], v[176:179], v[210:213], v[66:69]
	v_mfma_f32_16x16x32_bf16 v[94:97], v[172:175], v[190:193], v[94:97]
	v_mfma_f32_16x16x32_bf16 v[90:93], v[180:183], v[190:193], v[90:93]
	v_mfma_f32_16x16x32_bf16 v[86:89], v[172:175], v[198:201], v[86:89]
	v_mfma_f32_16x16x32_bf16 v[82:85], v[180:183], v[198:201], v[82:85]
	v_mfma_f32_16x16x32_bf16 v[78:81], v[172:175], v[206:209], v[78:81]
	v_mfma_f32_16x16x32_bf16 v[74:77], v[180:183], v[206:209], v[74:77]
	v_mfma_f32_16x16x32_bf16 v[70:73], v[172:175], v[214:217], v[70:73]
	v_mfma_f32_16x16x32_bf16 v[66:69], v[180:183], v[214:217], v[66:69]
	s_setprio 0
	s_barrier
	s_add_i32 s48, s73, s52
	v_lshl_add_u64 v[218:219], v[218:219], 0, s[20:21]
	s_mov_b32 m0, s48
	ds_read_b128 v[186:189], v167 offset:49152
	ds_read_b128 v[190:193], v167 offset:50176
	ds_read_b128 v[194:197], v167 offset:51200
	ds_read_b128 v[198:201], v167 offset:52224
	ds_read_b128 v[202:205], v167 offset:53248
	ds_read_b128 v[206:209], v167 offset:54272
	ds_read_b128 v[210:213], v167 offset:55296
	ds_read_b128 v[214:217], v167 offset:56320
	global_load_lds_dwordx4 v[218:219], off
	s_add_i32 m0, s48, 0x2000
	s_add_u32 s46, s46, 0x20080
	v_lshl_add_u64 v[218:219], v[220:221], 0, s[20:21]
	s_addc_u32 s47, s47, 0
	s_add_i32 s48, s74, s52
	global_load_lds_dwordx4 v[218:219], off
	s_mov_b32 m0, s48
	s_nop 0
	global_load_lds_dwordx4 v132, s[46:47]
	s_add_i32 m0, s48, 0x2000
	s_nop 0
	global_load_lds_dwordx4 v136, s[46:47]
	v_lshl_add_u64 v[218:219], v[222:223], 0, s[20:21]
	s_mov_b32 m0, s61
	s_nop 0
	global_load_lds_dwordx4 v[218:219], off
	v_lshl_add_u64 v[218:219], v[224:225], 0, s[20:21]
	s_mov_b32 m0, s62
	s_nop 0
	global_load_lds_dwordx4 v[218:219], off
	s_waitcnt vmcnt(8)
	s_waitcnt lgkmcnt(0)
	s_barrier
	s_setprio 1
	v_mfma_f32_16x16x32_bf16 v[62:65], v[146:149], v[186:189], v[62:65]
	v_mfma_f32_16x16x32_bf16 v[58:61], v[154:157], v[186:189], v[58:61]
	v_mfma_f32_16x16x32_bf16 v[54:57], v[146:149], v[194:197], v[54:57]
	v_mfma_f32_16x16x32_bf16 v[50:53], v[154:157], v[194:197], v[50:53]
	v_mfma_f32_16x16x32_bf16 v[46:49], v[146:149], v[202:205], v[46:49]
	v_mfma_f32_16x16x32_bf16 v[42:45], v[154:157], v[202:205], v[42:45]
	v_mfma_f32_16x16x32_bf16 v[38:41], v[146:149], v[210:213], v[38:41]
	v_mfma_f32_16x16x32_bf16 v[34:37], v[154:157], v[210:213], v[34:37]
	v_mfma_f32_16x16x32_bf16 v[62:65], v[150:153], v[190:193], v[62:65]
	v_mfma_f32_16x16x32_bf16 v[58:61], v[158:161], v[190:193], v[58:61]
	v_mfma_f32_16x16x32_bf16 v[54:57], v[150:153], v[198:201], v[54:57]
	v_mfma_f32_16x16x32_bf16 v[50:53], v[158:161], v[198:201], v[50:53]
	v_mfma_f32_16x16x32_bf16 v[46:49], v[150:153], v[206:209], v[46:49]
	v_mfma_f32_16x16x32_bf16 v[42:45], v[158:161], v[206:209], v[42:45]
	v_mfma_f32_16x16x32_bf16 v[38:41], v[150:153], v[214:217], v[38:41]
	v_mfma_f32_16x16x32_bf16 v[34:37], v[158:161], v[214:217], v[34:37]
	v_mfma_f32_16x16x32_bf16 v[30:33], v[168:171], v[186:189], v[30:33]
	v_mfma_f32_16x16x32_bf16 v[26:29], v[176:179], v[186:189], v[26:29]
	v_mfma_f32_16x16x32_bf16 v[22:25], v[168:171], v[194:197], v[22:25]
	v_mfma_f32_16x16x32_bf16 v[18:21], v[176:179], v[194:197], v[18:21]
	v_mfma_f32_16x16x32_bf16 v[14:17], v[168:171], v[202:205], v[14:17]
	v_mfma_f32_16x16x32_bf16 v[10:13], v[176:179], v[202:205], v[10:13]
	v_mfma_f32_16x16x32_bf16 v[6:9], v[168:171], v[210:213], v[6:9]
	v_mfma_f32_16x16x32_bf16 v[2:5], v[176:179], v[210:213], v[2:5]
	v_mfma_f32_16x16x32_bf16 v[30:33], v[172:175], v[190:193], v[30:33]
	v_mfma_f32_16x16x32_bf16 v[26:29], v[180:183], v[190:193], v[26:29]
	v_mfma_f32_16x16x32_bf16 v[22:25], v[172:175], v[198:201], v[22:25]
	v_mfma_f32_16x16x32_bf16 v[18:21], v[180:183], v[198:201], v[18:21]
	v_mfma_f32_16x16x32_bf16 v[14:17], v[172:175], v[206:209], v[14:17]
	v_mfma_f32_16x16x32_bf16 v[10:13], v[180:183], v[206:209], v[10:13]
	v_mfma_f32_16x16x32_bf16 v[6:9], v[172:175], v[214:217], v[6:9]
	v_mfma_f32_16x16x32_bf16 v[2:5], v[180:183], v[214:217], v[2:5]
	s_setprio 0
	s_barrier
	s_add_i32 s72, s72, 2
	s_add_u32 s44, s44, 0x100
	s_addc_u32 s45, s45, 0
	s_add_u32 s70, s70, 0x100
	s_addc_u32 s71, s71, 0
	s_cmp_gt_u32 s72, 5
	s_cbranch_scc0 .LBB0_972
	s_mov_b32 s99, 1
	s_and_b64 vcc, exec, s[34:35]
	s_cbranch_vccz .LBB0_975
	s_barrier

; #define PG8_STAGE(bufoff, gbase, voff) do { _Pragma("unroll") for (int _i = 0; _i < 2; ++_i) \
;         __builtin_amdgcn_global_load_lds((const unsigned*)((const char*)(gbase) + (voff)[_i]), (LAS unsigned*)(lds + (bufoff) + ldsw + _i * 8192), 16, 0, 0); } while (0)
; #define PG8_LDA(dst, b, h) do { _Pragma("unroll") for (int m = 0; m < 4; ++m) _Pragma("unroll") for (int k = 0; k < 2; ++k) dst[m][k] = *(const LAS bf16x8*)(lds + PG8_SA(b, h) + aoff + m * 2048 + k * 1024); } while (0)
; #define PG8_LDB(dst, b, h) do { _Pragma("unroll") for (int n = 0; n < 2; ++n) _Pragma("unroll") for (int k = 0; k < 2; ++k) dst[n][k] = *(const LAS bf16x8*)(lds + PG8_SB(b, h) + boff + n * 2048 + k * 1024); } while (0)
; #define PG8_MMA(ai, bj, At, Bt) do { __builtin_amdgcn_s_setprio(1); _Pragma("unroll") for (int m = 0; m < 4; ++m) _Pragma("unroll") for (int n = 0; n < 2; ++n) _Pragma("unroll") for (int k = 0; k < 2; ++k) \
;         acc[ai][bj][m][n] = __builtin_amdgcn_mfma_f32_16x16x32_bf16(Bt[n][k], At[m][k], acc[ai][bj][m][n], 0, 0, 0); __builtin_amdgcn_s_setprio(0); } while (0)
; #define PG8_WAIT_V(n) asm volatile("s_waitcnt vmcnt(" #n ")" ::: "memory")
; #define PG8_WAIT_L(n) asm volatile("s_waitcnt lgkmcnt(" #n ")" ::: "memory")
; #define PG8_BAR __builtin_amdgcn_s_barrier()
; template <class Epi, class Sched>
; DI void gemm_phase(LAS unsigned char* lds, const Gemm g, const Sched& S, const Epi& E) {
;     ...
;         const char* nA = has_next ? (const char*)(nxt.src ? g.A1 : g.A0) + (size_t)nxt.pm * tstepA : cA; const char* nB = has_next ? (const char*)(nxt.src ? g.B1 : g.B0) + (size_t)nxt.pn * tstepB : cB;
;         for (int t = 0; t < nt; t += 2) {
;             const bool last = (t == nt - 2);
;             const char* a1 = cA + (size_t)(t + 1) * kstep;
;             const char* a2 = last ? nA : cA + (size_t)(t + 2) * kstep; const char* b2 = last ? nB : cB + (size_t)(t + 2) * kstep;
;             const char* a3 = a2 + kstep; const char* b3 = b2 + kstep;
;             PG8_LDB(B0, 0, 0); PG8_LDB(B1, 0, 1); PG8_SCHED; PG8_LDA(At, 0, 0); PG8_STAGE(PG8_SA(1, 1), a1 + hstepA, voffA);
;             PG8_WAIT_V(8); PG8_WAIT_L(0); PG8_BAR; PG8_MMA(0, 0, At, B0); PG8_MMA(0, 1, At, B1); PG8_BAR; PG8_SCHED;
;             PG8_LDA(At, 0, 1); PG8_STAGE(PG8_SB(0, 0), b2, voffB); PG8_STAGE(PG8_SB(0, 1), b2 + hstepB, voffB); PG8_STAGE(PG8_SA(0, 0), a2, voffA);
.LBB0_1132:
	s_ashr_i32 s35, s34, 31
	s_lshl_b64 s[36:37], s[34:35], 19
	s_add_u32 s36, s28, s36
	s_addc_u32 s37, s29, s37
	s_and_b64 s[38:39], s[6:7], exec
	s_cselect_b32 s35, s37, s45
	s_cselect_b32 s41, s36, s44
	s_ashr_i32 s21, s20, 31
	s_lshl_b64 s[38:39], s[20:21], 19
	s_add_u32 s38, s50, s38
	s_addc_u32 s39, s51, s39
	s_and_b64 s[48:49], s[6:7], exec
	s_cselect_b32 s21, s39, s47
	s_cselect_b32 s63, s38, s46
	s_add_u32 s44, s44, 0x40080
	s_addc_u32 s45, s45, 0
	s_add_u32 s64, s46, 0x100
	s_addc_u32 s65, s47, 0
	s_mov_b32 s66, -2
	s_waitcnt lgkmcnt(0)
	ds_read_b128 v[146:149], v152
	ds_read_b128 v[156:159], v152 offset:1024
	ds_read_b128 v[160:163], v152 offset:2048
	ds_read_b128 v[164:167], v152 offset:3072
	ds_read_b128 v[168:171], v153
	ds_read_b128 v[172:175], v153 offset:1024
	ds_read_b128 v[176:179], v153 offset:2048
	ds_read_b128 v[180:183], v153 offset:3072
	s_add_u32 s46, s44, 0xfffc0080
	s_addc_u32 s47, s45, -1
	s_cmp_eq_u32 s66, 12
	s_cselect_b32 s49, s35, s47
	s_cselect_b32 s48, s41, s46
	s_cselect_b32 s47, s21, s65
	s_cselect_b32 s46, s63, s64
	s_add_i32 m0, s43, 0xc000
	ds_read_b128 v[186:189], v154
	ds_read_b128 v[190:193], v154 offset:1024
	ds_read_b128 v[194:197], v154 offset:2048
	ds_read_b128 v[198:201], v154 offset:3072
	ds_read_b128 v[202:205], v154 offset:4096
	ds_read_b128 v[206:209], v154 offset:5120
	ds_read_b128 v[210:213], v154 offset:6144
	ds_read_b128 v[214:217], v154 offset:7168
	global_load_lds_dwordx4 v138, s[44:45]
	s_add_i32 m0, s43, 0xe000
	s_nop 0
	global_load_lds_dwordx4 v140, s[44:45]
	s_cmp_lg_u32 s99, 0
	s_cbranch_scc1 .Lpk4_w1
	s_waitcnt vmcnt(8)
.Lpk4_w1:
	s_waitcnt lgkmcnt(0)
	s_barrier
	s_setprio 1
	v_mfma_f32_16x16x32_bf16 v[126:129], v[146:149], v[186:189], 0
	v_mfma_f32_16x16x32_bf16 v[122:125], v[160:163], v[186:189], 0
	v_mfma_f32_16x16x32_bf16 v[110:113], v[146:149], v[194:197], 0
	v_mfma_f32_16x16x32_bf16 v[106:109], v[160:163], v[194:197], 0
	v_mfma_f32_16x16x32_bf16 v[94:97], v[146:149], v[202:205], 0
	v_mfma_f32_16x16x32_bf16 v[90:93], v[160:163], v[202:205], 0
	v_mfma_f32_16x16x32_bf16 v[78:81], v[146:149], v[210:213], 0
	v_mfma_f32_16x16x32_bf16 v[74:77], v[160:163], v[210:213], 0
	v_mfma_f32_16x16x32_bf16 v[126:129], v[156:159], v[190:193], v[126:129]
	v_mfma_f32_16x16x32_bf16 v[122:125], v[164:167], v[190:193], v[122:125]
	v_mfma_f32_16x16x32_bf16 v[110:113], v[156:159], v[198:201], v[110:113]
	v_mfma_f32_16x16x32_bf16 v[106:109], v[164:167], v[198:201], v[106:109]
	v_mfma_f32_16x16x32_bf16 v[94:97], v[156:159], v[206:209], v[94:97]
	v_mfma_f32_16x16x32_bf16 v[90:93], v[164:167], v[206:209], v[90:93]
	v_mfma_f32_16x16x32_bf16 v[78:81], v[156:159], v[214:217], v[78:81]
	v_mfma_f32_16x16x32_bf16 v[74:77], v[164:167], v[214:217], v[74:77]
	v_mfma_f32_16x16x32_bf16 v[118:121], v[168:171], v[186:189], 0
	v_mfma_f32_16x16x32_bf16 v[114:117], v[176:179], v[186:189], 0
	v_mfma_f32_16x16x32_bf16 v[102:105], v[168:171], v[194:197], 0
	v_mfma_f32_16x16x32_bf16 v[98:101], v[176:179], v[194:197], 0
	v_mfma_f32_16x16x32_bf16 v[86:89], v[168:171], v[202:205], 0
	v_mfma_f32_16x16x32_bf16 v[82:85], v[176:179], v[202:205], 0
	v_mfma_f32_16x16x32_bf16 v[70:73], v[168:171], v[210:213], 0
	v_mfma_f32_16x16x32_bf16 v[66:69], v[176:179], v[210:213], 0
	v_mfma_f32_16x16x32_bf16 v[118:121], v[172:175], v[190:193], v[118:121]
	v_mfma_f32_16x16x32_bf16 v[114:117], v[180:183], v[190:193], v[114:117]
	v_mfma_f32_16x16x32_bf16 v[102:105], v[172:175], v[198:201], v[102:105]
	v_mfma_f32_16x16x32_bf16 v[98:101], v[180:183], v[198:201], v[98:101]
	v_mfma_f32_16x16x32_bf16 v[86:89], v[172:175], v[206:209], v[86:89]
	v_mfma_f32_16x16x32_bf16 v[82:85], v[180:183], v[206:209], v[82:85]
	v_mfma_f32_16x16x32_bf16 v[70:73], v[172:175], v[214:217], v[70:73]
	v_mfma_f32_16x16x32_bf16 v[66:69], v[180:183], v[214:217], v[66:69]
	s_setprio 0
	s_barrier
	s_add_i32 s67, s61, s52
	v_lshl_add_u64 v[218:219], s[46:47], 0, v[132:133]
	s_mov_b32 m0, s67
	ds_read_b128 v[186:189], v154 offset:16384
	ds_read_b128 v[190:193], v154 offset:17408
	ds_read_b128 v[194:197], v154 offset:18432
	ds_read_b128 v[198:201], v154 offset:19456
	ds_read_b128 v[202:205], v154 offset:20480
	ds_read_b128 v[206:209], v154 offset:21504
	ds_read_b128 v[210:213], v154 offset:22528
	ds_read_b128 v[214:217], v154 offset:23552
	global_load_lds_dwordx4 v[218:219], off
	s_add_i32 m0, s67, 0x2000
	s_add_u32 s68, s46, 0x40000
	v_lshl_add_u64 v[220:221], s[46:47], 0, v[136:137]
	s_addc_u32 s69, s47, 0
	s_add_i32 s67, s62, s52
	global_load_lds_dwordx4 v[220:221], off
	s_mov_b32 m0, s67
	v_lshl_add_u64 v[224:225], s[48:49], 0, v[134:135]
	global_load_lds_dwordx4 v132, s[68:69]
	s_add_i32 m0, s67, 0x2000
	s_nop 0
	global_load_lds_dwordx4 v136, s[68:69]
	v_lshl_add_u64 v[222:223], s[48:49], 0, v[130:131]
	s_mov_b32 m0, s43
	s_nop 0
	global_load_lds_dwordx4 v[222:223], off
	s_mov_b32 m0, s53
	s_nop 0
	global_load_lds_dwordx4 v[224:225], off
	s_cmp_lg_u32 s99, 0
	s_cbranch_scc1 .Lpk4_w2
	s_waitcnt vmcnt(8)
; #define PG8_STAGE(bufoff, gbase, voff) do { _Pragma("unroll") for (int _i = 0; _i < 2; ++_i) \
;         __builtin_amdgcn_global_load_lds((const unsigned*)((const char*)(gbase) + (voff)[_i]), (LAS unsigned*)(lds + (bufoff) + ldsw + _i * 8192), 16, 0, 0); } while (0)
; #define PG8_LDA(dst, b, h) do { _Pragma("unroll") for (int m = 0; m < 4; ++m) _Pragma("unroll") for (int k = 0; k < 2; ++k) dst[m][k] = *(const LAS bf16x8*)(lds + PG8_SA(b, h) + aoff + m * 2048 + k * 1024); } while (0)
; #define PG8_LDB(dst, b, h) do { _Pragma("unroll") for (int n = 0; n < 2; ++n) _Pragma("unroll") for (int k = 0; k < 2; ++k) dst[n][k] = *(const LAS bf16x8*)(lds + PG8_SB(b, h) + boff + n * 2048 + k * 1024); } while (0)
; #define PG8_MMA(ai, bj, At, Bt) do { __builtin_amdgcn_s_setprio(1); _Pragma("unroll") for (int m = 0; m < 4; ++m) _Pragma("unroll") for (int n = 0; n < 2; ++n) _Pragma("unroll") for (int k = 0; k < 2; ++k) \
;         acc[ai][bj][m][n] = __builtin_amdgcn_mfma_f32_16x16x32_bf16(Bt[n][k], At[m][k], acc[ai][bj][m][n], 0, 0, 0); __builtin_amdgcn_s_setprio(0); } while (0)
; #define PG8_WAIT_V(n) asm volatile("s_waitcnt vmcnt(" #n ")" ::: "memory")
; #define PG8_WAIT_L(n) asm volatile("s_waitcnt lgkmcnt(" #n ")" ::: "memory")
; #define PG8_BAR __builtin_amdgcn_s_barrier()
; #define PG8_SCHED __builtin_amdgcn_sched_barrier(0)
; template <class Epi, class Sched>
; DI void gemm_phase(LAS unsigned char* lds, const Gemm g, const Sched& S, const Epi& E) {
;     ...
;             PG8_WAIT_V(8); PG8_WAIT_L(0); PG8_BAR; PG8_MMA(1, 0, At, B0); PG8_MMA(1, 1, At, B1); PG8_BAR; PG8_SCHED;
;             PG8_LDB(B0, 1, 0); PG8_LDB(B1, 1, 1); PG8_SCHED; PG8_LDA(At, 1, 0); PG8_STAGE(PG8_SA(0, 1), a2 + hstepA, voffA);
;             PG8_WAIT_V(8); PG8_WAIT_L(0); PG8_BAR; PG8_MMA(0, 0, At, B0); PG8_MMA(0, 1, At, B1); PG8_BAR; PG8_SCHED;
.Lpk4_w2:
	s_mov_b32 s99, 0
	s_waitcnt lgkmcnt(0)
	s_barrier
	s_setprio 1
	v_mfma_f32_16x16x32_bf16 v[62:65], v[146:149], v[186:189], 0
	v_mfma_f32_16x16x32_bf16 v[58:61], v[160:163], v[186:189], 0
	v_mfma_f32_16x16x32_bf16 v[46:49], v[146:149], v[194:197], 0
	v_mfma_f32_16x16x32_bf16 v[42:45], v[160:163], v[194:197], 0
	v_mfma_f32_16x16x32_bf16 v[30:33], v[146:149], v[202:205], 0
	v_mfma_f32_16x16x32_bf16 v[26:29], v[160:163], v[202:205], 0
	v_mfma_f32_16x16x32_bf16 v[14:17], v[146:149], v[210:213], 0
	v_mfma_f32_16x16x32_bf16 v[10:13], v[160:163], v[210:213], 0
	v_mfma_f32_16x16x32_bf16 v[62:65], v[156:159], v[190:193], v[62:65]
	v_mfma_f32_16x16x32_bf16 v[58:61], v[164:167], v[190:193], v[58:61]
	v_mfma_f32_16x16x32_bf16 v[46:49], v[156:159], v[198:201], v[46:49]
	v_mfma_f32_16x16x32_bf16 v[42:45], v[164:167], v[198:201], v[42:45]
	v_mfma_f32_16x16x32_bf16 v[30:33], v[156:159], v[206:209], v[30:33]
	v_mfma_f32_16x16x32_bf16 v[26:29], v[164:167], v[206:209], v[26:29]
	v_mfma_f32_16x16x32_bf16 v[14:17], v[156:159], v[214:217], v[14:17]
	v_mfma_f32_16x16x32_bf16 v[10:13], v[164:167], v[214:217], v[10:13]
	v_mfma_f32_16x16x32_bf16 v[54:57], v[168:171], v[186:189], 0
	v_mfma_f32_16x16x32_bf16 v[50:53], v[176:179], v[186:189], 0
	v_mfma_f32_16x16x32_bf16 v[38:41], v[168:171], v[194:197], 0
	v_mfma_f32_16x16x32_bf16 v[34:37], v[176:179], v[194:197], 0
	v_mfma_f32_16x16x32_bf16 v[22:25], v[168:171], v[202:205], 0
	v_mfma_f32_16x16x32_bf16 v[18:21], v[176:179], v[202:205], 0
	v_mfma_f32_16x16x32_bf16 v[6:9], v[168:171], v[210:213], 0
	v_mfma_f32_16x16x32_bf16 v[2:5], v[176:179], v[210:213], 0
	v_mfma_f32_16x16x32_bf16 v[54:57], v[172:175], v[190:193], v[54:57]
	v_mfma_f32_16x16x32_bf16 v[50:53], v[180:183], v[190:193], v[50:53]
	v_mfma_f32_16x16x32_bf16 v[38:41], v[172:175], v[198:201], v[38:41]
	v_mfma_f32_16x16x32_bf16 v[34:37], v[180:183], v[198:201], v[34:37]
	v_mfma_f32_16x16x32_bf16 v[22:25], v[172:175], v[206:209], v[22:25]
	v_mfma_f32_16x16x32_bf16 v[18:21], v[180:183], v[206:209], v[18:21]
	v_mfma_f32_16x16x32_bf16 v[6:9], v[172:175], v[214:217], v[6:9]
	v_mfma_f32_16x16x32_bf16 v[2:5], v[180:183], v[214:217], v[2:5]
	s_setprio 0
	s_barrier
	s_add_i32 s67, 0, 0x18000
	s_add_i32 s68, 0, 0x1c000
	v_add_u32_e32 v164, s67, v150
	v_add_u32_e32 v180, s68, v150
	ds_read_b128 v[146:149], v164
	ds_read_b128 v[156:159], v164 offset:1024
	ds_read_b128 v[160:163], v164 offset:2048
	ds_read_b128 v[164:167], v164 offset:3072
	ds_read_b128 v[168:171], v180
	ds_read_b128 v[172:175], v180 offset:1024
	ds_read_b128 v[176:179], v180 offset:2048
	ds_read_b128 v[180:183], v180 offset:3072
	s_add_u32 s48, s48, 0x40000
	s_addc_u32 s49, s49, 0
	s_mov_b32 m0, s54
	ds_read_b128 v[186:189], v154 offset:32768
	ds_read_b128 v[190:193], v154 offset:33792
	ds_read_b128 v[194:197], v154 offset:34816
	ds_read_b128 v[198:201], v154 offset:35840
	ds_read_b128 v[202:205], v154 offset:36864
	ds_read_b128 v[206:209], v154 offset:37888
	ds_read_b128 v[210:213], v154 offset:38912
	ds_read_b128 v[214:217], v154 offset:39936
	global_load_lds_dwordx4 v130, s[48:49]
	s_mov_b32 m0, s55
	s_nop 0
	global_load_lds_dwordx4 v134, s[48:49]
	s_waitcnt vmcnt(8)
	s_waitcnt lgkmcnt(0)
	s_barrier
	s_setprio 1
	v_mfma_f32_16x16x32_bf16 v[126:129], v[146:149], v[186:189], v[126:129]
	v_mfma_f32_16x16x32_bf16 v[122:125], v[160:163], v[186:189], v[122:125]
	v_mfma_f32_16x16x32_bf16 v[110:113], v[146:149], v[194:197], v[110:113]
	v_mfma_f32_16x16x32_bf16 v[106:109], v[160:163], v[194:197], v[106:109]
	v_mfma_f32_16x16x32_bf16 v[94:97], v[146:149], v[202:205], v[94:97]
	v_mfma_f32_16x16x32_bf16 v[90:93], v[160:163], v[202:205], v[90:93]
	v_mfma_f32_16x16x32_bf16 v[78:81], v[146:149], v[210:213], v[78:81]
	v_mfma_f32_16x16x32_bf16 v[74:77], v[160:163], v[210:213], v[74:77]
	v_mfma_f32_16x16x32_bf16 v[126:129], v[156:159], v[190:193], v[126:129]
	v_mfma_f32_16x16x32_bf16 v[122:125], v[164:167], v[190:193], v[122:125]
	v_mfma_f32_16x16x32_bf16 v[110:113], v[156:159], v[198:201], v[110:113]
	v_mfma_f32_16x16x32_bf16 v[106:109], v[164:167], v[198:201], v[106:109]
	v_mfma_f32_16x16x32_bf16 v[94:97], v[156:159], v[206:209], v[94:97]
	v_mfma_f32_16x16x32_bf16 v[90:93], v[164:167], v[206:209], v[90:93]
	v_mfma_f32_16x16x32_bf16 v[78:81], v[156:159], v[214:217], v[78:81]
	v_mfma_f32_16x16x32_bf16 v[74:77], v[164:167], v[214:217], v[74:77]
	v_mfma_f32_16x16x32_bf16 v[118:121], v[168:171], v[186:189], v[118:121]
	v_mfma_f32_16x16x32_bf16 v[114:117], v[176:179], v[186:189], v[114:117]
	v_mfma_f32_16x16x32_bf16 v[102:105], v[168:171], v[194:197], v[102:105]
	v_mfma_f32_16x16x32_bf16 v[98:101], v[176:179], v[194:197], v[98:101]
	v_mfma_f32_16x16x32_bf16 v[86:89], v[168:171], v[202:205], v[86:89]
	v_mfma_f32_16x16x32_bf16 v[82:85], v[176:179], v[202:205], v[82:85]
	v_mfma_f32_16x16x32_bf16 v[70:73], v[168:171], v[210:213], v[70:73]
	v_mfma_f32_16x16x32_bf16 v[66:69], v[176:179], v[210:213], v[66:69]
	v_mfma_f32_16x16x32_bf16 v[118:121], v[172:175], v[190:193], v[118:121]
	v_mfma_f32_16x16x32_bf16 v[114:117], v[180:183], v[190:193], v[114:117]
	v_mfma_f32_16x16x32_bf16 v[102:105], v[172:175], v[198:201], v[102:105]
	v_mfma_f32_16x16x32_bf16 v[98:101], v[180:183], v[198:201], v[98:101]
	v_mfma_f32_16x16x32_bf16 v[86:89], v[172:175], v[206:209], v[86:89]
	v_mfma_f32_16x16x32_bf16 v[82:85], v[180:183], v[206:209], v[82:85]
	v_mfma_f32_16x16x32_bf16 v[70:73], v[172:175], v[214:217], v[70:73]
	v_mfma_f32_16x16x32_bf16 v[66:69], v[180:183], v[214:217], v[66:69]
	s_setprio 0
	s_barrier
; #define PG8_STAGE(bufoff, gbase, voff) do { _Pragma("unroll") for (int _i = 0; _i < 2; ++_i) \
;         __builtin_amdgcn_global_load_lds((const unsigned*)((const char*)(gbase) + (voff)[_i]), (LAS unsigned*)(lds + (bufoff) + ldsw + _i * 8192), 16, 0, 0); } while (0)
; #define PG8_LDA(dst, b, h) do { _Pragma("unroll") for (int m = 0; m < 4; ++m) _Pragma("unroll") for (int k = 0; k < 2; ++k) dst[m][k] = *(const LAS bf16x8*)(lds + PG8_SA(b, h) + aoff + m * 2048 + k * 1024); } while (0)
; #define PG8_LDB(dst, b, h) do { _Pragma("unroll") for (int n = 0; n < 2; ++n) _Pragma("unroll") for (int k = 0; k < 2; ++k) dst[n][k] = *(const LAS bf16x8*)(lds + PG8_SB(b, h) + boff + n * 2048 + k * 1024); } while (0)
; #define PG8_MMA(ai, bj, At, Bt) do { __builtin_amdgcn_s_setprio(1); _Pragma("unroll") for (int m = 0; m < 4; ++m) _Pragma("unroll") for (int n = 0; n < 2; ++n) _Pragma("unroll") for (int k = 0; k < 2; ++k) \
;         acc[ai][bj][m][n] = __builtin_amdgcn_mfma_f32_16x16x32_bf16(Bt[n][k], At[m][k], acc[ai][bj][m][n], 0, 0, 0); __builtin_amdgcn_s_setprio(0); } while (0)
; #define PG8_WAIT_V(n) asm volatile("s_waitcnt vmcnt(" #n ")" ::: "memory")
; #define PG8_WAIT_L(n) asm volatile("s_waitcnt lgkmcnt(" #n ")" ::: "memory")
; template <class Epi, class Sched>
; DI void gemm_phase(LAS unsigned char* lds, const Gemm g, const Sched& S, const Epi& E) {
;     ...
;             PG8_LDB(B0, 0, 0); PG8_LDB(B1, 0, 1); PG8_SCHED; PG8_LDA(At, 0, 0); PG8_STAGE(PG8_SA(1, 1), a1 + hstepA, voffA);
;             PG8_WAIT_V(8); PG8_WAIT_L(0); PG8_BAR; PG8_MMA(0, 0, At, B0); PG8_MMA(0, 1, At, B1); PG8_BAR; PG8_SCHED;
;             PG8_LDA(At, 0, 1); PG8_STAGE(PG8_SB(0, 0), b2, voffB); PG8_STAGE(PG8_SB(0, 1), b2 + hstepB, voffB); PG8_STAGE(PG8_SA(0, 0), a2, voffA);
;             PG8_WAIT_V(8); PG8_WAIT_L(0); PG8_BAR; PG8_MMA(1, 0, At, B0); PG8_MMA(1, 1, At, B1); PG8_BAR; PG8_SCHED;
;             PG8_LDB(B0, 1, 0); PG8_LDB(B1, 1, 1); PG8_SCHED; PG8_LDA(At, 1, 0); PG8_STAGE(PG8_SA(0, 1), a2 + hstepA, voffA);
;             PG8_WAIT_V(8); PG8_WAIT_L(0); PG8_BAR; PG8_MMA(0, 0, At, B0); PG8_MMA(0, 1, At, B1); PG8_BAR; PG8_SCHED;
;             PG8_LDA(At, 1, 1); PG8_STAGE(PG8_SB(1, 0), b3, voffB); PG8_STAGE(PG8_SB(1, 1), b3 + hstepB, voffB); PG8_STAGE(PG8_SA(1, 0), a3, voffA);
;             PG8_WAIT_V(8); PG8_WAIT_L(0); PG8_BAR; PG8_MMA(1, 0, At, B0); PG8_MMA(1, 1, At, B1); PG8_BAR; PG8_SCHED;
	s_add_i32 s48, s67, s52
	v_lshl_add_u64 v[218:219], v[218:219], 0, s[16:17]
	s_mov_b32 m0, s48
	ds_read_b128 v[186:189], v154 offset:49152
	ds_read_b128 v[190:193], v154 offset:50176
	ds_read_b128 v[194:197], v154 offset:51200
	ds_read_b128 v[198:201], v154 offset:52224
	ds_read_b128 v[202:205], v154 offset:53248
	ds_read_b128 v[206:209], v154 offset:54272
	ds_read_b128 v[210:213], v154 offset:55296
	ds_read_b128 v[214:217], v154 offset:56320
	global_load_lds_dwordx4 v[218:219], off
	s_add_i32 m0, s48, 0x2000
	s_add_u32 s46, s46, 0x40080
	v_lshl_add_u64 v[218:219], v[220:221], 0, s[16:17]
	s_addc_u32 s47, s47, 0
	s_add_i32 s48, s68, s52
	global_load_lds_dwordx4 v[218:219], off
	s_mov_b32 m0, s48
	s_nop 0
	global_load_lds_dwordx4 v132, s[46:47]
	s_add_i32 m0, s48, 0x2000
	s_nop 0
	global_load_lds_dwordx4 v136, s[46:47]
	v_lshl_add_u64 v[218:219], v[222:223], 0, s[16:17]
	s_mov_b32 m0, s57
	s_nop 0
	global_load_lds_dwordx4 v[218:219], off
	v_lshl_add_u64 v[218:219], v[224:225], 0, s[16:17]
	s_mov_b32 m0, s58
	s_nop 0
	global_load_lds_dwordx4 v[218:219], off
	s_waitcnt vmcnt(8)
	s_waitcnt lgkmcnt(0)
	s_barrier
	s_setprio 1
	v_mfma_f32_16x16x32_bf16 v[62:65], v[146:149], v[186:189], v[62:65]
	v_mfma_f32_16x16x32_bf16 v[58:61], v[160:163], v[186:189], v[58:61]
	v_mfma_f32_16x16x32_bf16 v[46:49], v[146:149], v[194:197], v[46:49]
	v_mfma_f32_16x16x32_bf16 v[42:45], v[160:163], v[194:197], v[42:45]
	v_mfma_f32_16x16x32_bf16 v[30:33], v[146:149], v[202:205], v[30:33]
	v_mfma_f32_16x16x32_bf16 v[26:29], v[160:163], v[202:205], v[26:29]
	v_mfma_f32_16x16x32_bf16 v[14:17], v[146:149], v[210:213], v[14:17]
	v_mfma_f32_16x16x32_bf16 v[10:13], v[160:163], v[210:213], v[10:13]
	v_mfma_f32_16x16x32_bf16 v[62:65], v[156:159], v[190:193], v[62:65]
	v_mfma_f32_16x16x32_bf16 v[58:61], v[164:167], v[190:193], v[58:61]
	v_mfma_f32_16x16x32_bf16 v[46:49], v[156:159], v[198:201], v[46:49]
	v_mfma_f32_16x16x32_bf16 v[42:45], v[164:167], v[198:201], v[42:45]
	v_mfma_f32_16x16x32_bf16 v[30:33], v[156:159], v[206:209], v[30:33]
	v_mfma_f32_16x16x32_bf16 v[26:29], v[164:167], v[206:209], v[26:29]
	v_mfma_f32_16x16x32_bf16 v[14:17], v[156:159], v[214:217], v[14:17]
	v_mfma_f32_16x16x32_bf16 v[10:13], v[164:167], v[214:217], v[10:13]
	v_mfma_f32_16x16x32_bf16 v[54:57], v[168:171], v[186:189], v[54:57]
	v_mfma_f32_16x16x32_bf16 v[50:53], v[176:179], v[186:189], v[50:53]
	v_mfma_f32_16x16x32_bf16 v[38:41], v[168:171], v[194:197], v[38:41]
	v_mfma_f32_16x16x32_bf16 v[34:37], v[176:179], v[194:197], v[34:37]
	v_mfma_f32_16x16x32_bf16 v[22:25], v[168:171], v[202:205], v[22:25]
	v_mfma_f32_16x16x32_bf16 v[18:21], v[176:179], v[202:205], v[18:21]
	v_mfma_f32_16x16x32_bf16 v[6:9], v[168:171], v[210:213], v[6:9]
	v_mfma_f32_16x16x32_bf16 v[2:5], v[176:179], v[210:213], v[2:5]
	v_mfma_f32_16x16x32_bf16 v[54:57], v[172:175], v[190:193], v[54:57]
	v_mfma_f32_16x16x32_bf16 v[50:53], v[180:183], v[190:193], v[50:53]
	v_mfma_f32_16x16x32_bf16 v[38:41], v[172:175], v[198:201], v[38:41]
	v_mfma_f32_16x16x32_bf16 v[34:37], v[180:183], v[198:201], v[34:37]
	v_mfma_f32_16x16x32_bf16 v[22:25], v[172:175], v[206:209], v[22:25]
	v_mfma_f32_16x16x32_bf16 v[18:21], v[180:183], v[206:209], v[18:21]
	v_mfma_f32_16x16x32_bf16 v[6:9], v[172:175], v[214:217], v[6:9]
	v_mfma_f32_16x16x32_bf16 v[2:5], v[180:183], v[214:217], v[2:5]
	s_setprio 0
	s_barrier
	s_add_i32 s66, s66, 2
	s_add_u32 s44, s44, 0x100
	s_addc_u32 s45, s45, 0
	s_add_u32 s64, s64, 0x100
	s_addc_u32 s65, s65, 0
	s_cmp_gt_u32 s66, 13
.LBB0_1133:
	ds_read_b128 v[146:149], v152
	ds_read_b128 v[156:159], v152 offset:1024
	ds_read_b128 v[160:163], v152 offset:2048
	ds_read_b128 v[164:167], v152 offset:3072
	ds_read_b128 v[168:171], v153
	ds_read_b128 v[172:175], v153 offset:1024
	ds_read_b128 v[176:179], v153 offset:2048
	ds_read_b128 v[180:183], v153 offset:3072
	s_add_u32 s46, s44, 0xfffc0080
	s_addc_u32 s47, s45, -1
	s_cmp_eq_u32 s66, 12
	s_cselect_b32 s49, s35, s47
	s_cselect_b32 s48, s41, s46
	s_cselect_b32 s47, s21, s65
	s_cselect_b32 s46, s63, s64
	s_add_i32 m0, s43, 0xc000
	ds_read_b128 v[186:189], v154
	ds_read_b128 v[190:193], v154 offset:1024
	ds_read_b128 v[194:197], v154 offset:2048
	ds_read_b128 v[198:201], v154 offset:3072
	ds_read_b128 v[202:205], v154 offset:4096
	ds_read_b128 v[206:209], v154 offset:5120
	ds_read_b128 v[210:213], v154 offset:6144
	ds_read_b128 v[214:217], v154 offset:7168
	global_load_lds_dwordx4 v138, s[44:45]
	s_add_i32 m0, s43, 0xe000
	s_nop 0
	global_load_lds_dwordx4 v140, s[44:45]
	s_waitcnt vmcnt(8)
	s_waitcnt lgkmcnt(0)
	s_barrier
; #define PG8_STAGE(bufoff, gbase, voff) do { _Pragma("unroll") for (int _i = 0; _i < 2; ++_i) \
;         __builtin_amdgcn_global_load_lds((const unsigned*)((const char*)(gbase) + (voff)[_i]), (LAS unsigned*)(lds + (bufoff) + ldsw + _i * 8192), 16, 0, 0); } while (0)
; #define PG8_LDA(dst, b, h) do { _Pragma("unroll") for (int m = 0; m < 4; ++m) _Pragma("unroll") for (int k = 0; k < 2; ++k) dst[m][k] = *(const LAS bf16x8*)(lds + PG8_SA(b, h) + aoff + m * 2048 + k * 1024); } while (0)
; #define PG8_MMA(ai, bj, At, Bt) do { __builtin_amdgcn_s_setprio(1); _Pragma("unroll") for (int m = 0; m < 4; ++m) _Pragma("unroll") for (int n = 0; n < 2; ++n) _Pragma("unroll") for (int k = 0; k < 2; ++k) \
;         acc[ai][bj][m][n] = __builtin_amdgcn_mfma_f32_16x16x32_bf16(Bt[n][k], At[m][k], acc[ai][bj][m][n], 0, 0, 0); __builtin_amdgcn_s_setprio(0); } while (0)
; #define PG8_WAIT_V(n) asm volatile("s_waitcnt vmcnt(" #n ")" ::: "memory")
; #define PG8_WAIT_L(n) asm volatile("s_waitcnt lgkmcnt(" #n ")" ::: "memory")
; #define PG8_BAR __builtin_amdgcn_s_barrier()
; #define PG8_SCHED __builtin_amdgcn_sched_barrier(0)
; template <class Epi, class Sched>
; DI void gemm_phase(LAS unsigned char* lds, const Gemm g, const Sched& S, const Epi& E) {
;     ...
;             PG8_WAIT_V(8); PG8_WAIT_L(0); PG8_BAR; PG8_MMA(0, 0, At, B0); PG8_MMA(0, 1, At, B1); PG8_BAR; PG8_SCHED;
;             PG8_LDA(At, 0, 1); PG8_STAGE(PG8_SB(0, 0), b2, voffB); PG8_STAGE(PG8_SB(0, 1), b2 + hstepB, voffB); PG8_STAGE(PG8_SA(0, 0), a2, voffA);
;             PG8_WAIT_V(8); PG8_WAIT_L(0); PG8_BAR; PG8_MMA(1, 0, At, B0); PG8_MMA(1, 1, At, B1); PG8_BAR; PG8_SCHED;
	s_setprio 1
	v_mfma_f32_16x16x32_bf16 v[126:129], v[146:149], v[186:189], v[126:129]
	v_mfma_f32_16x16x32_bf16 v[122:125], v[160:163], v[186:189], v[122:125]
	v_mfma_f32_16x16x32_bf16 v[110:113], v[146:149], v[194:197], v[110:113]
	v_mfma_f32_16x16x32_bf16 v[106:109], v[160:163], v[194:197], v[106:109]
	v_mfma_f32_16x16x32_bf16 v[94:97], v[146:149], v[202:205], v[94:97]
	v_mfma_f32_16x16x32_bf16 v[90:93], v[160:163], v[202:205], v[90:93]
	v_mfma_f32_16x16x32_bf16 v[78:81], v[146:149], v[210:213], v[78:81]
	v_mfma_f32_16x16x32_bf16 v[74:77], v[160:163], v[210:213], v[74:77]
	v_mfma_f32_16x16x32_bf16 v[126:129], v[156:159], v[190:193], v[126:129]
	v_mfma_f32_16x16x32_bf16 v[122:125], v[164:167], v[190:193], v[122:125]
	v_mfma_f32_16x16x32_bf16 v[110:113], v[156:159], v[198:201], v[110:113]
	v_mfma_f32_16x16x32_bf16 v[106:109], v[164:167], v[198:201], v[106:109]
	v_mfma_f32_16x16x32_bf16 v[94:97], v[156:159], v[206:209], v[94:97]
	v_mfma_f32_16x16x32_bf16 v[90:93], v[164:167], v[206:209], v[90:93]
	v_mfma_f32_16x16x32_bf16 v[78:81], v[156:159], v[214:217], v[78:81]
	v_mfma_f32_16x16x32_bf16 v[74:77], v[164:167], v[214:217], v[74:77]
	v_mfma_f32_16x16x32_bf16 v[118:121], v[168:171], v[186:189], v[118:121]
	v_mfma_f32_16x16x32_bf16 v[114:117], v[176:179], v[186:189], v[114:117]
	v_mfma_f32_16x16x32_bf16 v[102:105], v[168:171], v[194:197], v[102:105]
	v_mfma_f32_16x16x32_bf16 v[98:101], v[176:179], v[194:197], v[98:101]
	v_mfma_f32_16x16x32_bf16 v[86:89], v[168:171], v[202:205], v[86:89]
	v_mfma_f32_16x16x32_bf16 v[82:85], v[176:179], v[202:205], v[82:85]
	v_mfma_f32_16x16x32_bf16 v[70:73], v[168:171], v[210:213], v[70:73]
	v_mfma_f32_16x16x32_bf16 v[66:69], v[176:179], v[210:213], v[66:69]
	v_mfma_f32_16x16x32_bf16 v[118:121], v[172:175], v[190:193], v[118:121]
	v_mfma_f32_16x16x32_bf16 v[114:117], v[180:183], v[190:193], v[114:117]
	v_mfma_f32_16x16x32_bf16 v[102:105], v[172:175], v[198:201], v[102:105]
	v_mfma_f32_16x16x32_bf16 v[98:101], v[180:183], v[198:201], v[98:101]
	v_mfma_f32_16x16x32_bf16 v[86:89], v[172:175], v[206:209], v[86:89]
	v_mfma_f32_16x16x32_bf16 v[82:85], v[180:183], v[206:209], v[82:85]
	v_mfma_f32_16x16x32_bf16 v[70:73], v[172:175], v[214:217], v[70:73]
	v_mfma_f32_16x16x32_bf16 v[66:69], v[180:183], v[214:217], v[66:69]
	s_setprio 0
	s_barrier
	s_add_i32 s67, s61, s52
	v_lshl_add_u64 v[218:219], s[46:47], 0, v[132:133]
	s_mov_b32 m0, s67
	ds_read_b128 v[186:189], v154 offset:16384
	ds_read_b128 v[190:193], v154 offset:17408
	ds_read_b128 v[194:197], v154 offset:18432
	ds_read_b128 v[198:201], v154 offset:19456
	ds_read_b128 v[202:205], v154 offset:20480
	ds_read_b128 v[206:209], v154 offset:21504
	ds_read_b128 v[210:213], v154 offset:22528
	ds_read_b128 v[214:217], v154 offset:23552
	global_load_lds_dwordx4 v[218:219], off
	s_add_i32 m0, s67, 0x2000
	s_add_u32 s68, s46, 0x40000
	v_lshl_add_u64 v[220:221], s[46:47], 0, v[136:137]
	s_addc_u32 s69, s47, 0
	s_add_i32 s67, s62, s52
	global_load_lds_dwordx4 v[220:221], off
	s_mov_b32 m0, s67
	v_lshl_add_u64 v[224:225], s[48:49], 0, v[134:135]
	global_load_lds_dwordx4 v132, s[68:69]
	s_add_i32 m0, s67, 0x2000
	s_nop 0
	global_load_lds_dwordx4 v136, s[68:69]
	v_lshl_add_u64 v[222:223], s[48:49], 0, v[130:131]
	s_mov_b32 m0, s43
	s_nop 0
	global_load_lds_dwordx4 v[222:223], off
	s_mov_b32 m0, s53
	s_nop 0
	global_load_lds_dwordx4 v[224:225], off
	s_waitcnt vmcnt(8)
	s_waitcnt lgkmcnt(0)
	s_barrier
	s_setprio 1
	v_mfma_f32_16x16x32_bf16 v[62:65], v[146:149], v[186:189], v[62:65]
	v_mfma_f32_16x16x32_bf16 v[58:61], v[160:163], v[186:189], v[58:61]
	v_mfma_f32_16x16x32_bf16 v[46:49], v[146:149], v[194:197], v[46:49]
	v_mfma_f32_16x16x32_bf16 v[42:45], v[160:163], v[194:197], v[42:45]
	v_mfma_f32_16x16x32_bf16 v[30:33], v[146:149], v[202:205], v[30:33]
	v_mfma_f32_16x16x32_bf16 v[26:29], v[160:163], v[202:205], v[26:29]
	v_mfma_f32_16x16x32_bf16 v[14:17], v[146:149], v[210:213], v[14:17]
	v_mfma_f32_16x16x32_bf16 v[10:13], v[160:163], v[210:213], v[10:13]
	v_mfma_f32_16x16x32_bf16 v[62:65], v[156:159], v[190:193], v[62:65]
	v_mfma_f32_16x16x32_bf16 v[58:61], v[164:167], v[190:193], v[58:61]
	v_mfma_f32_16x16x32_bf16 v[46:49], v[156:159], v[198:201], v[46:49]
	v_mfma_f32_16x16x32_bf16 v[42:45], v[164:167], v[198:201], v[42:45]
	v_mfma_f32_16x16x32_bf16 v[30:33], v[156:159], v[206:209], v[30:33]
	v_mfma_f32_16x16x32_bf16 v[26:29], v[164:167], v[206:209], v[26:29]
	v_mfma_f32_16x16x32_bf16 v[14:17], v[156:159], v[214:217], v[14:17]
	v_mfma_f32_16x16x32_bf16 v[10:13], v[164:167], v[214:217], v[10:13]
	v_mfma_f32_16x16x32_bf16 v[54:57], v[168:171], v[186:189], v[54:57]
	v_mfma_f32_16x16x32_bf16 v[50:53], v[176:179], v[186:189], v[50:53]
	v_mfma_f32_16x16x32_bf16 v[38:41], v[168:171], v[194:197], v[38:41]
	v_mfma_f32_16x16x32_bf16 v[34:37], v[176:179], v[194:197], v[34:37]
	v_mfma_f32_16x16x32_bf16 v[22:25], v[168:171], v[202:205], v[22:25]
	v_mfma_f32_16x16x32_bf16 v[18:21], v[176:179], v[202:205], v[18:21]
	v_mfma_f32_16x16x32_bf16 v[6:9], v[168:171], v[210:213], v[6:9]
	v_mfma_f32_16x16x32_bf16 v[2:5], v[176:179], v[210:213], v[2:5]
	v_mfma_f32_16x16x32_bf16 v[54:57], v[172:175], v[190:193], v[54:57]
	v_mfma_f32_16x16x32_bf16 v[50:53], v[180:183], v[190:193], v[50:53]
	v_mfma_f32_16x16x32_bf16 v[38:41], v[172:175], v[198:201], v[38:41]
	v_mfma_f32_16x16x32_bf16 v[34:37], v[180:183], v[198:201], v[34:37]
	v_mfma_f32_16x16x32_bf16 v[22:25], v[172:175], v[206:209], v[22:25]
	v_mfma_f32_16x16x32_bf16 v[18:21], v[180:183], v[206:209], v[18:21]
	v_mfma_f32_16x16x32_bf16 v[6:9], v[172:175], v[214:217], v[6:9]
	v_mfma_f32_16x16x32_bf16 v[2:5], v[180:183], v[214:217], v[2:5]
	s_setprio 0
	s_barrier
; #define PG8_STAGE(bufoff, gbase, voff) do { _Pragma("unroll") for (int _i = 0; _i < 2; ++_i) \
;         __builtin_amdgcn_global_load_lds((const unsigned*)((const char*)(gbase) + (voff)[_i]), (LAS unsigned*)(lds + (bufoff) + ldsw + _i * 8192), 16, 0, 0); } while (0)
; #define PG8_LDA(dst, b, h) do { _Pragma("unroll") for (int m = 0; m < 4; ++m) _Pragma("unroll") for (int k = 0; k < 2; ++k) dst[m][k] = *(const LAS bf16x8*)(lds + PG8_SA(b, h) + aoff + m * 2048 + k * 1024); } while (0)
; #define PG8_LDB(dst, b, h) do { _Pragma("unroll") for (int n = 0; n < 2; ++n) _Pragma("unroll") for (int k = 0; k < 2; ++k) dst[n][k] = *(const LAS bf16x8*)(lds + PG8_SB(b, h) + boff + n * 2048 + k * 1024); } while (0)
; #define PG8_MMA(ai, bj, At, Bt) do { __builtin_amdgcn_s_setprio(1); _Pragma("unroll") for (int m = 0; m < 4; ++m) _Pragma("unroll") for (int n = 0; n < 2; ++n) _Pragma("unroll") for (int k = 0; k < 2; ++k) \
;         acc[ai][bj][m][n] = __builtin_amdgcn_mfma_f32_16x16x32_bf16(Bt[n][k], At[m][k], acc[ai][bj][m][n], 0, 0, 0); __builtin_amdgcn_s_setprio(0); } while (0)
; #define PG8_WAIT_V(n) asm volatile("s_waitcnt vmcnt(" #n ")" ::: "memory")
; #define PG8_WAIT_L(n) asm volatile("s_waitcnt lgkmcnt(" #n ")" ::: "memory")
; #define PG8_BAR __builtin_amdgcn_s_barrier()
; #define PG8_SCHED __builtin_amdgcn_sched_barrier(0)
; template <class Epi, class Sched>
; DI void gemm_phase(LAS unsigned char* lds, const Gemm g, const Sched& S, const Epi& E) {
;     ...
;             PG8_LDB(B0, 1, 0); PG8_LDB(B1, 1, 1); PG8_SCHED; PG8_LDA(At, 1, 0); PG8_STAGE(PG8_SA(0, 1), a2 + hstepA, voffA);
;             PG8_WAIT_V(8); PG8_WAIT_L(0); PG8_BAR; PG8_MMA(0, 0, At, B0); PG8_MMA(0, 1, At, B1); PG8_BAR; PG8_SCHED;
;             PG8_LDA(At, 1, 1); PG8_STAGE(PG8_SB(1, 0), b3, voffB); PG8_STAGE(PG8_SB(1, 1), b3 + hstepB, voffB); PG8_STAGE(PG8_SA(1, 0), a3, voffA);
;             PG8_WAIT_V(8); PG8_WAIT_L(0); PG8_BAR; PG8_MMA(1, 0, At, B0); PG8_MMA(1, 1, At, B1); PG8_BAR; PG8_SCHED;
;         }
	s_add_i32 s67, 0, 0x18000
	s_add_i32 s68, 0, 0x1c000
	v_add_u32_e32 v164, s67, v150
	v_add_u32_e32 v180, s68, v150
	ds_read_b128 v[146:149], v164
	ds_read_b128 v[156:159], v164 offset:1024
	ds_read_b128 v[160:163], v164 offset:2048
	ds_read_b128 v[164:167], v164 offset:3072
	ds_read_b128 v[168:171], v180
	ds_read_b128 v[172:175], v180 offset:1024
	ds_read_b128 v[176:179], v180 offset:2048
	ds_read_b128 v[180:183], v180 offset:3072
	s_add_u32 s48, s48, 0x40000
	s_addc_u32 s49, s49, 0
	s_mov_b32 m0, s54
	ds_read_b128 v[186:189], v154 offset:32768
	ds_read_b128 v[190:193], v154 offset:33792
	ds_read_b128 v[194:197], v154 offset:34816
	ds_read_b128 v[198:201], v154 offset:35840
	ds_read_b128 v[202:205], v154 offset:36864
	ds_read_b128 v[206:209], v154 offset:37888
	ds_read_b128 v[210:213], v154 offset:38912
	ds_read_b128 v[214:217], v154 offset:39936
	global_load_lds_dwordx4 v130, s[48:49]
	s_mov_b32 m0, s55
	s_nop 0
	global_load_lds_dwordx4 v134, s[48:49]
	s_waitcnt vmcnt(8)
	s_waitcnt lgkmcnt(0)
	s_barrier
	s_setprio 1
	v_mfma_f32_16x16x32_bf16 v[126:129], v[146:149], v[186:189], v[126:129]
	v_mfma_f32_16x16x32_bf16 v[122:125], v[160:163], v[186:189], v[122:125]
	v_mfma_f32_16x16x32_bf16 v[110:113], v[146:149], v[194:197], v[110:113]
	v_mfma_f32_16x16x32_bf16 v[106:109], v[160:163], v[194:197], v[106:109]
	v_mfma_f32_16x16x32_bf16 v[94:97], v[146:149], v[202:205], v[94:97]
	v_mfma_f32_16x16x32_bf16 v[90:93], v[160:163], v[202:205], v[90:93]
	v_mfma_f32_16x16x32_bf16 v[78:81], v[146:149], v[210:213], v[78:81]
	v_mfma_f32_16x16x32_bf16 v[74:77], v[160:163], v[210:213], v[74:77]
	v_mfma_f32_16x16x32_bf16 v[126:129], v[156:159], v[190:193], v[126:129]
	v_mfma_f32_16x16x32_bf16 v[122:125], v[164:167], v[190:193], v[122:125]
	v_mfma_f32_16x16x32_bf16 v[110:113], v[156:159], v[198:201], v[110:113]
	v_mfma_f32_16x16x32_bf16 v[106:109], v[164:167], v[198:201], v[106:109]
	v_mfma_f32_16x16x32_bf16 v[94:97], v[156:159], v[206:209], v[94:97]
	v_mfma_f32_16x16x32_bf16 v[90:93], v[164:167], v[206:209], v[90:93]
	v_mfma_f32_16x16x32_bf16 v[78:81], v[156:159], v[214:217], v[78:81]
	v_mfma_f32_16x16x32_bf16 v[74:77], v[164:167], v[214:217], v[74:77]
	v_mfma_f32_16x16x32_bf16 v[118:121], v[168:171], v[186:189], v[118:121]
	v_mfma_f32_16x16x32_bf16 v[114:117], v[176:179], v[186:189], v[114:117]
	v_mfma_f32_16x16x32_bf16 v[102:105], v[168:171], v[194:197], v[102:105]
	v_mfma_f32_16x16x32_bf16 v[98:101], v[176:179], v[194:197], v[98:101]
	v_mfma_f32_16x16x32_bf16 v[86:89], v[168:171], v[202:205], v[86:89]
	v_mfma_f32_16x16x32_bf16 v[82:85], v[176:179], v[202:205], v[82:85]
	v_mfma_f32_16x16x32_bf16 v[70:73], v[168:171], v[210:213], v[70:73]
	v_mfma_f32_16x16x32_bf16 v[66:69], v[176:179], v[210:213], v[66:69]
	v_mfma_f32_16x16x32_bf16 v[118:121], v[172:175], v[190:193], v[118:121]
	v_mfma_f32_16x16x32_bf16 v[114:117], v[180:183], v[190:193], v[114:117]
	v_mfma_f32_16x16x32_bf16 v[102:105], v[172:175], v[198:201], v[102:105]
	v_mfma_f32_16x16x32_bf16 v[98:101], v[180:183], v[198:201], v[98:101]
	v_mfma_f32_16x16x32_bf16 v[86:89], v[172:175], v[206:209], v[86:89]
	v_mfma_f32_16x16x32_bf16 v[82:85], v[180:183], v[206:209], v[82:85]
	v_mfma_f32_16x16x32_bf16 v[70:73], v[172:175], v[214:217], v[70:73]
	v_mfma_f32_16x16x32_bf16 v[66:69], v[180:183], v[214:217], v[66:69]
	s_setprio 0
	s_barrier
	s_add_i32 s48, s67, s52
	v_lshl_add_u64 v[218:219], v[218:219], 0, s[16:17]
	s_mov_b32 m0, s48
	ds_read_b128 v[186:189], v154 offset:49152
	ds_read_b128 v[190:193], v154 offset:50176
	ds_read_b128 v[194:197], v154 offset:51200
	ds_read_b128 v[198:201], v154 offset:52224
	ds_read_b128 v[202:205], v154 offset:53248
	ds_read_b128 v[206:209], v154 offset:54272
	ds_read_b128 v[210:213], v154 offset:55296
	ds_read_b128 v[214:217], v154 offset:56320
	global_load_lds_dwordx4 v[218:219], off
	s_add_i32 m0, s48, 0x2000
	s_add_u32 s46, s46, 0x40080
	v_lshl_add_u64 v[218:219], v[220:221], 0, s[16:17]
	s_addc_u32 s47, s47, 0
	s_add_i32 s48, s68, s52
	global_load_lds_dwordx4 v[218:219], off
	s_mov_b32 m0, s48
	s_nop 0
	global_load_lds_dwordx4 v132, s[46:47]
	s_add_i32 m0, s48, 0x2000
	s_nop 0
	global_load_lds_dwordx4 v136, s[46:47]
	v_lshl_add_u64 v[218:219], v[222:223], 0, s[16:17]
	s_mov_b32 m0, s57
	s_nop 0
	global_load_lds_dwordx4 v[218:219], off
	v_lshl_add_u64 v[218:219], v[224:225], 0, s[16:17]
	s_mov_b32 m0, s58
	s_nop 0
	global_load_lds_dwordx4 v[218:219], off
	s_waitcnt vmcnt(8)
	s_waitcnt lgkmcnt(0)
	s_barrier
	s_setprio 1
	v_mfma_f32_16x16x32_bf16 v[62:65], v[146:149], v[186:189], v[62:65]
	v_mfma_f32_16x16x32_bf16 v[58:61], v[160:163], v[186:189], v[58:61]
	v_mfma_f32_16x16x32_bf16 v[46:49], v[146:149], v[194:197], v[46:49]
	v_mfma_f32_16x16x32_bf16 v[42:45], v[160:163], v[194:197], v[42:45]
	v_mfma_f32_16x16x32_bf16 v[30:33], v[146:149], v[202:205], v[30:33]
	v_mfma_f32_16x16x32_bf16 v[26:29], v[160:163], v[202:205], v[26:29]
	v_mfma_f32_16x16x32_bf16 v[14:17], v[146:149], v[210:213], v[14:17]
	v_mfma_f32_16x16x32_bf16 v[10:13], v[160:163], v[210:213], v[10:13]
	v_mfma_f32_16x16x32_bf16 v[62:65], v[156:159], v[190:193], v[62:65]
	v_mfma_f32_16x16x32_bf16 v[58:61], v[164:167], v[190:193], v[58:61]
	v_mfma_f32_16x16x32_bf16 v[46:49], v[156:159], v[198:201], v[46:49]
	v_mfma_f32_16x16x32_bf16 v[42:45], v[164:167], v[198:201], v[42:45]
	v_mfma_f32_16x16x32_bf16 v[30:33], v[156:159], v[206:209], v[30:33]
	v_mfma_f32_16x16x32_bf16 v[26:29], v[164:167], v[206:209], v[26:29]
	v_mfma_f32_16x16x32_bf16 v[14:17], v[156:159], v[214:217], v[14:17]
	v_mfma_f32_16x16x32_bf16 v[10:13], v[164:167], v[214:217], v[10:13]
	v_mfma_f32_16x16x32_bf16 v[54:57], v[168:171], v[186:189], v[54:57]
	v_mfma_f32_16x16x32_bf16 v[50:53], v[176:179], v[186:189], v[50:53]
	v_mfma_f32_16x16x32_bf16 v[38:41], v[168:171], v[194:197], v[38:41]
	v_mfma_f32_16x16x32_bf16 v[34:37], v[176:179], v[194:197], v[34:37]
	v_mfma_f32_16x16x32_bf16 v[22:25], v[168:171], v[202:205], v[22:25]
	v_mfma_f32_16x16x32_bf16 v[18:21], v[176:179], v[202:205], v[18:21]
	v_mfma_f32_16x16x32_bf16 v[6:9], v[168:171], v[210:213], v[6:9]
	v_mfma_f32_16x16x32_bf16 v[2:5], v[176:179], v[210:213], v[2:5]
	v_mfma_f32_16x16x32_bf16 v[54:57], v[172:175], v[190:193], v[54:57]
	v_mfma_f32_16x16x32_bf16 v[50:53], v[180:183], v[190:193], v[50:53]
	v_mfma_f32_16x16x32_bf16 v[38:41], v[172:175], v[198:201], v[38:41]
	v_mfma_f32_16x16x32_bf16 v[34:37], v[180:183], v[198:201], v[34:37]
	v_mfma_f32_16x16x32_bf16 v[22:25], v[172:175], v[206:209], v[22:25]
	v_mfma_f32_16x16x32_bf16 v[18:21], v[180:183], v[206:209], v[18:21]
	v_mfma_f32_16x16x32_bf16 v[6:9], v[172:175], v[214:217], v[6:9]
	v_mfma_f32_16x16x32_bf16 v[2:5], v[180:183], v[214:217], v[2:5]
	s_setprio 0
	s_barrier
	s_add_i32 s66, s66, 2
	s_add_u32 s44, s44, 0x100
	s_addc_u32 s45, s45, 0
	s_add_u32 s64, s64, 0x100
	s_addc_u32 s65, s65, 0
	s_cmp_gt_u32 s66, 13
	s_cbranch_scc0 .LBB0_1133
	s_mov_b32 s99, 1
	s_and_b64 vcc, exec, s[18:19]
	s_cbranch_vccz .LBB0_1136
	s_barrier

; #define PG8_STAGE(bufoff, gbase, voff) do { _Pragma("unroll") for (int _i = 0; _i < 2; ++_i) \
;         __builtin_amdgcn_global_load_lds((const unsigned*)((const char*)(gbase) + (voff)[_i]), (LAS unsigned*)(lds + (bufoff) + ldsw + _i * 8192), 16, 0, 0); } while (0)
; #define PG8_LDA(dst, b, h) do { _Pragma("unroll") for (int m = 0; m < 4; ++m) _Pragma("unroll") for (int k = 0; k < 2; ++k) dst[m][k] = *(const LAS bf16x8*)(lds + PG8_SA(b, h) + aoff + m * 2048 + k * 1024); } while (0)
; #define PG8_LDB(dst, b, h) do { _Pragma("unroll") for (int n = 0; n < 2; ++n) _Pragma("unroll") for (int k = 0; k < 2; ++k) dst[n][k] = *(const LAS bf16x8*)(lds + PG8_SB(b, h) + boff + n * 2048 + k * 1024); } while (0)
; #define PG8_WAIT_V(n) asm volatile("s_waitcnt vmcnt(" #n ")" ::: "memory")
; #define PG8_WAIT_L(n) asm volatile("s_waitcnt lgkmcnt(" #n ")" ::: "memory")
; #define PG8_BAR __builtin_amdgcn_s_barrier()
; #define PG8_SCHED __builtin_amdgcn_sched_barrier(0)
; template <class Epi, class Sched>
; DI void gemm_phase(LAS unsigned char* lds, const Gemm g, const Sched& S, const Epi& E) {
;     ...
;         const char* nA = has_next ? (const char*)(nxt.src ? g.A1 : g.A0) + (size_t)nxt.pm * tstepA : cA; const char* nB = has_next ? (const char*)(nxt.src ? g.B1 : g.B0) + (size_t)nxt.pn * tstepB : cB;
;         for (int t = 0; t < nt; t += 2) {
;             const bool last = (t == nt - 2);
;             const char* a1 = cA + (size_t)(t + 1) * kstep;
;             const char* a2 = last ? nA : cA + (size_t)(t + 2) * kstep; const char* b2 = last ? nB : cB + (size_t)(t + 2) * kstep;
;             const char* a3 = a2 + kstep; const char* b3 = b2 + kstep;
;             PG8_LDB(B0, 0, 0); PG8_LDB(B1, 0, 1); PG8_SCHED; PG8_LDA(At, 0, 0); PG8_STAGE(PG8_SA(1, 1), a1 + hstepA, voffA);
;             PG8_WAIT_V(8); PG8_WAIT_L(0); PG8_BAR; PG8_MMA(0, 0, At, B0); PG8_MMA(0, 1, At, B1); PG8_BAR; PG8_SCHED;
;             PG8_LDA(At, 0, 1); PG8_STAGE(PG8_SB(0, 0), b2, voffB); PG8_STAGE(PG8_SB(0, 1), b2 + hstepB, voffB); PG8_STAGE(PG8_SA(0, 0), a2, voffA);
; DI void load_rows(PreRows& pr, const float* ssq, const pg8::Unit& u, int wr, int fr) {
; #pragma unroll
;     for (int ai = 0; ai < 2; ++ai)
; #pragma unroll
;         for (int m = 0; m < 4; ++m) pr.v[ai * 4 + m] = ssq[u.pm * 256 + ai * 128 + wr * 64 + m * 16 + fr];
; }
.LBB0_1233:
	v_lshl_add_u32 v154, s44, 8, v1
	v_ashrrev_i32_e32 v155, 31, v154
	v_add_u32_e32 v152, 0x80, v154
	v_add_u32_e32 v150, 0x90, v154
	v_add_u32_e32 v148, 0xa0, v154
	v_add_u32_e32 v146, 0xb0, v154
	v_lshl_add_u64 v[2:3], v[154:155], 2, s[8:9]
	v_ashrrev_i32_e32 v153, 31, v152
	v_ashrrev_i32_e32 v151, 31, v150
	v_ashrrev_i32_e32 v149, 31, v148
	v_ashrrev_i32_e32 v147, 31, v146
	v_lshl_add_u64 v[4:5], v[152:153], 2, s[8:9]
	v_lshl_add_u64 v[6:7], v[150:151], 2, s[8:9]
	v_lshl_add_u64 v[8:9], v[148:149], 2, s[8:9]
	v_lshl_add_u64 v[10:11], v[146:147], 2, s[8:9]
	global_load_dword v164, v[2:3], off
	global_load_dword v163, v[2:3], off offset:64
	global_load_dword v162, v[2:3], off offset:128
	global_load_dword v155, v[2:3], off offset:192
	global_load_dword v153, v[4:5], off
	global_load_dword v151, v[6:7], off
	global_load_dword v149, v[8:9], off
	global_load_dword v147, v[10:11], off
	s_ashr_i32 s35, s34, 31
	s_lshl_b64 s[36:37], s[34:35], 19
	s_add_u32 s36, s30, s36
	s_addc_u32 s37, s31, s37
	s_and_b64 s[38:39], s[4:5], exec
	s_cselect_b32 s35, s37, s41
	s_cselect_b32 s61, s36, s40
	s_ashr_i32 s21, s20, 31
	s_lshl_b64 s[38:39], s[20:21], 19
	s_add_u32 s38, s28, s38
	s_addc_u32 s39, s29, s39
	s_and_b64 s[44:45], s[4:5], exec
	s_cselect_b32 s21, s39, s43
	s_cselect_b32 s62, s38, s42
	s_add_u32 s40, s40, 0x40080
	s_addc_u32 s41, s41, 0
	s_add_u32 s63, s42, 0x100
	s_addc_u32 s64, s43, 0
	s_mov_b32 s65, -2
	ds_read_b128 v[166:169], v160
	ds_read_b128 v[170:173], v160 offset:1024
	ds_read_b128 v[174:177], v160 offset:2048
	ds_read_b128 v[178:181], v160 offset:3072
	ds_read_b128 v[186:189], v161
	ds_read_b128 v[190:193], v161 offset:1024
	ds_read_b128 v[194:197], v161 offset:2048
	ds_read_b128 v[198:201], v161 offset:3072
	s_add_u32 s42, s40, 0xfffc0080
	s_addc_u32 s43, s41, -1
	s_cmp_eq_u32 s65, 12
	s_cselect_b32 s45, s35, s43
	s_cselect_b32 s44, s61, s42
	s_cselect_b32 s43, s21, s64
	s_cselect_b32 s42, s62, s63
	s_add_i32 m0, s49, 0xc000
	ds_read_b128 v[202:205], v158
	ds_read_b128 v[206:209], v158 offset:1024
	ds_read_b128 v[210:213], v158 offset:2048
	ds_read_b128 v[214:217], v158 offset:3072
	ds_read_b128 v[218:221], v158 offset:4096
	ds_read_b128 v[222:225], v158 offset:5120
	ds_read_b128 v[226:229], v158 offset:6144
	ds_read_b128 v[230:233], v158 offset:7168
	global_load_lds_dwordx4 v138, s[40:41]
	s_add_i32 m0, s49, 0xe000
	s_nop 0
	global_load_lds_dwordx4 v140, s[40:41]
	s_cmp_lg_u32 s99, 0
	s_cbranch_scc1 .Lpk5_w1
	s_waitcnt vmcnt(8)
.Lpk5_w1:
	s_waitcnt lgkmcnt(0)
	s_barrier
	s_setprio 1
	v_mfma_f32_16x16x32_bf16 v[126:129], v[166:169], v[202:205], 0
	v_mfma_f32_16x16x32_bf16 v[118:121], v[174:177], v[202:205], 0
	v_mfma_f32_16x16x32_bf16 v[110:113], v[166:169], v[210:213], 0
	v_mfma_f32_16x16x32_bf16 v[102:105], v[174:177], v[210:213], 0
	v_mfma_f32_16x16x32_bf16 v[94:97], v[166:169], v[218:221], 0
	v_mfma_f32_16x16x32_bf16 v[86:89], v[174:177], v[218:221], 0
	v_mfma_f32_16x16x32_bf16 v[78:81], v[166:169], v[226:229], 0
	v_mfma_f32_16x16x32_bf16 v[70:73], v[174:177], v[226:229], 0
	v_mfma_f32_16x16x32_bf16 v[126:129], v[170:173], v[206:209], v[126:129]
	v_mfma_f32_16x16x32_bf16 v[118:121], v[178:181], v[206:209], v[118:121]
	v_mfma_f32_16x16x32_bf16 v[110:113], v[170:173], v[214:217], v[110:113]
	v_mfma_f32_16x16x32_bf16 v[102:105], v[178:181], v[214:217], v[102:105]
	v_mfma_f32_16x16x32_bf16 v[94:97], v[170:173], v[222:225], v[94:97]
	v_mfma_f32_16x16x32_bf16 v[86:89], v[178:181], v[222:225], v[86:89]
	v_mfma_f32_16x16x32_bf16 v[78:81], v[170:173], v[230:233], v[78:81]
	v_mfma_f32_16x16x32_bf16 v[70:73], v[178:181], v[230:233], v[70:73]
	v_mfma_f32_16x16x32_bf16 v[122:125], v[186:189], v[202:205], 0
	v_mfma_f32_16x16x32_bf16 v[114:117], v[194:197], v[202:205], 0
	v_mfma_f32_16x16x32_bf16 v[106:109], v[186:189], v[210:213], 0
	v_mfma_f32_16x16x32_bf16 v[98:101], v[194:197], v[210:213], 0
	v_mfma_f32_16x16x32_bf16 v[90:93], v[186:189], v[218:221], 0
	v_mfma_f32_16x16x32_bf16 v[82:85], v[194:197], v[218:221], 0
	v_mfma_f32_16x16x32_bf16 v[74:77], v[186:189], v[226:229], 0
	v_mfma_f32_16x16x32_bf16 v[66:69], v[194:197], v[226:229], 0
	v_mfma_f32_16x16x32_bf16 v[122:125], v[190:193], v[206:209], v[122:125]
	v_mfma_f32_16x16x32_bf16 v[114:117], v[198:201], v[206:209], v[114:117]
	v_mfma_f32_16x16x32_bf16 v[106:109], v[190:193], v[214:217], v[106:109]
	v_mfma_f32_16x16x32_bf16 v[98:101], v[198:201], v[214:217], v[98:101]
	v_mfma_f32_16x16x32_bf16 v[90:93], v[190:193], v[222:225], v[90:93]
	v_mfma_f32_16x16x32_bf16 v[82:85], v[198:201], v[222:225], v[82:85]
	v_mfma_f32_16x16x32_bf16 v[74:77], v[190:193], v[230:233], v[74:77]
	v_mfma_f32_16x16x32_bf16 v[66:69], v[198:201], v[230:233], v[66:69]
	s_setprio 0
	s_barrier
	s_add_i32 s66, s57, s46
	v_lshl_add_u64 v[182:183], s[42:43], 0, v[134:135]
	s_mov_b32 m0, s66
	ds_read_b128 v[202:205], v158 offset:16384
	ds_read_b128 v[206:209], v158 offset:17408
	ds_read_b128 v[210:213], v158 offset:18432
	ds_read_b128 v[214:217], v158 offset:19456
	ds_read_b128 v[218:221], v158 offset:20480
	ds_read_b128 v[222:225], v158 offset:21504
	ds_read_b128 v[226:229], v158 offset:22528
	ds_read_b128 v[230:233], v158 offset:23552
	global_load_lds_dwordx4 v[182:183], off
	s_add_i32 m0, s66, 0x2000
	s_add_u32 s66, s42, 0x40000
	v_lshl_add_u64 v[234:235], s[42:43], 0, v[130:131]
	s_addc_u32 s67, s43, 0
	s_add_i32 s68, s58, s46
	global_load_lds_dwordx4 v[234:235], off
	s_mov_b32 m0, s68
	v_lshl_add_u64 v[238:239], s[44:45], 0, v[132:133]
	global_load_lds_dwordx4 v134, s[66:67]
	s_add_i32 m0, s68, 0x2000
	s_nop 0
	global_load_lds_dwordx4 v130, s[66:67]
	v_lshl_add_u64 v[236:237], s[44:45], 0, v[136:137]
	s_mov_b32 m0, s49
	s_nop 0
	global_load_lds_dwordx4 v[236:237], off
	s_mov_b32 m0, s50
	s_nop 0
	global_load_lds_dwordx4 v[238:239], off
	s_cmp_lg_u32 s99, 0
	s_cbranch_scc1 .Lpk5_w2
	s_waitcnt vmcnt(8)
; #define PG8_STAGE(bufoff, gbase, voff) do { _Pragma("unroll") for (int _i = 0; _i < 2; ++_i) \
;         __builtin_amdgcn_global_load_lds((const unsigned*)((const char*)(gbase) + (voff)[_i]), (LAS unsigned*)(lds + (bufoff) + ldsw + _i * 8192), 16, 0, 0); } while (0)
; #define PG8_LDA(dst, b, h) do { _Pragma("unroll") for (int m = 0; m < 4; ++m) _Pragma("unroll") for (int k = 0; k < 2; ++k) dst[m][k] = *(const LAS bf16x8*)(lds + PG8_SA(b, h) + aoff + m * 2048 + k * 1024); } while (0)
; #define PG8_LDB(dst, b, h) do { _Pragma("unroll") for (int n = 0; n < 2; ++n) _Pragma("unroll") for (int k = 0; k < 2; ++k) dst[n][k] = *(const LAS bf16x8*)(lds + PG8_SB(b, h) + boff + n * 2048 + k * 1024); } while (0)
; #define PG8_MMA(ai, bj, At, Bt) do { __builtin_amdgcn_s_setprio(1); _Pragma("unroll") for (int m = 0; m < 4; ++m) _Pragma("unroll") for (int n = 0; n < 2; ++n) _Pragma("unroll") for (int k = 0; k < 2; ++k) \
;         acc[ai][bj][m][n] = __builtin_amdgcn_mfma_f32_16x16x32_bf16(Bt[n][k], At[m][k], acc[ai][bj][m][n], 0, 0, 0); __builtin_amdgcn_s_setprio(0); } while (0)
; #define PG8_WAIT_V(n) asm volatile("s_waitcnt vmcnt(" #n ")" ::: "memory")
; #define PG8_WAIT_L(n) asm volatile("s_waitcnt lgkmcnt(" #n ")" ::: "memory")
; #define PG8_BAR __builtin_amdgcn_s_barrier()
; #define PG8_SCHED __builtin_amdgcn_sched_barrier(0)
; template <class Epi, class Sched>
; DI void gemm_phase(LAS unsigned char* lds, const Gemm g, const Sched& S, const Epi& E) {
;     ...
;             PG8_WAIT_V(8); PG8_WAIT_L(0); PG8_BAR; PG8_MMA(1, 0, At, B0); PG8_MMA(1, 1, At, B1); PG8_BAR; PG8_SCHED;
;             PG8_LDB(B0, 1, 0); PG8_LDB(B1, 1, 1); PG8_SCHED; PG8_LDA(At, 1, 0); PG8_STAGE(PG8_SA(0, 1), a2 + hstepA, voffA);
;             PG8_WAIT_V(8); PG8_WAIT_L(0); PG8_BAR; PG8_MMA(0, 0, At, B0); PG8_MMA(0, 1, At, B1); PG8_BAR; PG8_SCHED;
.Lpk5_w2:
	s_mov_b32 s99, 0
	s_waitcnt lgkmcnt(0)
	s_barrier
	s_setprio 1
	v_mfma_f32_16x16x32_bf16 v[62:65], v[166:169], v[202:205], 0
	v_mfma_f32_16x16x32_bf16 v[54:57], v[174:177], v[202:205], 0
	v_mfma_f32_16x16x32_bf16 v[46:49], v[166:169], v[210:213], 0
	v_mfma_f32_16x16x32_bf16 v[38:41], v[174:177], v[210:213], 0
	v_mfma_f32_16x16x32_bf16 v[30:33], v[166:169], v[218:221], 0
	v_mfma_f32_16x16x32_bf16 v[22:25], v[174:177], v[218:221], 0
	v_mfma_f32_16x16x32_bf16 v[14:17], v[166:169], v[226:229], 0
	v_mfma_f32_16x16x32_bf16 v[6:9], v[174:177], v[226:229], 0
	v_mfma_f32_16x16x32_bf16 v[62:65], v[170:173], v[206:209], v[62:65]
	v_mfma_f32_16x16x32_bf16 v[54:57], v[178:181], v[206:209], v[54:57]
	v_mfma_f32_16x16x32_bf16 v[46:49], v[170:173], v[214:217], v[46:49]
	v_mfma_f32_16x16x32_bf16 v[38:41], v[178:181], v[214:217], v[38:41]
	v_mfma_f32_16x16x32_bf16 v[30:33], v[170:173], v[222:225], v[30:33]
	v_mfma_f32_16x16x32_bf16 v[22:25], v[178:181], v[222:225], v[22:25]
	v_mfma_f32_16x16x32_bf16 v[14:17], v[170:173], v[230:233], v[14:17]
	v_mfma_f32_16x16x32_bf16 v[6:9], v[178:181], v[230:233], v[6:9]
	v_mfma_f32_16x16x32_bf16 v[58:61], v[186:189], v[202:205], 0
	v_mfma_f32_16x16x32_bf16 v[50:53], v[194:197], v[202:205], 0
	v_mfma_f32_16x16x32_bf16 v[42:45], v[186:189], v[210:213], 0
	v_mfma_f32_16x16x32_bf16 v[34:37], v[194:197], v[210:213], 0
	v_mfma_f32_16x16x32_bf16 v[26:29], v[186:189], v[218:221], 0
	v_mfma_f32_16x16x32_bf16 v[18:21], v[194:197], v[218:221], 0
	v_mfma_f32_16x16x32_bf16 v[10:13], v[186:189], v[226:229], 0
	v_mfma_f32_16x16x32_bf16 v[2:5], v[194:197], v[226:229], 0
	v_mfma_f32_16x16x32_bf16 v[58:61], v[190:193], v[206:209], v[58:61]
	v_mfma_f32_16x16x32_bf16 v[50:53], v[198:201], v[206:209], v[50:53]
	v_mfma_f32_16x16x32_bf16 v[42:45], v[190:193], v[214:217], v[42:45]
	v_mfma_f32_16x16x32_bf16 v[34:37], v[198:201], v[214:217], v[34:37]
	v_mfma_f32_16x16x32_bf16 v[26:29], v[190:193], v[222:225], v[26:29]
	v_mfma_f32_16x16x32_bf16 v[18:21], v[198:201], v[222:225], v[18:21]
	v_mfma_f32_16x16x32_bf16 v[10:13], v[190:193], v[230:233], v[10:13]
	v_mfma_f32_16x16x32_bf16 v[2:5], v[198:201], v[230:233], v[2:5]
	s_setprio 0
	s_barrier
	s_add_i32 s66, 0, 0x18000
	v_add_u32_e32 v165, s66, v156
	s_add_i32 s67, 0, 0x1c000
	ds_read_b128 v[166:169], v165
	ds_read_b128 v[170:173], v165 offset:1024
	ds_read_b128 v[174:177], v165 offset:2048
	ds_read_b128 v[178:181], v165 offset:3072
	v_add_u32_e32 v165, s67, v156
	ds_read_b128 v[186:189], v165
	ds_read_b128 v[190:193], v165 offset:1024
	ds_read_b128 v[194:197], v165 offset:2048
	ds_read_b128 v[198:201], v165 offset:3072
	s_add_u32 s44, s44, 0x40000
	s_addc_u32 s45, s45, 0
	s_mov_b32 m0, s51
	ds_read_b128 v[202:205], v158 offset:32768
	ds_read_b128 v[206:209], v158 offset:33792
	ds_read_b128 v[210:213], v158 offset:34816
	ds_read_b128 v[214:217], v158 offset:35840
	ds_read_b128 v[218:221], v158 offset:36864
	ds_read_b128 v[222:225], v158 offset:37888
	ds_read_b128 v[226:229], v158 offset:38912
	ds_read_b128 v[230:233], v158 offset:39936
	global_load_lds_dwordx4 v136, s[44:45]
	s_mov_b32 m0, s52
	s_nop 0
	global_load_lds_dwordx4 v132, s[44:45]
	s_waitcnt vmcnt(8)
	s_waitcnt lgkmcnt(0)
	s_barrier
	s_setprio 1
	v_mfma_f32_16x16x32_bf16 v[126:129], v[166:169], v[202:205], v[126:129]
	v_mfma_f32_16x16x32_bf16 v[118:121], v[174:177], v[202:205], v[118:121]
	v_mfma_f32_16x16x32_bf16 v[110:113], v[166:169], v[210:213], v[110:113]
	v_mfma_f32_16x16x32_bf16 v[102:105], v[174:177], v[210:213], v[102:105]
	v_mfma_f32_16x16x32_bf16 v[94:97], v[166:169], v[218:221], v[94:97]
	v_mfma_f32_16x16x32_bf16 v[86:89], v[174:177], v[218:221], v[86:89]
	v_mfma_f32_16x16x32_bf16 v[78:81], v[166:169], v[226:229], v[78:81]
	v_mfma_f32_16x16x32_bf16 v[70:73], v[174:177], v[226:229], v[70:73]
	v_mfma_f32_16x16x32_bf16 v[126:129], v[170:173], v[206:209], v[126:129]
	v_mfma_f32_16x16x32_bf16 v[118:121], v[178:181], v[206:209], v[118:121]
	v_mfma_f32_16x16x32_bf16 v[110:113], v[170:173], v[214:217], v[110:113]
	v_mfma_f32_16x16x32_bf16 v[102:105], v[178:181], v[214:217], v[102:105]
	v_mfma_f32_16x16x32_bf16 v[94:97], v[170:173], v[222:225], v[94:97]
	v_mfma_f32_16x16x32_bf16 v[86:89], v[178:181], v[222:225], v[86:89]
	v_mfma_f32_16x16x32_bf16 v[78:81], v[170:173], v[230:233], v[78:81]
	v_mfma_f32_16x16x32_bf16 v[70:73], v[178:181], v[230:233], v[70:73]
	v_mfma_f32_16x16x32_bf16 v[122:125], v[186:189], v[202:205], v[122:125]
	v_mfma_f32_16x16x32_bf16 v[114:117], v[194:197], v[202:205], v[114:117]
	v_mfma_f32_16x16x32_bf16 v[106:109], v[186:189], v[210:213], v[106:109]
	v_mfma_f32_16x16x32_bf16 v[98:101], v[194:197], v[210:213], v[98:101]
	v_mfma_f32_16x16x32_bf16 v[90:93], v[186:189], v[218:221], v[90:93]
	v_mfma_f32_16x16x32_bf16 v[82:85], v[194:197], v[218:221], v[82:85]
	v_mfma_f32_16x16x32_bf16 v[74:77], v[186:189], v[226:229], v[74:77]
	v_mfma_f32_16x16x32_bf16 v[66:69], v[194:197], v[226:229], v[66:69]
	v_mfma_f32_16x16x32_bf16 v[122:125], v[190:193], v[206:209], v[122:125]
	v_mfma_f32_16x16x32_bf16 v[114:117], v[198:201], v[206:209], v[114:117]
	v_mfma_f32_16x16x32_bf16 v[106:109], v[190:193], v[214:217], v[106:109]
	v_mfma_f32_16x16x32_bf16 v[98:101], v[198:201], v[214:217], v[98:101]
	v_mfma_f32_16x16x32_bf16 v[90:93], v[190:193], v[222:225], v[90:93]
	v_mfma_f32_16x16x32_bf16 v[82:85], v[198:201], v[222:225], v[82:85]
	v_mfma_f32_16x16x32_bf16 v[74:77], v[190:193], v[230:233], v[74:77]
	v_mfma_f32_16x16x32_bf16 v[66:69], v[198:201], v[230:233], v[66:69]
	s_setprio 0
	s_barrier
; #define PG8_STAGE(bufoff, gbase, voff) do { _Pragma("unroll") for (int _i = 0; _i < 2; ++_i) \
;         __builtin_amdgcn_global_load_lds((const unsigned*)((const char*)(gbase) + (voff)[_i]), (LAS unsigned*)(lds + (bufoff) + ldsw + _i * 8192), 16, 0, 0); } while (0)
; #define PG8_LDA(dst, b, h) do { _Pragma("unroll") for (int m = 0; m < 4; ++m) _Pragma("unroll") for (int k = 0; k < 2; ++k) dst[m][k] = *(const LAS bf16x8*)(lds + PG8_SA(b, h) + aoff + m * 2048 + k * 1024); } while (0)
; #define PG8_LDB(dst, b, h) do { _Pragma("unroll") for (int n = 0; n < 2; ++n) _Pragma("unroll") for (int k = 0; k < 2; ++k) dst[n][k] = *(const LAS bf16x8*)(lds + PG8_SB(b, h) + boff + n * 2048 + k * 1024); } while (0)
; #define PG8_MMA(ai, bj, At, Bt) do { __builtin_amdgcn_s_setprio(1); _Pragma("unroll") for (int m = 0; m < 4; ++m) _Pragma("unroll") for (int n = 0; n < 2; ++n) _Pragma("unroll") for (int k = 0; k < 2; ++k) \
;         acc[ai][bj][m][n] = __builtin_amdgcn_mfma_f32_16x16x32_bf16(Bt[n][k], At[m][k], acc[ai][bj][m][n], 0, 0, 0); __builtin_amdgcn_s_setprio(0); } while (0)
; #define PG8_WAIT_V(n) asm volatile("s_waitcnt vmcnt(" #n ")" ::: "memory")
; #define PG8_WAIT_L(n) asm volatile("s_waitcnt lgkmcnt(" #n ")" ::: "memory")
; template <class Epi, class Sched>
; DI void gemm_phase(LAS unsigned char* lds, const Gemm g, const Sched& S, const Epi& E) {
;     ...
;             PG8_LDB(B0, 0, 0); PG8_LDB(B1, 0, 1); PG8_SCHED; PG8_LDA(At, 0, 0); PG8_STAGE(PG8_SA(1, 1), a1 + hstepA, voffA);
;             PG8_WAIT_V(8); PG8_WAIT_L(0); PG8_BAR; PG8_MMA(0, 0, At, B0); PG8_MMA(0, 1, At, B1); PG8_BAR; PG8_SCHED;
;             PG8_LDA(At, 0, 1); PG8_STAGE(PG8_SB(0, 0), b2, voffB); PG8_STAGE(PG8_SB(0, 1), b2 + hstepB, voffB); PG8_STAGE(PG8_SA(0, 0), a2, voffA);
;             PG8_WAIT_V(8); PG8_WAIT_L(0); PG8_BAR; PG8_MMA(1, 0, At, B0); PG8_MMA(1, 1, At, B1); PG8_BAR; PG8_SCHED;
;             PG8_LDB(B0, 1, 0); PG8_LDB(B1, 1, 1); PG8_SCHED; PG8_LDA(At, 1, 0); PG8_STAGE(PG8_SA(0, 1), a2 + hstepA, voffA);
;             PG8_WAIT_V(8); PG8_WAIT_L(0); PG8_BAR; PG8_MMA(0, 0, At, B0); PG8_MMA(0, 1, At, B1); PG8_BAR; PG8_SCHED;
;             PG8_LDA(At, 1, 1); PG8_STAGE(PG8_SB(1, 0), b3, voffB); PG8_STAGE(PG8_SB(1, 1), b3 + hstepB, voffB); PG8_STAGE(PG8_SA(1, 0), a3, voffA);
;             PG8_WAIT_V(8); PG8_WAIT_L(0); PG8_BAR; PG8_MMA(1, 0, At, B0); PG8_MMA(1, 1, At, B1); PG8_BAR; PG8_SCHED;
	s_add_i32 s44, s66, s46
	v_lshl_add_u64 v[182:183], v[182:183], 0, s[16:17]
	s_mov_b32 m0, s44
	ds_read_b128 v[202:205], v158 offset:49152
	ds_read_b128 v[206:209], v158 offset:50176
	ds_read_b128 v[210:213], v158 offset:51200
	ds_read_b128 v[214:217], v158 offset:52224
	ds_read_b128 v[218:221], v158 offset:53248
	ds_read_b128 v[222:225], v158 offset:54272
	ds_read_b128 v[226:229], v158 offset:55296
	ds_read_b128 v[230:233], v158 offset:56320
	global_load_lds_dwordx4 v[182:183], off
	s_add_i32 m0, s44, 0x2000
	s_add_u32 s42, s42, 0x40080
	v_lshl_add_u64 v[182:183], v[234:235], 0, s[16:17]
	s_addc_u32 s43, s43, 0
	s_add_i32 s44, s67, s46
	global_load_lds_dwordx4 v[182:183], off
	s_mov_b32 m0, s44
	s_nop 0
	global_load_lds_dwordx4 v134, s[42:43]
	s_add_i32 m0, s44, 0x2000
	s_nop 0
	global_load_lds_dwordx4 v130, s[42:43]
	v_lshl_add_u64 v[182:183], v[236:237], 0, s[16:17]
	s_mov_b32 m0, s54
	s_nop 0
	global_load_lds_dwordx4 v[182:183], off
	v_lshl_add_u64 v[182:183], v[238:239], 0, s[16:17]
	s_mov_b32 m0, s55
	s_nop 0
	global_load_lds_dwordx4 v[182:183], off
	s_waitcnt vmcnt(8)
	s_waitcnt lgkmcnt(0)
	s_barrier
	s_setprio 1
	v_mfma_f32_16x16x32_bf16 v[62:65], v[166:169], v[202:205], v[62:65]
	v_mfma_f32_16x16x32_bf16 v[54:57], v[174:177], v[202:205], v[54:57]
	v_mfma_f32_16x16x32_bf16 v[46:49], v[166:169], v[210:213], v[46:49]
	v_mfma_f32_16x16x32_bf16 v[38:41], v[174:177], v[210:213], v[38:41]
	v_mfma_f32_16x16x32_bf16 v[30:33], v[166:169], v[218:221], v[30:33]
	v_mfma_f32_16x16x32_bf16 v[22:25], v[174:177], v[218:221], v[22:25]
	v_mfma_f32_16x16x32_bf16 v[14:17], v[166:169], v[226:229], v[14:17]
	v_mfma_f32_16x16x32_bf16 v[6:9], v[174:177], v[226:229], v[6:9]
	v_mfma_f32_16x16x32_bf16 v[62:65], v[170:173], v[206:209], v[62:65]
	v_mfma_f32_16x16x32_bf16 v[54:57], v[178:181], v[206:209], v[54:57]
	v_mfma_f32_16x16x32_bf16 v[46:49], v[170:173], v[214:217], v[46:49]
	v_mfma_f32_16x16x32_bf16 v[38:41], v[178:181], v[214:217], v[38:41]
	v_mfma_f32_16x16x32_bf16 v[30:33], v[170:173], v[222:225], v[30:33]
	v_mfma_f32_16x16x32_bf16 v[22:25], v[178:181], v[222:225], v[22:25]
	v_mfma_f32_16x16x32_bf16 v[14:17], v[170:173], v[230:233], v[14:17]
	v_mfma_f32_16x16x32_bf16 v[6:9], v[178:181], v[230:233], v[6:9]
	v_mfma_f32_16x16x32_bf16 v[58:61], v[186:189], v[202:205], v[58:61]
	v_mfma_f32_16x16x32_bf16 v[50:53], v[194:197], v[202:205], v[50:53]
	v_mfma_f32_16x16x32_bf16 v[42:45], v[186:189], v[210:213], v[42:45]
	v_mfma_f32_16x16x32_bf16 v[34:37], v[194:197], v[210:213], v[34:37]
	v_mfma_f32_16x16x32_bf16 v[26:29], v[186:189], v[218:221], v[26:29]
	v_mfma_f32_16x16x32_bf16 v[18:21], v[194:197], v[218:221], v[18:21]
	v_mfma_f32_16x16x32_bf16 v[10:13], v[186:189], v[226:229], v[10:13]
	v_mfma_f32_16x16x32_bf16 v[2:5], v[194:197], v[226:229], v[2:5]
	v_mfma_f32_16x16x32_bf16 v[58:61], v[190:193], v[206:209], v[58:61]
	v_mfma_f32_16x16x32_bf16 v[50:53], v[198:201], v[206:209], v[50:53]
	v_mfma_f32_16x16x32_bf16 v[42:45], v[190:193], v[214:217], v[42:45]
	v_mfma_f32_16x16x32_bf16 v[34:37], v[198:201], v[214:217], v[34:37]
	v_mfma_f32_16x16x32_bf16 v[26:29], v[190:193], v[222:225], v[26:29]
	v_mfma_f32_16x16x32_bf16 v[18:21], v[198:201], v[222:225], v[18:21]
	v_mfma_f32_16x16x32_bf16 v[10:13], v[190:193], v[230:233], v[10:13]
	v_mfma_f32_16x16x32_bf16 v[2:5], v[198:201], v[230:233], v[2:5]
	s_setprio 0
	s_barrier
	s_add_i32 s65, s65, 2
	s_add_u32 s40, s40, 0x100
	s_addc_u32 s41, s41, 0
	s_add_u32 s63, s63, 0x100
	s_addc_u32 s64, s64, 0
	s_cmp_gt_u32 s65, 13
.LBB0_1234:
	ds_read_b128 v[166:169], v160
	ds_read_b128 v[170:173], v160 offset:1024
	ds_read_b128 v[174:177], v160 offset:2048
	ds_read_b128 v[178:181], v160 offset:3072
	ds_read_b128 v[186:189], v161
	ds_read_b128 v[190:193], v161 offset:1024
	ds_read_b128 v[194:197], v161 offset:2048
	ds_read_b128 v[198:201], v161 offset:3072
	s_add_u32 s42, s40, 0xfffc0080
	s_addc_u32 s43, s41, -1
	s_cmp_eq_u32 s65, 12
	s_cselect_b32 s45, s35, s43
	s_cselect_b32 s44, s61, s42
	s_cselect_b32 s43, s21, s64
	s_cselect_b32 s42, s62, s63
	s_add_i32 m0, s49, 0xc000
	ds_read_b128 v[202:205], v158
	ds_read_b128 v[206:209], v158 offset:1024
	ds_read_b128 v[210:213], v158 offset:2048
	ds_read_b128 v[214:217], v158 offset:3072
	ds_read_b128 v[218:221], v158 offset:4096
	ds_read_b128 v[222:225], v158 offset:5120
	ds_read_b128 v[226:229], v158 offset:6144
	ds_read_b128 v[230:233], v158 offset:7168
	global_load_lds_dwordx4 v138, s[40:41]
	s_add_i32 m0, s49, 0xe000
	s_nop 0
	global_load_lds_dwordx4 v140, s[40:41]
	s_waitcnt vmcnt(8)
	s_waitcnt lgkmcnt(0)
	s_barrier
; #define PG8_STAGE(bufoff, gbase, voff) do { _Pragma("unroll") for (int _i = 0; _i < 2; ++_i) \
;         __builtin_amdgcn_global_load_lds((const unsigned*)((const char*)(gbase) + (voff)[_i]), (LAS unsigned*)(lds + (bufoff) + ldsw + _i * 8192), 16, 0, 0); } while (0)
; #define PG8_LDA(dst, b, h) do { _Pragma("unroll") for (int m = 0; m < 4; ++m) _Pragma("unroll") for (int k = 0; k < 2; ++k) dst[m][k] = *(const LAS bf16x8*)(lds + PG8_SA(b, h) + aoff + m * 2048 + k * 1024); } while (0)
; #define PG8_MMA(ai, bj, At, Bt) do { __builtin_amdgcn_s_setprio(1); _Pragma("unroll") for (int m = 0; m < 4; ++m) _Pragma("unroll") for (int n = 0; n < 2; ++n) _Pragma("unroll") for (int k = 0; k < 2; ++k) \
;         acc[ai][bj][m][n] = __builtin_amdgcn_mfma_f32_16x16x32_bf16(Bt[n][k], At[m][k], acc[ai][bj][m][n], 0, 0, 0); __builtin_amdgcn_s_setprio(0); } while (0)
; #define PG8_WAIT_V(n) asm volatile("s_waitcnt vmcnt(" #n ")" ::: "memory")
; #define PG8_WAIT_L(n) asm volatile("s_waitcnt lgkmcnt(" #n ")" ::: "memory")
; #define PG8_BAR __builtin_amdgcn_s_barrier()
; #define PG8_SCHED __builtin_amdgcn_sched_barrier(0)
; template <class Epi, class Sched>
; DI void gemm_phase(LAS unsigned char* lds, const Gemm g, const Sched& S, const Epi& E) {
;     ...
;             PG8_WAIT_V(8); PG8_WAIT_L(0); PG8_BAR; PG8_MMA(0, 0, At, B0); PG8_MMA(0, 1, At, B1); PG8_BAR; PG8_SCHED;
;             PG8_LDA(At, 0, 1); PG8_STAGE(PG8_SB(0, 0), b2, voffB); PG8_STAGE(PG8_SB(0, 1), b2 + hstepB, voffB); PG8_STAGE(PG8_SA(0, 0), a2, voffA);
;             PG8_WAIT_V(8); PG8_WAIT_L(0); PG8_BAR; PG8_MMA(1, 0, At, B0); PG8_MMA(1, 1, At, B1); PG8_BAR; PG8_SCHED;
	s_setprio 1
	v_mfma_f32_16x16x32_bf16 v[126:129], v[166:169], v[202:205], v[126:129]
	v_mfma_f32_16x16x32_bf16 v[118:121], v[174:177], v[202:205], v[118:121]
	v_mfma_f32_16x16x32_bf16 v[110:113], v[166:169], v[210:213], v[110:113]
	v_mfma_f32_16x16x32_bf16 v[102:105], v[174:177], v[210:213], v[102:105]
	v_mfma_f32_16x16x32_bf16 v[94:97], v[166:169], v[218:221], v[94:97]
	v_mfma_f32_16x16x32_bf16 v[86:89], v[174:177], v[218:221], v[86:89]
	v_mfma_f32_16x16x32_bf16 v[78:81], v[166:169], v[226:229], v[78:81]
	v_mfma_f32_16x16x32_bf16 v[70:73], v[174:177], v[226:229], v[70:73]
	v_mfma_f32_16x16x32_bf16 v[126:129], v[170:173], v[206:209], v[126:129]
	v_mfma_f32_16x16x32_bf16 v[118:121], v[178:181], v[206:209], v[118:121]
	v_mfma_f32_16x16x32_bf16 v[110:113], v[170:173], v[214:217], v[110:113]
	v_mfma_f32_16x16x32_bf16 v[102:105], v[178:181], v[214:217], v[102:105]
	v_mfma_f32_16x16x32_bf16 v[94:97], v[170:173], v[222:225], v[94:97]
	v_mfma_f32_16x16x32_bf16 v[86:89], v[178:181], v[222:225], v[86:89]
	v_mfma_f32_16x16x32_bf16 v[78:81], v[170:173], v[230:233], v[78:81]
	v_mfma_f32_16x16x32_bf16 v[70:73], v[178:181], v[230:233], v[70:73]
	v_mfma_f32_16x16x32_bf16 v[122:125], v[186:189], v[202:205], v[122:125]
	v_mfma_f32_16x16x32_bf16 v[114:117], v[194:197], v[202:205], v[114:117]
	v_mfma_f32_16x16x32_bf16 v[106:109], v[186:189], v[210:213], v[106:109]
	v_mfma_f32_16x16x32_bf16 v[98:101], v[194:197], v[210:213], v[98:101]
	v_mfma_f32_16x16x32_bf16 v[90:93], v[186:189], v[218:221], v[90:93]
	v_mfma_f32_16x16x32_bf16 v[82:85], v[194:197], v[218:221], v[82:85]
	v_mfma_f32_16x16x32_bf16 v[74:77], v[186:189], v[226:229], v[74:77]
	v_mfma_f32_16x16x32_bf16 v[66:69], v[194:197], v[226:229], v[66:69]
	v_mfma_f32_16x16x32_bf16 v[122:125], v[190:193], v[206:209], v[122:125]
	v_mfma_f32_16x16x32_bf16 v[114:117], v[198:201], v[206:209], v[114:117]
	v_mfma_f32_16x16x32_bf16 v[106:109], v[190:193], v[214:217], v[106:109]
	v_mfma_f32_16x16x32_bf16 v[98:101], v[198:201], v[214:217], v[98:101]
	v_mfma_f32_16x16x32_bf16 v[90:93], v[190:193], v[222:225], v[90:93]
	v_mfma_f32_16x16x32_bf16 v[82:85], v[198:201], v[222:225], v[82:85]
	v_mfma_f32_16x16x32_bf16 v[74:77], v[190:193], v[230:233], v[74:77]
	v_mfma_f32_16x16x32_bf16 v[66:69], v[198:201], v[230:233], v[66:69]
	s_setprio 0
	s_barrier
	s_add_i32 s66, s57, s46
	v_lshl_add_u64 v[182:183], s[42:43], 0, v[134:135]
	s_mov_b32 m0, s66
	ds_read_b128 v[202:205], v158 offset:16384
	ds_read_b128 v[206:209], v158 offset:17408
	ds_read_b128 v[210:213], v158 offset:18432
	ds_read_b128 v[214:217], v158 offset:19456
	ds_read_b128 v[218:221], v158 offset:20480
	ds_read_b128 v[222:225], v158 offset:21504
	ds_read_b128 v[226:229], v158 offset:22528
	ds_read_b128 v[230:233], v158 offset:23552
	global_load_lds_dwordx4 v[182:183], off
	s_add_i32 m0, s66, 0x2000
	s_add_u32 s66, s42, 0x40000
	v_lshl_add_u64 v[234:235], s[42:43], 0, v[130:131]
	s_addc_u32 s67, s43, 0
	s_add_i32 s68, s58, s46
	global_load_lds_dwordx4 v[234:235], off
	s_mov_b32 m0, s68
	v_lshl_add_u64 v[238:239], s[44:45], 0, v[132:133]
	global_load_lds_dwordx4 v134, s[66:67]
	s_add_i32 m0, s68, 0x2000
	s_nop 0
	global_load_lds_dwordx4 v130, s[66:67]
	v_lshl_add_u64 v[236:237], s[44:45], 0, v[136:137]
	s_mov_b32 m0, s49
	s_nop 0
	global_load_lds_dwordx4 v[236:237], off
	s_mov_b32 m0, s50
	s_nop 0
	global_load_lds_dwordx4 v[238:239], off
	s_waitcnt vmcnt(8)
	s_waitcnt lgkmcnt(0)
	s_barrier
	s_setprio 1
	v_mfma_f32_16x16x32_bf16 v[62:65], v[166:169], v[202:205], v[62:65]
	v_mfma_f32_16x16x32_bf16 v[54:57], v[174:177], v[202:205], v[54:57]
	v_mfma_f32_16x16x32_bf16 v[46:49], v[166:169], v[210:213], v[46:49]
	v_mfma_f32_16x16x32_bf16 v[38:41], v[174:177], v[210:213], v[38:41]
	v_mfma_f32_16x16x32_bf16 v[30:33], v[166:169], v[218:221], v[30:33]
	v_mfma_f32_16x16x32_bf16 v[22:25], v[174:177], v[218:221], v[22:25]
	v_mfma_f32_16x16x32_bf16 v[14:17], v[166:169], v[226:229], v[14:17]
	v_mfma_f32_16x16x32_bf16 v[6:9], v[174:177], v[226:229], v[6:9]
	v_mfma_f32_16x16x32_bf16 v[62:65], v[170:173], v[206:209], v[62:65]
	v_mfma_f32_16x16x32_bf16 v[54:57], v[178:181], v[206:209], v[54:57]
	v_mfma_f32_16x16x32_bf16 v[46:49], v[170:173], v[214:217], v[46:49]
	v_mfma_f32_16x16x32_bf16 v[38:41], v[178:181], v[214:217], v[38:41]
	v_mfma_f32_16x16x32_bf16 v[30:33], v[170:173], v[222:225], v[30:33]
	v_mfma_f32_16x16x32_bf16 v[22:25], v[178:181], v[222:225], v[22:25]
	v_mfma_f32_16x16x32_bf16 v[14:17], v[170:173], v[230:233], v[14:17]
	v_mfma_f32_16x16x32_bf16 v[6:9], v[178:181], v[230:233], v[6:9]
	v_mfma_f32_16x16x32_bf16 v[58:61], v[186:189], v[202:205], v[58:61]
	v_mfma_f32_16x16x32_bf16 v[50:53], v[194:197], v[202:205], v[50:53]
	v_mfma_f32_16x16x32_bf16 v[42:45], v[186:189], v[210:213], v[42:45]
	v_mfma_f32_16x16x32_bf16 v[34:37], v[194:197], v[210:213], v[34:37]
	v_mfma_f32_16x16x32_bf16 v[26:29], v[186:189], v[218:221], v[26:29]
	v_mfma_f32_16x16x32_bf16 v[18:21], v[194:197], v[218:221], v[18:21]
	v_mfma_f32_16x16x32_bf16 v[10:13], v[186:189], v[226:229], v[10:13]
	v_mfma_f32_16x16x32_bf16 v[2:5], v[194:197], v[226:229], v[2:5]
	v_mfma_f32_16x16x32_bf16 v[58:61], v[190:193], v[206:209], v[58:61]
	v_mfma_f32_16x16x32_bf16 v[50:53], v[198:201], v[206:209], v[50:53]
	v_mfma_f32_16x16x32_bf16 v[42:45], v[190:193], v[214:217], v[42:45]
	v_mfma_f32_16x16x32_bf16 v[34:37], v[198:201], v[214:217], v[34:37]
	v_mfma_f32_16x16x32_bf16 v[26:29], v[190:193], v[222:225], v[26:29]
	v_mfma_f32_16x16x32_bf16 v[18:21], v[198:201], v[222:225], v[18:21]
	v_mfma_f32_16x16x32_bf16 v[10:13], v[190:193], v[230:233], v[10:13]
	v_mfma_f32_16x16x32_bf16 v[2:5], v[198:201], v[230:233], v[2:5]
	s_setprio 0
	s_barrier
; #define PG8_STAGE(bufoff, gbase, voff) do { _Pragma("unroll") for (int _i = 0; _i < 2; ++_i) \
;         __builtin_amdgcn_global_load_lds((const unsigned*)((const char*)(gbase) + (voff)[_i]), (LAS unsigned*)(lds + (bufoff) + ldsw + _i * 8192), 16, 0, 0); } while (0)
; #define PG8_LDA(dst, b, h) do { _Pragma("unroll") for (int m = 0; m < 4; ++m) _Pragma("unroll") for (int k = 0; k < 2; ++k) dst[m][k] = *(const LAS bf16x8*)(lds + PG8_SA(b, h) + aoff + m * 2048 + k * 1024); } while (0)
; #define PG8_LDB(dst, b, h) do { _Pragma("unroll") for (int n = 0; n < 2; ++n) _Pragma("unroll") for (int k = 0; k < 2; ++k) dst[n][k] = *(const LAS bf16x8*)(lds + PG8_SB(b, h) + boff + n * 2048 + k * 1024); } while (0)
; #define PG8_MMA(ai, bj, At, Bt) do { __builtin_amdgcn_s_setprio(1); _Pragma("unroll") for (int m = 0; m < 4; ++m) _Pragma("unroll") for (int n = 0; n < 2; ++n) _Pragma("unroll") for (int k = 0; k < 2; ++k) \
;         acc[ai][bj][m][n] = __builtin_amdgcn_mfma_f32_16x16x32_bf16(Bt[n][k], At[m][k], acc[ai][bj][m][n], 0, 0, 0); __builtin_amdgcn_s_setprio(0); } while (0)
; #define PG8_WAIT_V(n) asm volatile("s_waitcnt vmcnt(" #n ")" ::: "memory")
; #define PG8_WAIT_L(n) asm volatile("s_waitcnt lgkmcnt(" #n ")" ::: "memory")
; #define PG8_BAR __builtin_amdgcn_s_barrier()
; #define PG8_SCHED __builtin_amdgcn_sched_barrier(0)
; template <class Epi, class Sched>
; DI void gemm_phase(LAS unsigned char* lds, const Gemm g, const Sched& S, const Epi& E) {
;     ...
;             PG8_LDB(B0, 1, 0); PG8_LDB(B1, 1, 1); PG8_SCHED; PG8_LDA(At, 1, 0); PG8_STAGE(PG8_SA(0, 1), a2 + hstepA, voffA);
;             PG8_WAIT_V(8); PG8_WAIT_L(0); PG8_BAR; PG8_MMA(0, 0, At, B0); PG8_MMA(0, 1, At, B1); PG8_BAR; PG8_SCHED;
;             PG8_LDA(At, 1, 1); PG8_STAGE(PG8_SB(1, 0), b3, voffB); PG8_STAGE(PG8_SB(1, 1), b3 + hstepB, voffB); PG8_STAGE(PG8_SA(1, 0), a3, voffA);
;             PG8_WAIT_V(8); PG8_WAIT_L(0); PG8_BAR; PG8_MMA(1, 0, At, B0); PG8_MMA(1, 1, At, B1); PG8_BAR; PG8_SCHED;
;         }
	s_add_i32 s66, 0, 0x18000
	v_add_u32_e32 v165, s66, v156
	s_add_i32 s67, 0, 0x1c000
	ds_read_b128 v[166:169], v165
	ds_read_b128 v[170:173], v165 offset:1024
	ds_read_b128 v[174:177], v165 offset:2048
	ds_read_b128 v[178:181], v165 offset:3072
	v_add_u32_e32 v165, s67, v156
	ds_read_b128 v[186:189], v165
	ds_read_b128 v[190:193], v165 offset:1024
	ds_read_b128 v[194:197], v165 offset:2048
	ds_read_b128 v[198:201], v165 offset:3072
	s_add_u32 s44, s44, 0x40000
	s_addc_u32 s45, s45, 0
	s_mov_b32 m0, s51
	ds_read_b128 v[202:205], v158 offset:32768
	ds_read_b128 v[206:209], v158 offset:33792
	ds_read_b128 v[210:213], v158 offset:34816
	ds_read_b128 v[214:217], v158 offset:35840
	ds_read_b128 v[218:221], v158 offset:36864
	ds_read_b128 v[222:225], v158 offset:37888
	ds_read_b128 v[226:229], v158 offset:38912
	ds_read_b128 v[230:233], v158 offset:39936
	global_load_lds_dwordx4 v136, s[44:45]
	s_mov_b32 m0, s52
	s_nop 0
	global_load_lds_dwordx4 v132, s[44:45]
	s_waitcnt vmcnt(8)
	s_waitcnt lgkmcnt(0)
	s_barrier
	s_setprio 1
	v_mfma_f32_16x16x32_bf16 v[126:129], v[166:169], v[202:205], v[126:129]
	v_mfma_f32_16x16x32_bf16 v[118:121], v[174:177], v[202:205], v[118:121]
	v_mfma_f32_16x16x32_bf16 v[110:113], v[166:169], v[210:213], v[110:113]
	v_mfma_f32_16x16x32_bf16 v[102:105], v[174:177], v[210:213], v[102:105]
	v_mfma_f32_16x16x32_bf16 v[94:97], v[166:169], v[218:221], v[94:97]
	v_mfma_f32_16x16x32_bf16 v[86:89], v[174:177], v[218:221], v[86:89]
	v_mfma_f32_16x16x32_bf16 v[78:81], v[166:169], v[226:229], v[78:81]
	v_mfma_f32_16x16x32_bf16 v[70:73], v[174:177], v[226:229], v[70:73]
	v_mfma_f32_16x16x32_bf16 v[126:129], v[170:173], v[206:209], v[126:129]
	v_mfma_f32_16x16x32_bf16 v[118:121], v[178:181], v[206:209], v[118:121]
	v_mfma_f32_16x16x32_bf16 v[110:113], v[170:173], v[214:217], v[110:113]
	v_mfma_f32_16x16x32_bf16 v[102:105], v[178:181], v[214:217], v[102:105]
	v_mfma_f32_16x16x32_bf16 v[94:97], v[170:173], v[222:225], v[94:97]
	v_mfma_f32_16x16x32_bf16 v[86:89], v[178:181], v[222:225], v[86:89]
	v_mfma_f32_16x16x32_bf16 v[78:81], v[170:173], v[230:233], v[78:81]
	v_mfma_f32_16x16x32_bf16 v[70:73], v[178:181], v[230:233], v[70:73]
	v_mfma_f32_16x16x32_bf16 v[122:125], v[186:189], v[202:205], v[122:125]
	v_mfma_f32_16x16x32_bf16 v[114:117], v[194:197], v[202:205], v[114:117]
	v_mfma_f32_16x16x32_bf16 v[106:109], v[186:189], v[210:213], v[106:109]
	v_mfma_f32_16x16x32_bf16 v[98:101], v[194:197], v[210:213], v[98:101]
	v_mfma_f32_16x16x32_bf16 v[90:93], v[186:189], v[218:221], v[90:93]
	v_mfma_f32_16x16x32_bf16 v[82:85], v[194:197], v[218:221], v[82:85]
	v_mfma_f32_16x16x32_bf16 v[74:77], v[186:189], v[226:229], v[74:77]
	v_mfma_f32_16x16x32_bf16 v[66:69], v[194:197], v[226:229], v[66:69]
	v_mfma_f32_16x16x32_bf16 v[122:125], v[190:193], v[206:209], v[122:125]
	v_mfma_f32_16x16x32_bf16 v[114:117], v[198:201], v[206:209], v[114:117]
	v_mfma_f32_16x16x32_bf16 v[106:109], v[190:193], v[214:217], v[106:109]
	v_mfma_f32_16x16x32_bf16 v[98:101], v[198:201], v[214:217], v[98:101]
	v_mfma_f32_16x16x32_bf16 v[90:93], v[190:193], v[222:225], v[90:93]
	v_mfma_f32_16x16x32_bf16 v[82:85], v[198:201], v[222:225], v[82:85]
	v_mfma_f32_16x16x32_bf16 v[74:77], v[190:193], v[230:233], v[74:77]
	v_mfma_f32_16x16x32_bf16 v[66:69], v[198:201], v[230:233], v[66:69]
	s_setprio 0
	s_barrier
	s_add_i32 s44, s66, s46
	v_lshl_add_u64 v[182:183], v[182:183], 0, s[16:17]
	s_mov_b32 m0, s44
	ds_read_b128 v[202:205], v158 offset:49152
	ds_read_b128 v[206:209], v158 offset:50176
	ds_read_b128 v[210:213], v158 offset:51200
	ds_read_b128 v[214:217], v158 offset:52224
	ds_read_b128 v[218:221], v158 offset:53248
	ds_read_b128 v[222:225], v158 offset:54272
	ds_read_b128 v[226:229], v158 offset:55296
	ds_read_b128 v[230:233], v158 offset:56320
	global_load_lds_dwordx4 v[182:183], off
	s_add_i32 m0, s44, 0x2000
	s_add_u32 s42, s42, 0x40080
	v_lshl_add_u64 v[182:183], v[234:235], 0, s[16:17]
	s_addc_u32 s43, s43, 0
	s_add_i32 s44, s67, s46
	global_load_lds_dwordx4 v[182:183], off
	s_mov_b32 m0, s44
	s_nop 0
	global_load_lds_dwordx4 v134, s[42:43]
	s_add_i32 m0, s44, 0x2000
	s_nop 0
	global_load_lds_dwordx4 v130, s[42:43]
	v_lshl_add_u64 v[182:183], v[236:237], 0, s[16:17]
	s_mov_b32 m0, s54
	s_nop 0
	global_load_lds_dwordx4 v[182:183], off
	v_lshl_add_u64 v[182:183], v[238:239], 0, s[16:17]
	s_mov_b32 m0, s55
	s_nop 0
	global_load_lds_dwordx4 v[182:183], off
	s_waitcnt vmcnt(8)
	s_waitcnt lgkmcnt(0)
	s_barrier
	s_setprio 1
	v_mfma_f32_16x16x32_bf16 v[62:65], v[166:169], v[202:205], v[62:65]
	v_mfma_f32_16x16x32_bf16 v[54:57], v[174:177], v[202:205], v[54:57]
	v_mfma_f32_16x16x32_bf16 v[46:49], v[166:169], v[210:213], v[46:49]
	v_mfma_f32_16x16x32_bf16 v[38:41], v[174:177], v[210:213], v[38:41]
	v_mfma_f32_16x16x32_bf16 v[30:33], v[166:169], v[218:221], v[30:33]
	v_mfma_f32_16x16x32_bf16 v[22:25], v[174:177], v[218:221], v[22:25]
	v_mfma_f32_16x16x32_bf16 v[14:17], v[166:169], v[226:229], v[14:17]
	v_mfma_f32_16x16x32_bf16 v[6:9], v[174:177], v[226:229], v[6:9]
	v_mfma_f32_16x16x32_bf16 v[62:65], v[170:173], v[206:209], v[62:65]
	v_mfma_f32_16x16x32_bf16 v[54:57], v[178:181], v[206:209], v[54:57]
	v_mfma_f32_16x16x32_bf16 v[46:49], v[170:173], v[214:217], v[46:49]
	v_mfma_f32_16x16x32_bf16 v[38:41], v[178:181], v[214:217], v[38:41]
	v_mfma_f32_16x16x32_bf16 v[30:33], v[170:173], v[222:225], v[30:33]
	v_mfma_f32_16x16x32_bf16 v[22:25], v[178:181], v[222:225], v[22:25]
	v_mfma_f32_16x16x32_bf16 v[14:17], v[170:173], v[230:233], v[14:17]
	v_mfma_f32_16x16x32_bf16 v[6:9], v[178:181], v[230:233], v[6:9]
	v_mfma_f32_16x16x32_bf16 v[58:61], v[186:189], v[202:205], v[58:61]
	v_mfma_f32_16x16x32_bf16 v[50:53], v[194:197], v[202:205], v[50:53]
	v_mfma_f32_16x16x32_bf16 v[42:45], v[186:189], v[210:213], v[42:45]
	v_mfma_f32_16x16x32_bf16 v[34:37], v[194:197], v[210:213], v[34:37]
	v_mfma_f32_16x16x32_bf16 v[26:29], v[186:189], v[218:221], v[26:29]
	v_mfma_f32_16x16x32_bf16 v[18:21], v[194:197], v[218:221], v[18:21]
	v_mfma_f32_16x16x32_bf16 v[10:13], v[186:189], v[226:229], v[10:13]
	v_mfma_f32_16x16x32_bf16 v[2:5], v[194:197], v[226:229], v[2:5]
	v_mfma_f32_16x16x32_bf16 v[58:61], v[190:193], v[206:209], v[58:61]
	v_mfma_f32_16x16x32_bf16 v[50:53], v[198:201], v[206:209], v[50:53]
	v_mfma_f32_16x16x32_bf16 v[42:45], v[190:193], v[214:217], v[42:45]
	v_mfma_f32_16x16x32_bf16 v[34:37], v[198:201], v[214:217], v[34:37]
	v_mfma_f32_16x16x32_bf16 v[26:29], v[190:193], v[222:225], v[26:29]
	v_mfma_f32_16x16x32_bf16 v[18:21], v[198:201], v[222:225], v[18:21]
	v_mfma_f32_16x16x32_bf16 v[10:13], v[190:193], v[230:233], v[10:13]
	v_mfma_f32_16x16x32_bf16 v[2:5], v[198:201], v[230:233], v[2:5]
	s_setprio 0
	s_barrier
	s_add_i32 s65, s65, 2
	s_add_u32 s40, s40, 0x100
	s_addc_u32 s41, s41, 0
	s_add_u32 s63, s63, 0x100
	s_addc_u32 s64, s64, 0
	s_cmp_gt_u32 s65, 13
	s_cbranch_scc0 .LBB0_1234
	s_mov_b32 s99, 1
	s_and_b64 vcc, exec, s[18:19]
	s_cbranch_vccz .LBB0_1237
	s_barrier

; #define PG8_STAGE(bufoff, gbase, voff) do { _Pragma("unroll") for (int _i = 0; _i < 2; ++_i) \
;         __builtin_amdgcn_global_load_lds((const unsigned*)((const char*)(gbase) + (voff)[_i]), (LAS unsigned*)(lds + (bufoff) + ldsw + _i * 8192), 16, 0, 0); } while (0)
; #define PG8_LDA(dst, b, h) do { _Pragma("unroll") for (int m = 0; m < 4; ++m) _Pragma("unroll") for (int k = 0; k < 2; ++k) dst[m][k] = *(const LAS bf16x8*)(lds + PG8_SA(b, h) + aoff + m * 2048 + k * 1024); } while (0)
; #define PG8_LDB(dst, b, h) do { _Pragma("unroll") for (int n = 0; n < 2; ++n) _Pragma("unroll") for (int k = 0; k < 2; ++k) dst[n][k] = *(const LAS bf16x8*)(lds + PG8_SB(b, h) + boff + n * 2048 + k * 1024); } while (0)
; #define PG8_MMA(ai, bj, At, Bt) do { __builtin_amdgcn_s_setprio(1); _Pragma("unroll") for (int m = 0; m < 4; ++m) _Pragma("unroll") for (int n = 0; n < 2; ++n) _Pragma("unroll") for (int k = 0; k < 2; ++k) \
;         acc[ai][bj][m][n] = __builtin_amdgcn_mfma_f32_16x16x32_bf16(Bt[n][k], At[m][k], acc[ai][bj][m][n], 0, 0, 0); __builtin_amdgcn_s_setprio(0); } while (0)
; #define PG8_WAIT_V(n) asm volatile("s_waitcnt vmcnt(" #n ")" ::: "memory")
; #define PG8_WAIT_L(n) asm volatile("s_waitcnt lgkmcnt(" #n ")" ::: "memory")
; #define PG8_BAR __builtin_amdgcn_s_barrier()
; template <class Epi, class Sched>
; DI void gemm_phase(LAS unsigned char* lds, const Gemm g, const Sched& S, const Epi& E) {
;     ...
;         const char* nA = has_next ? (const char*)(nxt.src ? g.A1 : g.A0) + (size_t)nxt.pm * tstepA : cA; const char* nB = has_next ? (const char*)(nxt.src ? g.B1 : g.B0) + (size_t)nxt.pn * tstepB : cB;
;         for (int t = 0; t < nt; t += 2) {
;             const bool last = (t == nt - 2);
;             const char* a1 = cA + (size_t)(t + 1) * kstep;
;             const char* a2 = last ? nA : cA + (size_t)(t + 2) * kstep; const char* b2 = last ? nB : cB + (size_t)(t + 2) * kstep;
;             const char* a3 = a2 + kstep; const char* b3 = b2 + kstep;
;             PG8_LDB(B0, 0, 0); PG8_LDB(B1, 0, 1); PG8_SCHED; PG8_LDA(At, 0, 0); PG8_STAGE(PG8_SA(1, 1), a1 + hstepA, voffA);
;             PG8_WAIT_V(8); PG8_WAIT_L(0); PG8_BAR; PG8_MMA(0, 0, At, B0); PG8_MMA(0, 1, At, B1); PG8_BAR; PG8_SCHED;
;             PG8_LDA(At, 0, 1); PG8_STAGE(PG8_SB(0, 0), b2, voffB); PG8_STAGE(PG8_SB(0, 1), b2 + hstepB, voffB); PG8_STAGE(PG8_SA(0, 0), a2, voffA);
.LBB0_1330:
	s_add_u32 s16, s16, 0xb0080
	s_addc_u32 s17, s17, 0
	s_add_u32 s45, s18, 0x100
	s_addc_u32 s46, s19, 0
	s_mov_b32 s47, -2
	ds_read_b128 v[144:147], v151
	ds_read_b128 v[154:157], v151 offset:1024
	ds_read_b128 v[158:161], v151 offset:2048
	ds_read_b128 v[162:165], v151 offset:3072
	ds_read_b128 v[166:169], v152
	ds_read_b128 v[170:173], v152 offset:1024
	ds_read_b128 v[174:177], v152 offset:2048
	ds_read_b128 v[178:181], v152 offset:3072
	s_add_u32 s18, s16, 0xfff50080
	s_addc_u32 s19, s17, -1
	s_cmp_eq_u32 s47, 40
	s_cselect_b32 s21, s5, s19
	s_cselect_b32 s20, s4, s18
	s_cselect_b32 s19, s15, s46
	s_cselect_b32 s18, s14, s45
	s_add_i32 m0, s28, 0xc000
	ds_read_b128 v[182:185], v153
	ds_read_b128 v[186:189], v153 offset:1024
	ds_read_b128 v[190:193], v153 offset:2048
	ds_read_b128 v[194:197], v153 offset:3072
	ds_read_b128 v[198:201], v153 offset:4096
	ds_read_b128 v[202:205], v153 offset:5120
	ds_read_b128 v[206:209], v153 offset:6144
	ds_read_b128 v[210:213], v153 offset:7168
	global_load_lds_dwordx4 v136, s[16:17]
	s_add_i32 m0, s28, 0xe000
	s_nop 0
	global_load_lds_dwordx4 v138, s[16:17]
	s_cmp_lg_u32 s99, 0
	s_cbranch_scc1 .Lpk6_w1
	s_waitcnt vmcnt(8)
.Lpk6_w1:
	s_waitcnt lgkmcnt(0)
	s_barrier
	s_setprio 1
	v_mfma_f32_16x16x32_bf16 v[124:127], v[144:147], v[182:185], 0
	v_mfma_f32_16x16x32_bf16 v[120:123], v[158:161], v[182:185], 0
	v_mfma_f32_16x16x32_bf16 v[108:111], v[144:147], v[190:193], 0
	v_mfma_f32_16x16x32_bf16 v[104:107], v[158:161], v[190:193], 0
	v_mfma_f32_16x16x32_bf16 v[92:95], v[144:147], v[198:201], 0
	v_mfma_f32_16x16x32_bf16 v[88:91], v[158:161], v[198:201], 0
	v_mfma_f32_16x16x32_bf16 v[76:79], v[144:147], v[206:209], 0
	v_mfma_f32_16x16x32_bf16 v[72:75], v[158:161], v[206:209], 0
	v_mfma_f32_16x16x32_bf16 v[124:127], v[154:157], v[186:189], v[124:127]
	v_mfma_f32_16x16x32_bf16 v[120:123], v[162:165], v[186:189], v[120:123]
	v_mfma_f32_16x16x32_bf16 v[108:111], v[154:157], v[194:197], v[108:111]
	v_mfma_f32_16x16x32_bf16 v[104:107], v[162:165], v[194:197], v[104:107]
	v_mfma_f32_16x16x32_bf16 v[92:95], v[154:157], v[202:205], v[92:95]
	v_mfma_f32_16x16x32_bf16 v[88:91], v[162:165], v[202:205], v[88:91]
	v_mfma_f32_16x16x32_bf16 v[76:79], v[154:157], v[210:213], v[76:79]
	v_mfma_f32_16x16x32_bf16 v[72:75], v[162:165], v[210:213], v[72:75]
	v_mfma_f32_16x16x32_bf16 v[116:119], v[166:169], v[182:185], 0
	v_mfma_f32_16x16x32_bf16 v[112:115], v[174:177], v[182:185], 0
	v_mfma_f32_16x16x32_bf16 v[100:103], v[166:169], v[190:193], 0
	v_mfma_f32_16x16x32_bf16 v[96:99], v[174:177], v[190:193], 0
	v_mfma_f32_16x16x32_bf16 v[84:87], v[166:169], v[198:201], 0
	v_mfma_f32_16x16x32_bf16 v[80:83], v[174:177], v[198:201], 0
	v_mfma_f32_16x16x32_bf16 v[68:71], v[166:169], v[206:209], 0
	v_mfma_f32_16x16x32_bf16 v[64:67], v[174:177], v[206:209], 0
	v_mfma_f32_16x16x32_bf16 v[116:119], v[170:173], v[186:189], v[116:119]
	v_mfma_f32_16x16x32_bf16 v[112:115], v[178:181], v[186:189], v[112:115]
	v_mfma_f32_16x16x32_bf16 v[100:103], v[170:173], v[194:197], v[100:103]
	v_mfma_f32_16x16x32_bf16 v[96:99], v[178:181], v[194:197], v[96:99]
	v_mfma_f32_16x16x32_bf16 v[84:87], v[170:173], v[202:205], v[84:87]
	v_mfma_f32_16x16x32_bf16 v[80:83], v[178:181], v[202:205], v[80:83]
	v_mfma_f32_16x16x32_bf16 v[68:71], v[170:173], v[210:213], v[68:71]
	v_mfma_f32_16x16x32_bf16 v[64:67], v[178:181], v[210:213], v[64:67]
	s_setprio 0
	s_barrier
	s_add_i32 s48, s39, s27
	v_lshl_add_u64 v[214:215], s[18:19], 0, v[130:131]
	s_mov_b32 m0, s48
	ds_read_b128 v[182:185], v153 offset:16384
	ds_read_b128 v[186:189], v153 offset:17408
	ds_read_b128 v[190:193], v153 offset:18432
	ds_read_b128 v[194:197], v153 offset:19456
	ds_read_b128 v[198:201], v153 offset:20480
	ds_read_b128 v[202:205], v153 offset:21504
	ds_read_b128 v[206:209], v153 offset:22528
	ds_read_b128 v[210:213], v153 offset:23552
	global_load_lds_dwordx4 v[214:215], off
	s_add_i32 m0, s48, 0x2000
	s_add_u32 s48, s18, 0xb0000
	v_lshl_add_u64 v[216:217], s[18:19], 0, v[134:135]
	s_addc_u32 s49, s19, 0
	s_add_i32 s50, s40, s27
	global_load_lds_dwordx4 v[216:217], off
	s_mov_b32 m0, s50
	v_lshl_add_u64 v[220:221], s[20:21], 0, v[132:133]
	global_load_lds_dwordx4 v130, s[48:49]
	s_add_i32 m0, s50, 0x2000
	s_nop 0
	global_load_lds_dwordx4 v134, s[48:49]
	v_lshl_add_u64 v[218:219], s[20:21], 0, v[128:129]
	s_mov_b32 m0, s28
	s_nop 0
	global_load_lds_dwordx4 v[218:219], off
	s_mov_b32 m0, s29
	s_nop 0
	global_load_lds_dwordx4 v[220:221], off
	s_cmp_lg_u32 s99, 0
	s_cbranch_scc1 .Lpk6_w2
	s_waitcnt vmcnt(8)
; #define PG8_STAGE(bufoff, gbase, voff) do { _Pragma("unroll") for (int _i = 0; _i < 2; ++_i) \
;         __builtin_amdgcn_global_load_lds((const unsigned*)((const char*)(gbase) + (voff)[_i]), (LAS unsigned*)(lds + (bufoff) + ldsw + _i * 8192), 16, 0, 0); } while (0)
; #define PG8_LDA(dst, b, h) do { _Pragma("unroll") for (int m = 0; m < 4; ++m) _Pragma("unroll") for (int k = 0; k < 2; ++k) dst[m][k] = *(const LAS bf16x8*)(lds + PG8_SA(b, h) + aoff + m * 2048 + k * 1024); } while (0)
; #define PG8_LDB(dst, b, h) do { _Pragma("unroll") for (int n = 0; n < 2; ++n) _Pragma("unroll") for (int k = 0; k < 2; ++k) dst[n][k] = *(const LAS bf16x8*)(lds + PG8_SB(b, h) + boff + n * 2048 + k * 1024); } while (0)
; #define PG8_MMA(ai, bj, At, Bt) do { __builtin_amdgcn_s_setprio(1); _Pragma("unroll") for (int m = 0; m < 4; ++m) _Pragma("unroll") for (int n = 0; n < 2; ++n) _Pragma("unroll") for (int k = 0; k < 2; ++k) \
;         acc[ai][bj][m][n] = __builtin_amdgcn_mfma_f32_16x16x32_bf16(Bt[n][k], At[m][k], acc[ai][bj][m][n], 0, 0, 0); __builtin_amdgcn_s_setprio(0); } while (0)
; #define PG8_WAIT_V(n) asm volatile("s_waitcnt vmcnt(" #n ")" ::: "memory")
; #define PG8_WAIT_L(n) asm volatile("s_waitcnt lgkmcnt(" #n ")" ::: "memory")
; template <class Epi, class Sched>
; DI void gemm_phase(LAS unsigned char* lds, const Gemm g, const Sched& S, const Epi& E) {
;     ...
;             PG8_LDB(B0, 0, 0); PG8_LDB(B1, 0, 1); PG8_SCHED; PG8_LDA(At, 0, 0); PG8_STAGE(PG8_SA(1, 1), a1 + hstepA, voffA);
;             PG8_WAIT_V(8); PG8_WAIT_L(0); PG8_BAR; PG8_MMA(0, 0, At, B0); PG8_MMA(0, 1, At, B1); PG8_BAR; PG8_SCHED;
;             PG8_LDA(At, 0, 1); PG8_STAGE(PG8_SB(0, 0), b2, voffB); PG8_STAGE(PG8_SB(0, 1), b2 + hstepB, voffB); PG8_STAGE(PG8_SA(0, 0), a2, voffA);
;             PG8_WAIT_V(8); PG8_WAIT_L(0); PG8_BAR; PG8_MMA(1, 0, At, B0); PG8_MMA(1, 1, At, B1); PG8_BAR; PG8_SCHED;
;             PG8_LDB(B0, 1, 0); PG8_LDB(B1, 1, 1); PG8_SCHED; PG8_LDA(At, 1, 0); PG8_STAGE(PG8_SA(0, 1), a2 + hstepA, voffA);
;             PG8_WAIT_V(8); PG8_WAIT_L(0); PG8_BAR; PG8_MMA(0, 0, At, B0); PG8_MMA(0, 1, At, B1); PG8_BAR; PG8_SCHED;
;             PG8_LDA(At, 1, 1); PG8_STAGE(PG8_SB(1, 0), b3, voffB); PG8_STAGE(PG8_SB(1, 1), b3 + hstepB, voffB); PG8_STAGE(PG8_SA(1, 0), a3, voffA);
;             PG8_WAIT_V(8); PG8_WAIT_L(0); PG8_BAR; PG8_MMA(1, 0, At, B0); PG8_MMA(1, 1, At, B1); PG8_BAR; PG8_SCHED;
.Lpk6_w2:
	s_mov_b32 s99, 0
	s_waitcnt lgkmcnt(0)
	s_barrier
	s_setprio 1
	v_mfma_f32_16x16x32_bf16 v[60:63], v[144:147], v[182:185], 0
	v_mfma_f32_16x16x32_bf16 v[56:59], v[158:161], v[182:185], 0
	v_mfma_f32_16x16x32_bf16 v[44:47], v[144:147], v[190:193], 0
	v_mfma_f32_16x16x32_bf16 v[40:43], v[158:161], v[190:193], 0
	v_mfma_f32_16x16x32_bf16 v[28:31], v[144:147], v[198:201], 0
	v_mfma_f32_16x16x32_bf16 v[24:27], v[158:161], v[198:201], 0
	v_mfma_f32_16x16x32_bf16 v[12:15], v[144:147], v[206:209], 0
	v_mfma_f32_16x16x32_bf16 v[8:11], v[158:161], v[206:209], 0
	v_mfma_f32_16x16x32_bf16 v[60:63], v[154:157], v[186:189], v[60:63]
	v_mfma_f32_16x16x32_bf16 v[56:59], v[162:165], v[186:189], v[56:59]
	v_mfma_f32_16x16x32_bf16 v[44:47], v[154:157], v[194:197], v[44:47]
	v_mfma_f32_16x16x32_bf16 v[40:43], v[162:165], v[194:197], v[40:43]
	v_mfma_f32_16x16x32_bf16 v[28:31], v[154:157], v[202:205], v[28:31]
	v_mfma_f32_16x16x32_bf16 v[24:27], v[162:165], v[202:205], v[24:27]
	v_mfma_f32_16x16x32_bf16 v[12:15], v[154:157], v[210:213], v[12:15]
	v_mfma_f32_16x16x32_bf16 v[8:11], v[162:165], v[210:213], v[8:11]
	v_mfma_f32_16x16x32_bf16 v[52:55], v[166:169], v[182:185], 0
	v_mfma_f32_16x16x32_bf16 v[48:51], v[174:177], v[182:185], 0
	v_mfma_f32_16x16x32_bf16 v[36:39], v[166:169], v[190:193], 0
	v_mfma_f32_16x16x32_bf16 v[32:35], v[174:177], v[190:193], 0
	v_mfma_f32_16x16x32_bf16 v[20:23], v[166:169], v[198:201], 0
	v_mfma_f32_16x16x32_bf16 v[16:19], v[174:177], v[198:201], 0
	v_mfma_f32_16x16x32_bf16 v[4:7], v[166:169], v[206:209], 0
	v_mfma_f32_16x16x32_bf16 v[0:3], v[174:177], v[206:209], 0
	v_mfma_f32_16x16x32_bf16 v[52:55], v[170:173], v[186:189], v[52:55]
	v_mfma_f32_16x16x32_bf16 v[48:51], v[178:181], v[186:189], v[48:51]
	v_mfma_f32_16x16x32_bf16 v[36:39], v[170:173], v[194:197], v[36:39]
	v_mfma_f32_16x16x32_bf16 v[32:35], v[178:181], v[194:197], v[32:35]
	v_mfma_f32_16x16x32_bf16 v[20:23], v[170:173], v[202:205], v[20:23]
	v_mfma_f32_16x16x32_bf16 v[16:19], v[178:181], v[202:205], v[16:19]
	v_mfma_f32_16x16x32_bf16 v[4:7], v[170:173], v[210:213], v[4:7]
	v_mfma_f32_16x16x32_bf16 v[0:3], v[178:181], v[210:213], v[0:3]
	s_setprio 0
	s_barrier
	s_add_i32 s48, 0, 0x18000
	s_add_i32 s49, 0, 0x1c000
	v_add_u32_e32 v162, s48, v149
	v_add_u32_e32 v178, s49, v149
	ds_read_b128 v[144:147], v162
	ds_read_b128 v[154:157], v162 offset:1024
	ds_read_b128 v[158:161], v162 offset:2048
	ds_read_b128 v[162:165], v162 offset:3072
	ds_read_b128 v[166:169], v178
	ds_read_b128 v[170:173], v178 offset:1024
	ds_read_b128 v[174:177], v178 offset:2048
	ds_read_b128 v[178:181], v178 offset:3072
	s_add_u32 s20, s20, 0xb0000
	s_addc_u32 s21, s21, 0
	s_mov_b32 m0, s33
	ds_read_b128 v[182:185], v153 offset:32768
	ds_read_b128 v[186:189], v153 offset:33792
	ds_read_b128 v[190:193], v153 offset:34816
	ds_read_b128 v[194:197], v153 offset:35840
	ds_read_b128 v[198:201], v153 offset:36864
	ds_read_b128 v[202:205], v153 offset:37888
	ds_read_b128 v[206:209], v153 offset:38912
	ds_read_b128 v[210:213], v153 offset:39936
	global_load_lds_dwordx4 v128, s[20:21]
	s_mov_b32 m0, s34
	s_nop 0
	global_load_lds_dwordx4 v132, s[20:21]
	s_waitcnt vmcnt(8)
	s_waitcnt lgkmcnt(0)
	s_barrier
	s_setprio 1
	v_mfma_f32_16x16x32_bf16 v[124:127], v[144:147], v[182:185], v[124:127]
	v_mfma_f32_16x16x32_bf16 v[120:123], v[158:161], v[182:185], v[120:123]
	v_mfma_f32_16x16x32_bf16 v[108:111], v[144:147], v[190:193], v[108:111]
	v_mfma_f32_16x16x32_bf16 v[104:107], v[158:161], v[190:193], v[104:107]
	v_mfma_f32_16x16x32_bf16 v[92:95], v[144:147], v[198:201], v[92:95]
	v_mfma_f32_16x16x32_bf16 v[88:91], v[158:161], v[198:201], v[88:91]
	v_mfma_f32_16x16x32_bf16 v[76:79], v[144:147], v[206:209], v[76:79]
	v_mfma_f32_16x16x32_bf16 v[72:75], v[158:161], v[206:209], v[72:75]
	v_mfma_f32_16x16x32_bf16 v[124:127], v[154:157], v[186:189], v[124:127]
	v_mfma_f32_16x16x32_bf16 v[120:123], v[162:165], v[186:189], v[120:123]
	v_mfma_f32_16x16x32_bf16 v[108:111], v[154:157], v[194:197], v[108:111]
	v_mfma_f32_16x16x32_bf16 v[104:107], v[162:165], v[194:197], v[104:107]
	v_mfma_f32_16x16x32_bf16 v[92:95], v[154:157], v[202:205], v[92:95]
	v_mfma_f32_16x16x32_bf16 v[88:91], v[162:165], v[202:205], v[88:91]
	v_mfma_f32_16x16x32_bf16 v[76:79], v[154:157], v[210:213], v[76:79]
	v_mfma_f32_16x16x32_bf16 v[72:75], v[162:165], v[210:213], v[72:75]
	v_mfma_f32_16x16x32_bf16 v[116:119], v[166:169], v[182:185], v[116:119]
	v_mfma_f32_16x16x32_bf16 v[112:115], v[174:177], v[182:185], v[112:115]
	v_mfma_f32_16x16x32_bf16 v[100:103], v[166:169], v[190:193], v[100:103]
	v_mfma_f32_16x16x32_bf16 v[96:99], v[174:177], v[190:193], v[96:99]
	v_mfma_f32_16x16x32_bf16 v[84:87], v[166:169], v[198:201], v[84:87]
	v_mfma_f32_16x16x32_bf16 v[80:83], v[174:177], v[198:201], v[80:83]
	v_mfma_f32_16x16x32_bf16 v[68:71], v[166:169], v[206:209], v[68:71]
	v_mfma_f32_16x16x32_bf16 v[64:67], v[174:177], v[206:209], v[64:67]
	v_mfma_f32_16x16x32_bf16 v[116:119], v[170:173], v[186:189], v[116:119]
	v_mfma_f32_16x16x32_bf16 v[112:115], v[178:181], v[186:189], v[112:115]
	v_mfma_f32_16x16x32_bf16 v[100:103], v[170:173], v[194:197], v[100:103]
	v_mfma_f32_16x16x32_bf16 v[96:99], v[178:181], v[194:197], v[96:99]
	v_mfma_f32_16x16x32_bf16 v[84:87], v[170:173], v[202:205], v[84:87]
	v_mfma_f32_16x16x32_bf16 v[80:83], v[178:181], v[202:205], v[80:83]
	v_mfma_f32_16x16x32_bf16 v[68:71], v[170:173], v[210:213], v[68:71]
	v_mfma_f32_16x16x32_bf16 v[64:67], v[178:181], v[210:213], v[64:67]
	s_setprio 0
	s_barrier
; #define PG8_STAGE(bufoff, gbase, voff) do { _Pragma("unroll") for (int _i = 0; _i < 2; ++_i) \
;         __builtin_amdgcn_global_load_lds((const unsigned*)((const char*)(gbase) + (voff)[_i]), (LAS unsigned*)(lds + (bufoff) + ldsw + _i * 8192), 16, 0, 0); } while (0)
; #define PG8_LDA(dst, b, h) do { _Pragma("unroll") for (int m = 0; m < 4; ++m) _Pragma("unroll") for (int k = 0; k < 2; ++k) dst[m][k] = *(const LAS bf16x8*)(lds + PG8_SA(b, h) + aoff + m * 2048 + k * 1024); } while (0)
; #define PG8_LDB(dst, b, h) do { _Pragma("unroll") for (int n = 0; n < 2; ++n) _Pragma("unroll") for (int k = 0; k < 2; ++k) dst[n][k] = *(const LAS bf16x8*)(lds + PG8_SB(b, h) + boff + n * 2048 + k * 1024); } while (0)
; #define PG8_MMA(ai, bj, At, Bt) do { __builtin_amdgcn_s_setprio(1); _Pragma("unroll") for (int m = 0; m < 4; ++m) _Pragma("unroll") for (int n = 0; n < 2; ++n) _Pragma("unroll") for (int k = 0; k < 2; ++k) \
;         acc[ai][bj][m][n] = __builtin_amdgcn_mfma_f32_16x16x32_bf16(Bt[n][k], At[m][k], acc[ai][bj][m][n], 0, 0, 0); __builtin_amdgcn_s_setprio(0); } while (0)
; #define PG8_WAIT_V(n) asm volatile("s_waitcnt vmcnt(" #n ")" ::: "memory")
; #define PG8_BAR __builtin_amdgcn_s_barrier()
; template <class Epi, class Sched>
; DI void gemm_phase(LAS unsigned char* lds, const Gemm g, const Sched& S, const Epi& E) {
;     ...
;             PG8_LDB(B0, 0, 0); PG8_LDB(B1, 0, 1); PG8_SCHED; PG8_LDA(At, 0, 0); PG8_STAGE(PG8_SA(1, 1), a1 + hstepA, voffA);
;             PG8_WAIT_V(8); PG8_WAIT_L(0); PG8_BAR; PG8_MMA(0, 0, At, B0); PG8_MMA(0, 1, At, B1); PG8_BAR; PG8_SCHED;
;             PG8_LDA(At, 0, 1); PG8_STAGE(PG8_SB(0, 0), b2, voffB); PG8_STAGE(PG8_SB(0, 1), b2 + hstepB, voffB); PG8_STAGE(PG8_SA(0, 0), a2, voffA);
;             PG8_WAIT_V(8); PG8_WAIT_L(0); PG8_BAR; PG8_MMA(1, 0, At, B0); PG8_MMA(1, 1, At, B1); PG8_BAR; PG8_SCHED;
;             PG8_LDB(B0, 1, 0); PG8_LDB(B1, 1, 1); PG8_SCHED; PG8_LDA(At, 1, 0); PG8_STAGE(PG8_SA(0, 1), a2 + hstepA, voffA);
;             PG8_WAIT_V(8); PG8_WAIT_L(0); PG8_BAR; PG8_MMA(0, 0, At, B0); PG8_MMA(0, 1, At, B1); PG8_BAR; PG8_SCHED;
;             PG8_LDA(At, 1, 1); PG8_STAGE(PG8_SB(1, 0), b3, voffB); PG8_STAGE(PG8_SB(1, 1), b3 + hstepB, voffB); PG8_STAGE(PG8_SA(1, 0), a3, voffA);
;             PG8_WAIT_V(8); PG8_WAIT_L(0); PG8_BAR; PG8_MMA(1, 0, At, B0); PG8_MMA(1, 1, At, B1); PG8_BAR; PG8_SCHED;
;         }
	s_add_i32 s20, s48, s27
	v_lshl_add_u64 v[214:215], v[214:215], 0, s[10:11]
	s_mov_b32 m0, s20
	ds_read_b128 v[182:185], v153 offset:49152
	ds_read_b128 v[186:189], v153 offset:50176
	ds_read_b128 v[190:193], v153 offset:51200
	ds_read_b128 v[194:197], v153 offset:52224
	ds_read_b128 v[198:201], v153 offset:53248
	ds_read_b128 v[202:205], v153 offset:54272
	ds_read_b128 v[206:209], v153 offset:55296
	ds_read_b128 v[210:213], v153 offset:56320
	global_load_lds_dwordx4 v[214:215], off
	s_add_i32 m0, s20, 0x2000
	s_add_u32 s18, s18, 0xb0080
	v_lshl_add_u64 v[214:215], v[216:217], 0, s[10:11]
	s_addc_u32 s19, s19, 0
	s_add_i32 s20, s49, s27
	global_load_lds_dwordx4 v[214:215], off
	s_mov_b32 m0, s20
	s_nop 0
	global_load_lds_dwordx4 v130, s[18:19]
	s_add_i32 m0, s20, 0x2000
	s_nop 0
	global_load_lds_dwordx4 v134, s[18:19]
	v_lshl_add_u64 v[214:215], v[218:219], 0, s[10:11]
	s_mov_b32 m0, s36
	s_nop 0
	global_load_lds_dwordx4 v[214:215], off
	v_lshl_add_u64 v[214:215], v[220:221], 0, s[10:11]
	s_mov_b32 m0, s37
	s_nop 0
	global_load_lds_dwordx4 v[214:215], off
	s_waitcnt vmcnt(8)
	s_waitcnt lgkmcnt(0)
	s_barrier
	s_setprio 1
	v_mfma_f32_16x16x32_bf16 v[60:63], v[144:147], v[182:185], v[60:63]
	v_mfma_f32_16x16x32_bf16 v[56:59], v[158:161], v[182:185], v[56:59]
	v_mfma_f32_16x16x32_bf16 v[44:47], v[144:147], v[190:193], v[44:47]
	v_mfma_f32_16x16x32_bf16 v[40:43], v[158:161], v[190:193], v[40:43]
	v_mfma_f32_16x16x32_bf16 v[28:31], v[144:147], v[198:201], v[28:31]
	v_mfma_f32_16x16x32_bf16 v[24:27], v[158:161], v[198:201], v[24:27]
	v_mfma_f32_16x16x32_bf16 v[12:15], v[144:147], v[206:209], v[12:15]
	v_mfma_f32_16x16x32_bf16 v[8:11], v[158:161], v[206:209], v[8:11]
	v_mfma_f32_16x16x32_bf16 v[60:63], v[154:157], v[186:189], v[60:63]
	v_mfma_f32_16x16x32_bf16 v[56:59], v[162:165], v[186:189], v[56:59]
	v_mfma_f32_16x16x32_bf16 v[44:47], v[154:157], v[194:197], v[44:47]
	v_mfma_f32_16x16x32_bf16 v[40:43], v[162:165], v[194:197], v[40:43]
	v_mfma_f32_16x16x32_bf16 v[28:31], v[154:157], v[202:205], v[28:31]
	v_mfma_f32_16x16x32_bf16 v[24:27], v[162:165], v[202:205], v[24:27]
	v_mfma_f32_16x16x32_bf16 v[12:15], v[154:157], v[210:213], v[12:15]
	v_mfma_f32_16x16x32_bf16 v[8:11], v[162:165], v[210:213], v[8:11]
	v_mfma_f32_16x16x32_bf16 v[52:55], v[166:169], v[182:185], v[52:55]
	v_mfma_f32_16x16x32_bf16 v[48:51], v[174:177], v[182:185], v[48:51]
	v_mfma_f32_16x16x32_bf16 v[36:39], v[166:169], v[190:193], v[36:39]
	v_mfma_f32_16x16x32_bf16 v[32:35], v[174:177], v[190:193], v[32:35]
	v_mfma_f32_16x16x32_bf16 v[20:23], v[166:169], v[198:201], v[20:23]
	v_mfma_f32_16x16x32_bf16 v[16:19], v[174:177], v[198:201], v[16:19]
	v_mfma_f32_16x16x32_bf16 v[4:7], v[166:169], v[206:209], v[4:7]
	v_mfma_f32_16x16x32_bf16 v[0:3], v[174:177], v[206:209], v[0:3]
	v_mfma_f32_16x16x32_bf16 v[52:55], v[170:173], v[186:189], v[52:55]
	v_mfma_f32_16x16x32_bf16 v[48:51], v[178:181], v[186:189], v[48:51]
	v_mfma_f32_16x16x32_bf16 v[36:39], v[170:173], v[194:197], v[36:39]
	v_mfma_f32_16x16x32_bf16 v[32:35], v[178:181], v[194:197], v[32:35]
	v_mfma_f32_16x16x32_bf16 v[20:23], v[170:173], v[202:205], v[20:23]
	v_mfma_f32_16x16x32_bf16 v[16:19], v[178:181], v[202:205], v[16:19]
	v_mfma_f32_16x16x32_bf16 v[4:7], v[170:173], v[210:213], v[4:7]
	v_mfma_f32_16x16x32_bf16 v[0:3], v[178:181], v[210:213], v[0:3]
	s_setprio 0
	s_barrier
	s_add_i32 s47, s47, 2
	s_add_u32 s16, s16, 0x100
	s_addc_u32 s17, s17, 0
	s_add_u32 s45, s45, 0x100
	s_addc_u32 s46, s46, 0
	s_cmp_gt_u32 s47, 41
.LBB0_1331:
	ds_read_b128 v[144:147], v151
	ds_read_b128 v[154:157], v151 offset:1024
	ds_read_b128 v[158:161], v151 offset:2048
	ds_read_b128 v[162:165], v151 offset:3072
	ds_read_b128 v[166:169], v152
	ds_read_b128 v[170:173], v152 offset:1024
	ds_read_b128 v[174:177], v152 offset:2048
	ds_read_b128 v[178:181], v152 offset:3072
	s_add_u32 s18, s16, 0xfff50080
	s_addc_u32 s19, s17, -1
	s_cmp_eq_u32 s47, 40
	s_cselect_b32 s21, s5, s19
	s_cselect_b32 s20, s4, s18
	s_cselect_b32 s19, s15, s46
	s_cselect_b32 s18, s14, s45
	s_add_i32 m0, s28, 0xc000
	ds_read_b128 v[182:185], v153
	ds_read_b128 v[186:189], v153 offset:1024
	ds_read_b128 v[190:193], v153 offset:2048
	ds_read_b128 v[194:197], v153 offset:3072
	ds_read_b128 v[198:201], v153 offset:4096
	ds_read_b128 v[202:205], v153 offset:5120
	ds_read_b128 v[206:209], v153 offset:6144
	ds_read_b128 v[210:213], v153 offset:7168
	global_load_lds_dwordx4 v136, s[16:17]
	s_add_i32 m0, s28, 0xe000
	s_nop 0
	global_load_lds_dwordx4 v138, s[16:17]
	s_waitcnt vmcnt(8)
	s_waitcnt lgkmcnt(0)
	s_barrier
; #define PG8_STAGE(bufoff, gbase, voff) do { _Pragma("unroll") for (int _i = 0; _i < 2; ++_i) \
;         __builtin_amdgcn_global_load_lds((const unsigned*)((const char*)(gbase) + (voff)[_i]), (LAS unsigned*)(lds + (bufoff) + ldsw + _i * 8192), 16, 0, 0); } while (0)
; #define PG8_LDA(dst, b, h) do { _Pragma("unroll") for (int m = 0; m < 4; ++m) _Pragma("unroll") for (int k = 0; k < 2; ++k) dst[m][k] = *(const LAS bf16x8*)(lds + PG8_SA(b, h) + aoff + m * 2048 + k * 1024); } while (0)
; #define PG8_MMA(ai, bj, At, Bt) do { __builtin_amdgcn_s_setprio(1); _Pragma("unroll") for (int m = 0; m < 4; ++m) _Pragma("unroll") for (int n = 0; n < 2; ++n) _Pragma("unroll") for (int k = 0; k < 2; ++k) \
;         acc[ai][bj][m][n] = __builtin_amdgcn_mfma_f32_16x16x32_bf16(Bt[n][k], At[m][k], acc[ai][bj][m][n], 0, 0, 0); __builtin_amdgcn_s_setprio(0); } while (0)
; #define PG8_WAIT_V(n) asm volatile("s_waitcnt vmcnt(" #n ")" ::: "memory")
; #define PG8_WAIT_L(n) asm volatile("s_waitcnt lgkmcnt(" #n ")" ::: "memory")
; #define PG8_BAR __builtin_amdgcn_s_barrier()
; #define PG8_SCHED __builtin_amdgcn_sched_barrier(0)
; template <class Epi, class Sched>
; DI void gemm_phase(LAS unsigned char* lds, const Gemm g, const Sched& S, const Epi& E) {
;     ...
;             PG8_WAIT_V(8); PG8_WAIT_L(0); PG8_BAR; PG8_MMA(0, 0, At, B0); PG8_MMA(0, 1, At, B1); PG8_BAR; PG8_SCHED;
;             PG8_LDA(At, 0, 1); PG8_STAGE(PG8_SB(0, 0), b2, voffB); PG8_STAGE(PG8_SB(0, 1), b2 + hstepB, voffB); PG8_STAGE(PG8_SA(0, 0), a2, voffA);
;             PG8_WAIT_V(8); PG8_WAIT_L(0); PG8_BAR; PG8_MMA(1, 0, At, B0); PG8_MMA(1, 1, At, B1); PG8_BAR; PG8_SCHED;
	s_setprio 1
	v_mfma_f32_16x16x32_bf16 v[124:127], v[144:147], v[182:185], v[124:127]
	v_mfma_f32_16x16x32_bf16 v[120:123], v[158:161], v[182:185], v[120:123]
	v_mfma_f32_16x16x32_bf16 v[108:111], v[144:147], v[190:193], v[108:111]
	v_mfma_f32_16x16x32_bf16 v[104:107], v[158:161], v[190:193], v[104:107]
	v_mfma_f32_16x16x32_bf16 v[92:95], v[144:147], v[198:201], v[92:95]
	v_mfma_f32_16x16x32_bf16 v[88:91], v[158:161], v[198:201], v[88:91]
	v_mfma_f32_16x16x32_bf16 v[76:79], v[144:147], v[206:209], v[76:79]
	v_mfma_f32_16x16x32_bf16 v[72:75], v[158:161], v[206:209], v[72:75]
	v_mfma_f32_16x16x32_bf16 v[124:127], v[154:157], v[186:189], v[124:127]
	v_mfma_f32_16x16x32_bf16 v[120:123], v[162:165], v[186:189], v[120:123]
	v_mfma_f32_16x16x32_bf16 v[108:111], v[154:157], v[194:197], v[108:111]
	v_mfma_f32_16x16x32_bf16 v[104:107], v[162:165], v[194:197], v[104:107]
	v_mfma_f32_16x16x32_bf16 v[92:95], v[154:157], v[202:205], v[92:95]
	v_mfma_f32_16x16x32_bf16 v[88:91], v[162:165], v[202:205], v[88:91]
	v_mfma_f32_16x16x32_bf16 v[76:79], v[154:157], v[210:213], v[76:79]
	v_mfma_f32_16x16x32_bf16 v[72:75], v[162:165], v[210:213], v[72:75]
	v_mfma_f32_16x16x32_bf16 v[116:119], v[166:169], v[182:185], v[116:119]
	v_mfma_f32_16x16x32_bf16 v[112:115], v[174:177], v[182:185], v[112:115]
	v_mfma_f32_16x16x32_bf16 v[100:103], v[166:169], v[190:193], v[100:103]
	v_mfma_f32_16x16x32_bf16 v[96:99], v[174:177], v[190:193], v[96:99]
	v_mfma_f32_16x16x32_bf16 v[84:87], v[166:169], v[198:201], v[84:87]
	v_mfma_f32_16x16x32_bf16 v[80:83], v[174:177], v[198:201], v[80:83]
	v_mfma_f32_16x16x32_bf16 v[68:71], v[166:169], v[206:209], v[68:71]
	v_mfma_f32_16x16x32_bf16 v[64:67], v[174:177], v[206:209], v[64:67]
	v_mfma_f32_16x16x32_bf16 v[116:119], v[170:173], v[186:189], v[116:119]
	v_mfma_f32_16x16x32_bf16 v[112:115], v[178:181], v[186:189], v[112:115]
	v_mfma_f32_16x16x32_bf16 v[100:103], v[170:173], v[194:197], v[100:103]
	v_mfma_f32_16x16x32_bf16 v[96:99], v[178:181], v[194:197], v[96:99]
	v_mfma_f32_16x16x32_bf16 v[84:87], v[170:173], v[202:205], v[84:87]
	v_mfma_f32_16x16x32_bf16 v[80:83], v[178:181], v[202:205], v[80:83]
	v_mfma_f32_16x16x32_bf16 v[68:71], v[170:173], v[210:213], v[68:71]
	v_mfma_f32_16x16x32_bf16 v[64:67], v[178:181], v[210:213], v[64:67]
	s_setprio 0
	s_barrier
	s_add_i32 s48, s39, s27
	v_lshl_add_u64 v[214:215], s[18:19], 0, v[130:131]
	s_mov_b32 m0, s48
	ds_read_b128 v[182:185], v153 offset:16384
	ds_read_b128 v[186:189], v153 offset:17408
	ds_read_b128 v[190:193], v153 offset:18432
	ds_read_b128 v[194:197], v153 offset:19456
	ds_read_b128 v[198:201], v153 offset:20480
	ds_read_b128 v[202:205], v153 offset:21504
	ds_read_b128 v[206:209], v153 offset:22528
	ds_read_b128 v[210:213], v153 offset:23552
	global_load_lds_dwordx4 v[214:215], off
	s_add_i32 m0, s48, 0x2000
	s_add_u32 s48, s18, 0xb0000
	v_lshl_add_u64 v[216:217], s[18:19], 0, v[134:135]
	s_addc_u32 s49, s19, 0
	s_add_i32 s50, s40, s27
	global_load_lds_dwordx4 v[216:217], off
	s_mov_b32 m0, s50
	v_lshl_add_u64 v[220:221], s[20:21], 0, v[132:133]
	global_load_lds_dwordx4 v130, s[48:49]
	s_add_i32 m0, s50, 0x2000
	s_nop 0
	global_load_lds_dwordx4 v134, s[48:49]
	v_lshl_add_u64 v[218:219], s[20:21], 0, v[128:129]
	s_mov_b32 m0, s28
	s_nop 0
	global_load_lds_dwordx4 v[218:219], off
	s_mov_b32 m0, s29
	s_nop 0
	global_load_lds_dwordx4 v[220:221], off
	s_waitcnt vmcnt(8)
	s_waitcnt lgkmcnt(0)
	s_barrier
	s_setprio 1
	v_mfma_f32_16x16x32_bf16 v[60:63], v[144:147], v[182:185], v[60:63]
	v_mfma_f32_16x16x32_bf16 v[56:59], v[158:161], v[182:185], v[56:59]
	v_mfma_f32_16x16x32_bf16 v[44:47], v[144:147], v[190:193], v[44:47]
	v_mfma_f32_16x16x32_bf16 v[40:43], v[158:161], v[190:193], v[40:43]
	v_mfma_f32_16x16x32_bf16 v[28:31], v[144:147], v[198:201], v[28:31]
	v_mfma_f32_16x16x32_bf16 v[24:27], v[158:161], v[198:201], v[24:27]
	v_mfma_f32_16x16x32_bf16 v[12:15], v[144:147], v[206:209], v[12:15]
	v_mfma_f32_16x16x32_bf16 v[8:11], v[158:161], v[206:209], v[8:11]
	v_mfma_f32_16x16x32_bf16 v[60:63], v[154:157], v[186:189], v[60:63]
	v_mfma_f32_16x16x32_bf16 v[56:59], v[162:165], v[186:189], v[56:59]
	v_mfma_f32_16x16x32_bf16 v[44:47], v[154:157], v[194:197], v[44:47]
	v_mfma_f32_16x16x32_bf16 v[40:43], v[162:165], v[194:197], v[40:43]
	v_mfma_f32_16x16x32_bf16 v[28:31], v[154:157], v[202:205], v[28:31]
	v_mfma_f32_16x16x32_bf16 v[24:27], v[162:165], v[202:205], v[24:27]
	v_mfma_f32_16x16x32_bf16 v[12:15], v[154:157], v[210:213], v[12:15]
	v_mfma_f32_16x16x32_bf16 v[8:11], v[162:165], v[210:213], v[8:11]
	v_mfma_f32_16x16x32_bf16 v[52:55], v[166:169], v[182:185], v[52:55]
	v_mfma_f32_16x16x32_bf16 v[48:51], v[174:177], v[182:185], v[48:51]
	v_mfma_f32_16x16x32_bf16 v[36:39], v[166:169], v[190:193], v[36:39]
	v_mfma_f32_16x16x32_bf16 v[32:35], v[174:177], v[190:193], v[32:35]
	v_mfma_f32_16x16x32_bf16 v[20:23], v[166:169], v[198:201], v[20:23]
	v_mfma_f32_16x16x32_bf16 v[16:19], v[174:177], v[198:201], v[16:19]
	v_mfma_f32_16x16x32_bf16 v[4:7], v[166:169], v[206:209], v[4:7]
	v_mfma_f32_16x16x32_bf16 v[0:3], v[174:177], v[206:209], v[0:3]
	v_mfma_f32_16x16x32_bf16 v[52:55], v[170:173], v[186:189], v[52:55]
	v_mfma_f32_16x16x32_bf16 v[48:51], v[178:181], v[186:189], v[48:51]
	v_mfma_f32_16x16x32_bf16 v[36:39], v[170:173], v[194:197], v[36:39]
	v_mfma_f32_16x16x32_bf16 v[32:35], v[178:181], v[194:197], v[32:35]
	v_mfma_f32_16x16x32_bf16 v[20:23], v[170:173], v[202:205], v[20:23]
	v_mfma_f32_16x16x32_bf16 v[16:19], v[178:181], v[202:205], v[16:19]
	v_mfma_f32_16x16x32_bf16 v[4:7], v[170:173], v[210:213], v[4:7]
	v_mfma_f32_16x16x32_bf16 v[0:3], v[178:181], v[210:213], v[0:3]
	s_setprio 0
	s_barrier
; #define PG8_STAGE(bufoff, gbase, voff) do { _Pragma("unroll") for (int _i = 0; _i < 2; ++_i) \
;         __builtin_amdgcn_global_load_lds((const unsigned*)((const char*)(gbase) + (voff)[_i]), (LAS unsigned*)(lds + (bufoff) + ldsw + _i * 8192), 16, 0, 0); } while (0)
; #define PG8_LDA(dst, b, h) do { _Pragma("unroll") for (int m = 0; m < 4; ++m) _Pragma("unroll") for (int k = 0; k < 2; ++k) dst[m][k] = *(const LAS bf16x8*)(lds + PG8_SA(b, h) + aoff + m * 2048 + k * 1024); } while (0)
; #define PG8_LDB(dst, b, h) do { _Pragma("unroll") for (int n = 0; n < 2; ++n) _Pragma("unroll") for (int k = 0; k < 2; ++k) dst[n][k] = *(const LAS bf16x8*)(lds + PG8_SB(b, h) + boff + n * 2048 + k * 1024); } while (0)
; #define PG8_MMA(ai, bj, At, Bt) do { __builtin_amdgcn_s_setprio(1); _Pragma("unroll") for (int m = 0; m < 4; ++m) _Pragma("unroll") for (int n = 0; n < 2; ++n) _Pragma("unroll") for (int k = 0; k < 2; ++k) \
;         acc[ai][bj][m][n] = __builtin_amdgcn_mfma_f32_16x16x32_bf16(Bt[n][k], At[m][k], acc[ai][bj][m][n], 0, 0, 0); __builtin_amdgcn_s_setprio(0); } while (0)
; #define PG8_WAIT_V(n) asm volatile("s_waitcnt vmcnt(" #n ")" ::: "memory")
; #define PG8_WAIT_L(n) asm volatile("s_waitcnt lgkmcnt(" #n ")" ::: "memory")
; #define PG8_BAR __builtin_amdgcn_s_barrier()
; #define PG8_SCHED __builtin_amdgcn_sched_barrier(0)
; template <class Epi, class Sched>
; DI void gemm_phase(LAS unsigned char* lds, const Gemm g, const Sched& S, const Epi& E) {
;     ...
;             PG8_LDB(B0, 1, 0); PG8_LDB(B1, 1, 1); PG8_SCHED; PG8_LDA(At, 1, 0); PG8_STAGE(PG8_SA(0, 1), a2 + hstepA, voffA);
;             PG8_WAIT_V(8); PG8_WAIT_L(0); PG8_BAR; PG8_MMA(0, 0, At, B0); PG8_MMA(0, 1, At, B1); PG8_BAR; PG8_SCHED;
;             PG8_LDA(At, 1, 1); PG8_STAGE(PG8_SB(1, 0), b3, voffB); PG8_STAGE(PG8_SB(1, 1), b3 + hstepB, voffB); PG8_STAGE(PG8_SA(1, 0), a3, voffA);
;             PG8_WAIT_V(8); PG8_WAIT_L(0); PG8_BAR; PG8_MMA(1, 0, At, B0); PG8_MMA(1, 1, At, B1); PG8_BAR; PG8_SCHED;
;         }
;         if (wr == 0) PG8_BAR;
	s_add_i32 s48, 0, 0x18000
	s_add_i32 s49, 0, 0x1c000
	v_add_u32_e32 v162, s48, v149
	v_add_u32_e32 v178, s49, v149
	ds_read_b128 v[144:147], v162
	ds_read_b128 v[154:157], v162 offset:1024
	ds_read_b128 v[158:161], v162 offset:2048
	ds_read_b128 v[162:165], v162 offset:3072
	ds_read_b128 v[166:169], v178
	ds_read_b128 v[170:173], v178 offset:1024
	ds_read_b128 v[174:177], v178 offset:2048
	ds_read_b128 v[178:181], v178 offset:3072
	s_add_u32 s20, s20, 0xb0000
	s_addc_u32 s21, s21, 0
	s_mov_b32 m0, s33
	ds_read_b128 v[182:185], v153 offset:32768
	ds_read_b128 v[186:189], v153 offset:33792
	ds_read_b128 v[190:193], v153 offset:34816
	ds_read_b128 v[194:197], v153 offset:35840
	ds_read_b128 v[198:201], v153 offset:36864
	ds_read_b128 v[202:205], v153 offset:37888
	ds_read_b128 v[206:209], v153 offset:38912
	ds_read_b128 v[210:213], v153 offset:39936
	global_load_lds_dwordx4 v128, s[20:21]
	s_mov_b32 m0, s34
	s_nop 0
	global_load_lds_dwordx4 v132, s[20:21]
	s_waitcnt vmcnt(8)
	s_waitcnt lgkmcnt(0)
	s_barrier
	s_setprio 1
	v_mfma_f32_16x16x32_bf16 v[124:127], v[144:147], v[182:185], v[124:127]
	v_mfma_f32_16x16x32_bf16 v[120:123], v[158:161], v[182:185], v[120:123]
	v_mfma_f32_16x16x32_bf16 v[108:111], v[144:147], v[190:193], v[108:111]
	v_mfma_f32_16x16x32_bf16 v[104:107], v[158:161], v[190:193], v[104:107]
	v_mfma_f32_16x16x32_bf16 v[92:95], v[144:147], v[198:201], v[92:95]
	v_mfma_f32_16x16x32_bf16 v[88:91], v[158:161], v[198:201], v[88:91]
	v_mfma_f32_16x16x32_bf16 v[76:79], v[144:147], v[206:209], v[76:79]
	v_mfma_f32_16x16x32_bf16 v[72:75], v[158:161], v[206:209], v[72:75]
	v_mfma_f32_16x16x32_bf16 v[124:127], v[154:157], v[186:189], v[124:127]
	v_mfma_f32_16x16x32_bf16 v[120:123], v[162:165], v[186:189], v[120:123]
	v_mfma_f32_16x16x32_bf16 v[108:111], v[154:157], v[194:197], v[108:111]
	v_mfma_f32_16x16x32_bf16 v[104:107], v[162:165], v[194:197], v[104:107]
	v_mfma_f32_16x16x32_bf16 v[92:95], v[154:157], v[202:205], v[92:95]
	v_mfma_f32_16x16x32_bf16 v[88:91], v[162:165], v[202:205], v[88:91]
	v_mfma_f32_16x16x32_bf16 v[76:79], v[154:157], v[210:213], v[76:79]
	v_mfma_f32_16x16x32_bf16 v[72:75], v[162:165], v[210:213], v[72:75]
	v_mfma_f32_16x16x32_bf16 v[116:119], v[166:169], v[182:185], v[116:119]
	v_mfma_f32_16x16x32_bf16 v[112:115], v[174:177], v[182:185], v[112:115]
	v_mfma_f32_16x16x32_bf16 v[100:103], v[166:169], v[190:193], v[100:103]
	v_mfma_f32_16x16x32_bf16 v[96:99], v[174:177], v[190:193], v[96:99]
	v_mfma_f32_16x16x32_bf16 v[84:87], v[166:169], v[198:201], v[84:87]
	v_mfma_f32_16x16x32_bf16 v[80:83], v[174:177], v[198:201], v[80:83]
	v_mfma_f32_16x16x32_bf16 v[68:71], v[166:169], v[206:209], v[68:71]
	v_mfma_f32_16x16x32_bf16 v[64:67], v[174:177], v[206:209], v[64:67]
	v_mfma_f32_16x16x32_bf16 v[116:119], v[170:173], v[186:189], v[116:119]
	v_mfma_f32_16x16x32_bf16 v[112:115], v[178:181], v[186:189], v[112:115]
	v_mfma_f32_16x16x32_bf16 v[100:103], v[170:173], v[194:197], v[100:103]
	v_mfma_f32_16x16x32_bf16 v[96:99], v[178:181], v[194:197], v[96:99]
	v_mfma_f32_16x16x32_bf16 v[84:87], v[170:173], v[202:205], v[84:87]
	v_mfma_f32_16x16x32_bf16 v[80:83], v[178:181], v[202:205], v[80:83]
	v_mfma_f32_16x16x32_bf16 v[68:71], v[170:173], v[210:213], v[68:71]
	v_mfma_f32_16x16x32_bf16 v[64:67], v[178:181], v[210:213], v[64:67]
	s_setprio 0
	s_barrier
	s_add_i32 s20, s48, s27
	v_lshl_add_u64 v[214:215], v[214:215], 0, s[10:11]
	s_mov_b32 m0, s20
	ds_read_b128 v[182:185], v153 offset:49152
	ds_read_b128 v[186:189], v153 offset:50176
	ds_read_b128 v[190:193], v153 offset:51200
	ds_read_b128 v[194:197], v153 offset:52224
	ds_read_b128 v[198:201], v153 offset:53248
	ds_read_b128 v[202:205], v153 offset:54272
	ds_read_b128 v[206:209], v153 offset:55296
	ds_read_b128 v[210:213], v153 offset:56320
	global_load_lds_dwordx4 v[214:215], off
	s_add_i32 m0, s20, 0x2000
	s_add_u32 s18, s18, 0xb0080
	v_lshl_add_u64 v[214:215], v[216:217], 0, s[10:11]
	s_addc_u32 s19, s19, 0
	s_add_i32 s20, s49, s27
	global_load_lds_dwordx4 v[214:215], off
	s_mov_b32 m0, s20
	s_nop 0
	global_load_lds_dwordx4 v130, s[18:19]
	s_add_i32 m0, s20, 0x2000
	s_nop 0
	global_load_lds_dwordx4 v134, s[18:19]
	v_lshl_add_u64 v[214:215], v[218:219], 0, s[10:11]
	s_mov_b32 m0, s36
	s_nop 0
	global_load_lds_dwordx4 v[214:215], off
	v_lshl_add_u64 v[214:215], v[220:221], 0, s[10:11]
	s_mov_b32 m0, s37
	s_nop 0
	global_load_lds_dwordx4 v[214:215], off
	s_waitcnt vmcnt(8)
	s_waitcnt lgkmcnt(0)
	s_barrier
	s_setprio 1
	v_mfma_f32_16x16x32_bf16 v[60:63], v[144:147], v[182:185], v[60:63]
	v_mfma_f32_16x16x32_bf16 v[56:59], v[158:161], v[182:185], v[56:59]
	v_mfma_f32_16x16x32_bf16 v[44:47], v[144:147], v[190:193], v[44:47]
	v_mfma_f32_16x16x32_bf16 v[40:43], v[158:161], v[190:193], v[40:43]
	v_mfma_f32_16x16x32_bf16 v[28:31], v[144:147], v[198:201], v[28:31]
	v_mfma_f32_16x16x32_bf16 v[24:27], v[158:161], v[198:201], v[24:27]
	v_mfma_f32_16x16x32_bf16 v[12:15], v[144:147], v[206:209], v[12:15]
	v_mfma_f32_16x16x32_bf16 v[8:11], v[158:161], v[206:209], v[8:11]
	v_mfma_f32_16x16x32_bf16 v[60:63], v[154:157], v[186:189], v[60:63]
	v_mfma_f32_16x16x32_bf16 v[56:59], v[162:165], v[186:189], v[56:59]
	v_mfma_f32_16x16x32_bf16 v[44:47], v[154:157], v[194:197], v[44:47]
	v_mfma_f32_16x16x32_bf16 v[40:43], v[162:165], v[194:197], v[40:43]
	v_mfma_f32_16x16x32_bf16 v[28:31], v[154:157], v[202:205], v[28:31]
	v_mfma_f32_16x16x32_bf16 v[24:27], v[162:165], v[202:205], v[24:27]
	v_mfma_f32_16x16x32_bf16 v[12:15], v[154:157], v[210:213], v[12:15]
	v_mfma_f32_16x16x32_bf16 v[8:11], v[162:165], v[210:213], v[8:11]
	v_mfma_f32_16x16x32_bf16 v[52:55], v[166:169], v[182:185], v[52:55]
	v_mfma_f32_16x16x32_bf16 v[48:51], v[174:177], v[182:185], v[48:51]
	v_mfma_f32_16x16x32_bf16 v[36:39], v[166:169], v[190:193], v[36:39]
	v_mfma_f32_16x16x32_bf16 v[32:35], v[174:177], v[190:193], v[32:35]
	v_mfma_f32_16x16x32_bf16 v[20:23], v[166:169], v[198:201], v[20:23]
	v_mfma_f32_16x16x32_bf16 v[16:19], v[174:177], v[198:201], v[16:19]
	v_mfma_f32_16x16x32_bf16 v[4:7], v[166:169], v[206:209], v[4:7]
	v_mfma_f32_16x16x32_bf16 v[0:3], v[174:177], v[206:209], v[0:3]
	v_mfma_f32_16x16x32_bf16 v[52:55], v[170:173], v[186:189], v[52:55]
	v_mfma_f32_16x16x32_bf16 v[48:51], v[178:181], v[186:189], v[48:51]
	v_mfma_f32_16x16x32_bf16 v[36:39], v[170:173], v[194:197], v[36:39]
	v_mfma_f32_16x16x32_bf16 v[32:35], v[178:181], v[194:197], v[32:35]
	v_mfma_f32_16x16x32_bf16 v[20:23], v[170:173], v[202:205], v[20:23]
	v_mfma_f32_16x16x32_bf16 v[16:19], v[178:181], v[202:205], v[16:19]
	v_mfma_f32_16x16x32_bf16 v[4:7], v[170:173], v[210:213], v[4:7]
	v_mfma_f32_16x16x32_bf16 v[0:3], v[178:181], v[210:213], v[0:3]
	s_setprio 0
	s_barrier
	s_add_i32 s47, s47, 2
	s_add_u32 s16, s16, 0x100
	s_addc_u32 s17, s17, 0
	s_add_u32 s45, s45, 0x100
	s_addc_u32 s46, s46, 0
	s_cmp_gt_u32 s47, 41
	s_cbranch_scc0 .LBB0_1331
	s_mov_b32 s99, 1
	s_and_b64 vcc, exec, s[12:13]
	s_cbranch_vccz .LBB0_1334
	s_barrier
